# v27 + non-aligned epilogues on all 14 GEMMs + barrier signalled one MFMA early + post-MFMA priority 2
# speedup vs baseline: 1.0076x; 1.0027x over previous
.Lpeel_13:
	ds_read_b128 v[152:155], v149
	ds_read_b128 v[156:159], v149 offset:1024
	s_add_i32 s37, s25, 2
	s_add_u32 s40, s38, 0xfff80080
	s_addc_u32 s41, s39, -1
	s_cmp_eq_u32 s36, s25
	s_cselect_b32 s43, s27, s41
	s_cselect_b32 s42, s26, s40
	s_cselect_b32 s41, s29, s23
	s_cselect_b32 s40, s28, s21
	v_lshl_add_u64 v[144:145], s[38:39], 0, v[140:141]
	s_add_i32 m0, s35, 0xc000
	global_load_lds_dwordx4 v[144:145], off
	v_lshl_add_u64 v[144:145], s[38:39], 0, v[142:143]
	s_add_i32 m0, s35, 0xe000
	s_nop 0
	global_load_lds_dwordx4 v[144:145], off
	s_waitcnt vmcnt(8)
	s_waitcnt lgkmcnt(0)
	s_barrier
	s_setprio 1
	s_waitcnt lgkmcnt(0)
	v_mfma_f32_16x16x32_bf16 v[126:129], v[152:155], v[184:187], 0
	v_mfma_f32_16x16x32_bf16 v[122:125], v[160:163], v[184:187], 0
	v_mfma_f32_16x16x32_bf16 v[110:113], v[152:155], v[196:199], 0
	v_mfma_f32_16x16x32_bf16 v[106:109], v[160:163], v[196:199], 0
	v_mfma_f32_16x16x32_bf16 v[94:97], v[152:155], v[204:207], 0
	v_mfma_f32_16x16x32_bf16 v[90:93], v[160:163], v[204:207], 0
	v_mfma_f32_16x16x32_bf16 v[78:81], v[152:155], v[212:215], 0
	v_mfma_f32_16x16x32_bf16 v[74:77], v[160:163], v[212:215], 0
	v_mfma_f32_16x16x32_bf16 v[126:129], v[156:159], v[188:191], v[126:129]
	v_mfma_f32_16x16x32_bf16 v[122:125], v[164:167], v[188:191], v[122:125]
	v_mfma_f32_16x16x32_bf16 v[110:113], v[156:159], v[200:203], v[110:113]
	v_mfma_f32_16x16x32_bf16 v[106:109], v[164:167], v[200:203], v[106:109]
	v_mfma_f32_16x16x32_bf16 v[94:97], v[156:159], v[208:211], v[94:97]
	v_mfma_f32_16x16x32_bf16 v[90:93], v[164:167], v[208:211], v[90:93]
	v_mfma_f32_16x16x32_bf16 v[78:81], v[156:159], v[216:219], v[78:81]
	v_mfma_f32_16x16x32_bf16 v[74:77], v[164:167], v[216:219], v[74:77]
	v_mfma_f32_16x16x32_bf16 v[118:121], v[168:171], v[184:187], 0
	v_mfma_f32_16x16x32_bf16 v[114:117], v[176:179], v[184:187], 0
	v_mfma_f32_16x16x32_bf16 v[102:105], v[168:171], v[196:199], 0
	v_mfma_f32_16x16x32_bf16 v[98:101], v[176:179], v[196:199], 0
	v_mfma_f32_16x16x32_bf16 v[86:89], v[168:171], v[204:207], 0
	v_mfma_f32_16x16x32_bf16 v[82:85], v[176:179], v[204:207], 0
	v_mfma_f32_16x16x32_bf16 v[70:73], v[168:171], v[212:215], 0
	v_mfma_f32_16x16x32_bf16 v[66:69], v[176:179], v[212:215], 0
	v_mfma_f32_16x16x32_bf16 v[118:121], v[172:175], v[188:191], v[118:121]
	v_mfma_f32_16x16x32_bf16 v[114:117], v[180:183], v[188:191], v[114:117]
	v_mfma_f32_16x16x32_bf16 v[102:105], v[172:175], v[200:203], v[102:105]
	v_mfma_f32_16x16x32_bf16 v[98:101], v[180:183], v[200:203], v[98:101]
	v_mfma_f32_16x16x32_bf16 v[86:89], v[172:175], v[208:211], v[86:89]
	v_mfma_f32_16x16x32_bf16 v[82:85], v[180:183], v[208:211], v[82:85]
	v_mfma_f32_16x16x32_bf16 v[70:73], v[172:175], v[216:219], v[70:73]
	s_barrier
	v_mfma_f32_16x16x32_bf16 v[66:69], v[180:183], v[216:219], v[66:69]
	s_setprio 2
	s_add_i32 s25, s54, s33
	v_lshl_add_u64 v[144:145], s[40:41], 0, v[132:133]
	s_mov_b32 m0, s25
	ds_read_b128 v[184:187], v151 offset:16384
	ds_read_b128 v[188:191], v151 offset:17408
	ds_read_b128 v[196:199], v151 offset:18432
	ds_read_b128 v[200:203], v151 offset:19456
	ds_read_b128 v[204:207], v151 offset:20480
	ds_read_b128 v[208:211], v151 offset:21504
	ds_read_b128 v[212:215], v151 offset:22528
	ds_read_b128 v[216:219], v151 offset:23552
	global_load_lds_dwordx4 v[144:145], off
	s_add_i32 m0, s25, 0x2000
	s_add_u32 s44, s40, 0x80000
	v_lshl_add_u64 v[192:193], s[40:41], 0, v[136:137]
	s_addc_u32 s45, s41, 0
	s_add_i32 s25, s55, s33
	global_load_lds_dwordx4 v[192:193], off
	v_lshl_add_u64 v[220:221], s[44:45], 0, v[132:133]
	s_mov_b32 m0, s25
	v_lshl_add_u64 v[222:223], s[42:43], 0, v[134:135]
	global_load_lds_dwordx4 v[220:221], off
	v_lshl_add_u64 v[220:221], s[44:45], 0, v[136:137]
	s_add_i32 m0, s25, 0x2000
	s_nop 0
	global_load_lds_dwordx4 v[220:221], off
	v_lshl_add_u64 v[220:221], s[42:43], 0, v[130:131]
	s_mov_b32 m0, s35
	s_nop 0
	global_load_lds_dwordx4 v[220:221], off
	s_mov_b32 m0, s47
	s_nop 0
	global_load_lds_dwordx4 v[222:223], off
	s_waitcnt vmcnt(8)
	s_waitcnt lgkmcnt(0)
	s_barrier
	s_setprio 1
	s_waitcnt lgkmcnt(0)
	v_mfma_f32_16x16x32_bf16 v[62:65], v[152:155], v[184:187], 0
	v_mfma_f32_16x16x32_bf16 v[58:61], v[160:163], v[184:187], 0
	v_mfma_f32_16x16x32_bf16 v[46:49], v[152:155], v[196:199], 0
	v_mfma_f32_16x16x32_bf16 v[42:45], v[160:163], v[196:199], 0
	v_mfma_f32_16x16x32_bf16 v[30:33], v[152:155], v[204:207], 0
	v_mfma_f32_16x16x32_bf16 v[26:29], v[160:163], v[204:207], 0
	v_mfma_f32_16x16x32_bf16 v[14:17], v[152:155], v[212:215], 0
	v_mfma_f32_16x16x32_bf16 v[10:13], v[160:163], v[212:215], 0
	v_mfma_f32_16x16x32_bf16 v[62:65], v[156:159], v[188:191], v[62:65]
	v_mfma_f32_16x16x32_bf16 v[58:61], v[164:167], v[188:191], v[58:61]
	v_mfma_f32_16x16x32_bf16 v[46:49], v[156:159], v[200:203], v[46:49]
	v_mfma_f32_16x16x32_bf16 v[42:45], v[164:167], v[200:203], v[42:45]
	v_mfma_f32_16x16x32_bf16 v[30:33], v[156:159], v[208:211], v[30:33]
	v_mfma_f32_16x16x32_bf16 v[26:29], v[164:167], v[208:211], v[26:29]
	v_mfma_f32_16x16x32_bf16 v[14:17], v[156:159], v[216:219], v[14:17]
	v_mfma_f32_16x16x32_bf16 v[10:13], v[164:167], v[216:219], v[10:13]
	v_mfma_f32_16x16x32_bf16 v[54:57], v[168:171], v[184:187], 0
	v_mfma_f32_16x16x32_bf16 v[50:53], v[176:179], v[184:187], 0
	v_mfma_f32_16x16x32_bf16 v[38:41], v[168:171], v[196:199], 0
	v_mfma_f32_16x16x32_bf16 v[34:37], v[176:179], v[196:199], 0
	v_mfma_f32_16x16x32_bf16 v[22:25], v[168:171], v[204:207], 0
	v_mfma_f32_16x16x32_bf16 v[18:21], v[176:179], v[204:207], 0
	v_mfma_f32_16x16x32_bf16 v[6:9], v[168:171], v[212:215], 0
	v_mfma_f32_16x16x32_bf16 v[2:5], v[176:179], v[212:215], 0
	v_mfma_f32_16x16x32_bf16 v[54:57], v[172:175], v[188:191], v[54:57]
	v_mfma_f32_16x16x32_bf16 v[50:53], v[180:183], v[188:191], v[50:53]
	v_mfma_f32_16x16x32_bf16 v[38:41], v[172:175], v[200:203], v[38:41]
	v_mfma_f32_16x16x32_bf16 v[34:37], v[180:183], v[200:203], v[34:37]
	v_mfma_f32_16x16x32_bf16 v[22:25], v[172:175], v[208:211], v[22:25]
	v_mfma_f32_16x16x32_bf16 v[18:21], v[180:183], v[208:211], v[18:21]
	v_mfma_f32_16x16x32_bf16 v[6:9], v[172:175], v[216:219], v[6:9]
	s_barrier
	v_mfma_f32_16x16x32_bf16 v[2:5], v[180:183], v[216:219], v[2:5]
	s_setprio 2
	s_add_i32 s25, 0, 0x18000
	s_add_i32 s44, 0, 0x1c000
	v_add_u32_e32 v164, s25, v147
	v_add_u32_e32 v180, s44, v147
	ds_read_b128 v[152:155], v164
	ds_read_b128 v[156:159], v164 offset:1024
	ds_read_b128 v[160:163], v164 offset:2048
	ds_read_b128 v[164:167], v164 offset:3072
	ds_read_b128 v[168:171], v180
	ds_read_b128 v[172:175], v180 offset:1024
	ds_read_b128 v[176:179], v180 offset:2048
	ds_read_b128 v[180:183], v180 offset:3072
	s_add_u32 s42, s42, 0x80000
	s_addc_u32 s43, s43, 0
	s_mov_b32 m0, s48
	v_lshl_add_u64 v[224:225], s[42:43], 0, v[130:131]
	ds_read_b128 v[184:187], v151 offset:32768
	ds_read_b128 v[188:191], v151 offset:33792
	ds_read_b128 v[196:199], v151 offset:34816
	ds_read_b128 v[200:203], v151 offset:35840
	ds_read_b128 v[204:207], v151 offset:36864
	ds_read_b128 v[208:211], v151 offset:37888
	ds_read_b128 v[212:215], v151 offset:38912
	ds_read_b128 v[216:219], v151 offset:39936
	global_load_lds_dwordx4 v[224:225], off
	v_lshl_add_u64 v[224:225], s[42:43], 0, v[134:135]
	s_mov_b32 m0, s49
	s_nop 0
	global_load_lds_dwordx4 v[224:225], off
	s_waitcnt vmcnt(8)
	s_waitcnt lgkmcnt(0)
	s_barrier
	s_setprio 1
	s_waitcnt lgkmcnt(0)
	v_mfma_f32_16x16x32_bf16 v[126:129], v[152:155], v[184:187], v[126:129]
	v_mfma_f32_16x16x32_bf16 v[122:125], v[160:163], v[184:187], v[122:125]
	v_mfma_f32_16x16x32_bf16 v[110:113], v[152:155], v[196:199], v[110:113]
	v_mfma_f32_16x16x32_bf16 v[106:109], v[160:163], v[196:199], v[106:109]
	v_mfma_f32_16x16x32_bf16 v[94:97], v[152:155], v[204:207], v[94:97]
	v_mfma_f32_16x16x32_bf16 v[90:93], v[160:163], v[204:207], v[90:93]
	v_mfma_f32_16x16x32_bf16 v[78:81], v[152:155], v[212:215], v[78:81]
	v_mfma_f32_16x16x32_bf16 v[74:77], v[160:163], v[212:215], v[74:77]
	v_mfma_f32_16x16x32_bf16 v[126:129], v[156:159], v[188:191], v[126:129]
	v_mfma_f32_16x16x32_bf16 v[122:125], v[164:167], v[188:191], v[122:125]
	v_mfma_f32_16x16x32_bf16 v[110:113], v[156:159], v[200:203], v[110:113]
	v_mfma_f32_16x16x32_bf16 v[106:109], v[164:167], v[200:203], v[106:109]
	v_mfma_f32_16x16x32_bf16 v[94:97], v[156:159], v[208:211], v[94:97]
	v_mfma_f32_16x16x32_bf16 v[90:93], v[164:167], v[208:211], v[90:93]
	v_mfma_f32_16x16x32_bf16 v[78:81], v[156:159], v[216:219], v[78:81]
	v_mfma_f32_16x16x32_bf16 v[74:77], v[164:167], v[216:219], v[74:77]
	v_mfma_f32_16x16x32_bf16 v[118:121], v[168:171], v[184:187], v[118:121]
	v_mfma_f32_16x16x32_bf16 v[114:117], v[176:179], v[184:187], v[114:117]
	v_mfma_f32_16x16x32_bf16 v[102:105], v[168:171], v[196:199], v[102:105]
	v_mfma_f32_16x16x32_bf16 v[98:101], v[176:179], v[196:199], v[98:101]
	v_mfma_f32_16x16x32_bf16 v[86:89], v[168:171], v[204:207], v[86:89]
	v_mfma_f32_16x16x32_bf16 v[82:85], v[176:179], v[204:207], v[82:85]
	v_mfma_f32_16x16x32_bf16 v[70:73], v[168:171], v[212:215], v[70:73]
	v_mfma_f32_16x16x32_bf16 v[66:69], v[176:179], v[212:215], v[66:69]
	v_mfma_f32_16x16x32_bf16 v[118:121], v[172:175], v[188:191], v[118:121]
	v_mfma_f32_16x16x32_bf16 v[114:117], v[180:183], v[188:191], v[114:117]
	v_mfma_f32_16x16x32_bf16 v[102:105], v[172:175], v[200:203], v[102:105]
	v_mfma_f32_16x16x32_bf16 v[98:101], v[180:183], v[200:203], v[98:101]
	v_mfma_f32_16x16x32_bf16 v[86:89], v[172:175], v[208:211], v[86:89]
	v_mfma_f32_16x16x32_bf16 v[82:85], v[180:183], v[208:211], v[82:85]
	v_mfma_f32_16x16x32_bf16 v[70:73], v[172:175], v[216:219], v[70:73]
	s_barrier
	v_mfma_f32_16x16x32_bf16 v[66:69], v[180:183], v[216:219], v[66:69]
	s_setprio 2
	s_add_i32 s25, s25, s33
	v_lshl_add_u64 v[144:145], v[144:145], 0, s[16:17]
	s_mov_b32 m0, s25
	ds_read_b128 v[184:187], v151 offset:49152
	ds_read_b128 v[188:191], v151 offset:50176
	ds_read_b128 v[196:199], v151 offset:51200
	ds_read_b128 v[200:203], v151 offset:52224
	ds_read_b128 v[204:207], v151 offset:53248
	ds_read_b128 v[208:211], v151 offset:54272
	ds_read_b128 v[212:215], v151 offset:55296
	ds_read_b128 v[216:219], v151 offset:56320
	global_load_lds_dwordx4 v[144:145], off
	s_add_i32 m0, s25, 0x2000
	s_add_u32 s40, s40, 0x80080
	v_lshl_add_u64 v[144:145], v[192:193], 0, s[16:17]
	s_addc_u32 s41, s41, 0
	s_add_i32 s25, s44, s33
	global_load_lds_dwordx4 v[144:145], off
	v_lshl_add_u64 v[144:145], s[40:41], 0, v[132:133]
	s_mov_b32 m0, s25
	s_nop 0
	global_load_lds_dwordx4 v[144:145], off
	v_lshl_add_u64 v[144:145], s[40:41], 0, v[136:137]
	s_add_i32 m0, s25, 0x2000
	s_nop 0
	global_load_lds_dwordx4 v[144:145], off
	v_lshl_add_u64 v[144:145], v[220:221], 0, s[16:17]
	s_mov_b32 m0, s50
	s_nop 0
	global_load_lds_dwordx4 v[144:145], off
	v_lshl_add_u64 v[144:145], v[222:223], 0, s[16:17]
	s_mov_b32 m0, s51
	s_nop 0
	global_load_lds_dwordx4 v[144:145], off
	s_waitcnt vmcnt(8)
	s_waitcnt lgkmcnt(0)
	s_barrier
	s_setprio 1
	s_waitcnt lgkmcnt(0)
	v_mfma_f32_16x16x32_bf16 v[62:65], v[152:155], v[184:187], v[62:65]
	v_mfma_f32_16x16x32_bf16 v[58:61], v[160:163], v[184:187], v[58:61]
	v_mfma_f32_16x16x32_bf16 v[46:49], v[152:155], v[196:199], v[46:49]
	v_mfma_f32_16x16x32_bf16 v[42:45], v[160:163], v[196:199], v[42:45]
	v_mfma_f32_16x16x32_bf16 v[30:33], v[152:155], v[204:207], v[30:33]
	v_mfma_f32_16x16x32_bf16 v[26:29], v[160:163], v[204:207], v[26:29]
	v_mfma_f32_16x16x32_bf16 v[14:17], v[152:155], v[212:215], v[14:17]
	v_mfma_f32_16x16x32_bf16 v[10:13], v[160:163], v[212:215], v[10:13]
	v_mfma_f32_16x16x32_bf16 v[62:65], v[156:159], v[188:191], v[62:65]
	v_mfma_f32_16x16x32_bf16 v[58:61], v[164:167], v[188:191], v[58:61]
	v_mfma_f32_16x16x32_bf16 v[46:49], v[156:159], v[200:203], v[46:49]
	v_mfma_f32_16x16x32_bf16 v[42:45], v[164:167], v[200:203], v[42:45]
	v_mfma_f32_16x16x32_bf16 v[30:33], v[156:159], v[208:211], v[30:33]
	v_mfma_f32_16x16x32_bf16 v[26:29], v[164:167], v[208:211], v[26:29]
	v_mfma_f32_16x16x32_bf16 v[14:17], v[156:159], v[216:219], v[14:17]
	v_mfma_f32_16x16x32_bf16 v[10:13], v[164:167], v[216:219], v[10:13]
	v_mfma_f32_16x16x32_bf16 v[54:57], v[168:171], v[184:187], v[54:57]
	v_mfma_f32_16x16x32_bf16 v[50:53], v[176:179], v[184:187], v[50:53]
	v_mfma_f32_16x16x32_bf16 v[38:41], v[168:171], v[196:199], v[38:41]
	v_mfma_f32_16x16x32_bf16 v[34:37], v[176:179], v[196:199], v[34:37]
	v_mfma_f32_16x16x32_bf16 v[22:25], v[168:171], v[204:207], v[22:25]
	v_mfma_f32_16x16x32_bf16 v[18:21], v[176:179], v[204:207], v[18:21]
	v_mfma_f32_16x16x32_bf16 v[6:9], v[168:171], v[212:215], v[6:9]
	v_mfma_f32_16x16x32_bf16 v[2:5], v[176:179], v[212:215], v[2:5]
	v_mfma_f32_16x16x32_bf16 v[54:57], v[172:175], v[188:191], v[54:57]
	v_mfma_f32_16x16x32_bf16 v[50:53], v[180:183], v[188:191], v[50:53]
	v_mfma_f32_16x16x32_bf16 v[38:41], v[172:175], v[200:203], v[38:41]
	v_mfma_f32_16x16x32_bf16 v[34:37], v[180:183], v[200:203], v[34:37]
	v_mfma_f32_16x16x32_bf16 v[22:25], v[172:175], v[208:211], v[22:25]
	v_mfma_f32_16x16x32_bf16 v[18:21], v[180:183], v[208:211], v[18:21]
	v_mfma_f32_16x16x32_bf16 v[6:9], v[172:175], v[216:219], v[6:9]
	s_barrier
	v_mfma_f32_16x16x32_bf16 v[2:5], v[180:183], v[216:219], v[2:5]
	s_setprio 2
	s_add_u32 s38, s38, 0x100
	s_addc_u32 s39, s39, 0
	s_add_u32 s21, s21, 0x100
	s_addc_u32 s23, s23, 0
	s_cmp_ge_i32 s37, s62
	s_mov_b32 s25, s37
	s_cbranch_scc0 .LBB0_221
	s_branch .Lpeeldone_13
.LBB0_221:
	ds_read_b128 v[152:155], v149
	ds_read_b128 v[156:159], v149 offset:1024
	ds_read_b128 v[160:163], v149 offset:2048
	ds_read_b128 v[164:167], v149 offset:3072
	ds_read_b128 v[168:171], v150
	ds_read_b128 v[172:175], v150 offset:1024
	ds_read_b128 v[176:179], v150 offset:2048
	ds_read_b128 v[180:183], v150 offset:3072
	s_add_i32 s37, s25, 2
	s_add_u32 s40, s38, 0xfff80080
	s_addc_u32 s41, s39, -1
	s_cmp_eq_u32 s36, s25
	s_cselect_b32 s43, s27, s41
	s_cselect_b32 s42, s26, s40
	s_cselect_b32 s41, s29, s23
	s_cselect_b32 s40, s28, s21
	v_lshl_add_u64 v[144:145], s[38:39], 0, v[140:141]
	s_add_i32 m0, s35, 0xc000
	ds_read_b128 v[184:187], v151
	ds_read_b128 v[188:191], v151 offset:1024
	ds_read_b128 v[196:199], v151 offset:2048
	ds_read_b128 v[200:203], v151 offset:3072
	ds_read_b128 v[204:207], v151 offset:4096
	ds_read_b128 v[208:211], v151 offset:5120
	ds_read_b128 v[212:215], v151 offset:6144
	ds_read_b128 v[216:219], v151 offset:7168
	global_load_lds_dwordx4 v[144:145], off
	v_lshl_add_u64 v[144:145], s[38:39], 0, v[142:143]
	s_add_i32 m0, s35, 0xe000
	s_nop 0
	global_load_lds_dwordx4 v[144:145], off
	s_waitcnt vmcnt(8)
	s_waitcnt lgkmcnt(0)
	s_barrier
	s_setprio 1
	s_waitcnt lgkmcnt(0)
	v_mfma_f32_16x16x32_bf16 v[126:129], v[152:155], v[184:187], v[126:129]
	v_mfma_f32_16x16x32_bf16 v[122:125], v[160:163], v[184:187], v[122:125]
	v_mfma_f32_16x16x32_bf16 v[110:113], v[152:155], v[196:199], v[110:113]
	v_mfma_f32_16x16x32_bf16 v[106:109], v[160:163], v[196:199], v[106:109]
	v_mfma_f32_16x16x32_bf16 v[94:97], v[152:155], v[204:207], v[94:97]
	v_mfma_f32_16x16x32_bf16 v[90:93], v[160:163], v[204:207], v[90:93]
	v_mfma_f32_16x16x32_bf16 v[78:81], v[152:155], v[212:215], v[78:81]
	v_mfma_f32_16x16x32_bf16 v[74:77], v[160:163], v[212:215], v[74:77]
	v_mfma_f32_16x16x32_bf16 v[126:129], v[156:159], v[188:191], v[126:129]
	v_mfma_f32_16x16x32_bf16 v[122:125], v[164:167], v[188:191], v[122:125]
	v_mfma_f32_16x16x32_bf16 v[110:113], v[156:159], v[200:203], v[110:113]
	v_mfma_f32_16x16x32_bf16 v[106:109], v[164:167], v[200:203], v[106:109]
	v_mfma_f32_16x16x32_bf16 v[94:97], v[156:159], v[208:211], v[94:97]
	v_mfma_f32_16x16x32_bf16 v[90:93], v[164:167], v[208:211], v[90:93]
	v_mfma_f32_16x16x32_bf16 v[78:81], v[156:159], v[216:219], v[78:81]
	v_mfma_f32_16x16x32_bf16 v[74:77], v[164:167], v[216:219], v[74:77]
	v_mfma_f32_16x16x32_bf16 v[118:121], v[168:171], v[184:187], v[118:121]
	v_mfma_f32_16x16x32_bf16 v[114:117], v[176:179], v[184:187], v[114:117]
	v_mfma_f32_16x16x32_bf16 v[102:105], v[168:171], v[196:199], v[102:105]
	v_mfma_f32_16x16x32_bf16 v[98:101], v[176:179], v[196:199], v[98:101]
	v_mfma_f32_16x16x32_bf16 v[86:89], v[168:171], v[204:207], v[86:89]
	v_mfma_f32_16x16x32_bf16 v[82:85], v[176:179], v[204:207], v[82:85]
	v_mfma_f32_16x16x32_bf16 v[70:73], v[168:171], v[212:215], v[70:73]
	v_mfma_f32_16x16x32_bf16 v[66:69], v[176:179], v[212:215], v[66:69]
	v_mfma_f32_16x16x32_bf16 v[118:121], v[172:175], v[188:191], v[118:121]
	v_mfma_f32_16x16x32_bf16 v[114:117], v[180:183], v[188:191], v[114:117]
	v_mfma_f32_16x16x32_bf16 v[102:105], v[172:175], v[200:203], v[102:105]
	v_mfma_f32_16x16x32_bf16 v[98:101], v[180:183], v[200:203], v[98:101]
	v_mfma_f32_16x16x32_bf16 v[86:89], v[172:175], v[208:211], v[86:89]
	v_mfma_f32_16x16x32_bf16 v[82:85], v[180:183], v[208:211], v[82:85]
	v_mfma_f32_16x16x32_bf16 v[70:73], v[172:175], v[216:219], v[70:73]
	s_barrier
	v_mfma_f32_16x16x32_bf16 v[66:69], v[180:183], v[216:219], v[66:69]
	s_setprio 2
	s_add_i32 s25, s54, s33
	v_lshl_add_u64 v[144:145], s[40:41], 0, v[132:133]
	s_mov_b32 m0, s25
	ds_read_b128 v[184:187], v151 offset:16384
	ds_read_b128 v[188:191], v151 offset:17408
	ds_read_b128 v[196:199], v151 offset:18432
	ds_read_b128 v[200:203], v151 offset:19456
	ds_read_b128 v[204:207], v151 offset:20480
	ds_read_b128 v[208:211], v151 offset:21504
	ds_read_b128 v[212:215], v151 offset:22528
	ds_read_b128 v[216:219], v151 offset:23552
	global_load_lds_dwordx4 v[144:145], off
	s_add_i32 m0, s25, 0x2000
	s_add_u32 s44, s40, 0x80000
	v_lshl_add_u64 v[192:193], s[40:41], 0, v[136:137]
	s_addc_u32 s45, s41, 0
	s_add_i32 s25, s55, s33
	global_load_lds_dwordx4 v[192:193], off
	v_lshl_add_u64 v[220:221], s[44:45], 0, v[132:133]
	s_mov_b32 m0, s25
	v_lshl_add_u64 v[222:223], s[42:43], 0, v[134:135]
	global_load_lds_dwordx4 v[220:221], off
	v_lshl_add_u64 v[220:221], s[44:45], 0, v[136:137]
	s_add_i32 m0, s25, 0x2000
	s_nop 0
	global_load_lds_dwordx4 v[220:221], off
	v_lshl_add_u64 v[220:221], s[42:43], 0, v[130:131]
	s_mov_b32 m0, s35
	s_nop 0
	global_load_lds_dwordx4 v[220:221], off
	s_mov_b32 m0, s47
	s_nop 0
	global_load_lds_dwordx4 v[222:223], off
	s_waitcnt vmcnt(8)
	s_waitcnt lgkmcnt(0)
	s_barrier
	s_setprio 1
	s_waitcnt lgkmcnt(0)
	v_mfma_f32_16x16x32_bf16 v[62:65], v[152:155], v[184:187], v[62:65]
	v_mfma_f32_16x16x32_bf16 v[58:61], v[160:163], v[184:187], v[58:61]
	v_mfma_f32_16x16x32_bf16 v[46:49], v[152:155], v[196:199], v[46:49]
	v_mfma_f32_16x16x32_bf16 v[42:45], v[160:163], v[196:199], v[42:45]
	v_mfma_f32_16x16x32_bf16 v[30:33], v[152:155], v[204:207], v[30:33]
	v_mfma_f32_16x16x32_bf16 v[26:29], v[160:163], v[204:207], v[26:29]
	v_mfma_f32_16x16x32_bf16 v[14:17], v[152:155], v[212:215], v[14:17]
	v_mfma_f32_16x16x32_bf16 v[10:13], v[160:163], v[212:215], v[10:13]
	v_mfma_f32_16x16x32_bf16 v[62:65], v[156:159], v[188:191], v[62:65]
	v_mfma_f32_16x16x32_bf16 v[58:61], v[164:167], v[188:191], v[58:61]
	v_mfma_f32_16x16x32_bf16 v[46:49], v[156:159], v[200:203], v[46:49]
	v_mfma_f32_16x16x32_bf16 v[42:45], v[164:167], v[200:203], v[42:45]
	v_mfma_f32_16x16x32_bf16 v[30:33], v[156:159], v[208:211], v[30:33]
	v_mfma_f32_16x16x32_bf16 v[26:29], v[164:167], v[208:211], v[26:29]
	v_mfma_f32_16x16x32_bf16 v[14:17], v[156:159], v[216:219], v[14:17]
	v_mfma_f32_16x16x32_bf16 v[10:13], v[164:167], v[216:219], v[10:13]
	v_mfma_f32_16x16x32_bf16 v[54:57], v[168:171], v[184:187], v[54:57]
	v_mfma_f32_16x16x32_bf16 v[50:53], v[176:179], v[184:187], v[50:53]
	v_mfma_f32_16x16x32_bf16 v[38:41], v[168:171], v[196:199], v[38:41]
	v_mfma_f32_16x16x32_bf16 v[34:37], v[176:179], v[196:199], v[34:37]
	v_mfma_f32_16x16x32_bf16 v[22:25], v[168:171], v[204:207], v[22:25]
	v_mfma_f32_16x16x32_bf16 v[18:21], v[176:179], v[204:207], v[18:21]
	v_mfma_f32_16x16x32_bf16 v[6:9], v[168:171], v[212:215], v[6:9]
	v_mfma_f32_16x16x32_bf16 v[2:5], v[176:179], v[212:215], v[2:5]
	v_mfma_f32_16x16x32_bf16 v[54:57], v[172:175], v[188:191], v[54:57]
	v_mfma_f32_16x16x32_bf16 v[50:53], v[180:183], v[188:191], v[50:53]
	v_mfma_f32_16x16x32_bf16 v[38:41], v[172:175], v[200:203], v[38:41]
	v_mfma_f32_16x16x32_bf16 v[34:37], v[180:183], v[200:203], v[34:37]
	v_mfma_f32_16x16x32_bf16 v[22:25], v[172:175], v[208:211], v[22:25]
	v_mfma_f32_16x16x32_bf16 v[18:21], v[180:183], v[208:211], v[18:21]
	v_mfma_f32_16x16x32_bf16 v[6:9], v[172:175], v[216:219], v[6:9]
	s_barrier
	v_mfma_f32_16x16x32_bf16 v[2:5], v[180:183], v[216:219], v[2:5]
	s_setprio 2
	s_add_i32 s25, 0, 0x18000
	s_add_i32 s44, 0, 0x1c000
	v_add_u32_e32 v164, s25, v147
	v_add_u32_e32 v180, s44, v147
	ds_read_b128 v[152:155], v164
	ds_read_b128 v[156:159], v164 offset:1024
	ds_read_b128 v[160:163], v164 offset:2048
	ds_read_b128 v[164:167], v164 offset:3072
	ds_read_b128 v[168:171], v180
	ds_read_b128 v[172:175], v180 offset:1024
	ds_read_b128 v[176:179], v180 offset:2048
	ds_read_b128 v[180:183], v180 offset:3072
	s_add_u32 s42, s42, 0x80000
	s_addc_u32 s43, s43, 0
	s_mov_b32 m0, s48
	v_lshl_add_u64 v[224:225], s[42:43], 0, v[130:131]
	ds_read_b128 v[184:187], v151 offset:32768
	ds_read_b128 v[188:191], v151 offset:33792
	ds_read_b128 v[196:199], v151 offset:34816
	ds_read_b128 v[200:203], v151 offset:35840
	ds_read_b128 v[204:207], v151 offset:36864
	ds_read_b128 v[208:211], v151 offset:37888
	ds_read_b128 v[212:215], v151 offset:38912
	ds_read_b128 v[216:219], v151 offset:39936
	global_load_lds_dwordx4 v[224:225], off
	v_lshl_add_u64 v[224:225], s[42:43], 0, v[134:135]
	s_mov_b32 m0, s49
	s_nop 0
	global_load_lds_dwordx4 v[224:225], off
	s_waitcnt vmcnt(8)
	s_waitcnt lgkmcnt(0)
	s_barrier
	s_setprio 1
	s_waitcnt lgkmcnt(0)
	v_mfma_f32_16x16x32_bf16 v[126:129], v[152:155], v[184:187], v[126:129]
	v_mfma_f32_16x16x32_bf16 v[122:125], v[160:163], v[184:187], v[122:125]
	v_mfma_f32_16x16x32_bf16 v[110:113], v[152:155], v[196:199], v[110:113]
	v_mfma_f32_16x16x32_bf16 v[106:109], v[160:163], v[196:199], v[106:109]
	v_mfma_f32_16x16x32_bf16 v[94:97], v[152:155], v[204:207], v[94:97]
	v_mfma_f32_16x16x32_bf16 v[90:93], v[160:163], v[204:207], v[90:93]
	v_mfma_f32_16x16x32_bf16 v[78:81], v[152:155], v[212:215], v[78:81]
	v_mfma_f32_16x16x32_bf16 v[74:77], v[160:163], v[212:215], v[74:77]
	v_mfma_f32_16x16x32_bf16 v[126:129], v[156:159], v[188:191], v[126:129]
	v_mfma_f32_16x16x32_bf16 v[122:125], v[164:167], v[188:191], v[122:125]
	v_mfma_f32_16x16x32_bf16 v[110:113], v[156:159], v[200:203], v[110:113]
	v_mfma_f32_16x16x32_bf16 v[106:109], v[164:167], v[200:203], v[106:109]
	v_mfma_f32_16x16x32_bf16 v[94:97], v[156:159], v[208:211], v[94:97]
	v_mfma_f32_16x16x32_bf16 v[90:93], v[164:167], v[208:211], v[90:93]
	v_mfma_f32_16x16x32_bf16 v[78:81], v[156:159], v[216:219], v[78:81]
	v_mfma_f32_16x16x32_bf16 v[74:77], v[164:167], v[216:219], v[74:77]
	v_mfma_f32_16x16x32_bf16 v[118:121], v[168:171], v[184:187], v[118:121]
	v_mfma_f32_16x16x32_bf16 v[114:117], v[176:179], v[184:187], v[114:117]
	v_mfma_f32_16x16x32_bf16 v[102:105], v[168:171], v[196:199], v[102:105]
	v_mfma_f32_16x16x32_bf16 v[98:101], v[176:179], v[196:199], v[98:101]
	v_mfma_f32_16x16x32_bf16 v[86:89], v[168:171], v[204:207], v[86:89]
	v_mfma_f32_16x16x32_bf16 v[82:85], v[176:179], v[204:207], v[82:85]
	v_mfma_f32_16x16x32_bf16 v[70:73], v[168:171], v[212:215], v[70:73]
	v_mfma_f32_16x16x32_bf16 v[66:69], v[176:179], v[212:215], v[66:69]
	v_mfma_f32_16x16x32_bf16 v[118:121], v[172:175], v[188:191], v[118:121]
	v_mfma_f32_16x16x32_bf16 v[114:117], v[180:183], v[188:191], v[114:117]
	v_mfma_f32_16x16x32_bf16 v[102:105], v[172:175], v[200:203], v[102:105]
	v_mfma_f32_16x16x32_bf16 v[98:101], v[180:183], v[200:203], v[98:101]
	v_mfma_f32_16x16x32_bf16 v[86:89], v[172:175], v[208:211], v[86:89]
	v_mfma_f32_16x16x32_bf16 v[82:85], v[180:183], v[208:211], v[82:85]
	v_mfma_f32_16x16x32_bf16 v[70:73], v[172:175], v[216:219], v[70:73]
	s_barrier
	v_mfma_f32_16x16x32_bf16 v[66:69], v[180:183], v[216:219], v[66:69]
	s_setprio 2
	s_add_i32 s25, s25, s33
	v_lshl_add_u64 v[144:145], v[144:145], 0, s[16:17]
	s_mov_b32 m0, s25
	ds_read_b128 v[184:187], v151 offset:49152
	ds_read_b128 v[188:191], v151 offset:50176
	ds_read_b128 v[196:199], v151 offset:51200
	ds_read_b128 v[200:203], v151 offset:52224
	ds_read_b128 v[204:207], v151 offset:53248
	ds_read_b128 v[208:211], v151 offset:54272
	ds_read_b128 v[212:215], v151 offset:55296
	ds_read_b128 v[216:219], v151 offset:56320
	global_load_lds_dwordx4 v[144:145], off
	s_add_i32 m0, s25, 0x2000
	s_add_u32 s40, s40, 0x80080
	v_lshl_add_u64 v[144:145], v[192:193], 0, s[16:17]
	s_addc_u32 s41, s41, 0
	s_add_i32 s25, s44, s33
	global_load_lds_dwordx4 v[144:145], off
	v_lshl_add_u64 v[144:145], s[40:41], 0, v[132:133]
	s_mov_b32 m0, s25
	s_nop 0
	global_load_lds_dwordx4 v[144:145], off
	v_lshl_add_u64 v[144:145], s[40:41], 0, v[136:137]
	s_add_i32 m0, s25, 0x2000
	s_nop 0
	global_load_lds_dwordx4 v[144:145], off
	v_lshl_add_u64 v[144:145], v[220:221], 0, s[16:17]
	s_mov_b32 m0, s50
	s_nop 0
	global_load_lds_dwordx4 v[144:145], off
	v_lshl_add_u64 v[144:145], v[222:223], 0, s[16:17]
	s_mov_b32 m0, s51
	s_nop 0
	global_load_lds_dwordx4 v[144:145], off
	s_waitcnt vmcnt(8)
	s_waitcnt lgkmcnt(0)
	s_barrier
	s_setprio 1
	s_waitcnt lgkmcnt(0)
	v_mfma_f32_16x16x32_bf16 v[62:65], v[152:155], v[184:187], v[62:65]
	v_mfma_f32_16x16x32_bf16 v[58:61], v[160:163], v[184:187], v[58:61]
	v_mfma_f32_16x16x32_bf16 v[46:49], v[152:155], v[196:199], v[46:49]
	v_mfma_f32_16x16x32_bf16 v[42:45], v[160:163], v[196:199], v[42:45]
	v_mfma_f32_16x16x32_bf16 v[30:33], v[152:155], v[204:207], v[30:33]
	v_mfma_f32_16x16x32_bf16 v[26:29], v[160:163], v[204:207], v[26:29]
	v_mfma_f32_16x16x32_bf16 v[14:17], v[152:155], v[212:215], v[14:17]
	v_mfma_f32_16x16x32_bf16 v[10:13], v[160:163], v[212:215], v[10:13]
	v_mfma_f32_16x16x32_bf16 v[62:65], v[156:159], v[188:191], v[62:65]
	v_mfma_f32_16x16x32_bf16 v[58:61], v[164:167], v[188:191], v[58:61]
	v_mfma_f32_16x16x32_bf16 v[46:49], v[156:159], v[200:203], v[46:49]
	v_mfma_f32_16x16x32_bf16 v[42:45], v[164:167], v[200:203], v[42:45]
	v_mfma_f32_16x16x32_bf16 v[30:33], v[156:159], v[208:211], v[30:33]
	v_mfma_f32_16x16x32_bf16 v[26:29], v[164:167], v[208:211], v[26:29]
	v_mfma_f32_16x16x32_bf16 v[14:17], v[156:159], v[216:219], v[14:17]
	v_mfma_f32_16x16x32_bf16 v[10:13], v[164:167], v[216:219], v[10:13]
	v_mfma_f32_16x16x32_bf16 v[54:57], v[168:171], v[184:187], v[54:57]
	v_mfma_f32_16x16x32_bf16 v[50:53], v[176:179], v[184:187], v[50:53]
	v_mfma_f32_16x16x32_bf16 v[38:41], v[168:171], v[196:199], v[38:41]
	v_mfma_f32_16x16x32_bf16 v[34:37], v[176:179], v[196:199], v[34:37]
	v_mfma_f32_16x16x32_bf16 v[22:25], v[168:171], v[204:207], v[22:25]
	v_mfma_f32_16x16x32_bf16 v[18:21], v[176:179], v[204:207], v[18:21]
	v_mfma_f32_16x16x32_bf16 v[6:9], v[168:171], v[212:215], v[6:9]
	v_mfma_f32_16x16x32_bf16 v[2:5], v[176:179], v[212:215], v[2:5]
	v_mfma_f32_16x16x32_bf16 v[54:57], v[172:175], v[188:191], v[54:57]
	v_mfma_f32_16x16x32_bf16 v[50:53], v[180:183], v[188:191], v[50:53]
	v_mfma_f32_16x16x32_bf16 v[38:41], v[172:175], v[200:203], v[38:41]
	v_mfma_f32_16x16x32_bf16 v[34:37], v[180:183], v[200:203], v[34:37]
	v_mfma_f32_16x16x32_bf16 v[22:25], v[172:175], v[208:211], v[22:25]
	v_mfma_f32_16x16x32_bf16 v[18:21], v[180:183], v[208:211], v[18:21]
	v_mfma_f32_16x16x32_bf16 v[6:9], v[172:175], v[216:219], v[6:9]
	s_barrier
	v_mfma_f32_16x16x32_bf16 v[2:5], v[180:183], v[216:219], v[2:5]
	s_setprio 2
	s_add_u32 s38, s38, 0x100
	s_addc_u32 s39, s39, 0
	s_add_u32 s21, s21, 0x100
	s_addc_u32 s23, s23, 0
	s_cmp_ge_i32 s37, s62
	s_mov_b32 s25, s37
	s_cbranch_scc0 .LBB0_221

.Lpeel_12:
	ds_read_b128 v[130:133], v215
	ds_read_b128 v[134:137], v215 offset:1024
	ds_read_b128 v[138:141], v215 offset:2048
	ds_read_b128 v[142:145], v215 offset:3072
	ds_read_b128 v[146:149], v216
	ds_read_b128 v[150:153], v216 offset:1024
	ds_read_b128 v[154:157], v216 offset:2048
	ds_read_b128 v[158:161], v216 offset:3072
	s_add_i32 s38, s34, 2
	s_add_u32 s35, s30, 0xffea0080
	s_addc_u32 s36, s31, -1
	s_cmp_eq_u32 s28, s34
	s_cselect_b32 s34, s26, s23
	s_cselect_b32 s37, s25, s36
	s_cselect_b32 s36, s24, s35
	s_cselect_b32 s35, s27, s29
	v_lshl_add_u64 v[192:193], s[30:31], 0, v[188:189]
	s_add_i32 m0, s40, 0xc000
	ds_read_b128 v[162:165], v217
	ds_read_b128 v[166:169], v217 offset:1024
	ds_read_b128 v[170:173], v217 offset:2048
	ds_read_b128 v[174:177], v217 offset:3072
	ds_read_b128 v[196:199], v217 offset:4096
	ds_read_b128 v[200:203], v217 offset:5120
	ds_read_b128 v[204:207], v217 offset:6144
	ds_read_b128 v[208:211], v217 offset:7168
	global_load_lds_dwordx4 v[192:193], off
	v_lshl_add_u64 v[192:193], s[30:31], 0, v[190:191]
	s_add_i32 m0, s40, 0xe000
	s_nop 0
	global_load_lds_dwordx4 v[192:193], off
	s_waitcnt vmcnt(8)
	s_waitcnt lgkmcnt(0)
	s_barrier
	s_setprio 1
	s_waitcnt lgkmcnt(0)
	v_mfma_f32_16x16x32_bf16 v[126:129], v[130:133], v[162:165], 0
	v_mfma_f32_16x16x32_bf16 v[122:125], v[138:141], v[162:165], 0
	v_mfma_f32_16x16x32_bf16 v[118:121], v[130:133], v[170:173], 0
	v_mfma_f32_16x16x32_bf16 v[114:117], v[138:141], v[170:173], 0
	v_mfma_f32_16x16x32_bf16 v[94:97], v[130:133], v[196:199], 0
	v_mfma_f32_16x16x32_bf16 v[90:93], v[138:141], v[196:199], 0
	v_mfma_f32_16x16x32_bf16 v[86:89], v[130:133], v[204:207], 0
	v_mfma_f32_16x16x32_bf16 v[82:85], v[138:141], v[204:207], 0
	v_mfma_f32_16x16x32_bf16 v[126:129], v[134:137], v[166:169], v[126:129]
	v_mfma_f32_16x16x32_bf16 v[122:125], v[142:145], v[166:169], v[122:125]
	v_mfma_f32_16x16x32_bf16 v[118:121], v[134:137], v[174:177], v[118:121]
	v_mfma_f32_16x16x32_bf16 v[114:117], v[142:145], v[174:177], v[114:117]
	v_mfma_f32_16x16x32_bf16 v[94:97], v[134:137], v[200:203], v[94:97]
	v_mfma_f32_16x16x32_bf16 v[90:93], v[142:145], v[200:203], v[90:93]
	v_mfma_f32_16x16x32_bf16 v[86:89], v[134:137], v[208:211], v[86:89]
	v_mfma_f32_16x16x32_bf16 v[82:85], v[142:145], v[208:211], v[82:85]
	v_mfma_f32_16x16x32_bf16 v[110:113], v[146:149], v[162:165], 0
	v_mfma_f32_16x16x32_bf16 v[106:109], v[154:157], v[162:165], 0
	v_mfma_f32_16x16x32_bf16 v[102:105], v[146:149], v[170:173], 0
	v_mfma_f32_16x16x32_bf16 v[98:101], v[154:157], v[170:173], 0
	v_mfma_f32_16x16x32_bf16 v[78:81], v[146:149], v[196:199], 0
	v_mfma_f32_16x16x32_bf16 v[74:77], v[154:157], v[196:199], 0
	v_mfma_f32_16x16x32_bf16 v[70:73], v[146:149], v[204:207], 0
	v_mfma_f32_16x16x32_bf16 v[66:69], v[154:157], v[204:207], 0
	v_mfma_f32_16x16x32_bf16 v[110:113], v[150:153], v[166:169], v[110:113]
	v_mfma_f32_16x16x32_bf16 v[106:109], v[158:161], v[166:169], v[106:109]
	v_mfma_f32_16x16x32_bf16 v[102:105], v[150:153], v[174:177], v[102:105]
	v_mfma_f32_16x16x32_bf16 v[98:101], v[158:161], v[174:177], v[98:101]
	v_mfma_f32_16x16x32_bf16 v[78:81], v[150:153], v[200:203], v[78:81]
	v_mfma_f32_16x16x32_bf16 v[74:77], v[158:161], v[200:203], v[74:77]
	v_mfma_f32_16x16x32_bf16 v[70:73], v[150:153], v[208:211], v[70:73]
	s_barrier
	v_mfma_f32_16x16x32_bf16 v[66:69], v[158:161], v[208:211], v[66:69]
	s_setprio 2
	s_add_i32 s39, s53, s33
	v_lshl_add_u64 v[192:193], s[34:35], 0, v[180:181]
	s_mov_b32 m0, s39
	ds_read_b128 v[162:165], v217 offset:16384
	ds_read_b128 v[166:169], v217 offset:17408
	ds_read_b128 v[170:173], v217 offset:18432
	ds_read_b128 v[174:177], v217 offset:19456
	ds_read_b128 v[196:199], v217 offset:20480
	ds_read_b128 v[200:203], v217 offset:21504
	ds_read_b128 v[204:207], v217 offset:22528
	ds_read_b128 v[208:211], v217 offset:23552
	global_load_lds_dwordx4 v[192:193], off
	s_add_i32 m0, s39, 0x2000
	s_add_u32 s62, s34, 0x160000
	v_lshl_add_u64 v[218:219], s[34:35], 0, v[184:185]
	s_addc_u32 s63, s35, 0
	s_add_i32 s39, s54, s33
	global_load_lds_dwordx4 v[218:219], off
	v_lshl_add_u64 v[220:221], s[62:63], 0, v[180:181]
	s_mov_b32 m0, s39
	v_lshl_add_u64 v[222:223], s[36:37], 0, v[182:183]
	global_load_lds_dwordx4 v[220:221], off
	v_lshl_add_u64 v[220:221], s[62:63], 0, v[184:185]
	s_add_i32 m0, s39, 0x2000
	s_nop 0
	global_load_lds_dwordx4 v[220:221], off
	v_lshl_add_u64 v[220:221], s[36:37], 0, v[178:179]
	s_mov_b32 m0, s40
	s_nop 0
	global_load_lds_dwordx4 v[220:221], off
	s_mov_b32 m0, s41
	s_nop 0
	global_load_lds_dwordx4 v[222:223], off
	s_waitcnt vmcnt(8)
	s_waitcnt lgkmcnt(0)
	s_barrier
	s_setprio 1
	s_waitcnt lgkmcnt(0)
	v_mfma_f32_16x16x32_bf16 v[62:65], v[130:133], v[162:165], 0
	v_mfma_f32_16x16x32_bf16 v[58:61], v[138:141], v[162:165], 0
	v_mfma_f32_16x16x32_bf16 v[54:57], v[130:133], v[170:173], 0
	v_mfma_f32_16x16x32_bf16 v[50:53], v[138:141], v[170:173], 0
	v_mfma_f32_16x16x32_bf16 v[30:33], v[130:133], v[196:199], 0
	v_mfma_f32_16x16x32_bf16 v[26:29], v[138:141], v[196:199], 0
	v_mfma_f32_16x16x32_bf16 v[22:25], v[130:133], v[204:207], 0
	v_mfma_f32_16x16x32_bf16 v[18:21], v[138:141], v[204:207], 0
	v_mfma_f32_16x16x32_bf16 v[62:65], v[134:137], v[166:169], v[62:65]
	v_mfma_f32_16x16x32_bf16 v[58:61], v[142:145], v[166:169], v[58:61]
	v_mfma_f32_16x16x32_bf16 v[54:57], v[134:137], v[174:177], v[54:57]
	v_mfma_f32_16x16x32_bf16 v[50:53], v[142:145], v[174:177], v[50:53]
	v_mfma_f32_16x16x32_bf16 v[30:33], v[134:137], v[200:203], v[30:33]
	v_mfma_f32_16x16x32_bf16 v[26:29], v[142:145], v[200:203], v[26:29]
	v_mfma_f32_16x16x32_bf16 v[22:25], v[134:137], v[208:211], v[22:25]
	v_mfma_f32_16x16x32_bf16 v[18:21], v[142:145], v[208:211], v[18:21]
	v_mfma_f32_16x16x32_bf16 v[46:49], v[146:149], v[162:165], 0
	v_mfma_f32_16x16x32_bf16 v[42:45], v[154:157], v[162:165], 0
	v_mfma_f32_16x16x32_bf16 v[38:41], v[146:149], v[170:173], 0
	v_mfma_f32_16x16x32_bf16 v[34:37], v[154:157], v[170:173], 0
	v_mfma_f32_16x16x32_bf16 v[14:17], v[146:149], v[196:199], 0
	v_mfma_f32_16x16x32_bf16 v[10:13], v[154:157], v[196:199], 0
	v_mfma_f32_16x16x32_bf16 v[6:9], v[146:149], v[204:207], 0
	v_mfma_f32_16x16x32_bf16 v[2:5], v[154:157], v[204:207], 0
	v_mfma_f32_16x16x32_bf16 v[46:49], v[150:153], v[166:169], v[46:49]
	v_mfma_f32_16x16x32_bf16 v[42:45], v[158:161], v[166:169], v[42:45]
	v_mfma_f32_16x16x32_bf16 v[38:41], v[150:153], v[174:177], v[38:41]
	v_mfma_f32_16x16x32_bf16 v[34:37], v[158:161], v[174:177], v[34:37]
	v_mfma_f32_16x16x32_bf16 v[14:17], v[150:153], v[200:203], v[14:17]
	v_mfma_f32_16x16x32_bf16 v[10:13], v[158:161], v[200:203], v[10:13]
	v_mfma_f32_16x16x32_bf16 v[6:9], v[150:153], v[208:211], v[6:9]
	s_barrier
	v_mfma_f32_16x16x32_bf16 v[2:5], v[158:161], v[208:211], v[2:5]
	s_setprio 2
	s_add_i32 s39, 0, 0x18000
	s_add_i32 s62, 0, 0x1c000
	v_add_u32_e32 v142, s39, v213
	v_add_u32_e32 v158, s62, v213
	ds_read_b128 v[130:133], v142
	ds_read_b128 v[134:137], v142 offset:1024
	ds_read_b128 v[138:141], v142 offset:2048
	ds_read_b128 v[142:145], v142 offset:3072
	ds_read_b128 v[146:149], v158
	ds_read_b128 v[150:153], v158 offset:1024
	ds_read_b128 v[154:157], v158 offset:2048
	ds_read_b128 v[158:161], v158 offset:3072
	s_add_u32 s36, s36, 0x160000
	s_addc_u32 s37, s37, 0
	s_mov_b32 m0, s42
	v_lshl_add_u64 v[224:225], s[36:37], 0, v[178:179]
	ds_read_b128 v[162:165], v217 offset:32768
	ds_read_b128 v[166:169], v217 offset:33792
	ds_read_b128 v[170:173], v217 offset:34816
	ds_read_b128 v[174:177], v217 offset:35840
	ds_read_b128 v[196:199], v217 offset:36864
	ds_read_b128 v[200:203], v217 offset:37888
	ds_read_b128 v[204:207], v217 offset:38912
	ds_read_b128 v[208:211], v217 offset:39936
	global_load_lds_dwordx4 v[224:225], off
	v_lshl_add_u64 v[224:225], s[36:37], 0, v[182:183]
	s_mov_b32 m0, s43
	s_nop 0
	global_load_lds_dwordx4 v[224:225], off
	s_waitcnt vmcnt(8)
	s_waitcnt lgkmcnt(0)
	s_barrier
	s_setprio 1
	s_waitcnt lgkmcnt(0)
	v_mfma_f32_16x16x32_bf16 v[126:129], v[130:133], v[162:165], v[126:129]
	v_mfma_f32_16x16x32_bf16 v[122:125], v[138:141], v[162:165], v[122:125]
	v_mfma_f32_16x16x32_bf16 v[118:121], v[130:133], v[170:173], v[118:121]
	v_mfma_f32_16x16x32_bf16 v[114:117], v[138:141], v[170:173], v[114:117]
	v_mfma_f32_16x16x32_bf16 v[94:97], v[130:133], v[196:199], v[94:97]
	v_mfma_f32_16x16x32_bf16 v[90:93], v[138:141], v[196:199], v[90:93]
	v_mfma_f32_16x16x32_bf16 v[86:89], v[130:133], v[204:207], v[86:89]
	v_mfma_f32_16x16x32_bf16 v[82:85], v[138:141], v[204:207], v[82:85]
	v_mfma_f32_16x16x32_bf16 v[126:129], v[134:137], v[166:169], v[126:129]
	v_mfma_f32_16x16x32_bf16 v[122:125], v[142:145], v[166:169], v[122:125]
	v_mfma_f32_16x16x32_bf16 v[118:121], v[134:137], v[174:177], v[118:121]
	v_mfma_f32_16x16x32_bf16 v[114:117], v[142:145], v[174:177], v[114:117]
	v_mfma_f32_16x16x32_bf16 v[94:97], v[134:137], v[200:203], v[94:97]
	v_mfma_f32_16x16x32_bf16 v[90:93], v[142:145], v[200:203], v[90:93]
	v_mfma_f32_16x16x32_bf16 v[86:89], v[134:137], v[208:211], v[86:89]
	v_mfma_f32_16x16x32_bf16 v[82:85], v[142:145], v[208:211], v[82:85]
	v_mfma_f32_16x16x32_bf16 v[110:113], v[146:149], v[162:165], v[110:113]
	v_mfma_f32_16x16x32_bf16 v[106:109], v[154:157], v[162:165], v[106:109]
	v_mfma_f32_16x16x32_bf16 v[102:105], v[146:149], v[170:173], v[102:105]
	v_mfma_f32_16x16x32_bf16 v[98:101], v[154:157], v[170:173], v[98:101]
	v_mfma_f32_16x16x32_bf16 v[78:81], v[146:149], v[196:199], v[78:81]
	v_mfma_f32_16x16x32_bf16 v[74:77], v[154:157], v[196:199], v[74:77]
	v_mfma_f32_16x16x32_bf16 v[70:73], v[146:149], v[204:207], v[70:73]
	v_mfma_f32_16x16x32_bf16 v[66:69], v[154:157], v[204:207], v[66:69]
	v_mfma_f32_16x16x32_bf16 v[110:113], v[150:153], v[166:169], v[110:113]
	v_mfma_f32_16x16x32_bf16 v[106:109], v[158:161], v[166:169], v[106:109]
	v_mfma_f32_16x16x32_bf16 v[102:105], v[150:153], v[174:177], v[102:105]
	v_mfma_f32_16x16x32_bf16 v[98:101], v[158:161], v[174:177], v[98:101]
	v_mfma_f32_16x16x32_bf16 v[78:81], v[150:153], v[200:203], v[78:81]
	v_mfma_f32_16x16x32_bf16 v[74:77], v[158:161], v[200:203], v[74:77]
	v_mfma_f32_16x16x32_bf16 v[70:73], v[150:153], v[208:211], v[70:73]
	s_barrier
	v_mfma_f32_16x16x32_bf16 v[66:69], v[158:161], v[208:211], v[66:69]
	s_setprio 2
	s_add_i32 s36, s39, s33
	v_lshl_add_u64 v[192:193], v[192:193], 0, s[18:19]
	s_mov_b32 m0, s36
	ds_read_b128 v[162:165], v217 offset:49152
	ds_read_b128 v[166:169], v217 offset:50176
	ds_read_b128 v[170:173], v217 offset:51200
	ds_read_b128 v[174:177], v217 offset:52224
	ds_read_b128 v[196:199], v217 offset:53248
	ds_read_b128 v[200:203], v217 offset:54272
	ds_read_b128 v[204:207], v217 offset:55296
	ds_read_b128 v[208:211], v217 offset:56320
	global_load_lds_dwordx4 v[192:193], off
	s_add_i32 m0, s36, 0x2000
	s_add_u32 s34, s34, 0x160080
	v_lshl_add_u64 v[192:193], v[218:219], 0, s[18:19]
	s_addc_u32 s35, s35, 0
	s_add_i32 s36, s62, s33
	global_load_lds_dwordx4 v[192:193], off
	v_lshl_add_u64 v[192:193], s[34:35], 0, v[180:181]
	s_mov_b32 m0, s36
	s_nop 0
	global_load_lds_dwordx4 v[192:193], off
	v_lshl_add_u64 v[192:193], s[34:35], 0, v[184:185]
	s_add_i32 m0, s36, 0x2000
	s_nop 0
	global_load_lds_dwordx4 v[192:193], off
	v_lshl_add_u64 v[192:193], v[220:221], 0, s[18:19]
	s_mov_b32 m0, s46
	s_nop 0
	global_load_lds_dwordx4 v[192:193], off
	v_lshl_add_u64 v[192:193], v[222:223], 0, s[18:19]
	s_mov_b32 m0, s47
	s_nop 0
	global_load_lds_dwordx4 v[192:193], off
	s_waitcnt vmcnt(8)
	s_waitcnt lgkmcnt(0)
	s_barrier
	s_setprio 1
	s_waitcnt lgkmcnt(0)
	v_mfma_f32_16x16x32_bf16 v[62:65], v[130:133], v[162:165], v[62:65]
	v_mfma_f32_16x16x32_bf16 v[58:61], v[138:141], v[162:165], v[58:61]
	v_mfma_f32_16x16x32_bf16 v[54:57], v[130:133], v[170:173], v[54:57]
	v_mfma_f32_16x16x32_bf16 v[50:53], v[138:141], v[170:173], v[50:53]
	v_mfma_f32_16x16x32_bf16 v[30:33], v[130:133], v[196:199], v[30:33]
	v_mfma_f32_16x16x32_bf16 v[26:29], v[138:141], v[196:199], v[26:29]
	v_mfma_f32_16x16x32_bf16 v[22:25], v[130:133], v[204:207], v[22:25]
	v_mfma_f32_16x16x32_bf16 v[18:21], v[138:141], v[204:207], v[18:21]
	v_mfma_f32_16x16x32_bf16 v[62:65], v[134:137], v[166:169], v[62:65]
	v_mfma_f32_16x16x32_bf16 v[58:61], v[142:145], v[166:169], v[58:61]
	v_mfma_f32_16x16x32_bf16 v[54:57], v[134:137], v[174:177], v[54:57]
	v_mfma_f32_16x16x32_bf16 v[50:53], v[142:145], v[174:177], v[50:53]
	v_mfma_f32_16x16x32_bf16 v[30:33], v[134:137], v[200:203], v[30:33]
	v_mfma_f32_16x16x32_bf16 v[26:29], v[142:145], v[200:203], v[26:29]
	v_mfma_f32_16x16x32_bf16 v[22:25], v[134:137], v[208:211], v[22:25]
	v_mfma_f32_16x16x32_bf16 v[18:21], v[142:145], v[208:211], v[18:21]
	v_mfma_f32_16x16x32_bf16 v[46:49], v[146:149], v[162:165], v[46:49]
	v_mfma_f32_16x16x32_bf16 v[42:45], v[154:157], v[162:165], v[42:45]
	v_mfma_f32_16x16x32_bf16 v[38:41], v[146:149], v[170:173], v[38:41]
	v_mfma_f32_16x16x32_bf16 v[34:37], v[154:157], v[170:173], v[34:37]
	v_mfma_f32_16x16x32_bf16 v[14:17], v[146:149], v[196:199], v[14:17]
	v_mfma_f32_16x16x32_bf16 v[10:13], v[154:157], v[196:199], v[10:13]
	v_mfma_f32_16x16x32_bf16 v[6:9], v[146:149], v[204:207], v[6:9]
	v_mfma_f32_16x16x32_bf16 v[2:5], v[154:157], v[204:207], v[2:5]
	v_mfma_f32_16x16x32_bf16 v[46:49], v[150:153], v[166:169], v[46:49]
	v_mfma_f32_16x16x32_bf16 v[42:45], v[158:161], v[166:169], v[42:45]
	v_mfma_f32_16x16x32_bf16 v[38:41], v[150:153], v[174:177], v[38:41]
	v_mfma_f32_16x16x32_bf16 v[34:37], v[158:161], v[174:177], v[34:37]
	v_mfma_f32_16x16x32_bf16 v[14:17], v[150:153], v[200:203], v[14:17]
	v_mfma_f32_16x16x32_bf16 v[10:13], v[158:161], v[200:203], v[10:13]
	v_mfma_f32_16x16x32_bf16 v[6:9], v[150:153], v[208:211], v[6:9]
	s_barrier
	v_mfma_f32_16x16x32_bf16 v[2:5], v[158:161], v[208:211], v[2:5]
	s_setprio 2
	s_add_u32 s30, s30, 0x100
	s_addc_u32 s31, s31, 0
	s_add_u32 s23, s23, 0x100
	s_addc_u32 s29, s29, 0
	s_cmp_ge_i32 s38, s61
	s_mov_b32 s34, s38
	s_cbranch_scc0 .LBB0_357
	s_branch .Lpeeldone_12
.LBB0_357:
	ds_read_b128 v[130:133], v215
	ds_read_b128 v[134:137], v215 offset:1024
	ds_read_b128 v[138:141], v215 offset:2048
	ds_read_b128 v[142:145], v215 offset:3072
	ds_read_b128 v[146:149], v216
	ds_read_b128 v[150:153], v216 offset:1024
	ds_read_b128 v[154:157], v216 offset:2048
	ds_read_b128 v[158:161], v216 offset:3072
	s_add_i32 s38, s34, 2
	s_add_u32 s35, s30, 0xffea0080
	s_addc_u32 s36, s31, -1
	s_cmp_eq_u32 s28, s34
	s_cselect_b32 s34, s26, s23
	s_cselect_b32 s37, s25, s36
	s_cselect_b32 s36, s24, s35
	s_cselect_b32 s35, s27, s29
	v_lshl_add_u64 v[192:193], s[30:31], 0, v[188:189]
	s_add_i32 m0, s40, 0xc000
	ds_read_b128 v[162:165], v217
	ds_read_b128 v[166:169], v217 offset:1024
	ds_read_b128 v[170:173], v217 offset:2048
	ds_read_b128 v[174:177], v217 offset:3072
	ds_read_b128 v[196:199], v217 offset:4096
	ds_read_b128 v[200:203], v217 offset:5120
	ds_read_b128 v[204:207], v217 offset:6144
	ds_read_b128 v[208:211], v217 offset:7168
	global_load_lds_dwordx4 v[192:193], off
	v_lshl_add_u64 v[192:193], s[30:31], 0, v[190:191]
	s_add_i32 m0, s40, 0xe000
	s_nop 0
	global_load_lds_dwordx4 v[192:193], off
	s_waitcnt vmcnt(8)
	s_waitcnt lgkmcnt(0)
	s_barrier
	s_setprio 1
	s_waitcnt lgkmcnt(0)
	v_mfma_f32_16x16x32_bf16 v[126:129], v[130:133], v[162:165], v[126:129]
	v_mfma_f32_16x16x32_bf16 v[122:125], v[138:141], v[162:165], v[122:125]
	v_mfma_f32_16x16x32_bf16 v[118:121], v[130:133], v[170:173], v[118:121]
	v_mfma_f32_16x16x32_bf16 v[114:117], v[138:141], v[170:173], v[114:117]
	v_mfma_f32_16x16x32_bf16 v[94:97], v[130:133], v[196:199], v[94:97]
	v_mfma_f32_16x16x32_bf16 v[90:93], v[138:141], v[196:199], v[90:93]
	v_mfma_f32_16x16x32_bf16 v[86:89], v[130:133], v[204:207], v[86:89]
	v_mfma_f32_16x16x32_bf16 v[82:85], v[138:141], v[204:207], v[82:85]
	v_mfma_f32_16x16x32_bf16 v[126:129], v[134:137], v[166:169], v[126:129]
	v_mfma_f32_16x16x32_bf16 v[122:125], v[142:145], v[166:169], v[122:125]
	v_mfma_f32_16x16x32_bf16 v[118:121], v[134:137], v[174:177], v[118:121]
	v_mfma_f32_16x16x32_bf16 v[114:117], v[142:145], v[174:177], v[114:117]
	v_mfma_f32_16x16x32_bf16 v[94:97], v[134:137], v[200:203], v[94:97]
	v_mfma_f32_16x16x32_bf16 v[90:93], v[142:145], v[200:203], v[90:93]
	v_mfma_f32_16x16x32_bf16 v[86:89], v[134:137], v[208:211], v[86:89]
	v_mfma_f32_16x16x32_bf16 v[82:85], v[142:145], v[208:211], v[82:85]
	v_mfma_f32_16x16x32_bf16 v[110:113], v[146:149], v[162:165], v[110:113]
	v_mfma_f32_16x16x32_bf16 v[106:109], v[154:157], v[162:165], v[106:109]
	v_mfma_f32_16x16x32_bf16 v[102:105], v[146:149], v[170:173], v[102:105]
	v_mfma_f32_16x16x32_bf16 v[98:101], v[154:157], v[170:173], v[98:101]
	v_mfma_f32_16x16x32_bf16 v[78:81], v[146:149], v[196:199], v[78:81]
	v_mfma_f32_16x16x32_bf16 v[74:77], v[154:157], v[196:199], v[74:77]
	v_mfma_f32_16x16x32_bf16 v[70:73], v[146:149], v[204:207], v[70:73]
	v_mfma_f32_16x16x32_bf16 v[66:69], v[154:157], v[204:207], v[66:69]
	v_mfma_f32_16x16x32_bf16 v[110:113], v[150:153], v[166:169], v[110:113]
	v_mfma_f32_16x16x32_bf16 v[106:109], v[158:161], v[166:169], v[106:109]
	v_mfma_f32_16x16x32_bf16 v[102:105], v[150:153], v[174:177], v[102:105]
	v_mfma_f32_16x16x32_bf16 v[98:101], v[158:161], v[174:177], v[98:101]
	v_mfma_f32_16x16x32_bf16 v[78:81], v[150:153], v[200:203], v[78:81]
	v_mfma_f32_16x16x32_bf16 v[74:77], v[158:161], v[200:203], v[74:77]
	v_mfma_f32_16x16x32_bf16 v[70:73], v[150:153], v[208:211], v[70:73]
	s_barrier
	v_mfma_f32_16x16x32_bf16 v[66:69], v[158:161], v[208:211], v[66:69]
	s_setprio 2
	s_add_i32 s39, s53, s33
	v_lshl_add_u64 v[192:193], s[34:35], 0, v[180:181]
	s_mov_b32 m0, s39
	ds_read_b128 v[162:165], v217 offset:16384
	ds_read_b128 v[166:169], v217 offset:17408
	ds_read_b128 v[170:173], v217 offset:18432
	ds_read_b128 v[174:177], v217 offset:19456
	ds_read_b128 v[196:199], v217 offset:20480
	ds_read_b128 v[200:203], v217 offset:21504
	ds_read_b128 v[204:207], v217 offset:22528
	ds_read_b128 v[208:211], v217 offset:23552
	global_load_lds_dwordx4 v[192:193], off
	s_add_i32 m0, s39, 0x2000
	s_add_u32 s62, s34, 0x160000
	v_lshl_add_u64 v[218:219], s[34:35], 0, v[184:185]
	s_addc_u32 s63, s35, 0
	s_add_i32 s39, s54, s33
	global_load_lds_dwordx4 v[218:219], off
	v_lshl_add_u64 v[220:221], s[62:63], 0, v[180:181]
	s_mov_b32 m0, s39
	v_lshl_add_u64 v[222:223], s[36:37], 0, v[182:183]
	global_load_lds_dwordx4 v[220:221], off
	v_lshl_add_u64 v[220:221], s[62:63], 0, v[184:185]
	s_add_i32 m0, s39, 0x2000
	s_nop 0
	global_load_lds_dwordx4 v[220:221], off
	v_lshl_add_u64 v[220:221], s[36:37], 0, v[178:179]
	s_mov_b32 m0, s40
	s_nop 0
	global_load_lds_dwordx4 v[220:221], off
	s_mov_b32 m0, s41
	s_nop 0
	global_load_lds_dwordx4 v[222:223], off
	s_waitcnt vmcnt(8)
	s_waitcnt lgkmcnt(0)
	s_barrier
	s_setprio 1
	s_waitcnt lgkmcnt(0)
	v_mfma_f32_16x16x32_bf16 v[62:65], v[130:133], v[162:165], v[62:65]
	v_mfma_f32_16x16x32_bf16 v[58:61], v[138:141], v[162:165], v[58:61]
	v_mfma_f32_16x16x32_bf16 v[54:57], v[130:133], v[170:173], v[54:57]
	v_mfma_f32_16x16x32_bf16 v[50:53], v[138:141], v[170:173], v[50:53]
	v_mfma_f32_16x16x32_bf16 v[30:33], v[130:133], v[196:199], v[30:33]
	v_mfma_f32_16x16x32_bf16 v[26:29], v[138:141], v[196:199], v[26:29]
	v_mfma_f32_16x16x32_bf16 v[22:25], v[130:133], v[204:207], v[22:25]
	v_mfma_f32_16x16x32_bf16 v[18:21], v[138:141], v[204:207], v[18:21]
	v_mfma_f32_16x16x32_bf16 v[62:65], v[134:137], v[166:169], v[62:65]
	v_mfma_f32_16x16x32_bf16 v[58:61], v[142:145], v[166:169], v[58:61]
	v_mfma_f32_16x16x32_bf16 v[54:57], v[134:137], v[174:177], v[54:57]
	v_mfma_f32_16x16x32_bf16 v[50:53], v[142:145], v[174:177], v[50:53]
	v_mfma_f32_16x16x32_bf16 v[30:33], v[134:137], v[200:203], v[30:33]
	v_mfma_f32_16x16x32_bf16 v[26:29], v[142:145], v[200:203], v[26:29]
	v_mfma_f32_16x16x32_bf16 v[22:25], v[134:137], v[208:211], v[22:25]
	v_mfma_f32_16x16x32_bf16 v[18:21], v[142:145], v[208:211], v[18:21]
	v_mfma_f32_16x16x32_bf16 v[46:49], v[146:149], v[162:165], v[46:49]
	v_mfma_f32_16x16x32_bf16 v[42:45], v[154:157], v[162:165], v[42:45]
	v_mfma_f32_16x16x32_bf16 v[38:41], v[146:149], v[170:173], v[38:41]
	v_mfma_f32_16x16x32_bf16 v[34:37], v[154:157], v[170:173], v[34:37]
	v_mfma_f32_16x16x32_bf16 v[14:17], v[146:149], v[196:199], v[14:17]
	v_mfma_f32_16x16x32_bf16 v[10:13], v[154:157], v[196:199], v[10:13]
	v_mfma_f32_16x16x32_bf16 v[6:9], v[146:149], v[204:207], v[6:9]
	v_mfma_f32_16x16x32_bf16 v[2:5], v[154:157], v[204:207], v[2:5]
	v_mfma_f32_16x16x32_bf16 v[46:49], v[150:153], v[166:169], v[46:49]
	v_mfma_f32_16x16x32_bf16 v[42:45], v[158:161], v[166:169], v[42:45]
	v_mfma_f32_16x16x32_bf16 v[38:41], v[150:153], v[174:177], v[38:41]
	v_mfma_f32_16x16x32_bf16 v[34:37], v[158:161], v[174:177], v[34:37]
	v_mfma_f32_16x16x32_bf16 v[14:17], v[150:153], v[200:203], v[14:17]
	v_mfma_f32_16x16x32_bf16 v[10:13], v[158:161], v[200:203], v[10:13]
	v_mfma_f32_16x16x32_bf16 v[6:9], v[150:153], v[208:211], v[6:9]
	s_barrier
	v_mfma_f32_16x16x32_bf16 v[2:5], v[158:161], v[208:211], v[2:5]
	s_setprio 2
	s_add_i32 s39, 0, 0x18000
	s_add_i32 s62, 0, 0x1c000
	v_add_u32_e32 v142, s39, v213
	v_add_u32_e32 v158, s62, v213
	ds_read_b128 v[130:133], v142
	ds_read_b128 v[134:137], v142 offset:1024
	ds_read_b128 v[138:141], v142 offset:2048
	ds_read_b128 v[142:145], v142 offset:3072
	ds_read_b128 v[146:149], v158
	ds_read_b128 v[150:153], v158 offset:1024
	ds_read_b128 v[154:157], v158 offset:2048
	ds_read_b128 v[158:161], v158 offset:3072
	s_add_u32 s36, s36, 0x160000
	s_addc_u32 s37, s37, 0
	s_mov_b32 m0, s42
	v_lshl_add_u64 v[224:225], s[36:37], 0, v[178:179]
	ds_read_b128 v[162:165], v217 offset:32768
	ds_read_b128 v[166:169], v217 offset:33792
	ds_read_b128 v[170:173], v217 offset:34816
	ds_read_b128 v[174:177], v217 offset:35840
	ds_read_b128 v[196:199], v217 offset:36864
	ds_read_b128 v[200:203], v217 offset:37888
	ds_read_b128 v[204:207], v217 offset:38912
	ds_read_b128 v[208:211], v217 offset:39936
	global_load_lds_dwordx4 v[224:225], off
	v_lshl_add_u64 v[224:225], s[36:37], 0, v[182:183]
	s_mov_b32 m0, s43
	s_nop 0
	global_load_lds_dwordx4 v[224:225], off
	s_waitcnt vmcnt(8)
	s_waitcnt lgkmcnt(0)
	s_barrier
	s_setprio 1
	s_waitcnt lgkmcnt(0)
	v_mfma_f32_16x16x32_bf16 v[126:129], v[130:133], v[162:165], v[126:129]
	v_mfma_f32_16x16x32_bf16 v[122:125], v[138:141], v[162:165], v[122:125]
	v_mfma_f32_16x16x32_bf16 v[118:121], v[130:133], v[170:173], v[118:121]
	v_mfma_f32_16x16x32_bf16 v[114:117], v[138:141], v[170:173], v[114:117]
	v_mfma_f32_16x16x32_bf16 v[94:97], v[130:133], v[196:199], v[94:97]
	v_mfma_f32_16x16x32_bf16 v[90:93], v[138:141], v[196:199], v[90:93]
	v_mfma_f32_16x16x32_bf16 v[86:89], v[130:133], v[204:207], v[86:89]
	v_mfma_f32_16x16x32_bf16 v[82:85], v[138:141], v[204:207], v[82:85]
	v_mfma_f32_16x16x32_bf16 v[126:129], v[134:137], v[166:169], v[126:129]
	v_mfma_f32_16x16x32_bf16 v[122:125], v[142:145], v[166:169], v[122:125]
	v_mfma_f32_16x16x32_bf16 v[118:121], v[134:137], v[174:177], v[118:121]
	v_mfma_f32_16x16x32_bf16 v[114:117], v[142:145], v[174:177], v[114:117]
	v_mfma_f32_16x16x32_bf16 v[94:97], v[134:137], v[200:203], v[94:97]
	v_mfma_f32_16x16x32_bf16 v[90:93], v[142:145], v[200:203], v[90:93]
	v_mfma_f32_16x16x32_bf16 v[86:89], v[134:137], v[208:211], v[86:89]
	v_mfma_f32_16x16x32_bf16 v[82:85], v[142:145], v[208:211], v[82:85]
	v_mfma_f32_16x16x32_bf16 v[110:113], v[146:149], v[162:165], v[110:113]
	v_mfma_f32_16x16x32_bf16 v[106:109], v[154:157], v[162:165], v[106:109]
	v_mfma_f32_16x16x32_bf16 v[102:105], v[146:149], v[170:173], v[102:105]
	v_mfma_f32_16x16x32_bf16 v[98:101], v[154:157], v[170:173], v[98:101]
	v_mfma_f32_16x16x32_bf16 v[78:81], v[146:149], v[196:199], v[78:81]
	v_mfma_f32_16x16x32_bf16 v[74:77], v[154:157], v[196:199], v[74:77]
	v_mfma_f32_16x16x32_bf16 v[70:73], v[146:149], v[204:207], v[70:73]
	v_mfma_f32_16x16x32_bf16 v[66:69], v[154:157], v[204:207], v[66:69]
	v_mfma_f32_16x16x32_bf16 v[110:113], v[150:153], v[166:169], v[110:113]
	v_mfma_f32_16x16x32_bf16 v[106:109], v[158:161], v[166:169], v[106:109]
	v_mfma_f32_16x16x32_bf16 v[102:105], v[150:153], v[174:177], v[102:105]
	v_mfma_f32_16x16x32_bf16 v[98:101], v[158:161], v[174:177], v[98:101]
	v_mfma_f32_16x16x32_bf16 v[78:81], v[150:153], v[200:203], v[78:81]
	v_mfma_f32_16x16x32_bf16 v[74:77], v[158:161], v[200:203], v[74:77]
	v_mfma_f32_16x16x32_bf16 v[70:73], v[150:153], v[208:211], v[70:73]
	s_barrier
	v_mfma_f32_16x16x32_bf16 v[66:69], v[158:161], v[208:211], v[66:69]
	s_setprio 2
	s_add_i32 s36, s39, s33
	v_lshl_add_u64 v[192:193], v[192:193], 0, s[18:19]
	s_mov_b32 m0, s36
	ds_read_b128 v[162:165], v217 offset:49152
	ds_read_b128 v[166:169], v217 offset:50176
	ds_read_b128 v[170:173], v217 offset:51200
	ds_read_b128 v[174:177], v217 offset:52224
	ds_read_b128 v[196:199], v217 offset:53248
	ds_read_b128 v[200:203], v217 offset:54272
	ds_read_b128 v[204:207], v217 offset:55296
	ds_read_b128 v[208:211], v217 offset:56320
	global_load_lds_dwordx4 v[192:193], off
	s_add_i32 m0, s36, 0x2000
	s_add_u32 s34, s34, 0x160080
	v_lshl_add_u64 v[192:193], v[218:219], 0, s[18:19]
	s_addc_u32 s35, s35, 0
	s_add_i32 s36, s62, s33
	global_load_lds_dwordx4 v[192:193], off
	v_lshl_add_u64 v[192:193], s[34:35], 0, v[180:181]
	s_mov_b32 m0, s36
	s_nop 0
	global_load_lds_dwordx4 v[192:193], off
	v_lshl_add_u64 v[192:193], s[34:35], 0, v[184:185]
	s_add_i32 m0, s36, 0x2000
	s_nop 0
	global_load_lds_dwordx4 v[192:193], off
	v_lshl_add_u64 v[192:193], v[220:221], 0, s[18:19]
	s_mov_b32 m0, s46
	s_nop 0
	global_load_lds_dwordx4 v[192:193], off
	v_lshl_add_u64 v[192:193], v[222:223], 0, s[18:19]
	s_mov_b32 m0, s47
	s_nop 0
	global_load_lds_dwordx4 v[192:193], off
	s_waitcnt vmcnt(8)
	s_waitcnt lgkmcnt(0)
	s_barrier
	s_setprio 1
	s_waitcnt lgkmcnt(0)
	v_mfma_f32_16x16x32_bf16 v[62:65], v[130:133], v[162:165], v[62:65]
	v_mfma_f32_16x16x32_bf16 v[58:61], v[138:141], v[162:165], v[58:61]
	v_mfma_f32_16x16x32_bf16 v[54:57], v[130:133], v[170:173], v[54:57]
	v_mfma_f32_16x16x32_bf16 v[50:53], v[138:141], v[170:173], v[50:53]
	v_mfma_f32_16x16x32_bf16 v[30:33], v[130:133], v[196:199], v[30:33]
	v_mfma_f32_16x16x32_bf16 v[26:29], v[138:141], v[196:199], v[26:29]
	v_mfma_f32_16x16x32_bf16 v[22:25], v[130:133], v[204:207], v[22:25]
	v_mfma_f32_16x16x32_bf16 v[18:21], v[138:141], v[204:207], v[18:21]
	v_mfma_f32_16x16x32_bf16 v[62:65], v[134:137], v[166:169], v[62:65]
	v_mfma_f32_16x16x32_bf16 v[58:61], v[142:145], v[166:169], v[58:61]
	v_mfma_f32_16x16x32_bf16 v[54:57], v[134:137], v[174:177], v[54:57]
	v_mfma_f32_16x16x32_bf16 v[50:53], v[142:145], v[174:177], v[50:53]
	v_mfma_f32_16x16x32_bf16 v[30:33], v[134:137], v[200:203], v[30:33]
	v_mfma_f32_16x16x32_bf16 v[26:29], v[142:145], v[200:203], v[26:29]
	v_mfma_f32_16x16x32_bf16 v[22:25], v[134:137], v[208:211], v[22:25]
	v_mfma_f32_16x16x32_bf16 v[18:21], v[142:145], v[208:211], v[18:21]
	v_mfma_f32_16x16x32_bf16 v[46:49], v[146:149], v[162:165], v[46:49]
	v_mfma_f32_16x16x32_bf16 v[42:45], v[154:157], v[162:165], v[42:45]
	v_mfma_f32_16x16x32_bf16 v[38:41], v[146:149], v[170:173], v[38:41]
	v_mfma_f32_16x16x32_bf16 v[34:37], v[154:157], v[170:173], v[34:37]
	v_mfma_f32_16x16x32_bf16 v[14:17], v[146:149], v[196:199], v[14:17]
	v_mfma_f32_16x16x32_bf16 v[10:13], v[154:157], v[196:199], v[10:13]
	v_mfma_f32_16x16x32_bf16 v[6:9], v[146:149], v[204:207], v[6:9]
	v_mfma_f32_16x16x32_bf16 v[2:5], v[154:157], v[204:207], v[2:5]
	v_mfma_f32_16x16x32_bf16 v[46:49], v[150:153], v[166:169], v[46:49]
	v_mfma_f32_16x16x32_bf16 v[42:45], v[158:161], v[166:169], v[42:45]
	v_mfma_f32_16x16x32_bf16 v[38:41], v[150:153], v[174:177], v[38:41]
	v_mfma_f32_16x16x32_bf16 v[34:37], v[158:161], v[174:177], v[34:37]
	v_mfma_f32_16x16x32_bf16 v[14:17], v[150:153], v[200:203], v[14:17]
	v_mfma_f32_16x16x32_bf16 v[10:13], v[158:161], v[200:203], v[10:13]
	v_mfma_f32_16x16x32_bf16 v[6:9], v[150:153], v[208:211], v[6:9]
	s_barrier
	v_mfma_f32_16x16x32_bf16 v[2:5], v[158:161], v[208:211], v[2:5]
	s_setprio 2
	s_add_u32 s30, s30, 0x100
	s_addc_u32 s31, s31, 0
	s_add_u32 s23, s23, 0x100
	s_addc_u32 s29, s29, 0
	s_cmp_ge_i32 s38, s61
	s_mov_b32 s34, s38
	s_cbranch_scc0 .LBB0_357

.Lpeel_11:
	ds_read_b128 v[148:151], v145
	ds_read_b128 v[152:155], v145 offset:1024
	s_add_u32 s36, s34, 0xfff80080
	s_addc_u32 s37, s35, -1
	s_cmp_eq_u32 s58, 28
	s_cselect_b32 s39, s21, s37
	s_cselect_b32 s38, s54, s36
	s_cselect_b32 s37, s23, s57
	s_cselect_b32 s36, s55, s56
	v_lshl_add_u64 v[192:193], s[34:35], 0, v[138:139]
	s_add_i32 m0, s27, 0xc000
	global_load_lds_dwordx4 v[192:193], off
	v_lshl_add_u64 v[192:193], s[34:35], 0, v[140:141]
	s_add_i32 m0, s27, 0xe000
	s_nop 0
	global_load_lds_dwordx4 v[192:193], off
	s_waitcnt vmcnt(8)
	s_waitcnt lgkmcnt(0)
	s_barrier
	s_setprio 1
	s_waitcnt lgkmcnt(0)
	v_mfma_f32_16x16x32_bf16 v[126:129], v[148:151], v[180:183], 0
	v_mfma_f32_16x16x32_bf16 v[122:125], v[156:159], v[180:183], 0
	v_mfma_f32_16x16x32_bf16 v[118:121], v[148:151], v[188:191], 0
	v_mfma_f32_16x16x32_bf16 v[114:117], v[156:159], v[188:191], 0
	v_mfma_f32_16x16x32_bf16 v[102:105], v[148:151], v[200:203], 0
	v_mfma_f32_16x16x32_bf16 v[98:101], v[156:159], v[200:203], 0
	v_mfma_f32_16x16x32_bf16 v[86:89], v[148:151], v[208:211], 0
	v_mfma_f32_16x16x32_bf16 v[82:85], v[156:159], v[208:211], 0
	v_mfma_f32_16x16x32_bf16 v[126:129], v[152:155], v[184:187], v[126:129]
	v_mfma_f32_16x16x32_bf16 v[122:125], v[160:163], v[184:187], v[122:125]
	v_mfma_f32_16x16x32_bf16 v[118:121], v[152:155], v[196:199], v[118:121]
	v_mfma_f32_16x16x32_bf16 v[114:117], v[160:163], v[196:199], v[114:117]
	v_mfma_f32_16x16x32_bf16 v[102:105], v[152:155], v[204:207], v[102:105]
	v_mfma_f32_16x16x32_bf16 v[98:101], v[160:163], v[204:207], v[98:101]
	v_mfma_f32_16x16x32_bf16 v[86:89], v[152:155], v[212:215], v[86:89]
	v_mfma_f32_16x16x32_bf16 v[82:85], v[160:163], v[212:215], v[82:85]
	v_mfma_f32_16x16x32_bf16 v[110:113], v[164:167], v[180:183], 0
	v_mfma_f32_16x16x32_bf16 v[106:109], v[172:175], v[180:183], 0
	v_mfma_f32_16x16x32_bf16 v[94:97], v[164:167], v[188:191], 0
	v_mfma_f32_16x16x32_bf16 v[90:93], v[172:175], v[188:191], 0
	v_mfma_f32_16x16x32_bf16 v[78:81], v[164:167], v[200:203], 0
	v_mfma_f32_16x16x32_bf16 v[74:77], v[172:175], v[200:203], 0
	v_mfma_f32_16x16x32_bf16 v[70:73], v[164:167], v[208:211], 0
	v_mfma_f32_16x16x32_bf16 v[66:69], v[172:175], v[208:211], 0
	v_mfma_f32_16x16x32_bf16 v[110:113], v[168:171], v[184:187], v[110:113]
	v_mfma_f32_16x16x32_bf16 v[106:109], v[176:179], v[184:187], v[106:109]
	v_mfma_f32_16x16x32_bf16 v[94:97], v[168:171], v[196:199], v[94:97]
	v_mfma_f32_16x16x32_bf16 v[90:93], v[176:179], v[196:199], v[90:93]
	v_mfma_f32_16x16x32_bf16 v[78:81], v[168:171], v[204:207], v[78:81]
	v_mfma_f32_16x16x32_bf16 v[74:77], v[176:179], v[204:207], v[74:77]
	v_mfma_f32_16x16x32_bf16 v[70:73], v[168:171], v[212:215], v[70:73]
	s_barrier
	v_mfma_f32_16x16x32_bf16 v[66:69], v[176:179], v[212:215], v[66:69]
	s_setprio 2
	s_add_i32 s59, s47, s33
	v_lshl_add_u64 v[192:193], s[36:37], 0, v[134:135]
	s_mov_b32 m0, s59
	ds_read_b128 v[180:183], v147 offset:16384
	ds_read_b128 v[184:187], v147 offset:17408
	ds_read_b128 v[188:191], v147 offset:18432
	ds_read_b128 v[196:199], v147 offset:19456
	ds_read_b128 v[200:203], v147 offset:20480
	ds_read_b128 v[204:207], v147 offset:21504
	ds_read_b128 v[208:211], v147 offset:22528
	ds_read_b128 v[212:215], v147 offset:23552
	global_load_lds_dwordx4 v[192:193], off
	s_add_i32 m0, s59, 0x2000
	s_add_u32 s60, s36, 0x80000
	v_lshl_add_u64 v[216:217], s[36:37], 0, v[130:131]
	s_addc_u32 s61, s37, 0
	s_add_i32 s59, s48, s33
	global_load_lds_dwordx4 v[216:217], off
	v_lshl_add_u64 v[218:219], s[60:61], 0, v[134:135]
	s_mov_b32 m0, s59
	v_lshl_add_u64 v[220:221], s[38:39], 0, v[132:133]
	global_load_lds_dwordx4 v[218:219], off
	v_lshl_add_u64 v[218:219], s[60:61], 0, v[130:131]
	s_add_i32 m0, s59, 0x2000
	s_nop 0
	global_load_lds_dwordx4 v[218:219], off
	v_lshl_add_u64 v[218:219], s[38:39], 0, v[136:137]
	s_mov_b32 m0, s27
	s_nop 0
	global_load_lds_dwordx4 v[218:219], off
	s_mov_b32 m0, s41
	s_nop 0
	global_load_lds_dwordx4 v[220:221], off
	s_waitcnt vmcnt(8)
	s_waitcnt lgkmcnt(0)
	s_barrier
	s_setprio 1
	s_waitcnt lgkmcnt(0)
	v_mfma_f32_16x16x32_bf16 v[62:65], v[148:151], v[180:183], 0
	v_mfma_f32_16x16x32_bf16 v[58:61], v[156:159], v[180:183], 0
	v_mfma_f32_16x16x32_bf16 v[54:57], v[148:151], v[188:191], 0
	v_mfma_f32_16x16x32_bf16 v[50:53], v[156:159], v[188:191], 0
	v_mfma_f32_16x16x32_bf16 v[38:41], v[148:151], v[200:203], 0
	v_mfma_f32_16x16x32_bf16 v[34:37], v[156:159], v[200:203], 0
	v_mfma_f32_16x16x32_bf16 v[22:25], v[148:151], v[208:211], 0
	v_mfma_f32_16x16x32_bf16 v[18:21], v[156:159], v[208:211], 0
	v_mfma_f32_16x16x32_bf16 v[62:65], v[152:155], v[184:187], v[62:65]
	v_mfma_f32_16x16x32_bf16 v[58:61], v[160:163], v[184:187], v[58:61]
	v_mfma_f32_16x16x32_bf16 v[54:57], v[152:155], v[196:199], v[54:57]
	v_mfma_f32_16x16x32_bf16 v[50:53], v[160:163], v[196:199], v[50:53]
	v_mfma_f32_16x16x32_bf16 v[38:41], v[152:155], v[204:207], v[38:41]
	v_mfma_f32_16x16x32_bf16 v[34:37], v[160:163], v[204:207], v[34:37]
	v_mfma_f32_16x16x32_bf16 v[22:25], v[152:155], v[212:215], v[22:25]
	v_mfma_f32_16x16x32_bf16 v[18:21], v[160:163], v[212:215], v[18:21]
	v_mfma_f32_16x16x32_bf16 v[46:49], v[164:167], v[180:183], 0
	v_mfma_f32_16x16x32_bf16 v[42:45], v[172:175], v[180:183], 0
	v_mfma_f32_16x16x32_bf16 v[30:33], v[164:167], v[188:191], 0
	v_mfma_f32_16x16x32_bf16 v[26:29], v[172:175], v[188:191], 0
	v_mfma_f32_16x16x32_bf16 v[14:17], v[164:167], v[200:203], 0
	v_mfma_f32_16x16x32_bf16 v[10:13], v[172:175], v[200:203], 0
	v_mfma_f32_16x16x32_bf16 v[6:9], v[164:167], v[208:211], 0
	v_mfma_f32_16x16x32_bf16 v[2:5], v[172:175], v[208:211], 0
	v_mfma_f32_16x16x32_bf16 v[46:49], v[168:171], v[184:187], v[46:49]
	v_mfma_f32_16x16x32_bf16 v[42:45], v[176:179], v[184:187], v[42:45]
	v_mfma_f32_16x16x32_bf16 v[30:33], v[168:171], v[196:199], v[30:33]
	v_mfma_f32_16x16x32_bf16 v[26:29], v[176:179], v[196:199], v[26:29]
	v_mfma_f32_16x16x32_bf16 v[14:17], v[168:171], v[204:207], v[14:17]
	v_mfma_f32_16x16x32_bf16 v[10:13], v[176:179], v[204:207], v[10:13]
	v_mfma_f32_16x16x32_bf16 v[6:9], v[168:171], v[212:215], v[6:9]
	s_barrier
	v_mfma_f32_16x16x32_bf16 v[2:5], v[176:179], v[212:215], v[2:5]
	s_setprio 2
	s_add_i32 s59, 0, 0x18000
	s_add_i32 s60, 0, 0x1c000
	v_add_u32_e32 v160, s59, v143
	v_add_u32_e32 v176, s60, v143
	ds_read_b128 v[148:151], v160
	ds_read_b128 v[152:155], v160 offset:1024
	ds_read_b128 v[156:159], v160 offset:2048
	ds_read_b128 v[160:163], v160 offset:3072
	ds_read_b128 v[164:167], v176
	ds_read_b128 v[168:171], v176 offset:1024
	ds_read_b128 v[172:175], v176 offset:2048
	ds_read_b128 v[176:179], v176 offset:3072
	s_add_u32 s38, s38, 0x80000
	s_addc_u32 s39, s39, 0
	s_mov_b32 m0, s42
	v_lshl_add_u64 v[222:223], s[38:39], 0, v[136:137]
	ds_read_b128 v[180:183], v147 offset:32768
	ds_read_b128 v[184:187], v147 offset:33792
	ds_read_b128 v[188:191], v147 offset:34816
	ds_read_b128 v[196:199], v147 offset:35840
	ds_read_b128 v[200:203], v147 offset:36864
	ds_read_b128 v[204:207], v147 offset:37888
	ds_read_b128 v[208:211], v147 offset:38912
	ds_read_b128 v[212:215], v147 offset:39936
	global_load_lds_dwordx4 v[222:223], off
	v_lshl_add_u64 v[222:223], s[38:39], 0, v[132:133]
	s_mov_b32 m0, s43
	s_nop 0
	global_load_lds_dwordx4 v[222:223], off
	s_waitcnt vmcnt(8)
	s_waitcnt lgkmcnt(0)
	s_barrier
	s_setprio 1
	s_waitcnt lgkmcnt(0)
	v_mfma_f32_16x16x32_bf16 v[126:129], v[148:151], v[180:183], v[126:129]
	v_mfma_f32_16x16x32_bf16 v[122:125], v[156:159], v[180:183], v[122:125]
	v_mfma_f32_16x16x32_bf16 v[118:121], v[148:151], v[188:191], v[118:121]
	v_mfma_f32_16x16x32_bf16 v[114:117], v[156:159], v[188:191], v[114:117]
	v_mfma_f32_16x16x32_bf16 v[102:105], v[148:151], v[200:203], v[102:105]
	v_mfma_f32_16x16x32_bf16 v[98:101], v[156:159], v[200:203], v[98:101]
	v_mfma_f32_16x16x32_bf16 v[86:89], v[148:151], v[208:211], v[86:89]
	v_mfma_f32_16x16x32_bf16 v[82:85], v[156:159], v[208:211], v[82:85]
	v_mfma_f32_16x16x32_bf16 v[126:129], v[152:155], v[184:187], v[126:129]
	v_mfma_f32_16x16x32_bf16 v[122:125], v[160:163], v[184:187], v[122:125]
	v_mfma_f32_16x16x32_bf16 v[118:121], v[152:155], v[196:199], v[118:121]
	v_mfma_f32_16x16x32_bf16 v[114:117], v[160:163], v[196:199], v[114:117]
	v_mfma_f32_16x16x32_bf16 v[102:105], v[152:155], v[204:207], v[102:105]
	v_mfma_f32_16x16x32_bf16 v[98:101], v[160:163], v[204:207], v[98:101]
	v_mfma_f32_16x16x32_bf16 v[86:89], v[152:155], v[212:215], v[86:89]
	v_mfma_f32_16x16x32_bf16 v[82:85], v[160:163], v[212:215], v[82:85]
	v_mfma_f32_16x16x32_bf16 v[110:113], v[164:167], v[180:183], v[110:113]
	v_mfma_f32_16x16x32_bf16 v[106:109], v[172:175], v[180:183], v[106:109]
	v_mfma_f32_16x16x32_bf16 v[94:97], v[164:167], v[188:191], v[94:97]
	v_mfma_f32_16x16x32_bf16 v[90:93], v[172:175], v[188:191], v[90:93]
	v_mfma_f32_16x16x32_bf16 v[78:81], v[164:167], v[200:203], v[78:81]
	v_mfma_f32_16x16x32_bf16 v[74:77], v[172:175], v[200:203], v[74:77]
	v_mfma_f32_16x16x32_bf16 v[70:73], v[164:167], v[208:211], v[70:73]
	v_mfma_f32_16x16x32_bf16 v[66:69], v[172:175], v[208:211], v[66:69]
	v_mfma_f32_16x16x32_bf16 v[110:113], v[168:171], v[184:187], v[110:113]
	v_mfma_f32_16x16x32_bf16 v[106:109], v[176:179], v[184:187], v[106:109]
	v_mfma_f32_16x16x32_bf16 v[94:97], v[168:171], v[196:199], v[94:97]
	v_mfma_f32_16x16x32_bf16 v[90:93], v[176:179], v[196:199], v[90:93]
	v_mfma_f32_16x16x32_bf16 v[78:81], v[168:171], v[204:207], v[78:81]
	v_mfma_f32_16x16x32_bf16 v[74:77], v[176:179], v[204:207], v[74:77]
	v_mfma_f32_16x16x32_bf16 v[70:73], v[168:171], v[212:215], v[70:73]
	s_barrier
	v_mfma_f32_16x16x32_bf16 v[66:69], v[176:179], v[212:215], v[66:69]
	s_setprio 2
	s_add_i32 s38, s59, s33
	v_lshl_add_u64 v[192:193], v[192:193], 0, s[6:7]
	s_mov_b32 m0, s38
	ds_read_b128 v[180:183], v147 offset:49152
	ds_read_b128 v[184:187], v147 offset:50176
	ds_read_b128 v[188:191], v147 offset:51200
	ds_read_b128 v[196:199], v147 offset:52224
	ds_read_b128 v[200:203], v147 offset:53248
	ds_read_b128 v[204:207], v147 offset:54272
	ds_read_b128 v[208:211], v147 offset:55296
	ds_read_b128 v[212:215], v147 offset:56320
	global_load_lds_dwordx4 v[192:193], off
	s_add_i32 m0, s38, 0x2000
	s_add_u32 s36, s36, 0x80080
	v_lshl_add_u64 v[192:193], v[216:217], 0, s[6:7]
	s_addc_u32 s37, s37, 0
	s_add_i32 s38, s60, s33
	global_load_lds_dwordx4 v[192:193], off
	v_lshl_add_u64 v[192:193], s[36:37], 0, v[134:135]
	s_mov_b32 m0, s38
	s_nop 0
	global_load_lds_dwordx4 v[192:193], off
	v_lshl_add_u64 v[192:193], s[36:37], 0, v[130:131]
	s_add_i32 m0, s38, 0x2000
	s_nop 0
	global_load_lds_dwordx4 v[192:193], off
	v_lshl_add_u64 v[192:193], v[218:219], 0, s[6:7]
	s_mov_b32 m0, s45
	s_nop 0
	global_load_lds_dwordx4 v[192:193], off
	v_lshl_add_u64 v[192:193], v[220:221], 0, s[6:7]
	s_mov_b32 m0, s46
	s_nop 0
	global_load_lds_dwordx4 v[192:193], off
	s_waitcnt vmcnt(8)
	s_waitcnt lgkmcnt(0)
	s_barrier
	s_setprio 1
	s_waitcnt lgkmcnt(0)
	v_mfma_f32_16x16x32_bf16 v[62:65], v[148:151], v[180:183], v[62:65]
	v_mfma_f32_16x16x32_bf16 v[58:61], v[156:159], v[180:183], v[58:61]
	v_mfma_f32_16x16x32_bf16 v[54:57], v[148:151], v[188:191], v[54:57]
	v_mfma_f32_16x16x32_bf16 v[50:53], v[156:159], v[188:191], v[50:53]
	v_mfma_f32_16x16x32_bf16 v[38:41], v[148:151], v[200:203], v[38:41]
	v_mfma_f32_16x16x32_bf16 v[34:37], v[156:159], v[200:203], v[34:37]
	v_mfma_f32_16x16x32_bf16 v[22:25], v[148:151], v[208:211], v[22:25]
	v_mfma_f32_16x16x32_bf16 v[18:21], v[156:159], v[208:211], v[18:21]
	v_mfma_f32_16x16x32_bf16 v[62:65], v[152:155], v[184:187], v[62:65]
	v_mfma_f32_16x16x32_bf16 v[58:61], v[160:163], v[184:187], v[58:61]
	v_mfma_f32_16x16x32_bf16 v[54:57], v[152:155], v[196:199], v[54:57]
	v_mfma_f32_16x16x32_bf16 v[50:53], v[160:163], v[196:199], v[50:53]
	v_mfma_f32_16x16x32_bf16 v[38:41], v[152:155], v[204:207], v[38:41]
	v_mfma_f32_16x16x32_bf16 v[34:37], v[160:163], v[204:207], v[34:37]
	v_mfma_f32_16x16x32_bf16 v[22:25], v[152:155], v[212:215], v[22:25]
	v_mfma_f32_16x16x32_bf16 v[18:21], v[160:163], v[212:215], v[18:21]
	v_mfma_f32_16x16x32_bf16 v[46:49], v[164:167], v[180:183], v[46:49]
	v_mfma_f32_16x16x32_bf16 v[42:45], v[172:175], v[180:183], v[42:45]
	v_mfma_f32_16x16x32_bf16 v[30:33], v[164:167], v[188:191], v[30:33]
	v_mfma_f32_16x16x32_bf16 v[26:29], v[172:175], v[188:191], v[26:29]
	v_mfma_f32_16x16x32_bf16 v[14:17], v[164:167], v[200:203], v[14:17]
	v_mfma_f32_16x16x32_bf16 v[10:13], v[172:175], v[200:203], v[10:13]
	v_mfma_f32_16x16x32_bf16 v[6:9], v[164:167], v[208:211], v[6:9]
	v_mfma_f32_16x16x32_bf16 v[2:5], v[172:175], v[208:211], v[2:5]
	v_mfma_f32_16x16x32_bf16 v[46:49], v[168:171], v[184:187], v[46:49]
	v_mfma_f32_16x16x32_bf16 v[42:45], v[176:179], v[184:187], v[42:45]
	v_mfma_f32_16x16x32_bf16 v[30:33], v[168:171], v[196:199], v[30:33]
	v_mfma_f32_16x16x32_bf16 v[26:29], v[176:179], v[196:199], v[26:29]
	v_mfma_f32_16x16x32_bf16 v[14:17], v[168:171], v[204:207], v[14:17]
	v_mfma_f32_16x16x32_bf16 v[10:13], v[176:179], v[204:207], v[10:13]
	v_mfma_f32_16x16x32_bf16 v[6:9], v[168:171], v[212:215], v[6:9]
	s_barrier
	v_mfma_f32_16x16x32_bf16 v[2:5], v[176:179], v[212:215], v[2:5]
	s_setprio 2
	s_add_i32 s58, s58, 2
	s_add_u32 s34, s34, 0x100
	s_addc_u32 s35, s35, 0
	s_add_u32 s56, s56, 0x100
	s_addc_u32 s57, s57, 0
	s_cmp_gt_u32 s58, 29
	s_cbranch_scc0 .LBB0_541
	s_branch .Lpeeldone_11
.LBB0_541:
	ds_read_b128 v[148:151], v145
	ds_read_b128 v[152:155], v145 offset:1024
	ds_read_b128 v[156:159], v145 offset:2048
	ds_read_b128 v[160:163], v145 offset:3072
	ds_read_b128 v[164:167], v146
	ds_read_b128 v[168:171], v146 offset:1024
	ds_read_b128 v[172:175], v146 offset:2048
	ds_read_b128 v[176:179], v146 offset:3072
	s_add_u32 s36, s34, 0xfff80080
	s_addc_u32 s37, s35, -1
	s_cmp_eq_u32 s58, 28
	s_cselect_b32 s39, s21, s37
	s_cselect_b32 s38, s54, s36
	s_cselect_b32 s37, s23, s57
	s_cselect_b32 s36, s55, s56
	v_lshl_add_u64 v[192:193], s[34:35], 0, v[138:139]
	s_add_i32 m0, s27, 0xc000
	ds_read_b128 v[180:183], v147
	ds_read_b128 v[184:187], v147 offset:1024
	ds_read_b128 v[188:191], v147 offset:2048
	ds_read_b128 v[196:199], v147 offset:3072
	ds_read_b128 v[200:203], v147 offset:4096
	ds_read_b128 v[204:207], v147 offset:5120
	ds_read_b128 v[208:211], v147 offset:6144
	ds_read_b128 v[212:215], v147 offset:7168
	global_load_lds_dwordx4 v[192:193], off
	v_lshl_add_u64 v[192:193], s[34:35], 0, v[140:141]
	s_add_i32 m0, s27, 0xe000
	s_nop 0
	global_load_lds_dwordx4 v[192:193], off
	s_waitcnt vmcnt(8)
	s_waitcnt lgkmcnt(0)
	s_barrier
	s_setprio 1
	s_waitcnt lgkmcnt(0)
	v_mfma_f32_16x16x32_bf16 v[126:129], v[148:151], v[180:183], v[126:129]
	v_mfma_f32_16x16x32_bf16 v[122:125], v[156:159], v[180:183], v[122:125]
	v_mfma_f32_16x16x32_bf16 v[118:121], v[148:151], v[188:191], v[118:121]
	v_mfma_f32_16x16x32_bf16 v[114:117], v[156:159], v[188:191], v[114:117]
	v_mfma_f32_16x16x32_bf16 v[102:105], v[148:151], v[200:203], v[102:105]
	v_mfma_f32_16x16x32_bf16 v[98:101], v[156:159], v[200:203], v[98:101]
	v_mfma_f32_16x16x32_bf16 v[86:89], v[148:151], v[208:211], v[86:89]
	v_mfma_f32_16x16x32_bf16 v[82:85], v[156:159], v[208:211], v[82:85]
	v_mfma_f32_16x16x32_bf16 v[126:129], v[152:155], v[184:187], v[126:129]
	v_mfma_f32_16x16x32_bf16 v[122:125], v[160:163], v[184:187], v[122:125]
	v_mfma_f32_16x16x32_bf16 v[118:121], v[152:155], v[196:199], v[118:121]
	v_mfma_f32_16x16x32_bf16 v[114:117], v[160:163], v[196:199], v[114:117]
	v_mfma_f32_16x16x32_bf16 v[102:105], v[152:155], v[204:207], v[102:105]
	v_mfma_f32_16x16x32_bf16 v[98:101], v[160:163], v[204:207], v[98:101]
	v_mfma_f32_16x16x32_bf16 v[86:89], v[152:155], v[212:215], v[86:89]
	v_mfma_f32_16x16x32_bf16 v[82:85], v[160:163], v[212:215], v[82:85]
	v_mfma_f32_16x16x32_bf16 v[110:113], v[164:167], v[180:183], v[110:113]
	v_mfma_f32_16x16x32_bf16 v[106:109], v[172:175], v[180:183], v[106:109]
	v_mfma_f32_16x16x32_bf16 v[94:97], v[164:167], v[188:191], v[94:97]
	v_mfma_f32_16x16x32_bf16 v[90:93], v[172:175], v[188:191], v[90:93]
	v_mfma_f32_16x16x32_bf16 v[78:81], v[164:167], v[200:203], v[78:81]
	v_mfma_f32_16x16x32_bf16 v[74:77], v[172:175], v[200:203], v[74:77]
	v_mfma_f32_16x16x32_bf16 v[70:73], v[164:167], v[208:211], v[70:73]
	v_mfma_f32_16x16x32_bf16 v[66:69], v[172:175], v[208:211], v[66:69]
	v_mfma_f32_16x16x32_bf16 v[110:113], v[168:171], v[184:187], v[110:113]
	v_mfma_f32_16x16x32_bf16 v[106:109], v[176:179], v[184:187], v[106:109]
	v_mfma_f32_16x16x32_bf16 v[94:97], v[168:171], v[196:199], v[94:97]
	v_mfma_f32_16x16x32_bf16 v[90:93], v[176:179], v[196:199], v[90:93]
	v_mfma_f32_16x16x32_bf16 v[78:81], v[168:171], v[204:207], v[78:81]
	v_mfma_f32_16x16x32_bf16 v[74:77], v[176:179], v[204:207], v[74:77]
	v_mfma_f32_16x16x32_bf16 v[70:73], v[168:171], v[212:215], v[70:73]
	s_barrier
	v_mfma_f32_16x16x32_bf16 v[66:69], v[176:179], v[212:215], v[66:69]
	s_setprio 2
	s_add_i32 s59, s47, s33
	v_lshl_add_u64 v[192:193], s[36:37], 0, v[134:135]
	s_mov_b32 m0, s59
	ds_read_b128 v[180:183], v147 offset:16384
	ds_read_b128 v[184:187], v147 offset:17408
	ds_read_b128 v[188:191], v147 offset:18432
	ds_read_b128 v[196:199], v147 offset:19456
	ds_read_b128 v[200:203], v147 offset:20480
	ds_read_b128 v[204:207], v147 offset:21504
	ds_read_b128 v[208:211], v147 offset:22528
	ds_read_b128 v[212:215], v147 offset:23552
	global_load_lds_dwordx4 v[192:193], off
	s_add_i32 m0, s59, 0x2000
	s_add_u32 s60, s36, 0x80000
	v_lshl_add_u64 v[216:217], s[36:37], 0, v[130:131]
	s_addc_u32 s61, s37, 0
	s_add_i32 s59, s48, s33
	global_load_lds_dwordx4 v[216:217], off
	v_lshl_add_u64 v[218:219], s[60:61], 0, v[134:135]
	s_mov_b32 m0, s59
	v_lshl_add_u64 v[220:221], s[38:39], 0, v[132:133]
	global_load_lds_dwordx4 v[218:219], off
	v_lshl_add_u64 v[218:219], s[60:61], 0, v[130:131]
	s_add_i32 m0, s59, 0x2000
	s_nop 0
	global_load_lds_dwordx4 v[218:219], off
	v_lshl_add_u64 v[218:219], s[38:39], 0, v[136:137]
	s_mov_b32 m0, s27
	s_nop 0
	global_load_lds_dwordx4 v[218:219], off
	s_mov_b32 m0, s41
	s_nop 0
	global_load_lds_dwordx4 v[220:221], off
	s_waitcnt vmcnt(8)
	s_waitcnt lgkmcnt(0)
	s_barrier
	s_setprio 1
	s_waitcnt lgkmcnt(0)
	v_mfma_f32_16x16x32_bf16 v[62:65], v[148:151], v[180:183], v[62:65]
	v_mfma_f32_16x16x32_bf16 v[58:61], v[156:159], v[180:183], v[58:61]
	v_mfma_f32_16x16x32_bf16 v[54:57], v[148:151], v[188:191], v[54:57]
	v_mfma_f32_16x16x32_bf16 v[50:53], v[156:159], v[188:191], v[50:53]
	v_mfma_f32_16x16x32_bf16 v[38:41], v[148:151], v[200:203], v[38:41]
	v_mfma_f32_16x16x32_bf16 v[34:37], v[156:159], v[200:203], v[34:37]
	v_mfma_f32_16x16x32_bf16 v[22:25], v[148:151], v[208:211], v[22:25]
	v_mfma_f32_16x16x32_bf16 v[18:21], v[156:159], v[208:211], v[18:21]
	v_mfma_f32_16x16x32_bf16 v[62:65], v[152:155], v[184:187], v[62:65]
	v_mfma_f32_16x16x32_bf16 v[58:61], v[160:163], v[184:187], v[58:61]
	v_mfma_f32_16x16x32_bf16 v[54:57], v[152:155], v[196:199], v[54:57]
	v_mfma_f32_16x16x32_bf16 v[50:53], v[160:163], v[196:199], v[50:53]
	v_mfma_f32_16x16x32_bf16 v[38:41], v[152:155], v[204:207], v[38:41]
	v_mfma_f32_16x16x32_bf16 v[34:37], v[160:163], v[204:207], v[34:37]
	v_mfma_f32_16x16x32_bf16 v[22:25], v[152:155], v[212:215], v[22:25]
	v_mfma_f32_16x16x32_bf16 v[18:21], v[160:163], v[212:215], v[18:21]
	v_mfma_f32_16x16x32_bf16 v[46:49], v[164:167], v[180:183], v[46:49]
	v_mfma_f32_16x16x32_bf16 v[42:45], v[172:175], v[180:183], v[42:45]
	v_mfma_f32_16x16x32_bf16 v[30:33], v[164:167], v[188:191], v[30:33]
	v_mfma_f32_16x16x32_bf16 v[26:29], v[172:175], v[188:191], v[26:29]
	v_mfma_f32_16x16x32_bf16 v[14:17], v[164:167], v[200:203], v[14:17]
	v_mfma_f32_16x16x32_bf16 v[10:13], v[172:175], v[200:203], v[10:13]
	v_mfma_f32_16x16x32_bf16 v[6:9], v[164:167], v[208:211], v[6:9]
	v_mfma_f32_16x16x32_bf16 v[2:5], v[172:175], v[208:211], v[2:5]
	v_mfma_f32_16x16x32_bf16 v[46:49], v[168:171], v[184:187], v[46:49]
	v_mfma_f32_16x16x32_bf16 v[42:45], v[176:179], v[184:187], v[42:45]
	v_mfma_f32_16x16x32_bf16 v[30:33], v[168:171], v[196:199], v[30:33]
	v_mfma_f32_16x16x32_bf16 v[26:29], v[176:179], v[196:199], v[26:29]
	v_mfma_f32_16x16x32_bf16 v[14:17], v[168:171], v[204:207], v[14:17]
	v_mfma_f32_16x16x32_bf16 v[10:13], v[176:179], v[204:207], v[10:13]
	v_mfma_f32_16x16x32_bf16 v[6:9], v[168:171], v[212:215], v[6:9]
	s_barrier
	v_mfma_f32_16x16x32_bf16 v[2:5], v[176:179], v[212:215], v[2:5]
	s_setprio 2
	s_add_i32 s59, 0, 0x18000
	s_add_i32 s60, 0, 0x1c000
	v_add_u32_e32 v160, s59, v143
	v_add_u32_e32 v176, s60, v143
	ds_read_b128 v[148:151], v160
	ds_read_b128 v[152:155], v160 offset:1024
	ds_read_b128 v[156:159], v160 offset:2048
	ds_read_b128 v[160:163], v160 offset:3072
	ds_read_b128 v[164:167], v176
	ds_read_b128 v[168:171], v176 offset:1024
	ds_read_b128 v[172:175], v176 offset:2048
	ds_read_b128 v[176:179], v176 offset:3072
	s_add_u32 s38, s38, 0x80000
	s_addc_u32 s39, s39, 0
	s_mov_b32 m0, s42
	v_lshl_add_u64 v[222:223], s[38:39], 0, v[136:137]
	ds_read_b128 v[180:183], v147 offset:32768
	ds_read_b128 v[184:187], v147 offset:33792
	ds_read_b128 v[188:191], v147 offset:34816
	ds_read_b128 v[196:199], v147 offset:35840
	ds_read_b128 v[200:203], v147 offset:36864
	ds_read_b128 v[204:207], v147 offset:37888
	ds_read_b128 v[208:211], v147 offset:38912
	ds_read_b128 v[212:215], v147 offset:39936
	global_load_lds_dwordx4 v[222:223], off
	v_lshl_add_u64 v[222:223], s[38:39], 0, v[132:133]
	s_mov_b32 m0, s43
	s_nop 0
	global_load_lds_dwordx4 v[222:223], off
	s_waitcnt vmcnt(8)
	s_waitcnt lgkmcnt(0)
	s_barrier
	s_setprio 1
	s_waitcnt lgkmcnt(0)
	v_mfma_f32_16x16x32_bf16 v[126:129], v[148:151], v[180:183], v[126:129]
	v_mfma_f32_16x16x32_bf16 v[122:125], v[156:159], v[180:183], v[122:125]
	v_mfma_f32_16x16x32_bf16 v[118:121], v[148:151], v[188:191], v[118:121]
	v_mfma_f32_16x16x32_bf16 v[114:117], v[156:159], v[188:191], v[114:117]
	v_mfma_f32_16x16x32_bf16 v[102:105], v[148:151], v[200:203], v[102:105]
	v_mfma_f32_16x16x32_bf16 v[98:101], v[156:159], v[200:203], v[98:101]
	v_mfma_f32_16x16x32_bf16 v[86:89], v[148:151], v[208:211], v[86:89]
	v_mfma_f32_16x16x32_bf16 v[82:85], v[156:159], v[208:211], v[82:85]
	v_mfma_f32_16x16x32_bf16 v[126:129], v[152:155], v[184:187], v[126:129]
	v_mfma_f32_16x16x32_bf16 v[122:125], v[160:163], v[184:187], v[122:125]
	v_mfma_f32_16x16x32_bf16 v[118:121], v[152:155], v[196:199], v[118:121]
	v_mfma_f32_16x16x32_bf16 v[114:117], v[160:163], v[196:199], v[114:117]
	v_mfma_f32_16x16x32_bf16 v[102:105], v[152:155], v[204:207], v[102:105]
	v_mfma_f32_16x16x32_bf16 v[98:101], v[160:163], v[204:207], v[98:101]
	v_mfma_f32_16x16x32_bf16 v[86:89], v[152:155], v[212:215], v[86:89]
	v_mfma_f32_16x16x32_bf16 v[82:85], v[160:163], v[212:215], v[82:85]
	v_mfma_f32_16x16x32_bf16 v[110:113], v[164:167], v[180:183], v[110:113]
	v_mfma_f32_16x16x32_bf16 v[106:109], v[172:175], v[180:183], v[106:109]
	v_mfma_f32_16x16x32_bf16 v[94:97], v[164:167], v[188:191], v[94:97]
	v_mfma_f32_16x16x32_bf16 v[90:93], v[172:175], v[188:191], v[90:93]
	v_mfma_f32_16x16x32_bf16 v[78:81], v[164:167], v[200:203], v[78:81]
	v_mfma_f32_16x16x32_bf16 v[74:77], v[172:175], v[200:203], v[74:77]
	v_mfma_f32_16x16x32_bf16 v[70:73], v[164:167], v[208:211], v[70:73]
	v_mfma_f32_16x16x32_bf16 v[66:69], v[172:175], v[208:211], v[66:69]
	v_mfma_f32_16x16x32_bf16 v[110:113], v[168:171], v[184:187], v[110:113]
	v_mfma_f32_16x16x32_bf16 v[106:109], v[176:179], v[184:187], v[106:109]
	v_mfma_f32_16x16x32_bf16 v[94:97], v[168:171], v[196:199], v[94:97]
	v_mfma_f32_16x16x32_bf16 v[90:93], v[176:179], v[196:199], v[90:93]
	v_mfma_f32_16x16x32_bf16 v[78:81], v[168:171], v[204:207], v[78:81]
	v_mfma_f32_16x16x32_bf16 v[74:77], v[176:179], v[204:207], v[74:77]
	v_mfma_f32_16x16x32_bf16 v[70:73], v[168:171], v[212:215], v[70:73]
	s_barrier
	v_mfma_f32_16x16x32_bf16 v[66:69], v[176:179], v[212:215], v[66:69]
	s_setprio 2
	s_add_i32 s38, s59, s33
	v_lshl_add_u64 v[192:193], v[192:193], 0, s[6:7]
	s_mov_b32 m0, s38
	ds_read_b128 v[180:183], v147 offset:49152
	ds_read_b128 v[184:187], v147 offset:50176
	ds_read_b128 v[188:191], v147 offset:51200
	ds_read_b128 v[196:199], v147 offset:52224
	ds_read_b128 v[200:203], v147 offset:53248
	ds_read_b128 v[204:207], v147 offset:54272
	ds_read_b128 v[208:211], v147 offset:55296
	ds_read_b128 v[212:215], v147 offset:56320
	global_load_lds_dwordx4 v[192:193], off
	s_add_i32 m0, s38, 0x2000
	s_add_u32 s36, s36, 0x80080
	v_lshl_add_u64 v[192:193], v[216:217], 0, s[6:7]
	s_addc_u32 s37, s37, 0
	s_add_i32 s38, s60, s33
	global_load_lds_dwordx4 v[192:193], off
	v_lshl_add_u64 v[192:193], s[36:37], 0, v[134:135]
	s_mov_b32 m0, s38
	s_nop 0
	global_load_lds_dwordx4 v[192:193], off
	v_lshl_add_u64 v[192:193], s[36:37], 0, v[130:131]
	s_add_i32 m0, s38, 0x2000
	s_nop 0
	global_load_lds_dwordx4 v[192:193], off
	v_lshl_add_u64 v[192:193], v[218:219], 0, s[6:7]
	s_mov_b32 m0, s45
	s_nop 0
	global_load_lds_dwordx4 v[192:193], off
	v_lshl_add_u64 v[192:193], v[220:221], 0, s[6:7]
	s_mov_b32 m0, s46
	s_nop 0
	global_load_lds_dwordx4 v[192:193], off
	s_waitcnt vmcnt(8)
	s_waitcnt lgkmcnt(0)
	s_barrier
	s_setprio 1
	s_waitcnt lgkmcnt(0)
	v_mfma_f32_16x16x32_bf16 v[62:65], v[148:151], v[180:183], v[62:65]
	v_mfma_f32_16x16x32_bf16 v[58:61], v[156:159], v[180:183], v[58:61]
	v_mfma_f32_16x16x32_bf16 v[54:57], v[148:151], v[188:191], v[54:57]
	v_mfma_f32_16x16x32_bf16 v[50:53], v[156:159], v[188:191], v[50:53]
	v_mfma_f32_16x16x32_bf16 v[38:41], v[148:151], v[200:203], v[38:41]
	v_mfma_f32_16x16x32_bf16 v[34:37], v[156:159], v[200:203], v[34:37]
	v_mfma_f32_16x16x32_bf16 v[22:25], v[148:151], v[208:211], v[22:25]
	v_mfma_f32_16x16x32_bf16 v[18:21], v[156:159], v[208:211], v[18:21]
	v_mfma_f32_16x16x32_bf16 v[62:65], v[152:155], v[184:187], v[62:65]
	v_mfma_f32_16x16x32_bf16 v[58:61], v[160:163], v[184:187], v[58:61]
	v_mfma_f32_16x16x32_bf16 v[54:57], v[152:155], v[196:199], v[54:57]
	v_mfma_f32_16x16x32_bf16 v[50:53], v[160:163], v[196:199], v[50:53]
	v_mfma_f32_16x16x32_bf16 v[38:41], v[152:155], v[204:207], v[38:41]
	v_mfma_f32_16x16x32_bf16 v[34:37], v[160:163], v[204:207], v[34:37]
	v_mfma_f32_16x16x32_bf16 v[22:25], v[152:155], v[212:215], v[22:25]
	v_mfma_f32_16x16x32_bf16 v[18:21], v[160:163], v[212:215], v[18:21]
	v_mfma_f32_16x16x32_bf16 v[46:49], v[164:167], v[180:183], v[46:49]
	v_mfma_f32_16x16x32_bf16 v[42:45], v[172:175], v[180:183], v[42:45]
	v_mfma_f32_16x16x32_bf16 v[30:33], v[164:167], v[188:191], v[30:33]
	v_mfma_f32_16x16x32_bf16 v[26:29], v[172:175], v[188:191], v[26:29]
	v_mfma_f32_16x16x32_bf16 v[14:17], v[164:167], v[200:203], v[14:17]
	v_mfma_f32_16x16x32_bf16 v[10:13], v[172:175], v[200:203], v[10:13]
	v_mfma_f32_16x16x32_bf16 v[6:9], v[164:167], v[208:211], v[6:9]
	v_mfma_f32_16x16x32_bf16 v[2:5], v[172:175], v[208:211], v[2:5]
	v_mfma_f32_16x16x32_bf16 v[46:49], v[168:171], v[184:187], v[46:49]
	v_mfma_f32_16x16x32_bf16 v[42:45], v[176:179], v[184:187], v[42:45]
	v_mfma_f32_16x16x32_bf16 v[30:33], v[168:171], v[196:199], v[30:33]
	v_mfma_f32_16x16x32_bf16 v[26:29], v[176:179], v[196:199], v[26:29]
	v_mfma_f32_16x16x32_bf16 v[14:17], v[168:171], v[204:207], v[14:17]
	v_mfma_f32_16x16x32_bf16 v[10:13], v[176:179], v[204:207], v[10:13]
	v_mfma_f32_16x16x32_bf16 v[6:9], v[168:171], v[212:215], v[6:9]
	s_barrier
	v_mfma_f32_16x16x32_bf16 v[2:5], v[176:179], v[212:215], v[2:5]
	s_setprio 2
	s_add_i32 s58, s58, 2
	s_add_u32 s34, s34, 0x100
	s_addc_u32 s35, s35, 0
	s_add_u32 s56, s56, 0x100
	s_addc_u32 s57, s57, 0
	s_cmp_gt_u32 s58, 29
	s_cbranch_scc0 .LBB0_541

.Lpeel_10:
	ds_read_b128 v[150:153], v147
	ds_read_b128 v[154:157], v147 offset:1024
	s_add_u32 s28, s26, 0xfffe0080
	s_addc_u32 s29, s27, -1
	s_cmp_eq_u32 s50, 4
	s_cselect_b32 s31, s13, s29
	s_cselect_b32 s30, s46, s28
	s_cselect_b32 s29, s17, s49
	s_cselect_b32 s28, s47, s48
	v_lshl_add_u64 v[202:203], s[26:27], 0, v[138:139]
	s_add_i32 m0, s36, 0xc000
	global_load_lds_dwordx4 v[202:203], off
	v_lshl_add_u64 v[202:203], s[26:27], 0, v[140:141]
	s_add_i32 m0, s36, 0xe000
	s_nop 0
	global_load_lds_dwordx4 v[202:203], off
	s_waitcnt vmcnt(8)
	s_waitcnt lgkmcnt(0)
	s_barrier
	s_setprio 1
	s_waitcnt lgkmcnt(0)
	v_mfma_f32_16x16x32_bf16 v[126:129], v[150:153], v[182:185], 0
	v_mfma_f32_16x16x32_bf16 v[122:125], v[158:161], v[182:185], 0
	v_mfma_f32_16x16x32_bf16 v[118:121], v[150:153], v[190:193], 0
	v_mfma_f32_16x16x32_bf16 v[114:117], v[158:161], v[190:193], 0
	v_mfma_f32_16x16x32_bf16 v[102:105], v[150:153], v[210:213], 0
	v_mfma_f32_16x16x32_bf16 v[98:101], v[158:161], v[210:213], 0
	v_mfma_f32_16x16x32_bf16 v[86:89], v[150:153], v[218:221], 0
	v_mfma_f32_16x16x32_bf16 v[82:85], v[158:161], v[218:221], 0
	v_mfma_f32_16x16x32_bf16 v[126:129], v[154:157], v[186:189], v[126:129]
	v_mfma_f32_16x16x32_bf16 v[122:125], v[162:165], v[186:189], v[122:125]
	v_mfma_f32_16x16x32_bf16 v[118:121], v[154:157], v[198:201], v[118:121]
	v_mfma_f32_16x16x32_bf16 v[114:117], v[162:165], v[198:201], v[114:117]
	v_mfma_f32_16x16x32_bf16 v[102:105], v[154:157], v[214:217], v[102:105]
	v_mfma_f32_16x16x32_bf16 v[98:101], v[162:165], v[214:217], v[98:101]
	v_mfma_f32_16x16x32_bf16 v[86:89], v[154:157], v[222:225], v[86:89]
	v_mfma_f32_16x16x32_bf16 v[82:85], v[162:165], v[222:225], v[82:85]
	v_mfma_f32_16x16x32_bf16 v[110:113], v[166:169], v[182:185], 0
	v_mfma_f32_16x16x32_bf16 v[106:109], v[174:177], v[182:185], 0
	v_mfma_f32_16x16x32_bf16 v[94:97], v[166:169], v[190:193], 0
	v_mfma_f32_16x16x32_bf16 v[90:93], v[174:177], v[190:193], 0
	v_mfma_f32_16x16x32_bf16 v[78:81], v[166:169], v[210:213], 0
	v_mfma_f32_16x16x32_bf16 v[74:77], v[174:177], v[210:213], 0
	v_mfma_f32_16x16x32_bf16 v[70:73], v[166:169], v[218:221], 0
	v_mfma_f32_16x16x32_bf16 v[66:69], v[174:177], v[218:221], 0
	v_mfma_f32_16x16x32_bf16 v[110:113], v[170:173], v[186:189], v[110:113]
	v_mfma_f32_16x16x32_bf16 v[106:109], v[178:181], v[186:189], v[106:109]
	v_mfma_f32_16x16x32_bf16 v[94:97], v[170:173], v[198:201], v[94:97]
	v_mfma_f32_16x16x32_bf16 v[90:93], v[178:181], v[198:201], v[90:93]
	v_mfma_f32_16x16x32_bf16 v[78:81], v[170:173], v[214:217], v[78:81]
	v_mfma_f32_16x16x32_bf16 v[74:77], v[178:181], v[214:217], v[74:77]
	v_mfma_f32_16x16x32_bf16 v[70:73], v[170:173], v[222:225], v[70:73]
	s_barrier
	v_mfma_f32_16x16x32_bf16 v[66:69], v[178:181], v[222:225], v[66:69]
	s_setprio 2
	s_add_i32 s51, s43, s35
	v_lshl_add_u64 v[202:203], s[28:29], 0, v[132:133]
	s_mov_b32 m0, s51
	ds_read_b128 v[182:185], v149 offset:16384
	ds_read_b128 v[186:189], v149 offset:17408
	ds_read_b128 v[190:193], v149 offset:18432
	ds_read_b128 v[198:201], v149 offset:19456
	ds_read_b128 v[210:213], v149 offset:20480
	ds_read_b128 v[214:217], v149 offset:21504
	ds_read_b128 v[218:221], v149 offset:22528
	ds_read_b128 v[222:225], v149 offset:23552
	global_load_lds_dwordx4 v[202:203], off
	s_add_i32 m0, s51, 0x2000
	s_add_u32 s52, s28, 0x20000
	v_lshl_add_u64 v[206:207], s[28:29], 0, v[134:135]
	s_addc_u32 s53, s29, 0
	s_add_i32 s51, s44, s35
	global_load_lds_dwordx4 v[206:207], off
	v_lshl_add_u64 v[226:227], s[52:53], 0, v[132:133]
	s_mov_b32 m0, s51
	v_lshl_add_u64 v[228:229], s[30:31], 0, v[136:137]
	global_load_lds_dwordx4 v[226:227], off
	v_lshl_add_u64 v[226:227], s[52:53], 0, v[134:135]
	s_add_i32 m0, s51, 0x2000
	s_nop 0
	global_load_lds_dwordx4 v[226:227], off
	v_lshl_add_u64 v[226:227], s[30:31], 0, v[130:131]
	s_mov_b32 m0, s36
	s_nop 0
	global_load_lds_dwordx4 v[226:227], off
	s_mov_b32 m0, s37
	s_nop 0
	global_load_lds_dwordx4 v[228:229], off
	s_waitcnt vmcnt(8)
	s_waitcnt lgkmcnt(0)
	s_barrier
	s_setprio 1
	s_waitcnt lgkmcnt(0)
	v_mfma_f32_16x16x32_bf16 v[62:65], v[150:153], v[182:185], 0
	v_mfma_f32_16x16x32_bf16 v[58:61], v[158:161], v[182:185], 0
	v_mfma_f32_16x16x32_bf16 v[54:57], v[150:153], v[190:193], 0
	v_mfma_f32_16x16x32_bf16 v[50:53], v[158:161], v[190:193], 0
	v_mfma_f32_16x16x32_bf16 v[38:41], v[150:153], v[210:213], 0
	v_mfma_f32_16x16x32_bf16 v[34:37], v[158:161], v[210:213], 0
	v_mfma_f32_16x16x32_bf16 v[22:25], v[150:153], v[218:221], 0
	v_mfma_f32_16x16x32_bf16 v[18:21], v[158:161], v[218:221], 0
	v_mfma_f32_16x16x32_bf16 v[62:65], v[154:157], v[186:189], v[62:65]
	v_mfma_f32_16x16x32_bf16 v[58:61], v[162:165], v[186:189], v[58:61]
	v_mfma_f32_16x16x32_bf16 v[54:57], v[154:157], v[198:201], v[54:57]
	v_mfma_f32_16x16x32_bf16 v[50:53], v[162:165], v[198:201], v[50:53]
	v_mfma_f32_16x16x32_bf16 v[38:41], v[154:157], v[214:217], v[38:41]
	v_mfma_f32_16x16x32_bf16 v[34:37], v[162:165], v[214:217], v[34:37]
	v_mfma_f32_16x16x32_bf16 v[22:25], v[154:157], v[222:225], v[22:25]
	v_mfma_f32_16x16x32_bf16 v[18:21], v[162:165], v[222:225], v[18:21]
	v_mfma_f32_16x16x32_bf16 v[46:49], v[166:169], v[182:185], 0
	v_mfma_f32_16x16x32_bf16 v[42:45], v[174:177], v[182:185], 0
	v_mfma_f32_16x16x32_bf16 v[30:33], v[166:169], v[190:193], 0
	v_mfma_f32_16x16x32_bf16 v[26:29], v[174:177], v[190:193], 0
	v_mfma_f32_16x16x32_bf16 v[14:17], v[166:169], v[210:213], 0
	v_mfma_f32_16x16x32_bf16 v[10:13], v[174:177], v[210:213], 0
	v_mfma_f32_16x16x32_bf16 v[6:9], v[166:169], v[218:221], 0
	v_mfma_f32_16x16x32_bf16 v[2:5], v[174:177], v[218:221], 0
	v_mfma_f32_16x16x32_bf16 v[46:49], v[170:173], v[186:189], v[46:49]
	v_mfma_f32_16x16x32_bf16 v[42:45], v[178:181], v[186:189], v[42:45]
	v_mfma_f32_16x16x32_bf16 v[30:33], v[170:173], v[198:201], v[30:33]
	v_mfma_f32_16x16x32_bf16 v[26:29], v[178:181], v[198:201], v[26:29]
	v_mfma_f32_16x16x32_bf16 v[14:17], v[170:173], v[214:217], v[14:17]
	v_mfma_f32_16x16x32_bf16 v[10:13], v[178:181], v[214:217], v[10:13]
	v_mfma_f32_16x16x32_bf16 v[6:9], v[170:173], v[222:225], v[6:9]
	s_barrier
	v_mfma_f32_16x16x32_bf16 v[2:5], v[178:181], v[222:225], v[2:5]
	s_setprio 2
	s_add_i32 s51, 0, 0x18000
	s_add_i32 s52, 0, 0x1c000
	v_add_u32_e32 v162, s51, v145
	v_add_u32_e32 v178, s52, v145
	ds_read_b128 v[150:153], v162
	ds_read_b128 v[154:157], v162 offset:1024
	ds_read_b128 v[158:161], v162 offset:2048
	ds_read_b128 v[162:165], v162 offset:3072
	ds_read_b128 v[166:169], v178
	ds_read_b128 v[170:173], v178 offset:1024
	ds_read_b128 v[174:177], v178 offset:2048
	ds_read_b128 v[178:181], v178 offset:3072
	s_add_u32 s30, s30, 0x20000
	s_addc_u32 s31, s31, 0
	s_mov_b32 m0, s38
	v_lshl_add_u64 v[230:231], s[30:31], 0, v[130:131]
	ds_read_b128 v[182:185], v149 offset:32768
	ds_read_b128 v[186:189], v149 offset:33792
	ds_read_b128 v[190:193], v149 offset:34816
	ds_read_b128 v[198:201], v149 offset:35840
	ds_read_b128 v[210:213], v149 offset:36864
	ds_read_b128 v[214:217], v149 offset:37888
	ds_read_b128 v[218:221], v149 offset:38912
	ds_read_b128 v[222:225], v149 offset:39936
	global_load_lds_dwordx4 v[230:231], off
	v_lshl_add_u64 v[230:231], s[30:31], 0, v[136:137]
	s_mov_b32 m0, s39
	s_nop 0
	global_load_lds_dwordx4 v[230:231], off
	s_waitcnt vmcnt(8)
	s_waitcnt lgkmcnt(0)
	s_barrier
	s_setprio 1
	s_waitcnt lgkmcnt(0)
	v_mfma_f32_16x16x32_bf16 v[126:129], v[150:153], v[182:185], v[126:129]
	v_mfma_f32_16x16x32_bf16 v[122:125], v[158:161], v[182:185], v[122:125]
	v_mfma_f32_16x16x32_bf16 v[118:121], v[150:153], v[190:193], v[118:121]
	v_mfma_f32_16x16x32_bf16 v[114:117], v[158:161], v[190:193], v[114:117]
	v_mfma_f32_16x16x32_bf16 v[102:105], v[150:153], v[210:213], v[102:105]
	v_mfma_f32_16x16x32_bf16 v[98:101], v[158:161], v[210:213], v[98:101]
	v_mfma_f32_16x16x32_bf16 v[86:89], v[150:153], v[218:221], v[86:89]
	v_mfma_f32_16x16x32_bf16 v[82:85], v[158:161], v[218:221], v[82:85]
	v_mfma_f32_16x16x32_bf16 v[126:129], v[154:157], v[186:189], v[126:129]
	v_mfma_f32_16x16x32_bf16 v[122:125], v[162:165], v[186:189], v[122:125]
	v_mfma_f32_16x16x32_bf16 v[118:121], v[154:157], v[198:201], v[118:121]
	v_mfma_f32_16x16x32_bf16 v[114:117], v[162:165], v[198:201], v[114:117]
	v_mfma_f32_16x16x32_bf16 v[102:105], v[154:157], v[214:217], v[102:105]
	v_mfma_f32_16x16x32_bf16 v[98:101], v[162:165], v[214:217], v[98:101]
	v_mfma_f32_16x16x32_bf16 v[86:89], v[154:157], v[222:225], v[86:89]
	v_mfma_f32_16x16x32_bf16 v[82:85], v[162:165], v[222:225], v[82:85]
	v_mfma_f32_16x16x32_bf16 v[110:113], v[166:169], v[182:185], v[110:113]
	v_mfma_f32_16x16x32_bf16 v[106:109], v[174:177], v[182:185], v[106:109]
	v_mfma_f32_16x16x32_bf16 v[94:97], v[166:169], v[190:193], v[94:97]
	v_mfma_f32_16x16x32_bf16 v[90:93], v[174:177], v[190:193], v[90:93]
	v_mfma_f32_16x16x32_bf16 v[78:81], v[166:169], v[210:213], v[78:81]
	v_mfma_f32_16x16x32_bf16 v[74:77], v[174:177], v[210:213], v[74:77]
	v_mfma_f32_16x16x32_bf16 v[70:73], v[166:169], v[218:221], v[70:73]
	v_mfma_f32_16x16x32_bf16 v[66:69], v[174:177], v[218:221], v[66:69]
	v_mfma_f32_16x16x32_bf16 v[110:113], v[170:173], v[186:189], v[110:113]
	v_mfma_f32_16x16x32_bf16 v[106:109], v[178:181], v[186:189], v[106:109]
	v_mfma_f32_16x16x32_bf16 v[94:97], v[170:173], v[198:201], v[94:97]
	v_mfma_f32_16x16x32_bf16 v[90:93], v[178:181], v[198:201], v[90:93]
	v_mfma_f32_16x16x32_bf16 v[78:81], v[170:173], v[214:217], v[78:81]
	v_mfma_f32_16x16x32_bf16 v[74:77], v[178:181], v[214:217], v[74:77]
	v_mfma_f32_16x16x32_bf16 v[70:73], v[170:173], v[222:225], v[70:73]
	s_barrier
	v_mfma_f32_16x16x32_bf16 v[66:69], v[178:181], v[222:225], v[66:69]
	s_setprio 2
	s_add_i32 s30, s51, s35
	v_lshl_add_u64 v[202:203], v[202:203], 0, s[8:9]
	s_mov_b32 m0, s30
	ds_read_b128 v[182:185], v149 offset:49152
	ds_read_b128 v[186:189], v149 offset:50176
	ds_read_b128 v[190:193], v149 offset:51200
	ds_read_b128 v[198:201], v149 offset:52224
	ds_read_b128 v[210:213], v149 offset:53248
	ds_read_b128 v[214:217], v149 offset:54272
	ds_read_b128 v[218:221], v149 offset:55296
	ds_read_b128 v[222:225], v149 offset:56320
	global_load_lds_dwordx4 v[202:203], off
	s_add_i32 m0, s30, 0x2000
	s_add_u32 s28, s28, 0x20080
	v_lshl_add_u64 v[202:203], v[206:207], 0, s[8:9]
	s_addc_u32 s29, s29, 0
	s_add_i32 s30, s52, s35
	global_load_lds_dwordx4 v[202:203], off
	v_lshl_add_u64 v[202:203], s[28:29], 0, v[132:133]
	s_mov_b32 m0, s30
	s_nop 0
	global_load_lds_dwordx4 v[202:203], off
	v_lshl_add_u64 v[202:203], s[28:29], 0, v[134:135]
	s_add_i32 m0, s30, 0x2000
	s_nop 0
	global_load_lds_dwordx4 v[202:203], off
	v_lshl_add_u64 v[202:203], v[226:227], 0, s[8:9]
	s_mov_b32 m0, s41
	s_nop 0
	global_load_lds_dwordx4 v[202:203], off
	v_lshl_add_u64 v[202:203], v[228:229], 0, s[8:9]
	s_mov_b32 m0, s42
	s_nop 0
	global_load_lds_dwordx4 v[202:203], off
	s_waitcnt vmcnt(8)
	s_waitcnt lgkmcnt(0)
	s_barrier
	s_setprio 1
	s_waitcnt lgkmcnt(0)
	v_mfma_f32_16x16x32_bf16 v[62:65], v[150:153], v[182:185], v[62:65]
	v_mfma_f32_16x16x32_bf16 v[58:61], v[158:161], v[182:185], v[58:61]
	v_mfma_f32_16x16x32_bf16 v[54:57], v[150:153], v[190:193], v[54:57]
	v_mfma_f32_16x16x32_bf16 v[50:53], v[158:161], v[190:193], v[50:53]
	v_mfma_f32_16x16x32_bf16 v[38:41], v[150:153], v[210:213], v[38:41]
	v_mfma_f32_16x16x32_bf16 v[34:37], v[158:161], v[210:213], v[34:37]
	v_mfma_f32_16x16x32_bf16 v[22:25], v[150:153], v[218:221], v[22:25]
	v_mfma_f32_16x16x32_bf16 v[18:21], v[158:161], v[218:221], v[18:21]
	v_mfma_f32_16x16x32_bf16 v[62:65], v[154:157], v[186:189], v[62:65]
	v_mfma_f32_16x16x32_bf16 v[58:61], v[162:165], v[186:189], v[58:61]
	v_mfma_f32_16x16x32_bf16 v[54:57], v[154:157], v[198:201], v[54:57]
	v_mfma_f32_16x16x32_bf16 v[50:53], v[162:165], v[198:201], v[50:53]
	v_mfma_f32_16x16x32_bf16 v[38:41], v[154:157], v[214:217], v[38:41]
	v_mfma_f32_16x16x32_bf16 v[34:37], v[162:165], v[214:217], v[34:37]
	v_mfma_f32_16x16x32_bf16 v[22:25], v[154:157], v[222:225], v[22:25]
	v_mfma_f32_16x16x32_bf16 v[18:21], v[162:165], v[222:225], v[18:21]
	v_mfma_f32_16x16x32_bf16 v[46:49], v[166:169], v[182:185], v[46:49]
	v_mfma_f32_16x16x32_bf16 v[42:45], v[174:177], v[182:185], v[42:45]
	v_mfma_f32_16x16x32_bf16 v[30:33], v[166:169], v[190:193], v[30:33]
	v_mfma_f32_16x16x32_bf16 v[26:29], v[174:177], v[190:193], v[26:29]
	v_mfma_f32_16x16x32_bf16 v[14:17], v[166:169], v[210:213], v[14:17]
	v_mfma_f32_16x16x32_bf16 v[10:13], v[174:177], v[210:213], v[10:13]
	v_mfma_f32_16x16x32_bf16 v[6:9], v[166:169], v[218:221], v[6:9]
	v_mfma_f32_16x16x32_bf16 v[2:5], v[174:177], v[218:221], v[2:5]
	v_mfma_f32_16x16x32_bf16 v[46:49], v[170:173], v[186:189], v[46:49]
	v_mfma_f32_16x16x32_bf16 v[42:45], v[178:181], v[186:189], v[42:45]
	v_mfma_f32_16x16x32_bf16 v[30:33], v[170:173], v[198:201], v[30:33]
	v_mfma_f32_16x16x32_bf16 v[26:29], v[178:181], v[198:201], v[26:29]
	v_mfma_f32_16x16x32_bf16 v[14:17], v[170:173], v[214:217], v[14:17]
	v_mfma_f32_16x16x32_bf16 v[10:13], v[178:181], v[214:217], v[10:13]
	v_mfma_f32_16x16x32_bf16 v[6:9], v[170:173], v[222:225], v[6:9]
	s_barrier
	v_mfma_f32_16x16x32_bf16 v[2:5], v[178:181], v[222:225], v[2:5]
	s_setprio 2
	s_add_i32 s50, s50, 2
	s_add_u32 s26, s26, 0x100
	s_addc_u32 s27, s27, 0
	s_add_u32 s48, s48, 0x100
	s_addc_u32 s49, s49, 0
	s_cmp_gt_u32 s50, 5
	s_cbranch_scc0 .LBB0_690
	s_branch .Lpeeldone_10
.LBB0_690:
	ds_read_b128 v[150:153], v147
	ds_read_b128 v[154:157], v147 offset:1024
	ds_read_b128 v[158:161], v147 offset:2048
	ds_read_b128 v[162:165], v147 offset:3072
	ds_read_b128 v[166:169], v148
	ds_read_b128 v[170:173], v148 offset:1024
	ds_read_b128 v[174:177], v148 offset:2048
	ds_read_b128 v[178:181], v148 offset:3072
	s_add_u32 s28, s26, 0xfffe0080
	s_addc_u32 s29, s27, -1
	s_cmp_eq_u32 s50, 4
	s_cselect_b32 s31, s13, s29
	s_cselect_b32 s30, s46, s28
	s_cselect_b32 s29, s17, s49
	s_cselect_b32 s28, s47, s48
	v_lshl_add_u64 v[202:203], s[26:27], 0, v[138:139]
	s_add_i32 m0, s36, 0xc000
	ds_read_b128 v[182:185], v149
	ds_read_b128 v[186:189], v149 offset:1024
	ds_read_b128 v[190:193], v149 offset:2048
	ds_read_b128 v[198:201], v149 offset:3072
	ds_read_b128 v[210:213], v149 offset:4096
	ds_read_b128 v[214:217], v149 offset:5120
	ds_read_b128 v[218:221], v149 offset:6144
	ds_read_b128 v[222:225], v149 offset:7168
	global_load_lds_dwordx4 v[202:203], off
	v_lshl_add_u64 v[202:203], s[26:27], 0, v[140:141]
	s_add_i32 m0, s36, 0xe000
	s_nop 0
	global_load_lds_dwordx4 v[202:203], off
	s_waitcnt vmcnt(8)
	s_waitcnt lgkmcnt(0)
	s_barrier
	s_setprio 1
	s_waitcnt lgkmcnt(0)
	v_mfma_f32_16x16x32_bf16 v[126:129], v[150:153], v[182:185], v[126:129]
	v_mfma_f32_16x16x32_bf16 v[122:125], v[158:161], v[182:185], v[122:125]
	v_mfma_f32_16x16x32_bf16 v[118:121], v[150:153], v[190:193], v[118:121]
	v_mfma_f32_16x16x32_bf16 v[114:117], v[158:161], v[190:193], v[114:117]
	v_mfma_f32_16x16x32_bf16 v[102:105], v[150:153], v[210:213], v[102:105]
	v_mfma_f32_16x16x32_bf16 v[98:101], v[158:161], v[210:213], v[98:101]
	v_mfma_f32_16x16x32_bf16 v[86:89], v[150:153], v[218:221], v[86:89]
	v_mfma_f32_16x16x32_bf16 v[82:85], v[158:161], v[218:221], v[82:85]
	v_mfma_f32_16x16x32_bf16 v[126:129], v[154:157], v[186:189], v[126:129]
	v_mfma_f32_16x16x32_bf16 v[122:125], v[162:165], v[186:189], v[122:125]
	v_mfma_f32_16x16x32_bf16 v[118:121], v[154:157], v[198:201], v[118:121]
	v_mfma_f32_16x16x32_bf16 v[114:117], v[162:165], v[198:201], v[114:117]
	v_mfma_f32_16x16x32_bf16 v[102:105], v[154:157], v[214:217], v[102:105]
	v_mfma_f32_16x16x32_bf16 v[98:101], v[162:165], v[214:217], v[98:101]
	v_mfma_f32_16x16x32_bf16 v[86:89], v[154:157], v[222:225], v[86:89]
	v_mfma_f32_16x16x32_bf16 v[82:85], v[162:165], v[222:225], v[82:85]
	v_mfma_f32_16x16x32_bf16 v[110:113], v[166:169], v[182:185], v[110:113]
	v_mfma_f32_16x16x32_bf16 v[106:109], v[174:177], v[182:185], v[106:109]
	v_mfma_f32_16x16x32_bf16 v[94:97], v[166:169], v[190:193], v[94:97]
	v_mfma_f32_16x16x32_bf16 v[90:93], v[174:177], v[190:193], v[90:93]
	v_mfma_f32_16x16x32_bf16 v[78:81], v[166:169], v[210:213], v[78:81]
	v_mfma_f32_16x16x32_bf16 v[74:77], v[174:177], v[210:213], v[74:77]
	v_mfma_f32_16x16x32_bf16 v[70:73], v[166:169], v[218:221], v[70:73]
	v_mfma_f32_16x16x32_bf16 v[66:69], v[174:177], v[218:221], v[66:69]
	v_mfma_f32_16x16x32_bf16 v[110:113], v[170:173], v[186:189], v[110:113]
	v_mfma_f32_16x16x32_bf16 v[106:109], v[178:181], v[186:189], v[106:109]
	v_mfma_f32_16x16x32_bf16 v[94:97], v[170:173], v[198:201], v[94:97]
	v_mfma_f32_16x16x32_bf16 v[90:93], v[178:181], v[198:201], v[90:93]
	v_mfma_f32_16x16x32_bf16 v[78:81], v[170:173], v[214:217], v[78:81]
	v_mfma_f32_16x16x32_bf16 v[74:77], v[178:181], v[214:217], v[74:77]
	v_mfma_f32_16x16x32_bf16 v[70:73], v[170:173], v[222:225], v[70:73]
	s_barrier
	v_mfma_f32_16x16x32_bf16 v[66:69], v[178:181], v[222:225], v[66:69]
	s_setprio 2
	s_add_i32 s51, s43, s35
	v_lshl_add_u64 v[202:203], s[28:29], 0, v[132:133]
	s_mov_b32 m0, s51
	ds_read_b128 v[182:185], v149 offset:16384
	ds_read_b128 v[186:189], v149 offset:17408
	ds_read_b128 v[190:193], v149 offset:18432
	ds_read_b128 v[198:201], v149 offset:19456
	ds_read_b128 v[210:213], v149 offset:20480
	ds_read_b128 v[214:217], v149 offset:21504
	ds_read_b128 v[218:221], v149 offset:22528
	ds_read_b128 v[222:225], v149 offset:23552
	global_load_lds_dwordx4 v[202:203], off
	s_add_i32 m0, s51, 0x2000
	s_add_u32 s52, s28, 0x20000
	v_lshl_add_u64 v[206:207], s[28:29], 0, v[134:135]
	s_addc_u32 s53, s29, 0
	s_add_i32 s51, s44, s35
	global_load_lds_dwordx4 v[206:207], off
	v_lshl_add_u64 v[226:227], s[52:53], 0, v[132:133]
	s_mov_b32 m0, s51
	v_lshl_add_u64 v[228:229], s[30:31], 0, v[136:137]
	global_load_lds_dwordx4 v[226:227], off
	v_lshl_add_u64 v[226:227], s[52:53], 0, v[134:135]
	s_add_i32 m0, s51, 0x2000
	s_nop 0
	global_load_lds_dwordx4 v[226:227], off
	v_lshl_add_u64 v[226:227], s[30:31], 0, v[130:131]
	s_mov_b32 m0, s36
	s_nop 0
	global_load_lds_dwordx4 v[226:227], off
	s_mov_b32 m0, s37
	s_nop 0
	global_load_lds_dwordx4 v[228:229], off
	s_waitcnt vmcnt(8)
	s_waitcnt lgkmcnt(0)
	s_barrier
	s_setprio 1
	s_waitcnt lgkmcnt(0)
	v_mfma_f32_16x16x32_bf16 v[62:65], v[150:153], v[182:185], v[62:65]
	v_mfma_f32_16x16x32_bf16 v[58:61], v[158:161], v[182:185], v[58:61]
	v_mfma_f32_16x16x32_bf16 v[54:57], v[150:153], v[190:193], v[54:57]
	v_mfma_f32_16x16x32_bf16 v[50:53], v[158:161], v[190:193], v[50:53]
	v_mfma_f32_16x16x32_bf16 v[38:41], v[150:153], v[210:213], v[38:41]
	v_mfma_f32_16x16x32_bf16 v[34:37], v[158:161], v[210:213], v[34:37]
	v_mfma_f32_16x16x32_bf16 v[22:25], v[150:153], v[218:221], v[22:25]
	v_mfma_f32_16x16x32_bf16 v[18:21], v[158:161], v[218:221], v[18:21]
	v_mfma_f32_16x16x32_bf16 v[62:65], v[154:157], v[186:189], v[62:65]
	v_mfma_f32_16x16x32_bf16 v[58:61], v[162:165], v[186:189], v[58:61]
	v_mfma_f32_16x16x32_bf16 v[54:57], v[154:157], v[198:201], v[54:57]
	v_mfma_f32_16x16x32_bf16 v[50:53], v[162:165], v[198:201], v[50:53]
	v_mfma_f32_16x16x32_bf16 v[38:41], v[154:157], v[214:217], v[38:41]
	v_mfma_f32_16x16x32_bf16 v[34:37], v[162:165], v[214:217], v[34:37]
	v_mfma_f32_16x16x32_bf16 v[22:25], v[154:157], v[222:225], v[22:25]
	v_mfma_f32_16x16x32_bf16 v[18:21], v[162:165], v[222:225], v[18:21]
	v_mfma_f32_16x16x32_bf16 v[46:49], v[166:169], v[182:185], v[46:49]
	v_mfma_f32_16x16x32_bf16 v[42:45], v[174:177], v[182:185], v[42:45]
	v_mfma_f32_16x16x32_bf16 v[30:33], v[166:169], v[190:193], v[30:33]
	v_mfma_f32_16x16x32_bf16 v[26:29], v[174:177], v[190:193], v[26:29]
	v_mfma_f32_16x16x32_bf16 v[14:17], v[166:169], v[210:213], v[14:17]
	v_mfma_f32_16x16x32_bf16 v[10:13], v[174:177], v[210:213], v[10:13]
	v_mfma_f32_16x16x32_bf16 v[6:9], v[166:169], v[218:221], v[6:9]
	v_mfma_f32_16x16x32_bf16 v[2:5], v[174:177], v[218:221], v[2:5]
	v_mfma_f32_16x16x32_bf16 v[46:49], v[170:173], v[186:189], v[46:49]
	v_mfma_f32_16x16x32_bf16 v[42:45], v[178:181], v[186:189], v[42:45]
	v_mfma_f32_16x16x32_bf16 v[30:33], v[170:173], v[198:201], v[30:33]
	v_mfma_f32_16x16x32_bf16 v[26:29], v[178:181], v[198:201], v[26:29]
	v_mfma_f32_16x16x32_bf16 v[14:17], v[170:173], v[214:217], v[14:17]
	v_mfma_f32_16x16x32_bf16 v[10:13], v[178:181], v[214:217], v[10:13]
	v_mfma_f32_16x16x32_bf16 v[6:9], v[170:173], v[222:225], v[6:9]
	s_barrier
	v_mfma_f32_16x16x32_bf16 v[2:5], v[178:181], v[222:225], v[2:5]
	s_setprio 2
	s_add_i32 s51, 0, 0x18000
	s_add_i32 s52, 0, 0x1c000
	v_add_u32_e32 v162, s51, v145
	v_add_u32_e32 v178, s52, v145
	ds_read_b128 v[150:153], v162
	ds_read_b128 v[154:157], v162 offset:1024
	ds_read_b128 v[158:161], v162 offset:2048
	ds_read_b128 v[162:165], v162 offset:3072
	ds_read_b128 v[166:169], v178
	ds_read_b128 v[170:173], v178 offset:1024
	ds_read_b128 v[174:177], v178 offset:2048
	ds_read_b128 v[178:181], v178 offset:3072
	s_add_u32 s30, s30, 0x20000
	s_addc_u32 s31, s31, 0
	s_mov_b32 m0, s38
	v_lshl_add_u64 v[230:231], s[30:31], 0, v[130:131]
	ds_read_b128 v[182:185], v149 offset:32768
	ds_read_b128 v[186:189], v149 offset:33792
	ds_read_b128 v[190:193], v149 offset:34816
	ds_read_b128 v[198:201], v149 offset:35840
	ds_read_b128 v[210:213], v149 offset:36864
	ds_read_b128 v[214:217], v149 offset:37888
	ds_read_b128 v[218:221], v149 offset:38912
	ds_read_b128 v[222:225], v149 offset:39936
	global_load_lds_dwordx4 v[230:231], off
	v_lshl_add_u64 v[230:231], s[30:31], 0, v[136:137]
	s_mov_b32 m0, s39
	s_nop 0
	global_load_lds_dwordx4 v[230:231], off
	s_waitcnt vmcnt(8)
	s_waitcnt lgkmcnt(0)
	s_barrier
	s_setprio 1
	s_waitcnt lgkmcnt(0)
	v_mfma_f32_16x16x32_bf16 v[126:129], v[150:153], v[182:185], v[126:129]
	v_mfma_f32_16x16x32_bf16 v[122:125], v[158:161], v[182:185], v[122:125]
	v_mfma_f32_16x16x32_bf16 v[118:121], v[150:153], v[190:193], v[118:121]
	v_mfma_f32_16x16x32_bf16 v[114:117], v[158:161], v[190:193], v[114:117]
	v_mfma_f32_16x16x32_bf16 v[102:105], v[150:153], v[210:213], v[102:105]
	v_mfma_f32_16x16x32_bf16 v[98:101], v[158:161], v[210:213], v[98:101]
	v_mfma_f32_16x16x32_bf16 v[86:89], v[150:153], v[218:221], v[86:89]
	v_mfma_f32_16x16x32_bf16 v[82:85], v[158:161], v[218:221], v[82:85]
	v_mfma_f32_16x16x32_bf16 v[126:129], v[154:157], v[186:189], v[126:129]
	v_mfma_f32_16x16x32_bf16 v[122:125], v[162:165], v[186:189], v[122:125]
	v_mfma_f32_16x16x32_bf16 v[118:121], v[154:157], v[198:201], v[118:121]
	v_mfma_f32_16x16x32_bf16 v[114:117], v[162:165], v[198:201], v[114:117]
	v_mfma_f32_16x16x32_bf16 v[102:105], v[154:157], v[214:217], v[102:105]
	v_mfma_f32_16x16x32_bf16 v[98:101], v[162:165], v[214:217], v[98:101]
	v_mfma_f32_16x16x32_bf16 v[86:89], v[154:157], v[222:225], v[86:89]
	v_mfma_f32_16x16x32_bf16 v[82:85], v[162:165], v[222:225], v[82:85]
	v_mfma_f32_16x16x32_bf16 v[110:113], v[166:169], v[182:185], v[110:113]
	v_mfma_f32_16x16x32_bf16 v[106:109], v[174:177], v[182:185], v[106:109]
	v_mfma_f32_16x16x32_bf16 v[94:97], v[166:169], v[190:193], v[94:97]
	v_mfma_f32_16x16x32_bf16 v[90:93], v[174:177], v[190:193], v[90:93]
	v_mfma_f32_16x16x32_bf16 v[78:81], v[166:169], v[210:213], v[78:81]
	v_mfma_f32_16x16x32_bf16 v[74:77], v[174:177], v[210:213], v[74:77]
	v_mfma_f32_16x16x32_bf16 v[70:73], v[166:169], v[218:221], v[70:73]
	v_mfma_f32_16x16x32_bf16 v[66:69], v[174:177], v[218:221], v[66:69]
	v_mfma_f32_16x16x32_bf16 v[110:113], v[170:173], v[186:189], v[110:113]
	v_mfma_f32_16x16x32_bf16 v[106:109], v[178:181], v[186:189], v[106:109]
	v_mfma_f32_16x16x32_bf16 v[94:97], v[170:173], v[198:201], v[94:97]
	v_mfma_f32_16x16x32_bf16 v[90:93], v[178:181], v[198:201], v[90:93]
	v_mfma_f32_16x16x32_bf16 v[78:81], v[170:173], v[214:217], v[78:81]
	v_mfma_f32_16x16x32_bf16 v[74:77], v[178:181], v[214:217], v[74:77]
	v_mfma_f32_16x16x32_bf16 v[70:73], v[170:173], v[222:225], v[70:73]
	s_barrier
	v_mfma_f32_16x16x32_bf16 v[66:69], v[178:181], v[222:225], v[66:69]
	s_setprio 2
	s_add_i32 s30, s51, s35
	v_lshl_add_u64 v[202:203], v[202:203], 0, s[8:9]
	s_mov_b32 m0, s30
	ds_read_b128 v[182:185], v149 offset:49152
	ds_read_b128 v[186:189], v149 offset:50176
	ds_read_b128 v[190:193], v149 offset:51200
	ds_read_b128 v[198:201], v149 offset:52224
	ds_read_b128 v[210:213], v149 offset:53248
	ds_read_b128 v[214:217], v149 offset:54272
	ds_read_b128 v[218:221], v149 offset:55296
	ds_read_b128 v[222:225], v149 offset:56320
	global_load_lds_dwordx4 v[202:203], off
	s_add_i32 m0, s30, 0x2000
	s_add_u32 s28, s28, 0x20080
	v_lshl_add_u64 v[202:203], v[206:207], 0, s[8:9]
	s_addc_u32 s29, s29, 0
	s_add_i32 s30, s52, s35
	global_load_lds_dwordx4 v[202:203], off
	v_lshl_add_u64 v[202:203], s[28:29], 0, v[132:133]
	s_mov_b32 m0, s30
	s_nop 0
	global_load_lds_dwordx4 v[202:203], off
	v_lshl_add_u64 v[202:203], s[28:29], 0, v[134:135]
	s_add_i32 m0, s30, 0x2000
	s_nop 0
	global_load_lds_dwordx4 v[202:203], off
	v_lshl_add_u64 v[202:203], v[226:227], 0, s[8:9]
	s_mov_b32 m0, s41
	s_nop 0
	global_load_lds_dwordx4 v[202:203], off
	v_lshl_add_u64 v[202:203], v[228:229], 0, s[8:9]
	s_mov_b32 m0, s42
	s_nop 0
	global_load_lds_dwordx4 v[202:203], off
	s_waitcnt vmcnt(8)
	s_waitcnt lgkmcnt(0)
	s_barrier
	s_setprio 1
	s_waitcnt lgkmcnt(0)
	v_mfma_f32_16x16x32_bf16 v[62:65], v[150:153], v[182:185], v[62:65]
	v_mfma_f32_16x16x32_bf16 v[58:61], v[158:161], v[182:185], v[58:61]
	v_mfma_f32_16x16x32_bf16 v[54:57], v[150:153], v[190:193], v[54:57]
	v_mfma_f32_16x16x32_bf16 v[50:53], v[158:161], v[190:193], v[50:53]
	v_mfma_f32_16x16x32_bf16 v[38:41], v[150:153], v[210:213], v[38:41]
	v_mfma_f32_16x16x32_bf16 v[34:37], v[158:161], v[210:213], v[34:37]
	v_mfma_f32_16x16x32_bf16 v[22:25], v[150:153], v[218:221], v[22:25]
	v_mfma_f32_16x16x32_bf16 v[18:21], v[158:161], v[218:221], v[18:21]
	v_mfma_f32_16x16x32_bf16 v[62:65], v[154:157], v[186:189], v[62:65]
	v_mfma_f32_16x16x32_bf16 v[58:61], v[162:165], v[186:189], v[58:61]
	v_mfma_f32_16x16x32_bf16 v[54:57], v[154:157], v[198:201], v[54:57]
	v_mfma_f32_16x16x32_bf16 v[50:53], v[162:165], v[198:201], v[50:53]
	v_mfma_f32_16x16x32_bf16 v[38:41], v[154:157], v[214:217], v[38:41]
	v_mfma_f32_16x16x32_bf16 v[34:37], v[162:165], v[214:217], v[34:37]
	v_mfma_f32_16x16x32_bf16 v[22:25], v[154:157], v[222:225], v[22:25]
	v_mfma_f32_16x16x32_bf16 v[18:21], v[162:165], v[222:225], v[18:21]
	v_mfma_f32_16x16x32_bf16 v[46:49], v[166:169], v[182:185], v[46:49]
	v_mfma_f32_16x16x32_bf16 v[42:45], v[174:177], v[182:185], v[42:45]
	v_mfma_f32_16x16x32_bf16 v[30:33], v[166:169], v[190:193], v[30:33]
	v_mfma_f32_16x16x32_bf16 v[26:29], v[174:177], v[190:193], v[26:29]
	v_mfma_f32_16x16x32_bf16 v[14:17], v[166:169], v[210:213], v[14:17]
	v_mfma_f32_16x16x32_bf16 v[10:13], v[174:177], v[210:213], v[10:13]
	v_mfma_f32_16x16x32_bf16 v[6:9], v[166:169], v[218:221], v[6:9]
	v_mfma_f32_16x16x32_bf16 v[2:5], v[174:177], v[218:221], v[2:5]
	v_mfma_f32_16x16x32_bf16 v[46:49], v[170:173], v[186:189], v[46:49]
	v_mfma_f32_16x16x32_bf16 v[42:45], v[178:181], v[186:189], v[42:45]
	v_mfma_f32_16x16x32_bf16 v[30:33], v[170:173], v[198:201], v[30:33]
	v_mfma_f32_16x16x32_bf16 v[26:29], v[178:181], v[198:201], v[26:29]
	v_mfma_f32_16x16x32_bf16 v[14:17], v[170:173], v[214:217], v[14:17]
	v_mfma_f32_16x16x32_bf16 v[10:13], v[178:181], v[214:217], v[10:13]
	v_mfma_f32_16x16x32_bf16 v[6:9], v[170:173], v[222:225], v[6:9]
	s_barrier
	v_mfma_f32_16x16x32_bf16 v[2:5], v[178:181], v[222:225], v[2:5]
	s_setprio 2
	s_add_i32 s50, s50, 2
	s_add_u32 s26, s26, 0x100
	s_addc_u32 s27, s27, 0
	s_add_u32 s48, s48, 0x100
	s_addc_u32 s49, s49, 0
	s_cmp_gt_u32 s50, 5
	s_cbranch_scc0 .LBB0_690

.Lpeel_9:
	ds_read_b128 v[144:147], v140
	ds_read_b128 v[148:151], v140 offset:1024
	s_add_u32 s36, s34, 0xfffe0080
	s_addc_u32 s37, s35, -1
	s_cmp_eq_u32 s59, 4
	s_cselect_b32 s39, s21, s37
	s_cselect_b32 s38, s55, s36
	s_cselect_b32 s37, s25, s58
	s_cselect_b32 s36, s56, s57
	v_lshl_add_u64 v[192:193], s[34:35], 0, v[130:131]
	s_add_i32 m0, s27, 0xc000
	global_load_lds_dwordx4 v[192:193], off
	v_lshl_add_u64 v[192:193], s[34:35], 0, v[136:137]
	s_add_i32 m0, s27, 0xe000
	s_nop 0
	global_load_lds_dwordx4 v[192:193], off
	s_waitcnt vmcnt(8)
	s_waitcnt lgkmcnt(0)
	s_barrier
	s_setprio 1
	s_waitcnt lgkmcnt(0)
	v_mfma_f32_16x16x32_bf16 v[126:129], v[144:147], v[176:179], 0
	v_mfma_f32_16x16x32_bf16 v[122:125], v[152:155], v[176:179], 0
	v_mfma_f32_16x16x32_bf16 v[118:121], v[144:147], v[184:187], 0
	v_mfma_f32_16x16x32_bf16 v[114:117], v[152:155], v[184:187], 0
	v_mfma_f32_16x16x32_bf16 v[102:105], v[144:147], v[198:201], 0
	v_mfma_f32_16x16x32_bf16 v[98:101], v[152:155], v[198:201], 0
	v_mfma_f32_16x16x32_bf16 v[86:89], v[144:147], v[214:217], 0
	v_mfma_f32_16x16x32_bf16 v[82:85], v[152:155], v[214:217], 0
	v_mfma_f32_16x16x32_bf16 v[126:129], v[148:151], v[180:183], v[126:129]
	v_mfma_f32_16x16x32_bf16 v[122:125], v[156:159], v[180:183], v[122:125]
	v_mfma_f32_16x16x32_bf16 v[118:121], v[148:151], v[188:191], v[118:121]
	v_mfma_f32_16x16x32_bf16 v[114:117], v[156:159], v[188:191], v[114:117]
	v_mfma_f32_16x16x32_bf16 v[102:105], v[148:151], v[210:213], v[102:105]
	v_mfma_f32_16x16x32_bf16 v[98:101], v[156:159], v[210:213], v[98:101]
	v_mfma_f32_16x16x32_bf16 v[86:89], v[148:151], v[218:221], v[86:89]
	v_mfma_f32_16x16x32_bf16 v[82:85], v[156:159], v[218:221], v[82:85]
	v_mfma_f32_16x16x32_bf16 v[110:113], v[160:163], v[176:179], 0
	v_mfma_f32_16x16x32_bf16 v[106:109], v[168:171], v[176:179], 0
	v_mfma_f32_16x16x32_bf16 v[94:97], v[160:163], v[184:187], 0
	v_mfma_f32_16x16x32_bf16 v[90:93], v[168:171], v[184:187], 0
	v_mfma_f32_16x16x32_bf16 v[78:81], v[160:163], v[198:201], 0
	v_mfma_f32_16x16x32_bf16 v[74:77], v[168:171], v[198:201], 0
	v_mfma_f32_16x16x32_bf16 v[70:73], v[160:163], v[214:217], 0
	v_mfma_f32_16x16x32_bf16 v[66:69], v[168:171], v[214:217], 0
	v_mfma_f32_16x16x32_bf16 v[110:113], v[164:167], v[180:183], v[110:113]
	v_mfma_f32_16x16x32_bf16 v[106:109], v[172:175], v[180:183], v[106:109]
	v_mfma_f32_16x16x32_bf16 v[94:97], v[164:167], v[188:191], v[94:97]
	v_mfma_f32_16x16x32_bf16 v[90:93], v[172:175], v[188:191], v[90:93]
	v_mfma_f32_16x16x32_bf16 v[78:81], v[164:167], v[210:213], v[78:81]
	v_mfma_f32_16x16x32_bf16 v[74:77], v[172:175], v[210:213], v[74:77]
	v_mfma_f32_16x16x32_bf16 v[70:73], v[164:167], v[218:221], v[70:73]
	s_barrier
	v_mfma_f32_16x16x32_bf16 v[66:69], v[172:175], v[218:221], v[66:69]
	s_setprio 2
	s_add_i32 s60, s48, s41
	v_lshl_add_u64 v[192:193], s[36:37], 0, v[132:133]
	s_mov_b32 m0, s60
	ds_read_b128 v[176:179], v142 offset:16384
	ds_read_b128 v[180:183], v142 offset:17408
	ds_read_b128 v[184:187], v142 offset:18432
	ds_read_b128 v[188:191], v142 offset:19456
	ds_read_b128 v[198:201], v142 offset:20480
	ds_read_b128 v[210:213], v142 offset:21504
	ds_read_b128 v[214:217], v142 offset:22528
	ds_read_b128 v[218:221], v142 offset:23552
	global_load_lds_dwordx4 v[192:193], off
	s_add_i32 m0, s60, 0x2000
	s_add_u32 s60, s36, 0x20000
	v_lshl_add_u64 v[202:203], s[36:37], 0, v[134:135]
	s_addc_u32 s61, s37, 0
	s_add_i32 s62, s49, s41
	global_load_lds_dwordx4 v[202:203], off
	v_lshl_add_u64 v[206:207], s[60:61], 0, v[132:133]
	s_mov_b32 m0, s62
	v_lshl_add_u64 v[222:223], s[38:39], 0, v[136:137]
	global_load_lds_dwordx4 v[206:207], off
	v_lshl_add_u64 v[206:207], s[60:61], 0, v[134:135]
	s_add_i32 m0, s62, 0x2000
	s_nop 0
	global_load_lds_dwordx4 v[206:207], off
	v_lshl_add_u64 v[206:207], s[38:39], 0, v[130:131]
	s_mov_b32 m0, s27
	s_nop 0
	global_load_lds_dwordx4 v[206:207], off
	s_mov_b32 m0, s42
	s_nop 0
	global_load_lds_dwordx4 v[222:223], off
	s_waitcnt vmcnt(8)
	s_waitcnt lgkmcnt(0)
	s_barrier
	s_setprio 1
	s_waitcnt lgkmcnt(0)
	v_mfma_f32_16x16x32_bf16 v[62:65], v[144:147], v[176:179], 0
	v_mfma_f32_16x16x32_bf16 v[58:61], v[152:155], v[176:179], 0
	v_mfma_f32_16x16x32_bf16 v[54:57], v[144:147], v[184:187], 0
	v_mfma_f32_16x16x32_bf16 v[50:53], v[152:155], v[184:187], 0
	v_mfma_f32_16x16x32_bf16 v[38:41], v[144:147], v[198:201], 0
	v_mfma_f32_16x16x32_bf16 v[34:37], v[152:155], v[198:201], 0
	v_mfma_f32_16x16x32_bf16 v[22:25], v[144:147], v[214:217], 0
	v_mfma_f32_16x16x32_bf16 v[18:21], v[152:155], v[214:217], 0
	v_mfma_f32_16x16x32_bf16 v[62:65], v[148:151], v[180:183], v[62:65]
	v_mfma_f32_16x16x32_bf16 v[58:61], v[156:159], v[180:183], v[58:61]
	v_mfma_f32_16x16x32_bf16 v[54:57], v[148:151], v[188:191], v[54:57]
	v_mfma_f32_16x16x32_bf16 v[50:53], v[156:159], v[188:191], v[50:53]
	v_mfma_f32_16x16x32_bf16 v[38:41], v[148:151], v[210:213], v[38:41]
	v_mfma_f32_16x16x32_bf16 v[34:37], v[156:159], v[210:213], v[34:37]
	v_mfma_f32_16x16x32_bf16 v[22:25], v[148:151], v[218:221], v[22:25]
	v_mfma_f32_16x16x32_bf16 v[18:21], v[156:159], v[218:221], v[18:21]
	v_mfma_f32_16x16x32_bf16 v[46:49], v[160:163], v[176:179], 0
	v_mfma_f32_16x16x32_bf16 v[42:45], v[168:171], v[176:179], 0
	v_mfma_f32_16x16x32_bf16 v[30:33], v[160:163], v[184:187], 0
	v_mfma_f32_16x16x32_bf16 v[26:29], v[168:171], v[184:187], 0
	v_mfma_f32_16x16x32_bf16 v[14:17], v[160:163], v[198:201], 0
	v_mfma_f32_16x16x32_bf16 v[10:13], v[168:171], v[198:201], 0
	v_mfma_f32_16x16x32_bf16 v[6:9], v[160:163], v[214:217], 0
	v_mfma_f32_16x16x32_bf16 v[2:5], v[168:171], v[214:217], 0
	v_mfma_f32_16x16x32_bf16 v[46:49], v[164:167], v[180:183], v[46:49]
	v_mfma_f32_16x16x32_bf16 v[42:45], v[172:175], v[180:183], v[42:45]
	v_mfma_f32_16x16x32_bf16 v[30:33], v[164:167], v[188:191], v[30:33]
	v_mfma_f32_16x16x32_bf16 v[26:29], v[172:175], v[188:191], v[26:29]
	v_mfma_f32_16x16x32_bf16 v[14:17], v[164:167], v[210:213], v[14:17]
	v_mfma_f32_16x16x32_bf16 v[10:13], v[172:175], v[210:213], v[10:13]
	v_mfma_f32_16x16x32_bf16 v[6:9], v[164:167], v[218:221], v[6:9]
	s_barrier
	v_mfma_f32_16x16x32_bf16 v[2:5], v[172:175], v[218:221], v[2:5]
	s_setprio 2
	s_add_i32 s60, 0, 0x18000
	v_add_u32_e32 v143, s60, v139
	s_add_i32 s61, 0, 0x1c000
	ds_read_b128 v[144:147], v143
	ds_read_b128 v[148:151], v143 offset:1024
	ds_read_b128 v[152:155], v143 offset:2048
	ds_read_b128 v[156:159], v143 offset:3072
	v_add_u32_e32 v143, s61, v139
	ds_read_b128 v[160:163], v143
	ds_read_b128 v[164:167], v143 offset:1024
	ds_read_b128 v[168:171], v143 offset:2048
	ds_read_b128 v[172:175], v143 offset:3072
	s_add_u32 s38, s38, 0x20000
	s_addc_u32 s39, s39, 0
	s_mov_b32 m0, s43
	v_lshl_add_u64 v[224:225], s[38:39], 0, v[130:131]
	ds_read_b128 v[176:179], v142 offset:32768
	ds_read_b128 v[180:183], v142 offset:33792
	ds_read_b128 v[184:187], v142 offset:34816
	ds_read_b128 v[188:191], v142 offset:35840
	ds_read_b128 v[198:201], v142 offset:36864
	ds_read_b128 v[210:213], v142 offset:37888
	ds_read_b128 v[214:217], v142 offset:38912
	ds_read_b128 v[218:221], v142 offset:39936
	global_load_lds_dwordx4 v[224:225], off
	v_lshl_add_u64 v[224:225], s[38:39], 0, v[136:137]
	s_mov_b32 m0, s44
	s_nop 0
	global_load_lds_dwordx4 v[224:225], off
	s_waitcnt vmcnt(8)
	s_waitcnt lgkmcnt(0)
	s_barrier
	s_setprio 1
	s_waitcnt lgkmcnt(0)
	v_mfma_f32_16x16x32_bf16 v[126:129], v[144:147], v[176:179], v[126:129]
	v_mfma_f32_16x16x32_bf16 v[122:125], v[152:155], v[176:179], v[122:125]
	v_mfma_f32_16x16x32_bf16 v[118:121], v[144:147], v[184:187], v[118:121]
	v_mfma_f32_16x16x32_bf16 v[114:117], v[152:155], v[184:187], v[114:117]
	v_mfma_f32_16x16x32_bf16 v[102:105], v[144:147], v[198:201], v[102:105]
	v_mfma_f32_16x16x32_bf16 v[98:101], v[152:155], v[198:201], v[98:101]
	v_mfma_f32_16x16x32_bf16 v[86:89], v[144:147], v[214:217], v[86:89]
	v_mfma_f32_16x16x32_bf16 v[82:85], v[152:155], v[214:217], v[82:85]
	v_mfma_f32_16x16x32_bf16 v[126:129], v[148:151], v[180:183], v[126:129]
	v_mfma_f32_16x16x32_bf16 v[122:125], v[156:159], v[180:183], v[122:125]
	v_mfma_f32_16x16x32_bf16 v[118:121], v[148:151], v[188:191], v[118:121]
	v_mfma_f32_16x16x32_bf16 v[114:117], v[156:159], v[188:191], v[114:117]
	v_mfma_f32_16x16x32_bf16 v[102:105], v[148:151], v[210:213], v[102:105]
	v_mfma_f32_16x16x32_bf16 v[98:101], v[156:159], v[210:213], v[98:101]
	v_mfma_f32_16x16x32_bf16 v[86:89], v[148:151], v[218:221], v[86:89]
	v_mfma_f32_16x16x32_bf16 v[82:85], v[156:159], v[218:221], v[82:85]
	v_mfma_f32_16x16x32_bf16 v[110:113], v[160:163], v[176:179], v[110:113]
	v_mfma_f32_16x16x32_bf16 v[106:109], v[168:171], v[176:179], v[106:109]
	v_mfma_f32_16x16x32_bf16 v[94:97], v[160:163], v[184:187], v[94:97]
	v_mfma_f32_16x16x32_bf16 v[90:93], v[168:171], v[184:187], v[90:93]
	v_mfma_f32_16x16x32_bf16 v[78:81], v[160:163], v[198:201], v[78:81]
	v_mfma_f32_16x16x32_bf16 v[74:77], v[168:171], v[198:201], v[74:77]
	v_mfma_f32_16x16x32_bf16 v[70:73], v[160:163], v[214:217], v[70:73]
	v_mfma_f32_16x16x32_bf16 v[66:69], v[168:171], v[214:217], v[66:69]
	v_mfma_f32_16x16x32_bf16 v[110:113], v[164:167], v[180:183], v[110:113]
	v_mfma_f32_16x16x32_bf16 v[106:109], v[172:175], v[180:183], v[106:109]
	v_mfma_f32_16x16x32_bf16 v[94:97], v[164:167], v[188:191], v[94:97]
	v_mfma_f32_16x16x32_bf16 v[90:93], v[172:175], v[188:191], v[90:93]
	v_mfma_f32_16x16x32_bf16 v[78:81], v[164:167], v[210:213], v[78:81]
	v_mfma_f32_16x16x32_bf16 v[74:77], v[172:175], v[210:213], v[74:77]
	v_mfma_f32_16x16x32_bf16 v[70:73], v[164:167], v[218:221], v[70:73]
	s_barrier
	v_mfma_f32_16x16x32_bf16 v[66:69], v[172:175], v[218:221], v[66:69]
	s_setprio 2
	s_add_i32 s38, s60, s41
	v_lshl_add_u64 v[192:193], v[192:193], 0, s[6:7]
	s_mov_b32 m0, s38
	ds_read_b128 v[176:179], v142 offset:49152
	ds_read_b128 v[180:183], v142 offset:50176
	ds_read_b128 v[184:187], v142 offset:51200
	ds_read_b128 v[188:191], v142 offset:52224
	ds_read_b128 v[198:201], v142 offset:53248
	ds_read_b128 v[210:213], v142 offset:54272
	ds_read_b128 v[214:217], v142 offset:55296
	ds_read_b128 v[218:221], v142 offset:56320
	global_load_lds_dwordx4 v[192:193], off
	s_add_i32 m0, s38, 0x2000
	s_add_u32 s36, s36, 0x20080
	v_lshl_add_u64 v[192:193], v[202:203], 0, s[6:7]
	s_addc_u32 s37, s37, 0
	s_add_i32 s38, s61, s41
	global_load_lds_dwordx4 v[192:193], off
	v_lshl_add_u64 v[192:193], s[36:37], 0, v[132:133]
	s_mov_b32 m0, s38
	s_nop 0
	global_load_lds_dwordx4 v[192:193], off
	v_lshl_add_u64 v[192:193], s[36:37], 0, v[134:135]
	s_add_i32 m0, s38, 0x2000
	s_nop 0
	global_load_lds_dwordx4 v[192:193], off
	v_lshl_add_u64 v[192:193], v[206:207], 0, s[6:7]
	s_mov_b32 m0, s46
	s_nop 0
	global_load_lds_dwordx4 v[192:193], off
	v_lshl_add_u64 v[192:193], v[222:223], 0, s[6:7]
	s_mov_b32 m0, s47
	s_nop 0
	global_load_lds_dwordx4 v[192:193], off
	s_waitcnt vmcnt(8)
	s_waitcnt lgkmcnt(0)
	s_barrier
	s_setprio 1
	s_waitcnt lgkmcnt(0)
	v_mfma_f32_16x16x32_bf16 v[62:65], v[144:147], v[176:179], v[62:65]
	v_mfma_f32_16x16x32_bf16 v[58:61], v[152:155], v[176:179], v[58:61]
	v_mfma_f32_16x16x32_bf16 v[54:57], v[144:147], v[184:187], v[54:57]
	v_mfma_f32_16x16x32_bf16 v[50:53], v[152:155], v[184:187], v[50:53]
	v_mfma_f32_16x16x32_bf16 v[38:41], v[144:147], v[198:201], v[38:41]
	v_mfma_f32_16x16x32_bf16 v[34:37], v[152:155], v[198:201], v[34:37]
	v_mfma_f32_16x16x32_bf16 v[22:25], v[144:147], v[214:217], v[22:25]
	v_mfma_f32_16x16x32_bf16 v[18:21], v[152:155], v[214:217], v[18:21]
	v_mfma_f32_16x16x32_bf16 v[62:65], v[148:151], v[180:183], v[62:65]
	v_mfma_f32_16x16x32_bf16 v[58:61], v[156:159], v[180:183], v[58:61]
	v_mfma_f32_16x16x32_bf16 v[54:57], v[148:151], v[188:191], v[54:57]
	v_mfma_f32_16x16x32_bf16 v[50:53], v[156:159], v[188:191], v[50:53]
	v_mfma_f32_16x16x32_bf16 v[38:41], v[148:151], v[210:213], v[38:41]
	v_mfma_f32_16x16x32_bf16 v[34:37], v[156:159], v[210:213], v[34:37]
	v_mfma_f32_16x16x32_bf16 v[22:25], v[148:151], v[218:221], v[22:25]
	v_mfma_f32_16x16x32_bf16 v[18:21], v[156:159], v[218:221], v[18:21]
	v_mfma_f32_16x16x32_bf16 v[46:49], v[160:163], v[176:179], v[46:49]
	v_mfma_f32_16x16x32_bf16 v[42:45], v[168:171], v[176:179], v[42:45]
	v_mfma_f32_16x16x32_bf16 v[30:33], v[160:163], v[184:187], v[30:33]
	v_mfma_f32_16x16x32_bf16 v[26:29], v[168:171], v[184:187], v[26:29]
	v_mfma_f32_16x16x32_bf16 v[14:17], v[160:163], v[198:201], v[14:17]
	v_mfma_f32_16x16x32_bf16 v[10:13], v[168:171], v[198:201], v[10:13]
	v_mfma_f32_16x16x32_bf16 v[6:9], v[160:163], v[214:217], v[6:9]
	v_mfma_f32_16x16x32_bf16 v[2:5], v[168:171], v[214:217], v[2:5]
	v_mfma_f32_16x16x32_bf16 v[46:49], v[164:167], v[180:183], v[46:49]
	v_mfma_f32_16x16x32_bf16 v[42:45], v[172:175], v[180:183], v[42:45]
	v_mfma_f32_16x16x32_bf16 v[30:33], v[164:167], v[188:191], v[30:33]
	v_mfma_f32_16x16x32_bf16 v[26:29], v[172:175], v[188:191], v[26:29]
	v_mfma_f32_16x16x32_bf16 v[14:17], v[164:167], v[210:213], v[14:17]
	v_mfma_f32_16x16x32_bf16 v[10:13], v[172:175], v[210:213], v[10:13]
	v_mfma_f32_16x16x32_bf16 v[6:9], v[164:167], v[218:221], v[6:9]
	s_barrier
	v_mfma_f32_16x16x32_bf16 v[2:5], v[172:175], v[218:221], v[2:5]
	s_setprio 2
	s_add_i32 s59, s59, 2
	s_add_u32 s34, s34, 0x100
	s_addc_u32 s35, s35, 0
	s_add_u32 s57, s57, 0x100
	s_addc_u32 s58, s58, 0
	s_cmp_gt_u32 s59, 5
	s_cbranch_scc0 .LBB0_714
	s_branch .Lpeeldone_9
.LBB0_714:
	ds_read_b128 v[144:147], v140
	ds_read_b128 v[148:151], v140 offset:1024
	ds_read_b128 v[152:155], v140 offset:2048
	ds_read_b128 v[156:159], v140 offset:3072
	ds_read_b128 v[160:163], v141
	ds_read_b128 v[164:167], v141 offset:1024
	ds_read_b128 v[168:171], v141 offset:2048
	ds_read_b128 v[172:175], v141 offset:3072
	s_add_u32 s36, s34, 0xfffe0080
	s_addc_u32 s37, s35, -1
	s_cmp_eq_u32 s59, 4
	s_cselect_b32 s39, s21, s37
	s_cselect_b32 s38, s55, s36
	s_cselect_b32 s37, s25, s58
	s_cselect_b32 s36, s56, s57
	v_lshl_add_u64 v[192:193], s[34:35], 0, v[130:131]
	s_add_i32 m0, s27, 0xc000
	ds_read_b128 v[176:179], v142
	ds_read_b128 v[180:183], v142 offset:1024
	ds_read_b128 v[184:187], v142 offset:2048
	ds_read_b128 v[188:191], v142 offset:3072
	ds_read_b128 v[198:201], v142 offset:4096
	ds_read_b128 v[210:213], v142 offset:5120
	ds_read_b128 v[214:217], v142 offset:6144
	ds_read_b128 v[218:221], v142 offset:7168
	global_load_lds_dwordx4 v[192:193], off
	v_lshl_add_u64 v[192:193], s[34:35], 0, v[136:137]
	s_add_i32 m0, s27, 0xe000
	s_nop 0
	global_load_lds_dwordx4 v[192:193], off
	s_waitcnt vmcnt(8)
	s_waitcnt lgkmcnt(0)
	s_barrier
	s_setprio 1
	s_waitcnt lgkmcnt(0)
	v_mfma_f32_16x16x32_bf16 v[126:129], v[144:147], v[176:179], v[126:129]
	v_mfma_f32_16x16x32_bf16 v[122:125], v[152:155], v[176:179], v[122:125]
	v_mfma_f32_16x16x32_bf16 v[118:121], v[144:147], v[184:187], v[118:121]
	v_mfma_f32_16x16x32_bf16 v[114:117], v[152:155], v[184:187], v[114:117]
	v_mfma_f32_16x16x32_bf16 v[102:105], v[144:147], v[198:201], v[102:105]
	v_mfma_f32_16x16x32_bf16 v[98:101], v[152:155], v[198:201], v[98:101]
	v_mfma_f32_16x16x32_bf16 v[86:89], v[144:147], v[214:217], v[86:89]
	v_mfma_f32_16x16x32_bf16 v[82:85], v[152:155], v[214:217], v[82:85]
	v_mfma_f32_16x16x32_bf16 v[126:129], v[148:151], v[180:183], v[126:129]
	v_mfma_f32_16x16x32_bf16 v[122:125], v[156:159], v[180:183], v[122:125]
	v_mfma_f32_16x16x32_bf16 v[118:121], v[148:151], v[188:191], v[118:121]
	v_mfma_f32_16x16x32_bf16 v[114:117], v[156:159], v[188:191], v[114:117]
	v_mfma_f32_16x16x32_bf16 v[102:105], v[148:151], v[210:213], v[102:105]
	v_mfma_f32_16x16x32_bf16 v[98:101], v[156:159], v[210:213], v[98:101]
	v_mfma_f32_16x16x32_bf16 v[86:89], v[148:151], v[218:221], v[86:89]
	v_mfma_f32_16x16x32_bf16 v[82:85], v[156:159], v[218:221], v[82:85]
	v_mfma_f32_16x16x32_bf16 v[110:113], v[160:163], v[176:179], v[110:113]
	v_mfma_f32_16x16x32_bf16 v[106:109], v[168:171], v[176:179], v[106:109]
	v_mfma_f32_16x16x32_bf16 v[94:97], v[160:163], v[184:187], v[94:97]
	v_mfma_f32_16x16x32_bf16 v[90:93], v[168:171], v[184:187], v[90:93]
	v_mfma_f32_16x16x32_bf16 v[78:81], v[160:163], v[198:201], v[78:81]
	v_mfma_f32_16x16x32_bf16 v[74:77], v[168:171], v[198:201], v[74:77]
	v_mfma_f32_16x16x32_bf16 v[70:73], v[160:163], v[214:217], v[70:73]
	v_mfma_f32_16x16x32_bf16 v[66:69], v[168:171], v[214:217], v[66:69]
	v_mfma_f32_16x16x32_bf16 v[110:113], v[164:167], v[180:183], v[110:113]
	v_mfma_f32_16x16x32_bf16 v[106:109], v[172:175], v[180:183], v[106:109]
	v_mfma_f32_16x16x32_bf16 v[94:97], v[164:167], v[188:191], v[94:97]
	v_mfma_f32_16x16x32_bf16 v[90:93], v[172:175], v[188:191], v[90:93]
	v_mfma_f32_16x16x32_bf16 v[78:81], v[164:167], v[210:213], v[78:81]
	v_mfma_f32_16x16x32_bf16 v[74:77], v[172:175], v[210:213], v[74:77]
	v_mfma_f32_16x16x32_bf16 v[70:73], v[164:167], v[218:221], v[70:73]
	s_barrier
	v_mfma_f32_16x16x32_bf16 v[66:69], v[172:175], v[218:221], v[66:69]
	s_setprio 2
	s_add_i32 s60, s48, s41
	v_lshl_add_u64 v[192:193], s[36:37], 0, v[132:133]
	s_mov_b32 m0, s60
	ds_read_b128 v[176:179], v142 offset:16384
	ds_read_b128 v[180:183], v142 offset:17408
	ds_read_b128 v[184:187], v142 offset:18432
	ds_read_b128 v[188:191], v142 offset:19456
	ds_read_b128 v[198:201], v142 offset:20480
	ds_read_b128 v[210:213], v142 offset:21504
	ds_read_b128 v[214:217], v142 offset:22528
	ds_read_b128 v[218:221], v142 offset:23552
	global_load_lds_dwordx4 v[192:193], off
	s_add_i32 m0, s60, 0x2000
	s_add_u32 s60, s36, 0x20000
	v_lshl_add_u64 v[202:203], s[36:37], 0, v[134:135]
	s_addc_u32 s61, s37, 0
	s_add_i32 s62, s49, s41
	global_load_lds_dwordx4 v[202:203], off
	v_lshl_add_u64 v[206:207], s[60:61], 0, v[132:133]
	s_mov_b32 m0, s62
	v_lshl_add_u64 v[222:223], s[38:39], 0, v[136:137]
	global_load_lds_dwordx4 v[206:207], off
	v_lshl_add_u64 v[206:207], s[60:61], 0, v[134:135]
	s_add_i32 m0, s62, 0x2000
	s_nop 0
	global_load_lds_dwordx4 v[206:207], off
	v_lshl_add_u64 v[206:207], s[38:39], 0, v[130:131]
	s_mov_b32 m0, s27
	s_nop 0
	global_load_lds_dwordx4 v[206:207], off
	s_mov_b32 m0, s42
	s_nop 0
	global_load_lds_dwordx4 v[222:223], off
	s_waitcnt vmcnt(8)
	s_waitcnt lgkmcnt(0)
	s_barrier
	s_setprio 1
	s_waitcnt lgkmcnt(0)
	v_mfma_f32_16x16x32_bf16 v[62:65], v[144:147], v[176:179], v[62:65]
	v_mfma_f32_16x16x32_bf16 v[58:61], v[152:155], v[176:179], v[58:61]
	v_mfma_f32_16x16x32_bf16 v[54:57], v[144:147], v[184:187], v[54:57]
	v_mfma_f32_16x16x32_bf16 v[50:53], v[152:155], v[184:187], v[50:53]
	v_mfma_f32_16x16x32_bf16 v[38:41], v[144:147], v[198:201], v[38:41]
	v_mfma_f32_16x16x32_bf16 v[34:37], v[152:155], v[198:201], v[34:37]
	v_mfma_f32_16x16x32_bf16 v[22:25], v[144:147], v[214:217], v[22:25]
	v_mfma_f32_16x16x32_bf16 v[18:21], v[152:155], v[214:217], v[18:21]
	v_mfma_f32_16x16x32_bf16 v[62:65], v[148:151], v[180:183], v[62:65]
	v_mfma_f32_16x16x32_bf16 v[58:61], v[156:159], v[180:183], v[58:61]
	v_mfma_f32_16x16x32_bf16 v[54:57], v[148:151], v[188:191], v[54:57]
	v_mfma_f32_16x16x32_bf16 v[50:53], v[156:159], v[188:191], v[50:53]
	v_mfma_f32_16x16x32_bf16 v[38:41], v[148:151], v[210:213], v[38:41]
	v_mfma_f32_16x16x32_bf16 v[34:37], v[156:159], v[210:213], v[34:37]
	v_mfma_f32_16x16x32_bf16 v[22:25], v[148:151], v[218:221], v[22:25]
	v_mfma_f32_16x16x32_bf16 v[18:21], v[156:159], v[218:221], v[18:21]
	v_mfma_f32_16x16x32_bf16 v[46:49], v[160:163], v[176:179], v[46:49]
	v_mfma_f32_16x16x32_bf16 v[42:45], v[168:171], v[176:179], v[42:45]
	v_mfma_f32_16x16x32_bf16 v[30:33], v[160:163], v[184:187], v[30:33]
	v_mfma_f32_16x16x32_bf16 v[26:29], v[168:171], v[184:187], v[26:29]
	v_mfma_f32_16x16x32_bf16 v[14:17], v[160:163], v[198:201], v[14:17]
	v_mfma_f32_16x16x32_bf16 v[10:13], v[168:171], v[198:201], v[10:13]
	v_mfma_f32_16x16x32_bf16 v[6:9], v[160:163], v[214:217], v[6:9]
	v_mfma_f32_16x16x32_bf16 v[2:5], v[168:171], v[214:217], v[2:5]
	v_mfma_f32_16x16x32_bf16 v[46:49], v[164:167], v[180:183], v[46:49]
	v_mfma_f32_16x16x32_bf16 v[42:45], v[172:175], v[180:183], v[42:45]
	v_mfma_f32_16x16x32_bf16 v[30:33], v[164:167], v[188:191], v[30:33]
	v_mfma_f32_16x16x32_bf16 v[26:29], v[172:175], v[188:191], v[26:29]
	v_mfma_f32_16x16x32_bf16 v[14:17], v[164:167], v[210:213], v[14:17]
	v_mfma_f32_16x16x32_bf16 v[10:13], v[172:175], v[210:213], v[10:13]
	v_mfma_f32_16x16x32_bf16 v[6:9], v[164:167], v[218:221], v[6:9]
	s_barrier
	v_mfma_f32_16x16x32_bf16 v[2:5], v[172:175], v[218:221], v[2:5]
	s_setprio 2
	s_add_i32 s60, 0, 0x18000
	v_add_u32_e32 v143, s60, v139
	s_add_i32 s61, 0, 0x1c000
	ds_read_b128 v[144:147], v143
	ds_read_b128 v[148:151], v143 offset:1024
	ds_read_b128 v[152:155], v143 offset:2048
	ds_read_b128 v[156:159], v143 offset:3072
	v_add_u32_e32 v143, s61, v139
	ds_read_b128 v[160:163], v143
	ds_read_b128 v[164:167], v143 offset:1024
	ds_read_b128 v[168:171], v143 offset:2048
	ds_read_b128 v[172:175], v143 offset:3072
	s_add_u32 s38, s38, 0x20000
	s_addc_u32 s39, s39, 0
	s_mov_b32 m0, s43
	v_lshl_add_u64 v[224:225], s[38:39], 0, v[130:131]
	ds_read_b128 v[176:179], v142 offset:32768
	ds_read_b128 v[180:183], v142 offset:33792
	ds_read_b128 v[184:187], v142 offset:34816
	ds_read_b128 v[188:191], v142 offset:35840
	ds_read_b128 v[198:201], v142 offset:36864
	ds_read_b128 v[210:213], v142 offset:37888
	ds_read_b128 v[214:217], v142 offset:38912
	ds_read_b128 v[218:221], v142 offset:39936
	global_load_lds_dwordx4 v[224:225], off
	v_lshl_add_u64 v[224:225], s[38:39], 0, v[136:137]
	s_mov_b32 m0, s44
	s_nop 0
	global_load_lds_dwordx4 v[224:225], off
	s_waitcnt vmcnt(8)
	s_waitcnt lgkmcnt(0)
	s_barrier
	s_setprio 1
	s_waitcnt lgkmcnt(0)
	v_mfma_f32_16x16x32_bf16 v[126:129], v[144:147], v[176:179], v[126:129]
	v_mfma_f32_16x16x32_bf16 v[122:125], v[152:155], v[176:179], v[122:125]
	v_mfma_f32_16x16x32_bf16 v[118:121], v[144:147], v[184:187], v[118:121]
	v_mfma_f32_16x16x32_bf16 v[114:117], v[152:155], v[184:187], v[114:117]
	v_mfma_f32_16x16x32_bf16 v[102:105], v[144:147], v[198:201], v[102:105]
	v_mfma_f32_16x16x32_bf16 v[98:101], v[152:155], v[198:201], v[98:101]
	v_mfma_f32_16x16x32_bf16 v[86:89], v[144:147], v[214:217], v[86:89]
	v_mfma_f32_16x16x32_bf16 v[82:85], v[152:155], v[214:217], v[82:85]
	v_mfma_f32_16x16x32_bf16 v[126:129], v[148:151], v[180:183], v[126:129]
	v_mfma_f32_16x16x32_bf16 v[122:125], v[156:159], v[180:183], v[122:125]
	v_mfma_f32_16x16x32_bf16 v[118:121], v[148:151], v[188:191], v[118:121]
	v_mfma_f32_16x16x32_bf16 v[114:117], v[156:159], v[188:191], v[114:117]
	v_mfma_f32_16x16x32_bf16 v[102:105], v[148:151], v[210:213], v[102:105]
	v_mfma_f32_16x16x32_bf16 v[98:101], v[156:159], v[210:213], v[98:101]
	v_mfma_f32_16x16x32_bf16 v[86:89], v[148:151], v[218:221], v[86:89]
	v_mfma_f32_16x16x32_bf16 v[82:85], v[156:159], v[218:221], v[82:85]
	v_mfma_f32_16x16x32_bf16 v[110:113], v[160:163], v[176:179], v[110:113]
	v_mfma_f32_16x16x32_bf16 v[106:109], v[168:171], v[176:179], v[106:109]
	v_mfma_f32_16x16x32_bf16 v[94:97], v[160:163], v[184:187], v[94:97]
	v_mfma_f32_16x16x32_bf16 v[90:93], v[168:171], v[184:187], v[90:93]
	v_mfma_f32_16x16x32_bf16 v[78:81], v[160:163], v[198:201], v[78:81]
	v_mfma_f32_16x16x32_bf16 v[74:77], v[168:171], v[198:201], v[74:77]
	v_mfma_f32_16x16x32_bf16 v[70:73], v[160:163], v[214:217], v[70:73]
	v_mfma_f32_16x16x32_bf16 v[66:69], v[168:171], v[214:217], v[66:69]
	v_mfma_f32_16x16x32_bf16 v[110:113], v[164:167], v[180:183], v[110:113]
	v_mfma_f32_16x16x32_bf16 v[106:109], v[172:175], v[180:183], v[106:109]
	v_mfma_f32_16x16x32_bf16 v[94:97], v[164:167], v[188:191], v[94:97]
	v_mfma_f32_16x16x32_bf16 v[90:93], v[172:175], v[188:191], v[90:93]
	v_mfma_f32_16x16x32_bf16 v[78:81], v[164:167], v[210:213], v[78:81]
	v_mfma_f32_16x16x32_bf16 v[74:77], v[172:175], v[210:213], v[74:77]
	v_mfma_f32_16x16x32_bf16 v[70:73], v[164:167], v[218:221], v[70:73]
	s_barrier
	v_mfma_f32_16x16x32_bf16 v[66:69], v[172:175], v[218:221], v[66:69]
	s_setprio 2
	s_add_i32 s38, s60, s41
	v_lshl_add_u64 v[192:193], v[192:193], 0, s[6:7]
	s_mov_b32 m0, s38
	ds_read_b128 v[176:179], v142 offset:49152
	ds_read_b128 v[180:183], v142 offset:50176
	ds_read_b128 v[184:187], v142 offset:51200
	ds_read_b128 v[188:191], v142 offset:52224
	ds_read_b128 v[198:201], v142 offset:53248
	ds_read_b128 v[210:213], v142 offset:54272
	ds_read_b128 v[214:217], v142 offset:55296
	ds_read_b128 v[218:221], v142 offset:56320
	global_load_lds_dwordx4 v[192:193], off
	s_add_i32 m0, s38, 0x2000
	s_add_u32 s36, s36, 0x20080
	v_lshl_add_u64 v[192:193], v[202:203], 0, s[6:7]
	s_addc_u32 s37, s37, 0
	s_add_i32 s38, s61, s41
	global_load_lds_dwordx4 v[192:193], off
	v_lshl_add_u64 v[192:193], s[36:37], 0, v[132:133]
	s_mov_b32 m0, s38
	s_nop 0
	global_load_lds_dwordx4 v[192:193], off
	v_lshl_add_u64 v[192:193], s[36:37], 0, v[134:135]
	s_add_i32 m0, s38, 0x2000
	s_nop 0
	global_load_lds_dwordx4 v[192:193], off
	v_lshl_add_u64 v[192:193], v[206:207], 0, s[6:7]
	s_mov_b32 m0, s46
	s_nop 0
	global_load_lds_dwordx4 v[192:193], off
	v_lshl_add_u64 v[192:193], v[222:223], 0, s[6:7]
	s_mov_b32 m0, s47
	s_nop 0
	global_load_lds_dwordx4 v[192:193], off
	s_waitcnt vmcnt(8)
	s_waitcnt lgkmcnt(0)
	s_barrier
	s_setprio 1
	s_waitcnt lgkmcnt(0)
	v_mfma_f32_16x16x32_bf16 v[62:65], v[144:147], v[176:179], v[62:65]
	v_mfma_f32_16x16x32_bf16 v[58:61], v[152:155], v[176:179], v[58:61]
	v_mfma_f32_16x16x32_bf16 v[54:57], v[144:147], v[184:187], v[54:57]
	v_mfma_f32_16x16x32_bf16 v[50:53], v[152:155], v[184:187], v[50:53]
	v_mfma_f32_16x16x32_bf16 v[38:41], v[144:147], v[198:201], v[38:41]
	v_mfma_f32_16x16x32_bf16 v[34:37], v[152:155], v[198:201], v[34:37]
	v_mfma_f32_16x16x32_bf16 v[22:25], v[144:147], v[214:217], v[22:25]
	v_mfma_f32_16x16x32_bf16 v[18:21], v[152:155], v[214:217], v[18:21]
	v_mfma_f32_16x16x32_bf16 v[62:65], v[148:151], v[180:183], v[62:65]
	v_mfma_f32_16x16x32_bf16 v[58:61], v[156:159], v[180:183], v[58:61]
	v_mfma_f32_16x16x32_bf16 v[54:57], v[148:151], v[188:191], v[54:57]
	v_mfma_f32_16x16x32_bf16 v[50:53], v[156:159], v[188:191], v[50:53]
	v_mfma_f32_16x16x32_bf16 v[38:41], v[148:151], v[210:213], v[38:41]
	v_mfma_f32_16x16x32_bf16 v[34:37], v[156:159], v[210:213], v[34:37]
	v_mfma_f32_16x16x32_bf16 v[22:25], v[148:151], v[218:221], v[22:25]
	v_mfma_f32_16x16x32_bf16 v[18:21], v[156:159], v[218:221], v[18:21]
	v_mfma_f32_16x16x32_bf16 v[46:49], v[160:163], v[176:179], v[46:49]
	v_mfma_f32_16x16x32_bf16 v[42:45], v[168:171], v[176:179], v[42:45]
	v_mfma_f32_16x16x32_bf16 v[30:33], v[160:163], v[184:187], v[30:33]
	v_mfma_f32_16x16x32_bf16 v[26:29], v[168:171], v[184:187], v[26:29]
	v_mfma_f32_16x16x32_bf16 v[14:17], v[160:163], v[198:201], v[14:17]
	v_mfma_f32_16x16x32_bf16 v[10:13], v[168:171], v[198:201], v[10:13]
	v_mfma_f32_16x16x32_bf16 v[6:9], v[160:163], v[214:217], v[6:9]
	v_mfma_f32_16x16x32_bf16 v[2:5], v[168:171], v[214:217], v[2:5]
	v_mfma_f32_16x16x32_bf16 v[46:49], v[164:167], v[180:183], v[46:49]
	v_mfma_f32_16x16x32_bf16 v[42:45], v[172:175], v[180:183], v[42:45]
	v_mfma_f32_16x16x32_bf16 v[30:33], v[164:167], v[188:191], v[30:33]
	v_mfma_f32_16x16x32_bf16 v[26:29], v[172:175], v[188:191], v[26:29]
	v_mfma_f32_16x16x32_bf16 v[14:17], v[164:167], v[210:213], v[14:17]
	v_mfma_f32_16x16x32_bf16 v[10:13], v[172:175], v[210:213], v[10:13]
	v_mfma_f32_16x16x32_bf16 v[6:9], v[164:167], v[218:221], v[6:9]
	s_barrier
	v_mfma_f32_16x16x32_bf16 v[2:5], v[172:175], v[218:221], v[2:5]
	s_setprio 2
	s_add_i32 s59, s59, 2
	s_add_u32 s34, s34, 0x100
	s_addc_u32 s35, s35, 0
	s_add_u32 s57, s57, 0x100
	s_addc_u32 s58, s58, 0
	s_cmp_gt_u32 s59, 5
	s_cbranch_scc0 .LBB0_714

.Lpeel_8:
	ds_read_b128 v[130:133], v170
	ds_read_b128 v[134:137], v170 offset:1024
	ds_read_b128 v[138:141], v170 offset:2048
	ds_read_b128 v[142:145], v170 offset:3072
	ds_read_b128 v[160:163], v171
	ds_read_b128 v[164:167], v171 offset:1024
	ds_read_b128 v[174:177], v171 offset:2048
	ds_read_b128 v[178:181], v171 offset:3072
	s_add_i32 s31, s21, 2
	s_add_u32 s36, s34, 0xfff80080
	s_addc_u32 s37, s35, -1
	s_cmp_eq_u32 s30, s21
	s_cselect_b32 s39, s23, s37
	s_cselect_b32 s38, s22, s36
	s_cselect_b32 s37, s25, s19
	s_cselect_b32 s36, s24, s17
	v_lshl_add_u64 v[202:203], s[34:35], 0, v[156:157]
	s_add_i32 m0, s27, 0xc000
	ds_read_b128 v[182:185], v172
	ds_read_b128 v[186:189], v172 offset:1024
	ds_read_b128 v[190:193], v172 offset:2048
	ds_read_b128 v[198:201], v172 offset:3072
	ds_read_b128 v[210:213], v172 offset:4096
	ds_read_b128 v[214:217], v172 offset:5120
	global_load_lds_dwordx4 v[202:203], off
	v_lshl_add_u64 v[202:203], s[34:35], 0, v[158:159]
	s_add_i32 m0, s27, 0xe000
	s_nop 0
	global_load_lds_dwordx4 v[202:203], off
	s_waitcnt vmcnt(8)
	s_waitcnt lgkmcnt(0)
	s_barrier
	s_setprio 1
	s_waitcnt lgkmcnt(0)
	v_mfma_f32_16x16x32_bf16 v[126:129], v[130:133], v[182:185], 0
	v_mfma_f32_16x16x32_bf16 v[122:125], v[138:141], v[182:185], 0
	v_mfma_f32_16x16x32_bf16 v[118:121], v[130:133], v[190:193], 0
	v_mfma_f32_16x16x32_bf16 v[110:113], v[138:141], v[190:193], 0
	v_mfma_f32_16x16x32_bf16 v[94:97], v[130:133], v[210:213], 0
	v_mfma_f32_16x16x32_bf16 v[90:93], v[138:141], v[210:213], 0
	v_mfma_f32_16x16x32_bf16 v[78:81], v[130:133], v[218:221], 0
	v_mfma_f32_16x16x32_bf16 v[74:77], v[138:141], v[218:221], 0
	v_mfma_f32_16x16x32_bf16 v[126:129], v[134:137], v[186:189], v[126:129]
	v_mfma_f32_16x16x32_bf16 v[122:125], v[142:145], v[186:189], v[122:125]
	v_mfma_f32_16x16x32_bf16 v[118:121], v[134:137], v[198:201], v[118:121]
	v_mfma_f32_16x16x32_bf16 v[110:113], v[142:145], v[198:201], v[110:113]
	v_mfma_f32_16x16x32_bf16 v[94:97], v[134:137], v[214:217], v[94:97]
	v_mfma_f32_16x16x32_bf16 v[90:93], v[142:145], v[214:217], v[90:93]
	v_mfma_f32_16x16x32_bf16 v[78:81], v[134:137], v[222:225], v[78:81]
	v_mfma_f32_16x16x32_bf16 v[74:77], v[142:145], v[222:225], v[74:77]
	v_mfma_f32_16x16x32_bf16 v[114:117], v[160:163], v[182:185], 0
	v_mfma_f32_16x16x32_bf16 v[106:109], v[174:177], v[182:185], 0
	v_mfma_f32_16x16x32_bf16 v[102:105], v[160:163], v[190:193], 0
	v_mfma_f32_16x16x32_bf16 v[98:101], v[174:177], v[190:193], 0
	v_mfma_f32_16x16x32_bf16 v[86:89], v[160:163], v[210:213], 0
	v_mfma_f32_16x16x32_bf16 v[82:85], v[174:177], v[210:213], 0
	v_mfma_f32_16x16x32_bf16 v[70:73], v[160:163], v[218:221], 0
	v_mfma_f32_16x16x32_bf16 v[66:69], v[174:177], v[218:221], 0
	v_mfma_f32_16x16x32_bf16 v[114:117], v[164:167], v[186:189], v[114:117]
	v_mfma_f32_16x16x32_bf16 v[106:109], v[178:181], v[186:189], v[106:109]
	v_mfma_f32_16x16x32_bf16 v[102:105], v[164:167], v[198:201], v[102:105]
	v_mfma_f32_16x16x32_bf16 v[98:101], v[178:181], v[198:201], v[98:101]
	v_mfma_f32_16x16x32_bf16 v[86:89], v[164:167], v[214:217], v[86:89]
	v_mfma_f32_16x16x32_bf16 v[82:85], v[178:181], v[214:217], v[82:85]
	v_mfma_f32_16x16x32_bf16 v[70:73], v[164:167], v[222:225], v[70:73]
	s_barrier
	v_mfma_f32_16x16x32_bf16 v[66:69], v[178:181], v[222:225], v[66:69]
	s_setprio 2
	s_add_i32 s21, s63, s33
	v_lshl_add_u64 v[202:203], s[36:37], 0, v[148:149]
	s_mov_b32 m0, s21
	ds_read_b128 v[182:185], v172 offset:16384
	ds_read_b128 v[186:189], v172 offset:17408
	ds_read_b128 v[190:193], v172 offset:18432
	ds_read_b128 v[198:201], v172 offset:19456
	ds_read_b128 v[210:213], v172 offset:20480
	ds_read_b128 v[214:217], v172 offset:21504
	ds_read_b128 v[218:221], v172 offset:22528
	ds_read_b128 v[222:225], v172 offset:23552
	global_load_lds_dwordx4 v[202:203], off
	s_add_i32 m0, s21, 0x2000
	s_add_u32 s40, s36, 0x80000
	v_lshl_add_u64 v[206:207], s[36:37], 0, v[152:153]
	s_addc_u32 s41, s37, 0
	s_add_i32 s21, s64, s33
	global_load_lds_dwordx4 v[206:207], off
	v_lshl_add_u64 v[226:227], s[40:41], 0, v[148:149]
	s_mov_b32 m0, s21
	v_lshl_add_u64 v[228:229], s[38:39], 0, v[150:151]
	global_load_lds_dwordx4 v[226:227], off
	v_lshl_add_u64 v[226:227], s[40:41], 0, v[152:153]
	s_add_i32 m0, s21, 0x2000
	s_nop 0
	global_load_lds_dwordx4 v[226:227], off
	v_lshl_add_u64 v[226:227], s[38:39], 0, v[146:147]
	s_mov_b32 m0, s27
	s_nop 0
	global_load_lds_dwordx4 v[226:227], off
	s_mov_b32 m0, s29
	s_nop 0
	global_load_lds_dwordx4 v[228:229], off
	s_waitcnt vmcnt(8)
	s_waitcnt lgkmcnt(0)
	s_barrier
	s_setprio 1
	s_waitcnt lgkmcnt(0)
	v_mfma_f32_16x16x32_bf16 v[62:65], v[130:133], v[182:185], 0
	v_mfma_f32_16x16x32_bf16 v[58:61], v[138:141], v[182:185], 0
	v_mfma_f32_16x16x32_bf16 v[46:49], v[130:133], v[190:193], 0
	v_mfma_f32_16x16x32_bf16 v[42:45], v[138:141], v[190:193], 0
	v_mfma_f32_16x16x32_bf16 v[30:33], v[130:133], v[210:213], 0
	v_mfma_f32_16x16x32_bf16 v[26:29], v[138:141], v[210:213], 0
	v_mfma_f32_16x16x32_bf16 v[14:17], v[130:133], v[218:221], 0
	v_mfma_f32_16x16x32_bf16 v[10:13], v[138:141], v[218:221], 0
	v_mfma_f32_16x16x32_bf16 v[62:65], v[134:137], v[186:189], v[62:65]
	v_mfma_f32_16x16x32_bf16 v[58:61], v[142:145], v[186:189], v[58:61]
	v_mfma_f32_16x16x32_bf16 v[46:49], v[134:137], v[198:201], v[46:49]
	v_mfma_f32_16x16x32_bf16 v[42:45], v[142:145], v[198:201], v[42:45]
	v_mfma_f32_16x16x32_bf16 v[30:33], v[134:137], v[214:217], v[30:33]
	v_mfma_f32_16x16x32_bf16 v[26:29], v[142:145], v[214:217], v[26:29]
	v_mfma_f32_16x16x32_bf16 v[14:17], v[134:137], v[222:225], v[14:17]
	v_mfma_f32_16x16x32_bf16 v[10:13], v[142:145], v[222:225], v[10:13]
	v_mfma_f32_16x16x32_bf16 v[54:57], v[160:163], v[182:185], 0
	v_mfma_f32_16x16x32_bf16 v[50:53], v[174:177], v[182:185], 0
	v_mfma_f32_16x16x32_bf16 v[38:41], v[160:163], v[190:193], 0
	v_mfma_f32_16x16x32_bf16 v[34:37], v[174:177], v[190:193], 0
	v_mfma_f32_16x16x32_bf16 v[22:25], v[160:163], v[210:213], 0
	v_mfma_f32_16x16x32_bf16 v[18:21], v[174:177], v[210:213], 0
	v_mfma_f32_16x16x32_bf16 v[6:9], v[160:163], v[218:221], 0
	v_mfma_f32_16x16x32_bf16 v[2:5], v[174:177], v[218:221], 0
	v_mfma_f32_16x16x32_bf16 v[54:57], v[164:167], v[186:189], v[54:57]
	v_mfma_f32_16x16x32_bf16 v[50:53], v[178:181], v[186:189], v[50:53]
	v_mfma_f32_16x16x32_bf16 v[38:41], v[164:167], v[198:201], v[38:41]
	v_mfma_f32_16x16x32_bf16 v[34:37], v[178:181], v[198:201], v[34:37]
	v_mfma_f32_16x16x32_bf16 v[22:25], v[164:167], v[214:217], v[22:25]
	v_mfma_f32_16x16x32_bf16 v[18:21], v[178:181], v[214:217], v[18:21]
	v_mfma_f32_16x16x32_bf16 v[6:9], v[164:167], v[222:225], v[6:9]
	s_barrier
	v_mfma_f32_16x16x32_bf16 v[2:5], v[178:181], v[222:225], v[2:5]
	s_setprio 2
	s_add_i32 s21, 0, 0x18000
	s_add_i32 s40, 0, 0x1c000
	v_add_u32_e32 v142, s21, v168
	v_add_u32_e32 v173, s40, v168
	ds_read_b128 v[130:133], v142
	ds_read_b128 v[134:137], v142 offset:1024
	ds_read_b128 v[138:141], v142 offset:2048
	ds_read_b128 v[142:145], v142 offset:3072
	ds_read_b128 v[160:163], v173
	ds_read_b128 v[164:167], v173 offset:1024
	ds_read_b128 v[174:177], v173 offset:2048
	ds_read_b128 v[178:181], v173 offset:3072
	s_add_u32 s38, s38, 0x80000
	s_addc_u32 s39, s39, 0
	s_mov_b32 m0, s42
	v_lshl_add_u64 v[230:231], s[38:39], 0, v[146:147]
	ds_read_b128 v[182:185], v172 offset:32768
	ds_read_b128 v[186:189], v172 offset:33792
	ds_read_b128 v[190:193], v172 offset:34816
	ds_read_b128 v[198:201], v172 offset:35840
	ds_read_b128 v[210:213], v172 offset:36864
	ds_read_b128 v[214:217], v172 offset:37888
	ds_read_b128 v[218:221], v172 offset:38912
	ds_read_b128 v[222:225], v172 offset:39936
	global_load_lds_dwordx4 v[230:231], off
	v_lshl_add_u64 v[230:231], s[38:39], 0, v[150:151]
	s_mov_b32 m0, s43
	s_nop 0
	global_load_lds_dwordx4 v[230:231], off
	s_waitcnt vmcnt(8)
	s_waitcnt lgkmcnt(0)
	s_barrier
	s_setprio 1
	s_waitcnt lgkmcnt(0)
	v_mfma_f32_16x16x32_bf16 v[126:129], v[130:133], v[182:185], v[126:129]
	v_mfma_f32_16x16x32_bf16 v[122:125], v[138:141], v[182:185], v[122:125]
	v_mfma_f32_16x16x32_bf16 v[118:121], v[130:133], v[190:193], v[118:121]
	v_mfma_f32_16x16x32_bf16 v[110:113], v[138:141], v[190:193], v[110:113]
	v_mfma_f32_16x16x32_bf16 v[94:97], v[130:133], v[210:213], v[94:97]
	v_mfma_f32_16x16x32_bf16 v[90:93], v[138:141], v[210:213], v[90:93]
	v_mfma_f32_16x16x32_bf16 v[78:81], v[130:133], v[218:221], v[78:81]
	v_mfma_f32_16x16x32_bf16 v[74:77], v[138:141], v[218:221], v[74:77]
	v_mfma_f32_16x16x32_bf16 v[126:129], v[134:137], v[186:189], v[126:129]
	v_mfma_f32_16x16x32_bf16 v[122:125], v[142:145], v[186:189], v[122:125]
	v_mfma_f32_16x16x32_bf16 v[118:121], v[134:137], v[198:201], v[118:121]
	v_mfma_f32_16x16x32_bf16 v[110:113], v[142:145], v[198:201], v[110:113]
	v_mfma_f32_16x16x32_bf16 v[94:97], v[134:137], v[214:217], v[94:97]
	v_mfma_f32_16x16x32_bf16 v[90:93], v[142:145], v[214:217], v[90:93]
	v_mfma_f32_16x16x32_bf16 v[78:81], v[134:137], v[222:225], v[78:81]
	v_mfma_f32_16x16x32_bf16 v[74:77], v[142:145], v[222:225], v[74:77]
	v_mfma_f32_16x16x32_bf16 v[114:117], v[160:163], v[182:185], v[114:117]
	v_mfma_f32_16x16x32_bf16 v[106:109], v[174:177], v[182:185], v[106:109]
	v_mfma_f32_16x16x32_bf16 v[102:105], v[160:163], v[190:193], v[102:105]
	v_mfma_f32_16x16x32_bf16 v[98:101], v[174:177], v[190:193], v[98:101]
	v_mfma_f32_16x16x32_bf16 v[86:89], v[160:163], v[210:213], v[86:89]
	v_mfma_f32_16x16x32_bf16 v[82:85], v[174:177], v[210:213], v[82:85]
	v_mfma_f32_16x16x32_bf16 v[70:73], v[160:163], v[218:221], v[70:73]
	v_mfma_f32_16x16x32_bf16 v[66:69], v[174:177], v[218:221], v[66:69]
	v_mfma_f32_16x16x32_bf16 v[114:117], v[164:167], v[186:189], v[114:117]
	v_mfma_f32_16x16x32_bf16 v[106:109], v[178:181], v[186:189], v[106:109]
	v_mfma_f32_16x16x32_bf16 v[102:105], v[164:167], v[198:201], v[102:105]
	v_mfma_f32_16x16x32_bf16 v[98:101], v[178:181], v[198:201], v[98:101]
	v_mfma_f32_16x16x32_bf16 v[86:89], v[164:167], v[214:217], v[86:89]
	v_mfma_f32_16x16x32_bf16 v[82:85], v[178:181], v[214:217], v[82:85]
	v_mfma_f32_16x16x32_bf16 v[70:73], v[164:167], v[222:225], v[70:73]
	s_barrier
	v_mfma_f32_16x16x32_bf16 v[66:69], v[178:181], v[222:225], v[66:69]
	s_setprio 2
	s_add_i32 s21, s21, s33
	v_lshl_add_u64 v[202:203], v[202:203], 0, s[12:13]
	s_mov_b32 m0, s21
	ds_read_b128 v[182:185], v172 offset:49152
	ds_read_b128 v[186:189], v172 offset:50176
	ds_read_b128 v[190:193], v172 offset:51200
	ds_read_b128 v[198:201], v172 offset:52224
	ds_read_b128 v[210:213], v172 offset:53248
	ds_read_b128 v[214:217], v172 offset:54272
	ds_read_b128 v[218:221], v172 offset:55296
	ds_read_b128 v[222:225], v172 offset:56320
	global_load_lds_dwordx4 v[202:203], off
	s_add_i32 m0, s21, 0x2000
	s_add_u32 s36, s36, 0x80080
	v_lshl_add_u64 v[202:203], v[206:207], 0, s[12:13]
	s_addc_u32 s37, s37, 0
	s_add_i32 s21, s40, s33
	global_load_lds_dwordx4 v[202:203], off
	v_lshl_add_u64 v[202:203], s[36:37], 0, v[148:149]
	s_mov_b32 m0, s21
	s_nop 0
	global_load_lds_dwordx4 v[202:203], off
	v_lshl_add_u64 v[202:203], s[36:37], 0, v[152:153]
	s_add_i32 m0, s21, 0x2000
	s_nop 0
	global_load_lds_dwordx4 v[202:203], off
	v_lshl_add_u64 v[202:203], v[226:227], 0, s[12:13]
	s_mov_b32 m0, s53
	s_nop 0
	global_load_lds_dwordx4 v[202:203], off
	v_lshl_add_u64 v[202:203], v[228:229], 0, s[12:13]
	s_mov_b32 m0, s54
	s_nop 0
	global_load_lds_dwordx4 v[202:203], off
	s_waitcnt vmcnt(8)
	s_waitcnt lgkmcnt(0)
	s_barrier
	s_setprio 1
	s_waitcnt lgkmcnt(0)
	v_mfma_f32_16x16x32_bf16 v[62:65], v[130:133], v[182:185], v[62:65]
	v_mfma_f32_16x16x32_bf16 v[58:61], v[138:141], v[182:185], v[58:61]
	v_mfma_f32_16x16x32_bf16 v[46:49], v[130:133], v[190:193], v[46:49]
	v_mfma_f32_16x16x32_bf16 v[42:45], v[138:141], v[190:193], v[42:45]
	v_mfma_f32_16x16x32_bf16 v[30:33], v[130:133], v[210:213], v[30:33]
	v_mfma_f32_16x16x32_bf16 v[26:29], v[138:141], v[210:213], v[26:29]
	v_mfma_f32_16x16x32_bf16 v[14:17], v[130:133], v[218:221], v[14:17]
	v_mfma_f32_16x16x32_bf16 v[10:13], v[138:141], v[218:221], v[10:13]
	v_mfma_f32_16x16x32_bf16 v[62:65], v[134:137], v[186:189], v[62:65]
	v_mfma_f32_16x16x32_bf16 v[58:61], v[142:145], v[186:189], v[58:61]
	v_mfma_f32_16x16x32_bf16 v[46:49], v[134:137], v[198:201], v[46:49]
	v_mfma_f32_16x16x32_bf16 v[42:45], v[142:145], v[198:201], v[42:45]
	v_mfma_f32_16x16x32_bf16 v[30:33], v[134:137], v[214:217], v[30:33]
	v_mfma_f32_16x16x32_bf16 v[26:29], v[142:145], v[214:217], v[26:29]
	v_mfma_f32_16x16x32_bf16 v[14:17], v[134:137], v[222:225], v[14:17]
	v_mfma_f32_16x16x32_bf16 v[10:13], v[142:145], v[222:225], v[10:13]
	v_mfma_f32_16x16x32_bf16 v[54:57], v[160:163], v[182:185], v[54:57]
	v_mfma_f32_16x16x32_bf16 v[50:53], v[174:177], v[182:185], v[50:53]
	v_mfma_f32_16x16x32_bf16 v[38:41], v[160:163], v[190:193], v[38:41]
	v_mfma_f32_16x16x32_bf16 v[34:37], v[174:177], v[190:193], v[34:37]
	v_mfma_f32_16x16x32_bf16 v[22:25], v[160:163], v[210:213], v[22:25]
	v_mfma_f32_16x16x32_bf16 v[18:21], v[174:177], v[210:213], v[18:21]
	v_mfma_f32_16x16x32_bf16 v[6:9], v[160:163], v[218:221], v[6:9]
	v_mfma_f32_16x16x32_bf16 v[2:5], v[174:177], v[218:221], v[2:5]
	v_mfma_f32_16x16x32_bf16 v[54:57], v[164:167], v[186:189], v[54:57]
	v_mfma_f32_16x16x32_bf16 v[50:53], v[178:181], v[186:189], v[50:53]
	v_mfma_f32_16x16x32_bf16 v[38:41], v[164:167], v[198:201], v[38:41]
	v_mfma_f32_16x16x32_bf16 v[34:37], v[178:181], v[198:201], v[34:37]
	v_mfma_f32_16x16x32_bf16 v[22:25], v[164:167], v[214:217], v[22:25]
	v_mfma_f32_16x16x32_bf16 v[18:21], v[178:181], v[214:217], v[18:21]
	v_mfma_f32_16x16x32_bf16 v[6:9], v[164:167], v[222:225], v[6:9]
	s_barrier
	v_mfma_f32_16x16x32_bf16 v[2:5], v[178:181], v[222:225], v[2:5]
	s_setprio 2
	s_add_u32 s34, s34, 0x100
	s_addc_u32 s35, s35, 0
	s_add_u32 s17, s17, 0x100
	s_addc_u32 s19, s19, 0
	s_cmp_ge_i32 s31, s69
	s_mov_b32 s21, s31
	s_cbranch_scc0 .LBB0_1122
	s_branch .Lpeeldone_8
.LBB0_1122:
	ds_read_b128 v[130:133], v170
	ds_read_b128 v[134:137], v170 offset:1024
	ds_read_b128 v[138:141], v170 offset:2048
	ds_read_b128 v[142:145], v170 offset:3072
	ds_read_b128 v[160:163], v171
	ds_read_b128 v[164:167], v171 offset:1024
	ds_read_b128 v[174:177], v171 offset:2048
	ds_read_b128 v[178:181], v171 offset:3072
	s_add_i32 s31, s21, 2
	s_add_u32 s36, s34, 0xfff80080
	s_addc_u32 s37, s35, -1
	s_cmp_eq_u32 s30, s21
	s_cselect_b32 s39, s23, s37
	s_cselect_b32 s38, s22, s36
	s_cselect_b32 s37, s25, s19
	s_cselect_b32 s36, s24, s17
	v_lshl_add_u64 v[202:203], s[34:35], 0, v[156:157]
	s_add_i32 m0, s27, 0xc000
	ds_read_b128 v[182:185], v172
	ds_read_b128 v[186:189], v172 offset:1024
	ds_read_b128 v[190:193], v172 offset:2048
	ds_read_b128 v[198:201], v172 offset:3072
	ds_read_b128 v[210:213], v172 offset:4096
	ds_read_b128 v[214:217], v172 offset:5120
	ds_read_b128 v[218:221], v172 offset:6144
	ds_read_b128 v[222:225], v172 offset:7168
	global_load_lds_dwordx4 v[202:203], off
	v_lshl_add_u64 v[202:203], s[34:35], 0, v[158:159]
	s_add_i32 m0, s27, 0xe000
	s_nop 0
	global_load_lds_dwordx4 v[202:203], off
	s_waitcnt vmcnt(8)
	s_waitcnt lgkmcnt(0)
	s_barrier
	s_setprio 1
	s_waitcnt lgkmcnt(0)
	v_mfma_f32_16x16x32_bf16 v[126:129], v[130:133], v[182:185], v[126:129]
	v_mfma_f32_16x16x32_bf16 v[122:125], v[138:141], v[182:185], v[122:125]
	v_mfma_f32_16x16x32_bf16 v[118:121], v[130:133], v[190:193], v[118:121]
	v_mfma_f32_16x16x32_bf16 v[110:113], v[138:141], v[190:193], v[110:113]
	v_mfma_f32_16x16x32_bf16 v[94:97], v[130:133], v[210:213], v[94:97]
	v_mfma_f32_16x16x32_bf16 v[90:93], v[138:141], v[210:213], v[90:93]
	v_mfma_f32_16x16x32_bf16 v[78:81], v[130:133], v[218:221], v[78:81]
	v_mfma_f32_16x16x32_bf16 v[74:77], v[138:141], v[218:221], v[74:77]
	v_mfma_f32_16x16x32_bf16 v[126:129], v[134:137], v[186:189], v[126:129]
	v_mfma_f32_16x16x32_bf16 v[122:125], v[142:145], v[186:189], v[122:125]
	v_mfma_f32_16x16x32_bf16 v[118:121], v[134:137], v[198:201], v[118:121]
	v_mfma_f32_16x16x32_bf16 v[110:113], v[142:145], v[198:201], v[110:113]
	v_mfma_f32_16x16x32_bf16 v[94:97], v[134:137], v[214:217], v[94:97]
	v_mfma_f32_16x16x32_bf16 v[90:93], v[142:145], v[214:217], v[90:93]
	v_mfma_f32_16x16x32_bf16 v[78:81], v[134:137], v[222:225], v[78:81]
	v_mfma_f32_16x16x32_bf16 v[74:77], v[142:145], v[222:225], v[74:77]
	v_mfma_f32_16x16x32_bf16 v[114:117], v[160:163], v[182:185], v[114:117]
	v_mfma_f32_16x16x32_bf16 v[106:109], v[174:177], v[182:185], v[106:109]
	v_mfma_f32_16x16x32_bf16 v[102:105], v[160:163], v[190:193], v[102:105]
	v_mfma_f32_16x16x32_bf16 v[98:101], v[174:177], v[190:193], v[98:101]
	v_mfma_f32_16x16x32_bf16 v[86:89], v[160:163], v[210:213], v[86:89]
	v_mfma_f32_16x16x32_bf16 v[82:85], v[174:177], v[210:213], v[82:85]
	v_mfma_f32_16x16x32_bf16 v[70:73], v[160:163], v[218:221], v[70:73]
	v_mfma_f32_16x16x32_bf16 v[66:69], v[174:177], v[218:221], v[66:69]
	v_mfma_f32_16x16x32_bf16 v[114:117], v[164:167], v[186:189], v[114:117]
	v_mfma_f32_16x16x32_bf16 v[106:109], v[178:181], v[186:189], v[106:109]
	v_mfma_f32_16x16x32_bf16 v[102:105], v[164:167], v[198:201], v[102:105]
	v_mfma_f32_16x16x32_bf16 v[98:101], v[178:181], v[198:201], v[98:101]
	v_mfma_f32_16x16x32_bf16 v[86:89], v[164:167], v[214:217], v[86:89]
	v_mfma_f32_16x16x32_bf16 v[82:85], v[178:181], v[214:217], v[82:85]
	v_mfma_f32_16x16x32_bf16 v[70:73], v[164:167], v[222:225], v[70:73]
	s_barrier
	v_mfma_f32_16x16x32_bf16 v[66:69], v[178:181], v[222:225], v[66:69]
	s_setprio 2
	s_add_i32 s21, s63, s33
	v_lshl_add_u64 v[202:203], s[36:37], 0, v[148:149]
	s_mov_b32 m0, s21
	ds_read_b128 v[182:185], v172 offset:16384
	ds_read_b128 v[186:189], v172 offset:17408
	ds_read_b128 v[190:193], v172 offset:18432
	ds_read_b128 v[198:201], v172 offset:19456
	ds_read_b128 v[210:213], v172 offset:20480
	ds_read_b128 v[214:217], v172 offset:21504
	ds_read_b128 v[218:221], v172 offset:22528
	ds_read_b128 v[222:225], v172 offset:23552
	global_load_lds_dwordx4 v[202:203], off
	s_add_i32 m0, s21, 0x2000
	s_add_u32 s40, s36, 0x80000
	v_lshl_add_u64 v[206:207], s[36:37], 0, v[152:153]
	s_addc_u32 s41, s37, 0
	s_add_i32 s21, s64, s33
	global_load_lds_dwordx4 v[206:207], off
	v_lshl_add_u64 v[226:227], s[40:41], 0, v[148:149]
	s_mov_b32 m0, s21
	v_lshl_add_u64 v[228:229], s[38:39], 0, v[150:151]
	global_load_lds_dwordx4 v[226:227], off
	v_lshl_add_u64 v[226:227], s[40:41], 0, v[152:153]
	s_add_i32 m0, s21, 0x2000
	s_nop 0
	global_load_lds_dwordx4 v[226:227], off
	v_lshl_add_u64 v[226:227], s[38:39], 0, v[146:147]
	s_mov_b32 m0, s27
	s_nop 0
	global_load_lds_dwordx4 v[226:227], off
	s_mov_b32 m0, s29
	s_nop 0
	global_load_lds_dwordx4 v[228:229], off
	s_waitcnt vmcnt(8)
	s_waitcnt lgkmcnt(0)
	s_barrier
	s_setprio 1
	s_waitcnt lgkmcnt(0)
	v_mfma_f32_16x16x32_bf16 v[62:65], v[130:133], v[182:185], v[62:65]
	v_mfma_f32_16x16x32_bf16 v[58:61], v[138:141], v[182:185], v[58:61]
	v_mfma_f32_16x16x32_bf16 v[46:49], v[130:133], v[190:193], v[46:49]
	v_mfma_f32_16x16x32_bf16 v[42:45], v[138:141], v[190:193], v[42:45]
	v_mfma_f32_16x16x32_bf16 v[30:33], v[130:133], v[210:213], v[30:33]
	v_mfma_f32_16x16x32_bf16 v[26:29], v[138:141], v[210:213], v[26:29]
	v_mfma_f32_16x16x32_bf16 v[14:17], v[130:133], v[218:221], v[14:17]
	v_mfma_f32_16x16x32_bf16 v[10:13], v[138:141], v[218:221], v[10:13]
	v_mfma_f32_16x16x32_bf16 v[62:65], v[134:137], v[186:189], v[62:65]
	v_mfma_f32_16x16x32_bf16 v[58:61], v[142:145], v[186:189], v[58:61]
	v_mfma_f32_16x16x32_bf16 v[46:49], v[134:137], v[198:201], v[46:49]
	v_mfma_f32_16x16x32_bf16 v[42:45], v[142:145], v[198:201], v[42:45]
	v_mfma_f32_16x16x32_bf16 v[30:33], v[134:137], v[214:217], v[30:33]
	v_mfma_f32_16x16x32_bf16 v[26:29], v[142:145], v[214:217], v[26:29]
	v_mfma_f32_16x16x32_bf16 v[14:17], v[134:137], v[222:225], v[14:17]
	v_mfma_f32_16x16x32_bf16 v[10:13], v[142:145], v[222:225], v[10:13]
	v_mfma_f32_16x16x32_bf16 v[54:57], v[160:163], v[182:185], v[54:57]
	v_mfma_f32_16x16x32_bf16 v[50:53], v[174:177], v[182:185], v[50:53]
	v_mfma_f32_16x16x32_bf16 v[38:41], v[160:163], v[190:193], v[38:41]
	v_mfma_f32_16x16x32_bf16 v[34:37], v[174:177], v[190:193], v[34:37]
	v_mfma_f32_16x16x32_bf16 v[22:25], v[160:163], v[210:213], v[22:25]
	v_mfma_f32_16x16x32_bf16 v[18:21], v[174:177], v[210:213], v[18:21]
	v_mfma_f32_16x16x32_bf16 v[6:9], v[160:163], v[218:221], v[6:9]
	v_mfma_f32_16x16x32_bf16 v[2:5], v[174:177], v[218:221], v[2:5]
	v_mfma_f32_16x16x32_bf16 v[54:57], v[164:167], v[186:189], v[54:57]
	v_mfma_f32_16x16x32_bf16 v[50:53], v[178:181], v[186:189], v[50:53]
	v_mfma_f32_16x16x32_bf16 v[38:41], v[164:167], v[198:201], v[38:41]
	v_mfma_f32_16x16x32_bf16 v[34:37], v[178:181], v[198:201], v[34:37]
	v_mfma_f32_16x16x32_bf16 v[22:25], v[164:167], v[214:217], v[22:25]
	v_mfma_f32_16x16x32_bf16 v[18:21], v[178:181], v[214:217], v[18:21]
	v_mfma_f32_16x16x32_bf16 v[6:9], v[164:167], v[222:225], v[6:9]
	s_barrier
	v_mfma_f32_16x16x32_bf16 v[2:5], v[178:181], v[222:225], v[2:5]
	s_setprio 2
	s_add_i32 s21, 0, 0x18000
	s_add_i32 s40, 0, 0x1c000
	v_add_u32_e32 v142, s21, v168
	v_add_u32_e32 v173, s40, v168
	ds_read_b128 v[130:133], v142
	ds_read_b128 v[134:137], v142 offset:1024
	ds_read_b128 v[138:141], v142 offset:2048
	ds_read_b128 v[142:145], v142 offset:3072
	ds_read_b128 v[160:163], v173
	ds_read_b128 v[164:167], v173 offset:1024
	ds_read_b128 v[174:177], v173 offset:2048
	ds_read_b128 v[178:181], v173 offset:3072
	s_add_u32 s38, s38, 0x80000
	s_addc_u32 s39, s39, 0
	s_mov_b32 m0, s42
	v_lshl_add_u64 v[230:231], s[38:39], 0, v[146:147]
	ds_read_b128 v[182:185], v172 offset:32768
	ds_read_b128 v[186:189], v172 offset:33792
	ds_read_b128 v[190:193], v172 offset:34816
	ds_read_b128 v[198:201], v172 offset:35840
	ds_read_b128 v[210:213], v172 offset:36864
	ds_read_b128 v[214:217], v172 offset:37888
	ds_read_b128 v[218:221], v172 offset:38912
	ds_read_b128 v[222:225], v172 offset:39936
	global_load_lds_dwordx4 v[230:231], off
	v_lshl_add_u64 v[230:231], s[38:39], 0, v[150:151]
	s_mov_b32 m0, s43
	s_nop 0
	global_load_lds_dwordx4 v[230:231], off
	s_waitcnt vmcnt(8)
	s_waitcnt lgkmcnt(0)
	s_barrier
	s_setprio 1
	s_waitcnt lgkmcnt(0)
	v_mfma_f32_16x16x32_bf16 v[126:129], v[130:133], v[182:185], v[126:129]
	v_mfma_f32_16x16x32_bf16 v[122:125], v[138:141], v[182:185], v[122:125]
	v_mfma_f32_16x16x32_bf16 v[118:121], v[130:133], v[190:193], v[118:121]
	v_mfma_f32_16x16x32_bf16 v[110:113], v[138:141], v[190:193], v[110:113]
	v_mfma_f32_16x16x32_bf16 v[94:97], v[130:133], v[210:213], v[94:97]
	v_mfma_f32_16x16x32_bf16 v[90:93], v[138:141], v[210:213], v[90:93]
	v_mfma_f32_16x16x32_bf16 v[78:81], v[130:133], v[218:221], v[78:81]
	v_mfma_f32_16x16x32_bf16 v[74:77], v[138:141], v[218:221], v[74:77]
	v_mfma_f32_16x16x32_bf16 v[126:129], v[134:137], v[186:189], v[126:129]
	v_mfma_f32_16x16x32_bf16 v[122:125], v[142:145], v[186:189], v[122:125]
	v_mfma_f32_16x16x32_bf16 v[118:121], v[134:137], v[198:201], v[118:121]
	v_mfma_f32_16x16x32_bf16 v[110:113], v[142:145], v[198:201], v[110:113]
	v_mfma_f32_16x16x32_bf16 v[94:97], v[134:137], v[214:217], v[94:97]
	v_mfma_f32_16x16x32_bf16 v[90:93], v[142:145], v[214:217], v[90:93]
	v_mfma_f32_16x16x32_bf16 v[78:81], v[134:137], v[222:225], v[78:81]
	v_mfma_f32_16x16x32_bf16 v[74:77], v[142:145], v[222:225], v[74:77]
	v_mfma_f32_16x16x32_bf16 v[114:117], v[160:163], v[182:185], v[114:117]
	v_mfma_f32_16x16x32_bf16 v[106:109], v[174:177], v[182:185], v[106:109]
	v_mfma_f32_16x16x32_bf16 v[102:105], v[160:163], v[190:193], v[102:105]
	v_mfma_f32_16x16x32_bf16 v[98:101], v[174:177], v[190:193], v[98:101]
	v_mfma_f32_16x16x32_bf16 v[86:89], v[160:163], v[210:213], v[86:89]
	v_mfma_f32_16x16x32_bf16 v[82:85], v[174:177], v[210:213], v[82:85]
	v_mfma_f32_16x16x32_bf16 v[70:73], v[160:163], v[218:221], v[70:73]
	v_mfma_f32_16x16x32_bf16 v[66:69], v[174:177], v[218:221], v[66:69]
	v_mfma_f32_16x16x32_bf16 v[114:117], v[164:167], v[186:189], v[114:117]
	v_mfma_f32_16x16x32_bf16 v[106:109], v[178:181], v[186:189], v[106:109]
	v_mfma_f32_16x16x32_bf16 v[102:105], v[164:167], v[198:201], v[102:105]
	v_mfma_f32_16x16x32_bf16 v[98:101], v[178:181], v[198:201], v[98:101]
	v_mfma_f32_16x16x32_bf16 v[86:89], v[164:167], v[214:217], v[86:89]
	v_mfma_f32_16x16x32_bf16 v[82:85], v[178:181], v[214:217], v[82:85]
	v_mfma_f32_16x16x32_bf16 v[70:73], v[164:167], v[222:225], v[70:73]
	s_barrier
	v_mfma_f32_16x16x32_bf16 v[66:69], v[178:181], v[222:225], v[66:69]
	s_setprio 2
	s_add_i32 s21, s21, s33
	v_lshl_add_u64 v[202:203], v[202:203], 0, s[12:13]
	s_mov_b32 m0, s21
	ds_read_b128 v[182:185], v172 offset:49152
	ds_read_b128 v[186:189], v172 offset:50176
	ds_read_b128 v[190:193], v172 offset:51200
	ds_read_b128 v[198:201], v172 offset:52224
	ds_read_b128 v[210:213], v172 offset:53248
	ds_read_b128 v[214:217], v172 offset:54272
	ds_read_b128 v[218:221], v172 offset:55296
	ds_read_b128 v[222:225], v172 offset:56320
	global_load_lds_dwordx4 v[202:203], off
	s_add_i32 m0, s21, 0x2000
	s_add_u32 s36, s36, 0x80080
	v_lshl_add_u64 v[202:203], v[206:207], 0, s[12:13]
	s_addc_u32 s37, s37, 0
	s_add_i32 s21, s40, s33
	global_load_lds_dwordx4 v[202:203], off
	v_lshl_add_u64 v[202:203], s[36:37], 0, v[148:149]
	s_mov_b32 m0, s21
	s_nop 0
	global_load_lds_dwordx4 v[202:203], off
	v_lshl_add_u64 v[202:203], s[36:37], 0, v[152:153]
	s_add_i32 m0, s21, 0x2000
	s_nop 0
	global_load_lds_dwordx4 v[202:203], off
	v_lshl_add_u64 v[202:203], v[226:227], 0, s[12:13]
	s_mov_b32 m0, s53
	s_nop 0
	global_load_lds_dwordx4 v[202:203], off
	v_lshl_add_u64 v[202:203], v[228:229], 0, s[12:13]
	s_mov_b32 m0, s54
	s_nop 0
	global_load_lds_dwordx4 v[202:203], off
	s_waitcnt vmcnt(8)
	s_waitcnt lgkmcnt(0)
	s_barrier
	s_setprio 1
	s_waitcnt lgkmcnt(0)
	v_mfma_f32_16x16x32_bf16 v[62:65], v[130:133], v[182:185], v[62:65]
	v_mfma_f32_16x16x32_bf16 v[58:61], v[138:141], v[182:185], v[58:61]
	v_mfma_f32_16x16x32_bf16 v[46:49], v[130:133], v[190:193], v[46:49]
	v_mfma_f32_16x16x32_bf16 v[42:45], v[138:141], v[190:193], v[42:45]
	v_mfma_f32_16x16x32_bf16 v[30:33], v[130:133], v[210:213], v[30:33]
	v_mfma_f32_16x16x32_bf16 v[26:29], v[138:141], v[210:213], v[26:29]
	v_mfma_f32_16x16x32_bf16 v[14:17], v[130:133], v[218:221], v[14:17]
	v_mfma_f32_16x16x32_bf16 v[10:13], v[138:141], v[218:221], v[10:13]
	v_mfma_f32_16x16x32_bf16 v[62:65], v[134:137], v[186:189], v[62:65]
	v_mfma_f32_16x16x32_bf16 v[58:61], v[142:145], v[186:189], v[58:61]
	v_mfma_f32_16x16x32_bf16 v[46:49], v[134:137], v[198:201], v[46:49]
	v_mfma_f32_16x16x32_bf16 v[42:45], v[142:145], v[198:201], v[42:45]
	v_mfma_f32_16x16x32_bf16 v[30:33], v[134:137], v[214:217], v[30:33]
	v_mfma_f32_16x16x32_bf16 v[26:29], v[142:145], v[214:217], v[26:29]
	v_mfma_f32_16x16x32_bf16 v[14:17], v[134:137], v[222:225], v[14:17]
	v_mfma_f32_16x16x32_bf16 v[10:13], v[142:145], v[222:225], v[10:13]
	v_mfma_f32_16x16x32_bf16 v[54:57], v[160:163], v[182:185], v[54:57]
	v_mfma_f32_16x16x32_bf16 v[50:53], v[174:177], v[182:185], v[50:53]
	v_mfma_f32_16x16x32_bf16 v[38:41], v[160:163], v[190:193], v[38:41]
	v_mfma_f32_16x16x32_bf16 v[34:37], v[174:177], v[190:193], v[34:37]
	v_mfma_f32_16x16x32_bf16 v[22:25], v[160:163], v[210:213], v[22:25]
	v_mfma_f32_16x16x32_bf16 v[18:21], v[174:177], v[210:213], v[18:21]
	v_mfma_f32_16x16x32_bf16 v[6:9], v[160:163], v[218:221], v[6:9]
	v_mfma_f32_16x16x32_bf16 v[2:5], v[174:177], v[218:221], v[2:5]
	v_mfma_f32_16x16x32_bf16 v[54:57], v[164:167], v[186:189], v[54:57]
	v_mfma_f32_16x16x32_bf16 v[50:53], v[178:181], v[186:189], v[50:53]
	v_mfma_f32_16x16x32_bf16 v[38:41], v[164:167], v[198:201], v[38:41]
	v_mfma_f32_16x16x32_bf16 v[34:37], v[178:181], v[198:201], v[34:37]
	v_mfma_f32_16x16x32_bf16 v[22:25], v[164:167], v[214:217], v[22:25]
	v_mfma_f32_16x16x32_bf16 v[18:21], v[178:181], v[214:217], v[18:21]
	v_mfma_f32_16x16x32_bf16 v[6:9], v[164:167], v[222:225], v[6:9]
	s_barrier
	v_mfma_f32_16x16x32_bf16 v[2:5], v[178:181], v[222:225], v[2:5]
	s_setprio 2
	s_add_u32 s34, s34, 0x100
	s_addc_u32 s35, s35, 0
	s_add_u32 s17, s17, 0x100
	s_addc_u32 s19, s19, 0
	s_cmp_ge_i32 s31, s69
	s_mov_b32 s21, s31
	s_cbranch_scc0 .LBB0_1122

.Lpeel_7:
	ds_read_b128 v[152:155], v148
	ds_read_b128 v[156:159], v148 offset:1024
	s_add_i32 s29, s19, 2
	s_add_u32 s34, s30, 0xfff80080
	s_addc_u32 s35, s31, -1
	s_cmp_eq_u32 s28, s19
	s_cselect_b32 s37, s21, s35
	s_cselect_b32 s36, s20, s34
	s_cselect_b32 s35, s23, s17
	s_cselect_b32 s34, s22, s15
	v_lshl_add_u64 v[144:145], s[30:31], 0, v[140:141]
	s_add_i32 m0, s27, 0xc000
	global_load_lds_dwordx4 v[144:145], off
	v_lshl_add_u64 v[144:145], s[30:31], 0, v[142:143]
	s_add_i32 m0, s27, 0xe000
	s_nop 0
	global_load_lds_dwordx4 v[144:145], off
	s_waitcnt vmcnt(8)
	s_waitcnt lgkmcnt(0)
	s_barrier
	s_setprio 1
	s_waitcnt lgkmcnt(0)
	v_mfma_f32_16x16x32_bf16 v[126:129], v[152:155], v[184:187], 0
	v_mfma_f32_16x16x32_bf16 v[122:125], v[160:163], v[184:187], 0
	v_mfma_f32_16x16x32_bf16 v[110:113], v[152:155], v[198:201], 0
	v_mfma_f32_16x16x32_bf16 v[106:109], v[160:163], v[198:201], 0
	v_mfma_f32_16x16x32_bf16 v[94:97], v[152:155], v[214:217], 0
	v_mfma_f32_16x16x32_bf16 v[90:93], v[160:163], v[214:217], 0
	v_mfma_f32_16x16x32_bf16 v[78:81], v[152:155], v[222:225], 0
	v_mfma_f32_16x16x32_bf16 v[74:77], v[160:163], v[222:225], 0
	v_mfma_f32_16x16x32_bf16 v[126:129], v[156:159], v[188:191], v[126:129]
	v_mfma_f32_16x16x32_bf16 v[122:125], v[164:167], v[188:191], v[122:125]
	v_mfma_f32_16x16x32_bf16 v[110:113], v[156:159], v[210:213], v[110:113]
	v_mfma_f32_16x16x32_bf16 v[106:109], v[164:167], v[210:213], v[106:109]
	v_mfma_f32_16x16x32_bf16 v[94:97], v[156:159], v[218:221], v[94:97]
	v_mfma_f32_16x16x32_bf16 v[90:93], v[164:167], v[218:221], v[90:93]
	v_mfma_f32_16x16x32_bf16 v[78:81], v[156:159], v[226:229], v[78:81]
	v_mfma_f32_16x16x32_bf16 v[74:77], v[164:167], v[226:229], v[74:77]
	v_mfma_f32_16x16x32_bf16 v[118:121], v[168:171], v[184:187], 0
	v_mfma_f32_16x16x32_bf16 v[114:117], v[176:179], v[184:187], 0
	v_mfma_f32_16x16x32_bf16 v[102:105], v[168:171], v[198:201], 0
	v_mfma_f32_16x16x32_bf16 v[98:101], v[176:179], v[198:201], 0
	v_mfma_f32_16x16x32_bf16 v[86:89], v[168:171], v[214:217], 0
	v_mfma_f32_16x16x32_bf16 v[82:85], v[176:179], v[214:217], 0
	v_mfma_f32_16x16x32_bf16 v[70:73], v[168:171], v[222:225], 0
	v_mfma_f32_16x16x32_bf16 v[66:69], v[176:179], v[222:225], 0
	v_mfma_f32_16x16x32_bf16 v[118:121], v[172:175], v[188:191], v[118:121]
	v_mfma_f32_16x16x32_bf16 v[114:117], v[180:183], v[188:191], v[114:117]
	v_mfma_f32_16x16x32_bf16 v[102:105], v[172:175], v[210:213], v[102:105]
	v_mfma_f32_16x16x32_bf16 v[98:101], v[180:183], v[210:213], v[98:101]
	v_mfma_f32_16x16x32_bf16 v[86:89], v[172:175], v[218:221], v[86:89]
	v_mfma_f32_16x16x32_bf16 v[82:85], v[180:183], v[218:221], v[82:85]
	v_mfma_f32_16x16x32_bf16 v[70:73], v[172:175], v[226:229], v[70:73]
	s_barrier
	v_mfma_f32_16x16x32_bf16 v[66:69], v[180:183], v[226:229], v[66:69]
	s_setprio 2
	s_add_i32 s19, s60, s33
	v_lshl_add_u64 v[144:145], s[34:35], 0, v[132:133]
	s_mov_b32 m0, s19
	ds_read_b128 v[184:187], v150 offset:16384
	ds_read_b128 v[188:191], v150 offset:17408
	ds_read_b128 v[198:201], v150 offset:18432
	ds_read_b128 v[210:213], v150 offset:19456
	ds_read_b128 v[214:217], v150 offset:20480
	ds_read_b128 v[218:221], v150 offset:21504
	ds_read_b128 v[222:225], v150 offset:22528
	ds_read_b128 v[226:229], v150 offset:23552
	global_load_lds_dwordx4 v[144:145], off
	s_add_i32 m0, s19, 0x2000
	s_add_u32 s38, s34, 0x80000
	v_lshl_add_u64 v[192:193], s[34:35], 0, v[136:137]
	s_addc_u32 s39, s35, 0
	s_add_i32 s19, s61, s33
	global_load_lds_dwordx4 v[192:193], off
	v_lshl_add_u64 v[202:203], s[38:39], 0, v[132:133]
	s_mov_b32 m0, s19
	v_lshl_add_u64 v[206:207], s[36:37], 0, v[134:135]
	global_load_lds_dwordx4 v[202:203], off
	v_lshl_add_u64 v[202:203], s[38:39], 0, v[136:137]
	s_add_i32 m0, s19, 0x2000
	s_nop 0
	global_load_lds_dwordx4 v[202:203], off
	v_lshl_add_u64 v[202:203], s[36:37], 0, v[130:131]
	s_mov_b32 m0, s27
	s_nop 0
	global_load_lds_dwordx4 v[202:203], off
	s_mov_b32 m0, s41
	s_nop 0
	global_load_lds_dwordx4 v[206:207], off
	s_waitcnt vmcnt(8)
	s_waitcnt lgkmcnt(0)
	s_barrier
	s_setprio 1
	s_waitcnt lgkmcnt(0)
	v_mfma_f32_16x16x32_bf16 v[62:65], v[152:155], v[184:187], 0
	v_mfma_f32_16x16x32_bf16 v[58:61], v[160:163], v[184:187], 0
	v_mfma_f32_16x16x32_bf16 v[46:49], v[152:155], v[198:201], 0
	v_mfma_f32_16x16x32_bf16 v[42:45], v[160:163], v[198:201], 0
	v_mfma_f32_16x16x32_bf16 v[30:33], v[152:155], v[214:217], 0
	v_mfma_f32_16x16x32_bf16 v[26:29], v[160:163], v[214:217], 0
	v_mfma_f32_16x16x32_bf16 v[14:17], v[152:155], v[222:225], 0
	v_mfma_f32_16x16x32_bf16 v[10:13], v[160:163], v[222:225], 0
	v_mfma_f32_16x16x32_bf16 v[62:65], v[156:159], v[188:191], v[62:65]
	v_mfma_f32_16x16x32_bf16 v[58:61], v[164:167], v[188:191], v[58:61]
	v_mfma_f32_16x16x32_bf16 v[46:49], v[156:159], v[210:213], v[46:49]
	v_mfma_f32_16x16x32_bf16 v[42:45], v[164:167], v[210:213], v[42:45]
	v_mfma_f32_16x16x32_bf16 v[30:33], v[156:159], v[218:221], v[30:33]
	v_mfma_f32_16x16x32_bf16 v[26:29], v[164:167], v[218:221], v[26:29]
	v_mfma_f32_16x16x32_bf16 v[14:17], v[156:159], v[226:229], v[14:17]
	v_mfma_f32_16x16x32_bf16 v[10:13], v[164:167], v[226:229], v[10:13]
	v_mfma_f32_16x16x32_bf16 v[54:57], v[168:171], v[184:187], 0
	v_mfma_f32_16x16x32_bf16 v[50:53], v[176:179], v[184:187], 0
	v_mfma_f32_16x16x32_bf16 v[38:41], v[168:171], v[198:201], 0
	v_mfma_f32_16x16x32_bf16 v[34:37], v[176:179], v[198:201], 0
	v_mfma_f32_16x16x32_bf16 v[22:25], v[168:171], v[214:217], 0
	v_mfma_f32_16x16x32_bf16 v[18:21], v[176:179], v[214:217], 0
	v_mfma_f32_16x16x32_bf16 v[6:9], v[168:171], v[222:225], 0
	v_mfma_f32_16x16x32_bf16 v[2:5], v[176:179], v[222:225], 0
	v_mfma_f32_16x16x32_bf16 v[54:57], v[172:175], v[188:191], v[54:57]
	v_mfma_f32_16x16x32_bf16 v[50:53], v[180:183], v[188:191], v[50:53]
	v_mfma_f32_16x16x32_bf16 v[38:41], v[172:175], v[210:213], v[38:41]
	v_mfma_f32_16x16x32_bf16 v[34:37], v[180:183], v[210:213], v[34:37]
	v_mfma_f32_16x16x32_bf16 v[22:25], v[172:175], v[218:221], v[22:25]
	v_mfma_f32_16x16x32_bf16 v[18:21], v[180:183], v[218:221], v[18:21]
	v_mfma_f32_16x16x32_bf16 v[6:9], v[172:175], v[226:229], v[6:9]
	s_barrier
	v_mfma_f32_16x16x32_bf16 v[2:5], v[180:183], v[226:229], v[2:5]
	s_setprio 2
	s_add_i32 s19, 0, 0x18000
	v_add_u32_e32 v151, s19, v146
	s_add_i32 s38, 0, 0x1c000
	ds_read_b128 v[152:155], v151
	ds_read_b128 v[156:159], v151 offset:1024
	ds_read_b128 v[160:163], v151 offset:2048
	ds_read_b128 v[164:167], v151 offset:3072
	v_add_u32_e32 v151, s38, v146
	ds_read_b128 v[168:171], v151
	ds_read_b128 v[172:175], v151 offset:1024
	ds_read_b128 v[176:179], v151 offset:2048
	ds_read_b128 v[180:183], v151 offset:3072
	s_add_u32 s36, s36, 0x80000
	s_addc_u32 s37, s37, 0
	s_mov_b32 m0, s42
	v_lshl_add_u64 v[230:231], s[36:37], 0, v[130:131]
	ds_read_b128 v[184:187], v150 offset:32768
	ds_read_b128 v[188:191], v150 offset:33792
	ds_read_b128 v[198:201], v150 offset:34816
	ds_read_b128 v[210:213], v150 offset:35840
	ds_read_b128 v[214:217], v150 offset:36864
	ds_read_b128 v[218:221], v150 offset:37888
	ds_read_b128 v[222:225], v150 offset:38912
	ds_read_b128 v[226:229], v150 offset:39936
	global_load_lds_dwordx4 v[230:231], off
	v_lshl_add_u64 v[230:231], s[36:37], 0, v[134:135]
	s_mov_b32 m0, s43
	s_nop 0
	global_load_lds_dwordx4 v[230:231], off
	s_waitcnt vmcnt(8)
	s_waitcnt lgkmcnt(0)
	s_barrier
	s_setprio 1
	s_waitcnt lgkmcnt(0)
	v_mfma_f32_16x16x32_bf16 v[126:129], v[152:155], v[184:187], v[126:129]
	v_mfma_f32_16x16x32_bf16 v[122:125], v[160:163], v[184:187], v[122:125]
	v_mfma_f32_16x16x32_bf16 v[110:113], v[152:155], v[198:201], v[110:113]
	v_mfma_f32_16x16x32_bf16 v[106:109], v[160:163], v[198:201], v[106:109]
	v_mfma_f32_16x16x32_bf16 v[94:97], v[152:155], v[214:217], v[94:97]
	v_mfma_f32_16x16x32_bf16 v[90:93], v[160:163], v[214:217], v[90:93]
	v_mfma_f32_16x16x32_bf16 v[78:81], v[152:155], v[222:225], v[78:81]
	v_mfma_f32_16x16x32_bf16 v[74:77], v[160:163], v[222:225], v[74:77]
	v_mfma_f32_16x16x32_bf16 v[126:129], v[156:159], v[188:191], v[126:129]
	v_mfma_f32_16x16x32_bf16 v[122:125], v[164:167], v[188:191], v[122:125]
	v_mfma_f32_16x16x32_bf16 v[110:113], v[156:159], v[210:213], v[110:113]
	v_mfma_f32_16x16x32_bf16 v[106:109], v[164:167], v[210:213], v[106:109]
	v_mfma_f32_16x16x32_bf16 v[94:97], v[156:159], v[218:221], v[94:97]
	v_mfma_f32_16x16x32_bf16 v[90:93], v[164:167], v[218:221], v[90:93]
	v_mfma_f32_16x16x32_bf16 v[78:81], v[156:159], v[226:229], v[78:81]
	v_mfma_f32_16x16x32_bf16 v[74:77], v[164:167], v[226:229], v[74:77]
	v_mfma_f32_16x16x32_bf16 v[118:121], v[168:171], v[184:187], v[118:121]
	v_mfma_f32_16x16x32_bf16 v[114:117], v[176:179], v[184:187], v[114:117]
	v_mfma_f32_16x16x32_bf16 v[102:105], v[168:171], v[198:201], v[102:105]
	v_mfma_f32_16x16x32_bf16 v[98:101], v[176:179], v[198:201], v[98:101]
	v_mfma_f32_16x16x32_bf16 v[86:89], v[168:171], v[214:217], v[86:89]
	v_mfma_f32_16x16x32_bf16 v[82:85], v[176:179], v[214:217], v[82:85]
	v_mfma_f32_16x16x32_bf16 v[70:73], v[168:171], v[222:225], v[70:73]
	v_mfma_f32_16x16x32_bf16 v[66:69], v[176:179], v[222:225], v[66:69]
	v_mfma_f32_16x16x32_bf16 v[118:121], v[172:175], v[188:191], v[118:121]
	v_mfma_f32_16x16x32_bf16 v[114:117], v[180:183], v[188:191], v[114:117]
	v_mfma_f32_16x16x32_bf16 v[102:105], v[172:175], v[210:213], v[102:105]
	v_mfma_f32_16x16x32_bf16 v[98:101], v[180:183], v[210:213], v[98:101]
	v_mfma_f32_16x16x32_bf16 v[86:89], v[172:175], v[218:221], v[86:89]
	v_mfma_f32_16x16x32_bf16 v[82:85], v[180:183], v[218:221], v[82:85]
	v_mfma_f32_16x16x32_bf16 v[70:73], v[172:175], v[226:229], v[70:73]
	s_barrier
	v_mfma_f32_16x16x32_bf16 v[66:69], v[180:183], v[226:229], v[66:69]
	s_setprio 2
	s_add_i32 s19, s19, s33
	v_lshl_add_u64 v[144:145], v[144:145], 0, s[10:11]
	s_mov_b32 m0, s19
	ds_read_b128 v[184:187], v150 offset:49152
	ds_read_b128 v[188:191], v150 offset:50176
	ds_read_b128 v[198:201], v150 offset:51200
	ds_read_b128 v[210:213], v150 offset:52224
	ds_read_b128 v[214:217], v150 offset:53248
	ds_read_b128 v[218:221], v150 offset:54272
	ds_read_b128 v[222:225], v150 offset:55296
	ds_read_b128 v[226:229], v150 offset:56320
	global_load_lds_dwordx4 v[144:145], off
	s_add_i32 m0, s19, 0x2000
	s_add_u32 s34, s34, 0x80080
	v_lshl_add_u64 v[144:145], v[192:193], 0, s[10:11]
	s_addc_u32 s35, s35, 0
	s_add_i32 s19, s38, s33
	global_load_lds_dwordx4 v[144:145], off
	v_lshl_add_u64 v[144:145], s[34:35], 0, v[132:133]
	s_mov_b32 m0, s19
	s_nop 0
	global_load_lds_dwordx4 v[144:145], off
	v_lshl_add_u64 v[144:145], s[34:35], 0, v[136:137]
	s_add_i32 m0, s19, 0x2000
	s_nop 0
	global_load_lds_dwordx4 v[144:145], off
	v_lshl_add_u64 v[144:145], v[202:203], 0, s[10:11]
	s_mov_b32 m0, s51
	s_nop 0
	global_load_lds_dwordx4 v[144:145], off
	v_lshl_add_u64 v[144:145], v[206:207], 0, s[10:11]
	s_mov_b32 m0, s52
	s_nop 0
	global_load_lds_dwordx4 v[144:145], off
	s_waitcnt vmcnt(8)
	s_waitcnt lgkmcnt(0)
	s_barrier
	s_setprio 1
	s_waitcnt lgkmcnt(0)
	v_mfma_f32_16x16x32_bf16 v[62:65], v[152:155], v[184:187], v[62:65]
	v_mfma_f32_16x16x32_bf16 v[58:61], v[160:163], v[184:187], v[58:61]
	v_mfma_f32_16x16x32_bf16 v[46:49], v[152:155], v[198:201], v[46:49]
	v_mfma_f32_16x16x32_bf16 v[42:45], v[160:163], v[198:201], v[42:45]
	v_mfma_f32_16x16x32_bf16 v[30:33], v[152:155], v[214:217], v[30:33]
	v_mfma_f32_16x16x32_bf16 v[26:29], v[160:163], v[214:217], v[26:29]
	v_mfma_f32_16x16x32_bf16 v[14:17], v[152:155], v[222:225], v[14:17]
	v_mfma_f32_16x16x32_bf16 v[10:13], v[160:163], v[222:225], v[10:13]
	v_mfma_f32_16x16x32_bf16 v[62:65], v[156:159], v[188:191], v[62:65]
	v_mfma_f32_16x16x32_bf16 v[58:61], v[164:167], v[188:191], v[58:61]
	v_mfma_f32_16x16x32_bf16 v[46:49], v[156:159], v[210:213], v[46:49]
	v_mfma_f32_16x16x32_bf16 v[42:45], v[164:167], v[210:213], v[42:45]
	v_mfma_f32_16x16x32_bf16 v[30:33], v[156:159], v[218:221], v[30:33]
	v_mfma_f32_16x16x32_bf16 v[26:29], v[164:167], v[218:221], v[26:29]
	v_mfma_f32_16x16x32_bf16 v[14:17], v[156:159], v[226:229], v[14:17]
	v_mfma_f32_16x16x32_bf16 v[10:13], v[164:167], v[226:229], v[10:13]
	v_mfma_f32_16x16x32_bf16 v[54:57], v[168:171], v[184:187], v[54:57]
	v_mfma_f32_16x16x32_bf16 v[50:53], v[176:179], v[184:187], v[50:53]
	v_mfma_f32_16x16x32_bf16 v[38:41], v[168:171], v[198:201], v[38:41]
	v_mfma_f32_16x16x32_bf16 v[34:37], v[176:179], v[198:201], v[34:37]
	v_mfma_f32_16x16x32_bf16 v[22:25], v[168:171], v[214:217], v[22:25]
	v_mfma_f32_16x16x32_bf16 v[18:21], v[176:179], v[214:217], v[18:21]
	v_mfma_f32_16x16x32_bf16 v[6:9], v[168:171], v[222:225], v[6:9]
	v_mfma_f32_16x16x32_bf16 v[2:5], v[176:179], v[222:225], v[2:5]
	v_mfma_f32_16x16x32_bf16 v[54:57], v[172:175], v[188:191], v[54:57]
	v_mfma_f32_16x16x32_bf16 v[50:53], v[180:183], v[188:191], v[50:53]
	v_mfma_f32_16x16x32_bf16 v[38:41], v[172:175], v[210:213], v[38:41]
	v_mfma_f32_16x16x32_bf16 v[34:37], v[180:183], v[210:213], v[34:37]
	v_mfma_f32_16x16x32_bf16 v[22:25], v[172:175], v[218:221], v[22:25]
	v_mfma_f32_16x16x32_bf16 v[18:21], v[180:183], v[218:221], v[18:21]
	v_mfma_f32_16x16x32_bf16 v[6:9], v[172:175], v[226:229], v[6:9]
	s_barrier
	v_mfma_f32_16x16x32_bf16 v[2:5], v[180:183], v[226:229], v[2:5]
	s_setprio 2
	s_add_u32 s30, s30, 0x100
	s_addc_u32 s31, s31, 0
	s_add_u32 s15, s15, 0x100
	s_addc_u32 s17, s17, 0
	s_cmp_ge_i32 s29, s68
	s_mov_b32 s19, s29
	s_cbranch_scc0 .LBB0_1315
	s_branch .Lpeeldone_7
.LBB0_1315:
	ds_read_b128 v[152:155], v148
	ds_read_b128 v[156:159], v148 offset:1024
	ds_read_b128 v[160:163], v148 offset:2048
	ds_read_b128 v[164:167], v148 offset:3072
	ds_read_b128 v[168:171], v149
	ds_read_b128 v[172:175], v149 offset:1024
	ds_read_b128 v[176:179], v149 offset:2048
	ds_read_b128 v[180:183], v149 offset:3072
	s_add_i32 s29, s19, 2
	s_add_u32 s34, s30, 0xfff80080
	s_addc_u32 s35, s31, -1
	s_cmp_eq_u32 s28, s19
	s_cselect_b32 s37, s21, s35
	s_cselect_b32 s36, s20, s34
	s_cselect_b32 s35, s23, s17
	s_cselect_b32 s34, s22, s15
	v_lshl_add_u64 v[144:145], s[30:31], 0, v[140:141]
	s_add_i32 m0, s27, 0xc000
	ds_read_b128 v[184:187], v150
	ds_read_b128 v[188:191], v150 offset:1024
	ds_read_b128 v[198:201], v150 offset:2048
	ds_read_b128 v[210:213], v150 offset:3072
	ds_read_b128 v[214:217], v150 offset:4096
	ds_read_b128 v[218:221], v150 offset:5120
	ds_read_b128 v[222:225], v150 offset:6144
	ds_read_b128 v[226:229], v150 offset:7168
	global_load_lds_dwordx4 v[144:145], off
	v_lshl_add_u64 v[144:145], s[30:31], 0, v[142:143]
	s_add_i32 m0, s27, 0xe000
	s_nop 0
	global_load_lds_dwordx4 v[144:145], off
	s_waitcnt vmcnt(8)
	s_waitcnt lgkmcnt(0)
	s_barrier
	s_setprio 1
	s_waitcnt lgkmcnt(0)
	v_mfma_f32_16x16x32_bf16 v[126:129], v[152:155], v[184:187], v[126:129]
	v_mfma_f32_16x16x32_bf16 v[122:125], v[160:163], v[184:187], v[122:125]
	v_mfma_f32_16x16x32_bf16 v[110:113], v[152:155], v[198:201], v[110:113]
	v_mfma_f32_16x16x32_bf16 v[106:109], v[160:163], v[198:201], v[106:109]
	v_mfma_f32_16x16x32_bf16 v[94:97], v[152:155], v[214:217], v[94:97]
	v_mfma_f32_16x16x32_bf16 v[90:93], v[160:163], v[214:217], v[90:93]
	v_mfma_f32_16x16x32_bf16 v[78:81], v[152:155], v[222:225], v[78:81]
	v_mfma_f32_16x16x32_bf16 v[74:77], v[160:163], v[222:225], v[74:77]
	v_mfma_f32_16x16x32_bf16 v[126:129], v[156:159], v[188:191], v[126:129]
	v_mfma_f32_16x16x32_bf16 v[122:125], v[164:167], v[188:191], v[122:125]
	v_mfma_f32_16x16x32_bf16 v[110:113], v[156:159], v[210:213], v[110:113]
	v_mfma_f32_16x16x32_bf16 v[106:109], v[164:167], v[210:213], v[106:109]
	v_mfma_f32_16x16x32_bf16 v[94:97], v[156:159], v[218:221], v[94:97]
	v_mfma_f32_16x16x32_bf16 v[90:93], v[164:167], v[218:221], v[90:93]
	v_mfma_f32_16x16x32_bf16 v[78:81], v[156:159], v[226:229], v[78:81]
	v_mfma_f32_16x16x32_bf16 v[74:77], v[164:167], v[226:229], v[74:77]
	v_mfma_f32_16x16x32_bf16 v[118:121], v[168:171], v[184:187], v[118:121]
	v_mfma_f32_16x16x32_bf16 v[114:117], v[176:179], v[184:187], v[114:117]
	v_mfma_f32_16x16x32_bf16 v[102:105], v[168:171], v[198:201], v[102:105]
	v_mfma_f32_16x16x32_bf16 v[98:101], v[176:179], v[198:201], v[98:101]
	v_mfma_f32_16x16x32_bf16 v[86:89], v[168:171], v[214:217], v[86:89]
	v_mfma_f32_16x16x32_bf16 v[82:85], v[176:179], v[214:217], v[82:85]
	v_mfma_f32_16x16x32_bf16 v[70:73], v[168:171], v[222:225], v[70:73]
	v_mfma_f32_16x16x32_bf16 v[66:69], v[176:179], v[222:225], v[66:69]
	v_mfma_f32_16x16x32_bf16 v[118:121], v[172:175], v[188:191], v[118:121]
	v_mfma_f32_16x16x32_bf16 v[114:117], v[180:183], v[188:191], v[114:117]
	v_mfma_f32_16x16x32_bf16 v[102:105], v[172:175], v[210:213], v[102:105]
	v_mfma_f32_16x16x32_bf16 v[98:101], v[180:183], v[210:213], v[98:101]
	v_mfma_f32_16x16x32_bf16 v[86:89], v[172:175], v[218:221], v[86:89]
	v_mfma_f32_16x16x32_bf16 v[82:85], v[180:183], v[218:221], v[82:85]
	v_mfma_f32_16x16x32_bf16 v[70:73], v[172:175], v[226:229], v[70:73]
	s_barrier
	v_mfma_f32_16x16x32_bf16 v[66:69], v[180:183], v[226:229], v[66:69]
	s_setprio 2
	s_add_i32 s19, s60, s33
	v_lshl_add_u64 v[144:145], s[34:35], 0, v[132:133]
	s_mov_b32 m0, s19
	ds_read_b128 v[184:187], v150 offset:16384
	ds_read_b128 v[188:191], v150 offset:17408
	ds_read_b128 v[198:201], v150 offset:18432
	ds_read_b128 v[210:213], v150 offset:19456
	ds_read_b128 v[214:217], v150 offset:20480
	ds_read_b128 v[218:221], v150 offset:21504
	ds_read_b128 v[222:225], v150 offset:22528
	ds_read_b128 v[226:229], v150 offset:23552
	global_load_lds_dwordx4 v[144:145], off
	s_add_i32 m0, s19, 0x2000
	s_add_u32 s38, s34, 0x80000
	v_lshl_add_u64 v[192:193], s[34:35], 0, v[136:137]
	s_addc_u32 s39, s35, 0
	s_add_i32 s19, s61, s33
	global_load_lds_dwordx4 v[192:193], off
	v_lshl_add_u64 v[202:203], s[38:39], 0, v[132:133]
	s_mov_b32 m0, s19
	v_lshl_add_u64 v[206:207], s[36:37], 0, v[134:135]
	global_load_lds_dwordx4 v[202:203], off
	v_lshl_add_u64 v[202:203], s[38:39], 0, v[136:137]
	s_add_i32 m0, s19, 0x2000
	s_nop 0
	global_load_lds_dwordx4 v[202:203], off
	v_lshl_add_u64 v[202:203], s[36:37], 0, v[130:131]
	s_mov_b32 m0, s27
	s_nop 0
	global_load_lds_dwordx4 v[202:203], off
	s_mov_b32 m0, s41
	s_nop 0
	global_load_lds_dwordx4 v[206:207], off
	s_waitcnt vmcnt(8)
	s_waitcnt lgkmcnt(0)
	s_barrier
	s_setprio 1
	s_waitcnt lgkmcnt(0)
	v_mfma_f32_16x16x32_bf16 v[62:65], v[152:155], v[184:187], v[62:65]
	v_mfma_f32_16x16x32_bf16 v[58:61], v[160:163], v[184:187], v[58:61]
	v_mfma_f32_16x16x32_bf16 v[46:49], v[152:155], v[198:201], v[46:49]
	v_mfma_f32_16x16x32_bf16 v[42:45], v[160:163], v[198:201], v[42:45]
	v_mfma_f32_16x16x32_bf16 v[30:33], v[152:155], v[214:217], v[30:33]
	v_mfma_f32_16x16x32_bf16 v[26:29], v[160:163], v[214:217], v[26:29]
	v_mfma_f32_16x16x32_bf16 v[14:17], v[152:155], v[222:225], v[14:17]
	v_mfma_f32_16x16x32_bf16 v[10:13], v[160:163], v[222:225], v[10:13]
	v_mfma_f32_16x16x32_bf16 v[62:65], v[156:159], v[188:191], v[62:65]
	v_mfma_f32_16x16x32_bf16 v[58:61], v[164:167], v[188:191], v[58:61]
	v_mfma_f32_16x16x32_bf16 v[46:49], v[156:159], v[210:213], v[46:49]
	v_mfma_f32_16x16x32_bf16 v[42:45], v[164:167], v[210:213], v[42:45]
	v_mfma_f32_16x16x32_bf16 v[30:33], v[156:159], v[218:221], v[30:33]
	v_mfma_f32_16x16x32_bf16 v[26:29], v[164:167], v[218:221], v[26:29]
	v_mfma_f32_16x16x32_bf16 v[14:17], v[156:159], v[226:229], v[14:17]
	v_mfma_f32_16x16x32_bf16 v[10:13], v[164:167], v[226:229], v[10:13]
	v_mfma_f32_16x16x32_bf16 v[54:57], v[168:171], v[184:187], v[54:57]
	v_mfma_f32_16x16x32_bf16 v[50:53], v[176:179], v[184:187], v[50:53]
	v_mfma_f32_16x16x32_bf16 v[38:41], v[168:171], v[198:201], v[38:41]
	v_mfma_f32_16x16x32_bf16 v[34:37], v[176:179], v[198:201], v[34:37]
	v_mfma_f32_16x16x32_bf16 v[22:25], v[168:171], v[214:217], v[22:25]
	v_mfma_f32_16x16x32_bf16 v[18:21], v[176:179], v[214:217], v[18:21]
	v_mfma_f32_16x16x32_bf16 v[6:9], v[168:171], v[222:225], v[6:9]
	v_mfma_f32_16x16x32_bf16 v[2:5], v[176:179], v[222:225], v[2:5]
	v_mfma_f32_16x16x32_bf16 v[54:57], v[172:175], v[188:191], v[54:57]
	v_mfma_f32_16x16x32_bf16 v[50:53], v[180:183], v[188:191], v[50:53]
	v_mfma_f32_16x16x32_bf16 v[38:41], v[172:175], v[210:213], v[38:41]
	v_mfma_f32_16x16x32_bf16 v[34:37], v[180:183], v[210:213], v[34:37]
	v_mfma_f32_16x16x32_bf16 v[22:25], v[172:175], v[218:221], v[22:25]
	v_mfma_f32_16x16x32_bf16 v[18:21], v[180:183], v[218:221], v[18:21]
	v_mfma_f32_16x16x32_bf16 v[6:9], v[172:175], v[226:229], v[6:9]
	s_barrier
	v_mfma_f32_16x16x32_bf16 v[2:5], v[180:183], v[226:229], v[2:5]
	s_setprio 2
	s_add_i32 s19, 0, 0x18000
	v_add_u32_e32 v151, s19, v146
	s_add_i32 s38, 0, 0x1c000
	ds_read_b128 v[152:155], v151
	ds_read_b128 v[156:159], v151 offset:1024
	ds_read_b128 v[160:163], v151 offset:2048
	ds_read_b128 v[164:167], v151 offset:3072
	v_add_u32_e32 v151, s38, v146
	ds_read_b128 v[168:171], v151
	ds_read_b128 v[172:175], v151 offset:1024
	ds_read_b128 v[176:179], v151 offset:2048
	ds_read_b128 v[180:183], v151 offset:3072
	s_add_u32 s36, s36, 0x80000
	s_addc_u32 s37, s37, 0
	s_mov_b32 m0, s42
	v_lshl_add_u64 v[230:231], s[36:37], 0, v[130:131]
	ds_read_b128 v[184:187], v150 offset:32768
	ds_read_b128 v[188:191], v150 offset:33792
	ds_read_b128 v[198:201], v150 offset:34816
	ds_read_b128 v[210:213], v150 offset:35840
	ds_read_b128 v[214:217], v150 offset:36864
	ds_read_b128 v[218:221], v150 offset:37888
	ds_read_b128 v[222:225], v150 offset:38912
	ds_read_b128 v[226:229], v150 offset:39936
	global_load_lds_dwordx4 v[230:231], off
	v_lshl_add_u64 v[230:231], s[36:37], 0, v[134:135]
	s_mov_b32 m0, s43
	s_nop 0
	global_load_lds_dwordx4 v[230:231], off
	s_waitcnt vmcnt(8)
	s_waitcnt lgkmcnt(0)
	s_barrier
	s_setprio 1
	s_waitcnt lgkmcnt(0)
	v_mfma_f32_16x16x32_bf16 v[126:129], v[152:155], v[184:187], v[126:129]
	v_mfma_f32_16x16x32_bf16 v[122:125], v[160:163], v[184:187], v[122:125]
	v_mfma_f32_16x16x32_bf16 v[110:113], v[152:155], v[198:201], v[110:113]
	v_mfma_f32_16x16x32_bf16 v[106:109], v[160:163], v[198:201], v[106:109]
	v_mfma_f32_16x16x32_bf16 v[94:97], v[152:155], v[214:217], v[94:97]
	v_mfma_f32_16x16x32_bf16 v[90:93], v[160:163], v[214:217], v[90:93]
	v_mfma_f32_16x16x32_bf16 v[78:81], v[152:155], v[222:225], v[78:81]
	v_mfma_f32_16x16x32_bf16 v[74:77], v[160:163], v[222:225], v[74:77]
	v_mfma_f32_16x16x32_bf16 v[126:129], v[156:159], v[188:191], v[126:129]
	v_mfma_f32_16x16x32_bf16 v[122:125], v[164:167], v[188:191], v[122:125]
	v_mfma_f32_16x16x32_bf16 v[110:113], v[156:159], v[210:213], v[110:113]
	v_mfma_f32_16x16x32_bf16 v[106:109], v[164:167], v[210:213], v[106:109]
	v_mfma_f32_16x16x32_bf16 v[94:97], v[156:159], v[218:221], v[94:97]
	v_mfma_f32_16x16x32_bf16 v[90:93], v[164:167], v[218:221], v[90:93]
	v_mfma_f32_16x16x32_bf16 v[78:81], v[156:159], v[226:229], v[78:81]
	v_mfma_f32_16x16x32_bf16 v[74:77], v[164:167], v[226:229], v[74:77]
	v_mfma_f32_16x16x32_bf16 v[118:121], v[168:171], v[184:187], v[118:121]
	v_mfma_f32_16x16x32_bf16 v[114:117], v[176:179], v[184:187], v[114:117]
	v_mfma_f32_16x16x32_bf16 v[102:105], v[168:171], v[198:201], v[102:105]
	v_mfma_f32_16x16x32_bf16 v[98:101], v[176:179], v[198:201], v[98:101]
	v_mfma_f32_16x16x32_bf16 v[86:89], v[168:171], v[214:217], v[86:89]
	v_mfma_f32_16x16x32_bf16 v[82:85], v[176:179], v[214:217], v[82:85]
	v_mfma_f32_16x16x32_bf16 v[70:73], v[168:171], v[222:225], v[70:73]
	v_mfma_f32_16x16x32_bf16 v[66:69], v[176:179], v[222:225], v[66:69]
	v_mfma_f32_16x16x32_bf16 v[118:121], v[172:175], v[188:191], v[118:121]
	v_mfma_f32_16x16x32_bf16 v[114:117], v[180:183], v[188:191], v[114:117]
	v_mfma_f32_16x16x32_bf16 v[102:105], v[172:175], v[210:213], v[102:105]
	v_mfma_f32_16x16x32_bf16 v[98:101], v[180:183], v[210:213], v[98:101]
	v_mfma_f32_16x16x32_bf16 v[86:89], v[172:175], v[218:221], v[86:89]
	v_mfma_f32_16x16x32_bf16 v[82:85], v[180:183], v[218:221], v[82:85]
	v_mfma_f32_16x16x32_bf16 v[70:73], v[172:175], v[226:229], v[70:73]
	s_barrier
	v_mfma_f32_16x16x32_bf16 v[66:69], v[180:183], v[226:229], v[66:69]
	s_setprio 2
	s_add_i32 s19, s19, s33
	v_lshl_add_u64 v[144:145], v[144:145], 0, s[10:11]
	s_mov_b32 m0, s19
	ds_read_b128 v[184:187], v150 offset:49152
	ds_read_b128 v[188:191], v150 offset:50176
	ds_read_b128 v[198:201], v150 offset:51200
	ds_read_b128 v[210:213], v150 offset:52224
	ds_read_b128 v[214:217], v150 offset:53248
	ds_read_b128 v[218:221], v150 offset:54272
	ds_read_b128 v[222:225], v150 offset:55296
	ds_read_b128 v[226:229], v150 offset:56320
	global_load_lds_dwordx4 v[144:145], off
	s_add_i32 m0, s19, 0x2000
	s_add_u32 s34, s34, 0x80080
	v_lshl_add_u64 v[144:145], v[192:193], 0, s[10:11]
	s_addc_u32 s35, s35, 0
	s_add_i32 s19, s38, s33
	global_load_lds_dwordx4 v[144:145], off
	v_lshl_add_u64 v[144:145], s[34:35], 0, v[132:133]
	s_mov_b32 m0, s19
	s_nop 0
	global_load_lds_dwordx4 v[144:145], off
	v_lshl_add_u64 v[144:145], s[34:35], 0, v[136:137]
	s_add_i32 m0, s19, 0x2000
	s_nop 0
	global_load_lds_dwordx4 v[144:145], off
	v_lshl_add_u64 v[144:145], v[202:203], 0, s[10:11]
	s_mov_b32 m0, s51
	s_nop 0
	global_load_lds_dwordx4 v[144:145], off
	v_lshl_add_u64 v[144:145], v[206:207], 0, s[10:11]
	s_mov_b32 m0, s52
	s_nop 0
	global_load_lds_dwordx4 v[144:145], off
	s_waitcnt vmcnt(8)
	s_waitcnt lgkmcnt(0)
	s_barrier
	s_setprio 1
	s_waitcnt lgkmcnt(0)
	v_mfma_f32_16x16x32_bf16 v[62:65], v[152:155], v[184:187], v[62:65]
	v_mfma_f32_16x16x32_bf16 v[58:61], v[160:163], v[184:187], v[58:61]
	v_mfma_f32_16x16x32_bf16 v[46:49], v[152:155], v[198:201], v[46:49]
	v_mfma_f32_16x16x32_bf16 v[42:45], v[160:163], v[198:201], v[42:45]
	v_mfma_f32_16x16x32_bf16 v[30:33], v[152:155], v[214:217], v[30:33]
	v_mfma_f32_16x16x32_bf16 v[26:29], v[160:163], v[214:217], v[26:29]
	v_mfma_f32_16x16x32_bf16 v[14:17], v[152:155], v[222:225], v[14:17]
	v_mfma_f32_16x16x32_bf16 v[10:13], v[160:163], v[222:225], v[10:13]
	v_mfma_f32_16x16x32_bf16 v[62:65], v[156:159], v[188:191], v[62:65]
	v_mfma_f32_16x16x32_bf16 v[58:61], v[164:167], v[188:191], v[58:61]
	v_mfma_f32_16x16x32_bf16 v[46:49], v[156:159], v[210:213], v[46:49]
	v_mfma_f32_16x16x32_bf16 v[42:45], v[164:167], v[210:213], v[42:45]
	v_mfma_f32_16x16x32_bf16 v[30:33], v[156:159], v[218:221], v[30:33]
	v_mfma_f32_16x16x32_bf16 v[26:29], v[164:167], v[218:221], v[26:29]
	v_mfma_f32_16x16x32_bf16 v[14:17], v[156:159], v[226:229], v[14:17]
	v_mfma_f32_16x16x32_bf16 v[10:13], v[164:167], v[226:229], v[10:13]
	v_mfma_f32_16x16x32_bf16 v[54:57], v[168:171], v[184:187], v[54:57]
	v_mfma_f32_16x16x32_bf16 v[50:53], v[176:179], v[184:187], v[50:53]
	v_mfma_f32_16x16x32_bf16 v[38:41], v[168:171], v[198:201], v[38:41]
	v_mfma_f32_16x16x32_bf16 v[34:37], v[176:179], v[198:201], v[34:37]
	v_mfma_f32_16x16x32_bf16 v[22:25], v[168:171], v[214:217], v[22:25]
	v_mfma_f32_16x16x32_bf16 v[18:21], v[176:179], v[214:217], v[18:21]
	v_mfma_f32_16x16x32_bf16 v[6:9], v[168:171], v[222:225], v[6:9]
	v_mfma_f32_16x16x32_bf16 v[2:5], v[176:179], v[222:225], v[2:5]
	v_mfma_f32_16x16x32_bf16 v[54:57], v[172:175], v[188:191], v[54:57]
	v_mfma_f32_16x16x32_bf16 v[50:53], v[180:183], v[188:191], v[50:53]
	v_mfma_f32_16x16x32_bf16 v[38:41], v[172:175], v[210:213], v[38:41]
	v_mfma_f32_16x16x32_bf16 v[34:37], v[180:183], v[210:213], v[34:37]
	v_mfma_f32_16x16x32_bf16 v[22:25], v[172:175], v[218:221], v[22:25]
	v_mfma_f32_16x16x32_bf16 v[18:21], v[180:183], v[218:221], v[18:21]
	v_mfma_f32_16x16x32_bf16 v[6:9], v[172:175], v[226:229], v[6:9]
	s_barrier
	v_mfma_f32_16x16x32_bf16 v[2:5], v[180:183], v[226:229], v[2:5]
	s_setprio 2
	s_add_u32 s30, s30, 0x100
	s_addc_u32 s31, s31, 0
	s_add_u32 s15, s15, 0x100
	s_addc_u32 s17, s17, 0
	s_cmp_ge_i32 s29, s68
	s_mov_b32 s19, s29
	s_cbranch_scc0 .LBB0_1315

.Lpeel_6:
	ds_read_b128 v[144:147], v166
	ds_read_b128 v[148:151], v166 offset:1024
	ds_read_b128 v[152:155], v166 offset:2048
	ds_read_b128 v[156:159], v166 offset:3072
	ds_read_b128 v[160:163], v167
	ds_read_b128 v[170:173], v167 offset:1024
	ds_read_b128 v[174:177], v167 offset:2048
	ds_read_b128 v[178:181], v167 offset:3072
	s_add_i32 s30, s26, 2
	s_add_u32 s27, s24, 0xffea0080
	s_addc_u32 s28, s25, -1
	s_cmp_eq_u32 s22, s26
	s_cselect_b32 s26, s20, s17
	s_cselect_b32 s29, s19, s28
	s_cselect_b32 s28, s18, s27
	s_cselect_b32 s27, s21, s23
	v_lshl_add_u64 v[202:203], s[24:25], 0, v[140:141]
	s_add_i32 m0, s34, 0xc000
	ds_read_b128 v[182:185], v168
	ds_read_b128 v[186:189], v168 offset:1024
	ds_read_b128 v[190:193], v168 offset:2048
	ds_read_b128 v[198:201], v168 offset:3072
	ds_read_b128 v[210:213], v168 offset:4096
	ds_read_b128 v[214:217], v168 offset:5120
	ds_read_b128 v[218:221], v168 offset:6144
	ds_read_b128 v[222:225], v168 offset:7168
	global_load_lds_dwordx4 v[202:203], off
	v_lshl_add_u64 v[202:203], s[24:25], 0, v[142:143]
	s_add_i32 m0, s34, 0xe000
	s_nop 0
	global_load_lds_dwordx4 v[202:203], off
	s_waitcnt vmcnt(8)
	s_waitcnt lgkmcnt(0)
	s_barrier
	s_setprio 1
	s_waitcnt lgkmcnt(0)
	v_mfma_f32_16x16x32_bf16 v[126:129], v[144:147], v[182:185], 0
	v_mfma_f32_16x16x32_bf16 v[122:125], v[152:155], v[182:185], 0
	v_mfma_f32_16x16x32_bf16 v[114:117], v[144:147], v[190:193], 0
	v_mfma_f32_16x16x32_bf16 v[106:109], v[152:155], v[190:193], 0
	v_mfma_f32_16x16x32_bf16 v[94:97], v[144:147], v[210:213], 0
	v_mfma_f32_16x16x32_bf16 v[90:93], v[152:155], v[210:213], 0
	v_mfma_f32_16x16x32_bf16 v[78:81], v[144:147], v[218:221], 0
	v_mfma_f32_16x16x32_bf16 v[74:77], v[152:155], v[218:221], 0
	v_mfma_f32_16x16x32_bf16 v[126:129], v[148:151], v[186:189], v[126:129]
	v_mfma_f32_16x16x32_bf16 v[122:125], v[156:159], v[186:189], v[122:125]
	v_mfma_f32_16x16x32_bf16 v[114:117], v[148:151], v[198:201], v[114:117]
	v_mfma_f32_16x16x32_bf16 v[106:109], v[156:159], v[198:201], v[106:109]
	v_mfma_f32_16x16x32_bf16 v[94:97], v[148:151], v[214:217], v[94:97]
	v_mfma_f32_16x16x32_bf16 v[90:93], v[156:159], v[214:217], v[90:93]
	v_mfma_f32_16x16x32_bf16 v[78:81], v[148:151], v[222:225], v[78:81]
	v_mfma_f32_16x16x32_bf16 v[74:77], v[156:159], v[222:225], v[74:77]
	v_mfma_f32_16x16x32_bf16 v[118:121], v[160:163], v[182:185], 0
	v_mfma_f32_16x16x32_bf16 v[110:113], v[174:177], v[182:185], 0
	v_mfma_f32_16x16x32_bf16 v[102:105], v[160:163], v[190:193], 0
	v_mfma_f32_16x16x32_bf16 v[98:101], v[174:177], v[190:193], 0
	v_mfma_f32_16x16x32_bf16 v[86:89], v[160:163], v[210:213], 0
	v_mfma_f32_16x16x32_bf16 v[82:85], v[174:177], v[210:213], 0
	v_mfma_f32_16x16x32_bf16 v[70:73], v[160:163], v[218:221], 0
	v_mfma_f32_16x16x32_bf16 v[66:69], v[174:177], v[218:221], 0
	v_mfma_f32_16x16x32_bf16 v[118:121], v[170:173], v[186:189], v[118:121]
	v_mfma_f32_16x16x32_bf16 v[110:113], v[178:181], v[186:189], v[110:113]
	v_mfma_f32_16x16x32_bf16 v[102:105], v[170:173], v[198:201], v[102:105]
	v_mfma_f32_16x16x32_bf16 v[98:101], v[178:181], v[198:201], v[98:101]
	v_mfma_f32_16x16x32_bf16 v[86:89], v[170:173], v[214:217], v[86:89]
	v_mfma_f32_16x16x32_bf16 v[82:85], v[178:181], v[214:217], v[82:85]
	v_mfma_f32_16x16x32_bf16 v[70:73], v[170:173], v[222:225], v[70:73]
	s_barrier
	v_mfma_f32_16x16x32_bf16 v[66:69], v[178:181], v[222:225], v[66:69]
	s_setprio 2
	s_add_i32 s31, s57, s33
	v_lshl_add_u64 v[202:203], s[26:27], 0, v[132:133]
	s_mov_b32 m0, s31
	ds_read_b128 v[182:185], v168 offset:16384
	ds_read_b128 v[186:189], v168 offset:17408
	ds_read_b128 v[190:193], v168 offset:18432
	ds_read_b128 v[198:201], v168 offset:19456
	ds_read_b128 v[210:213], v168 offset:20480
	ds_read_b128 v[214:217], v168 offset:21504
	ds_read_b128 v[218:221], v168 offset:22528
	ds_read_b128 v[222:225], v168 offset:23552
	global_load_lds_dwordx4 v[202:203], off
	s_add_i32 m0, s31, 0x2000
	s_add_u32 s68, s26, 0x160000
	v_lshl_add_u64 v[206:207], s[26:27], 0, v[136:137]
	s_addc_u32 s69, s27, 0
	s_add_i32 s31, s58, s33
	global_load_lds_dwordx4 v[206:207], off
	v_lshl_add_u64 v[226:227], s[68:69], 0, v[132:133]
	s_mov_b32 m0, s31
	v_lshl_add_u64 v[228:229], s[28:29], 0, v[134:135]
	global_load_lds_dwordx4 v[226:227], off
	v_lshl_add_u64 v[226:227], s[68:69], 0, v[136:137]
	s_add_i32 m0, s31, 0x2000
	s_nop 0
	global_load_lds_dwordx4 v[226:227], off
	v_lshl_add_u64 v[226:227], s[28:29], 0, v[130:131]
	s_mov_b32 m0, s34
	s_nop 0
	global_load_lds_dwordx4 v[226:227], off
	s_mov_b32 m0, s35
	s_nop 0
	global_load_lds_dwordx4 v[228:229], off
	s_waitcnt vmcnt(8)
	s_waitcnt lgkmcnt(0)
	s_barrier
	s_setprio 1
	s_waitcnt lgkmcnt(0)
	v_mfma_f32_16x16x32_bf16 v[62:65], v[144:147], v[182:185], 0
	v_mfma_f32_16x16x32_bf16 v[58:61], v[152:155], v[182:185], 0
	v_mfma_f32_16x16x32_bf16 v[46:49], v[144:147], v[190:193], 0
	v_mfma_f32_16x16x32_bf16 v[42:45], v[152:155], v[190:193], 0
	v_mfma_f32_16x16x32_bf16 v[30:33], v[144:147], v[210:213], 0
	v_mfma_f32_16x16x32_bf16 v[26:29], v[152:155], v[210:213], 0
	v_mfma_f32_16x16x32_bf16 v[14:17], v[144:147], v[218:221], 0
	v_mfma_f32_16x16x32_bf16 v[10:13], v[152:155], v[218:221], 0
	v_mfma_f32_16x16x32_bf16 v[62:65], v[148:151], v[186:189], v[62:65]
	v_mfma_f32_16x16x32_bf16 v[58:61], v[156:159], v[186:189], v[58:61]
	v_mfma_f32_16x16x32_bf16 v[46:49], v[148:151], v[198:201], v[46:49]
	v_mfma_f32_16x16x32_bf16 v[42:45], v[156:159], v[198:201], v[42:45]
	v_mfma_f32_16x16x32_bf16 v[30:33], v[148:151], v[214:217], v[30:33]
	v_mfma_f32_16x16x32_bf16 v[26:29], v[156:159], v[214:217], v[26:29]
	v_mfma_f32_16x16x32_bf16 v[14:17], v[148:151], v[222:225], v[14:17]
	v_mfma_f32_16x16x32_bf16 v[10:13], v[156:159], v[222:225], v[10:13]
	v_mfma_f32_16x16x32_bf16 v[54:57], v[160:163], v[182:185], 0
	v_mfma_f32_16x16x32_bf16 v[50:53], v[174:177], v[182:185], 0
	v_mfma_f32_16x16x32_bf16 v[38:41], v[160:163], v[190:193], 0
	v_mfma_f32_16x16x32_bf16 v[34:37], v[174:177], v[190:193], 0
	v_mfma_f32_16x16x32_bf16 v[22:25], v[160:163], v[210:213], 0
	v_mfma_f32_16x16x32_bf16 v[18:21], v[174:177], v[210:213], 0
	v_mfma_f32_16x16x32_bf16 v[6:9], v[160:163], v[218:221], 0
	v_mfma_f32_16x16x32_bf16 v[2:5], v[174:177], v[218:221], 0
	v_mfma_f32_16x16x32_bf16 v[54:57], v[170:173], v[186:189], v[54:57]
	v_mfma_f32_16x16x32_bf16 v[50:53], v[178:181], v[186:189], v[50:53]
	v_mfma_f32_16x16x32_bf16 v[38:41], v[170:173], v[198:201], v[38:41]
	v_mfma_f32_16x16x32_bf16 v[34:37], v[178:181], v[198:201], v[34:37]
	v_mfma_f32_16x16x32_bf16 v[22:25], v[170:173], v[214:217], v[22:25]
	v_mfma_f32_16x16x32_bf16 v[18:21], v[178:181], v[214:217], v[18:21]
	v_mfma_f32_16x16x32_bf16 v[6:9], v[170:173], v[222:225], v[6:9]
	s_barrier
	v_mfma_f32_16x16x32_bf16 v[2:5], v[178:181], v[222:225], v[2:5]
	s_setprio 2
	s_add_i32 s31, 0, 0x18000
	s_add_i32 s68, 0, 0x1c000
	v_add_u32_e32 v156, s31, v164
	v_add_u32_e32 v169, s68, v164
	ds_read_b128 v[144:147], v156
	ds_read_b128 v[148:151], v156 offset:1024
	ds_read_b128 v[152:155], v156 offset:2048
	ds_read_b128 v[156:159], v156 offset:3072
	ds_read_b128 v[160:163], v169
	ds_read_b128 v[170:173], v169 offset:1024
	ds_read_b128 v[174:177], v169 offset:2048
	ds_read_b128 v[178:181], v169 offset:3072
	s_add_u32 s28, s28, 0x160000
	s_addc_u32 s29, s29, 0
	s_mov_b32 m0, s36
	v_lshl_add_u64 v[230:231], s[28:29], 0, v[130:131]
	ds_read_b128 v[182:185], v168 offset:32768
	ds_read_b128 v[186:189], v168 offset:33792
	ds_read_b128 v[190:193], v168 offset:34816
	ds_read_b128 v[198:201], v168 offset:35840
	ds_read_b128 v[210:213], v168 offset:36864
	ds_read_b128 v[214:217], v168 offset:37888
	ds_read_b128 v[218:221], v168 offset:38912
	ds_read_b128 v[222:225], v168 offset:39936
	global_load_lds_dwordx4 v[230:231], off
	v_lshl_add_u64 v[230:231], s[28:29], 0, v[134:135]
	s_mov_b32 m0, s37
	s_nop 0
	global_load_lds_dwordx4 v[230:231], off
	s_waitcnt vmcnt(8)
	s_waitcnt lgkmcnt(0)
	s_barrier
	s_setprio 1
	s_waitcnt lgkmcnt(0)
	v_mfma_f32_16x16x32_bf16 v[126:129], v[144:147], v[182:185], v[126:129]
	v_mfma_f32_16x16x32_bf16 v[122:125], v[152:155], v[182:185], v[122:125]
	v_mfma_f32_16x16x32_bf16 v[114:117], v[144:147], v[190:193], v[114:117]
	v_mfma_f32_16x16x32_bf16 v[106:109], v[152:155], v[190:193], v[106:109]
	v_mfma_f32_16x16x32_bf16 v[94:97], v[144:147], v[210:213], v[94:97]
	v_mfma_f32_16x16x32_bf16 v[90:93], v[152:155], v[210:213], v[90:93]
	v_mfma_f32_16x16x32_bf16 v[78:81], v[144:147], v[218:221], v[78:81]
	v_mfma_f32_16x16x32_bf16 v[74:77], v[152:155], v[218:221], v[74:77]
	v_mfma_f32_16x16x32_bf16 v[126:129], v[148:151], v[186:189], v[126:129]
	v_mfma_f32_16x16x32_bf16 v[122:125], v[156:159], v[186:189], v[122:125]
	v_mfma_f32_16x16x32_bf16 v[114:117], v[148:151], v[198:201], v[114:117]
	v_mfma_f32_16x16x32_bf16 v[106:109], v[156:159], v[198:201], v[106:109]
	v_mfma_f32_16x16x32_bf16 v[94:97], v[148:151], v[214:217], v[94:97]
	v_mfma_f32_16x16x32_bf16 v[90:93], v[156:159], v[214:217], v[90:93]
	v_mfma_f32_16x16x32_bf16 v[78:81], v[148:151], v[222:225], v[78:81]
	v_mfma_f32_16x16x32_bf16 v[74:77], v[156:159], v[222:225], v[74:77]
	v_mfma_f32_16x16x32_bf16 v[118:121], v[160:163], v[182:185], v[118:121]
	v_mfma_f32_16x16x32_bf16 v[110:113], v[174:177], v[182:185], v[110:113]
	v_mfma_f32_16x16x32_bf16 v[102:105], v[160:163], v[190:193], v[102:105]
	v_mfma_f32_16x16x32_bf16 v[98:101], v[174:177], v[190:193], v[98:101]
	v_mfma_f32_16x16x32_bf16 v[86:89], v[160:163], v[210:213], v[86:89]
	v_mfma_f32_16x16x32_bf16 v[82:85], v[174:177], v[210:213], v[82:85]
	v_mfma_f32_16x16x32_bf16 v[70:73], v[160:163], v[218:221], v[70:73]
	v_mfma_f32_16x16x32_bf16 v[66:69], v[174:177], v[218:221], v[66:69]
	v_mfma_f32_16x16x32_bf16 v[118:121], v[170:173], v[186:189], v[118:121]
	v_mfma_f32_16x16x32_bf16 v[110:113], v[178:181], v[186:189], v[110:113]
	v_mfma_f32_16x16x32_bf16 v[102:105], v[170:173], v[198:201], v[102:105]
	v_mfma_f32_16x16x32_bf16 v[98:101], v[178:181], v[198:201], v[98:101]
	v_mfma_f32_16x16x32_bf16 v[86:89], v[170:173], v[214:217], v[86:89]
	v_mfma_f32_16x16x32_bf16 v[82:85], v[178:181], v[214:217], v[82:85]
	v_mfma_f32_16x16x32_bf16 v[70:73], v[170:173], v[222:225], v[70:73]
	s_barrier
	v_mfma_f32_16x16x32_bf16 v[66:69], v[178:181], v[222:225], v[66:69]
	s_setprio 2
	s_add_i32 s28, s31, s33
	v_lshl_add_u64 v[202:203], v[202:203], 0, s[12:13]
	s_mov_b32 m0, s28
	ds_read_b128 v[182:185], v168 offset:49152
	ds_read_b128 v[186:189], v168 offset:50176
	ds_read_b128 v[190:193], v168 offset:51200
	ds_read_b128 v[198:201], v168 offset:52224
	ds_read_b128 v[210:213], v168 offset:53248
	ds_read_b128 v[214:217], v168 offset:54272
	ds_read_b128 v[218:221], v168 offset:55296
	ds_read_b128 v[222:225], v168 offset:56320
	global_load_lds_dwordx4 v[202:203], off
	s_add_i32 m0, s28, 0x2000
	s_add_u32 s26, s26, 0x160080
	v_lshl_add_u64 v[202:203], v[206:207], 0, s[12:13]
	s_addc_u32 s27, s27, 0
	s_add_i32 s28, s68, s33
	global_load_lds_dwordx4 v[202:203], off
	v_lshl_add_u64 v[202:203], s[26:27], 0, v[132:133]
	s_mov_b32 m0, s28
	s_nop 0
	global_load_lds_dwordx4 v[202:203], off
	v_lshl_add_u64 v[202:203], s[26:27], 0, v[136:137]
	s_add_i32 m0, s28, 0x2000
	s_nop 0
	global_load_lds_dwordx4 v[202:203], off
	v_lshl_add_u64 v[202:203], v[226:227], 0, s[12:13]
	s_mov_b32 m0, s47
	s_nop 0
	global_load_lds_dwordx4 v[202:203], off
	v_lshl_add_u64 v[202:203], v[228:229], 0, s[12:13]
	s_mov_b32 m0, s48
	s_nop 0
	global_load_lds_dwordx4 v[202:203], off
	s_waitcnt vmcnt(8)
	s_waitcnt lgkmcnt(0)
	s_barrier
	s_setprio 1
	s_waitcnt lgkmcnt(0)
	v_mfma_f32_16x16x32_bf16 v[62:65], v[144:147], v[182:185], v[62:65]
	v_mfma_f32_16x16x32_bf16 v[58:61], v[152:155], v[182:185], v[58:61]
	v_mfma_f32_16x16x32_bf16 v[46:49], v[144:147], v[190:193], v[46:49]
	v_mfma_f32_16x16x32_bf16 v[42:45], v[152:155], v[190:193], v[42:45]
	v_mfma_f32_16x16x32_bf16 v[30:33], v[144:147], v[210:213], v[30:33]
	v_mfma_f32_16x16x32_bf16 v[26:29], v[152:155], v[210:213], v[26:29]
	v_mfma_f32_16x16x32_bf16 v[14:17], v[144:147], v[218:221], v[14:17]
	v_mfma_f32_16x16x32_bf16 v[10:13], v[152:155], v[218:221], v[10:13]
	v_mfma_f32_16x16x32_bf16 v[62:65], v[148:151], v[186:189], v[62:65]
	v_mfma_f32_16x16x32_bf16 v[58:61], v[156:159], v[186:189], v[58:61]
	v_mfma_f32_16x16x32_bf16 v[46:49], v[148:151], v[198:201], v[46:49]
	v_mfma_f32_16x16x32_bf16 v[42:45], v[156:159], v[198:201], v[42:45]
	v_mfma_f32_16x16x32_bf16 v[30:33], v[148:151], v[214:217], v[30:33]
	v_mfma_f32_16x16x32_bf16 v[26:29], v[156:159], v[214:217], v[26:29]
	v_mfma_f32_16x16x32_bf16 v[14:17], v[148:151], v[222:225], v[14:17]
	v_mfma_f32_16x16x32_bf16 v[10:13], v[156:159], v[222:225], v[10:13]
	v_mfma_f32_16x16x32_bf16 v[54:57], v[160:163], v[182:185], v[54:57]
	v_mfma_f32_16x16x32_bf16 v[50:53], v[174:177], v[182:185], v[50:53]
	v_mfma_f32_16x16x32_bf16 v[38:41], v[160:163], v[190:193], v[38:41]
	v_mfma_f32_16x16x32_bf16 v[34:37], v[174:177], v[190:193], v[34:37]
	v_mfma_f32_16x16x32_bf16 v[22:25], v[160:163], v[210:213], v[22:25]
	v_mfma_f32_16x16x32_bf16 v[18:21], v[174:177], v[210:213], v[18:21]
	v_mfma_f32_16x16x32_bf16 v[6:9], v[160:163], v[218:221], v[6:9]
	v_mfma_f32_16x16x32_bf16 v[2:5], v[174:177], v[218:221], v[2:5]
	v_mfma_f32_16x16x32_bf16 v[54:57], v[170:173], v[186:189], v[54:57]
	v_mfma_f32_16x16x32_bf16 v[50:53], v[178:181], v[186:189], v[50:53]
	v_mfma_f32_16x16x32_bf16 v[38:41], v[170:173], v[198:201], v[38:41]
	v_mfma_f32_16x16x32_bf16 v[34:37], v[178:181], v[198:201], v[34:37]
	v_mfma_f32_16x16x32_bf16 v[22:25], v[170:173], v[214:217], v[22:25]
	v_mfma_f32_16x16x32_bf16 v[18:21], v[178:181], v[214:217], v[18:21]
	v_mfma_f32_16x16x32_bf16 v[6:9], v[170:173], v[222:225], v[6:9]
	s_barrier
	v_mfma_f32_16x16x32_bf16 v[2:5], v[178:181], v[222:225], v[2:5]
	s_setprio 2
	s_add_u32 s24, s24, 0x100
	s_addc_u32 s25, s25, 0
	s_add_u32 s17, s17, 0x100
	s_addc_u32 s23, s23, 0
	s_cmp_ge_i32 s30, s67
	s_mov_b32 s26, s30
	s_cbranch_scc0 .LBB0_1451
	s_branch .Lpeeldone_6
.LBB0_1451:
	ds_read_b128 v[144:147], v166
	ds_read_b128 v[148:151], v166 offset:1024
	ds_read_b128 v[152:155], v166 offset:2048
	ds_read_b128 v[156:159], v166 offset:3072
	ds_read_b128 v[160:163], v167
	ds_read_b128 v[170:173], v167 offset:1024
	ds_read_b128 v[174:177], v167 offset:2048
	ds_read_b128 v[178:181], v167 offset:3072
	s_add_i32 s30, s26, 2
	s_add_u32 s27, s24, 0xffea0080
	s_addc_u32 s28, s25, -1
	s_cmp_eq_u32 s22, s26
	s_cselect_b32 s26, s20, s17
	s_cselect_b32 s29, s19, s28
	s_cselect_b32 s28, s18, s27
	s_cselect_b32 s27, s21, s23
	v_lshl_add_u64 v[202:203], s[24:25], 0, v[140:141]
	s_add_i32 m0, s34, 0xc000
	ds_read_b128 v[182:185], v168
	ds_read_b128 v[186:189], v168 offset:1024
	ds_read_b128 v[190:193], v168 offset:2048
	ds_read_b128 v[198:201], v168 offset:3072
	ds_read_b128 v[210:213], v168 offset:4096
	ds_read_b128 v[214:217], v168 offset:5120
	ds_read_b128 v[218:221], v168 offset:6144
	ds_read_b128 v[222:225], v168 offset:7168
	global_load_lds_dwordx4 v[202:203], off
	v_lshl_add_u64 v[202:203], s[24:25], 0, v[142:143]
	s_add_i32 m0, s34, 0xe000
	s_nop 0
	global_load_lds_dwordx4 v[202:203], off
	s_waitcnt vmcnt(8)
	s_waitcnt lgkmcnt(0)
	s_barrier
	s_setprio 1
	s_waitcnt lgkmcnt(0)
	v_mfma_f32_16x16x32_bf16 v[126:129], v[144:147], v[182:185], v[126:129]
	v_mfma_f32_16x16x32_bf16 v[122:125], v[152:155], v[182:185], v[122:125]
	v_mfma_f32_16x16x32_bf16 v[114:117], v[144:147], v[190:193], v[114:117]
	v_mfma_f32_16x16x32_bf16 v[106:109], v[152:155], v[190:193], v[106:109]
	v_mfma_f32_16x16x32_bf16 v[94:97], v[144:147], v[210:213], v[94:97]
	v_mfma_f32_16x16x32_bf16 v[90:93], v[152:155], v[210:213], v[90:93]
	v_mfma_f32_16x16x32_bf16 v[78:81], v[144:147], v[218:221], v[78:81]
	v_mfma_f32_16x16x32_bf16 v[74:77], v[152:155], v[218:221], v[74:77]
	v_mfma_f32_16x16x32_bf16 v[126:129], v[148:151], v[186:189], v[126:129]
	v_mfma_f32_16x16x32_bf16 v[122:125], v[156:159], v[186:189], v[122:125]
	v_mfma_f32_16x16x32_bf16 v[114:117], v[148:151], v[198:201], v[114:117]
	v_mfma_f32_16x16x32_bf16 v[106:109], v[156:159], v[198:201], v[106:109]
	v_mfma_f32_16x16x32_bf16 v[94:97], v[148:151], v[214:217], v[94:97]
	v_mfma_f32_16x16x32_bf16 v[90:93], v[156:159], v[214:217], v[90:93]
	v_mfma_f32_16x16x32_bf16 v[78:81], v[148:151], v[222:225], v[78:81]
	v_mfma_f32_16x16x32_bf16 v[74:77], v[156:159], v[222:225], v[74:77]
	v_mfma_f32_16x16x32_bf16 v[118:121], v[160:163], v[182:185], v[118:121]
	v_mfma_f32_16x16x32_bf16 v[110:113], v[174:177], v[182:185], v[110:113]
	v_mfma_f32_16x16x32_bf16 v[102:105], v[160:163], v[190:193], v[102:105]
	v_mfma_f32_16x16x32_bf16 v[98:101], v[174:177], v[190:193], v[98:101]
	v_mfma_f32_16x16x32_bf16 v[86:89], v[160:163], v[210:213], v[86:89]
	v_mfma_f32_16x16x32_bf16 v[82:85], v[174:177], v[210:213], v[82:85]
	v_mfma_f32_16x16x32_bf16 v[70:73], v[160:163], v[218:221], v[70:73]
	v_mfma_f32_16x16x32_bf16 v[66:69], v[174:177], v[218:221], v[66:69]
	v_mfma_f32_16x16x32_bf16 v[118:121], v[170:173], v[186:189], v[118:121]
	v_mfma_f32_16x16x32_bf16 v[110:113], v[178:181], v[186:189], v[110:113]
	v_mfma_f32_16x16x32_bf16 v[102:105], v[170:173], v[198:201], v[102:105]
	v_mfma_f32_16x16x32_bf16 v[98:101], v[178:181], v[198:201], v[98:101]
	v_mfma_f32_16x16x32_bf16 v[86:89], v[170:173], v[214:217], v[86:89]
	v_mfma_f32_16x16x32_bf16 v[82:85], v[178:181], v[214:217], v[82:85]
	v_mfma_f32_16x16x32_bf16 v[70:73], v[170:173], v[222:225], v[70:73]
	s_barrier
	v_mfma_f32_16x16x32_bf16 v[66:69], v[178:181], v[222:225], v[66:69]
	s_setprio 2
	s_add_i32 s31, s57, s33
	v_lshl_add_u64 v[202:203], s[26:27], 0, v[132:133]
	s_mov_b32 m0, s31
	ds_read_b128 v[182:185], v168 offset:16384
	ds_read_b128 v[186:189], v168 offset:17408
	ds_read_b128 v[190:193], v168 offset:18432
	ds_read_b128 v[198:201], v168 offset:19456
	ds_read_b128 v[210:213], v168 offset:20480
	ds_read_b128 v[214:217], v168 offset:21504
	ds_read_b128 v[218:221], v168 offset:22528
	ds_read_b128 v[222:225], v168 offset:23552
	global_load_lds_dwordx4 v[202:203], off
	s_add_i32 m0, s31, 0x2000
	s_add_u32 s68, s26, 0x160000
	v_lshl_add_u64 v[206:207], s[26:27], 0, v[136:137]
	s_addc_u32 s69, s27, 0
	s_add_i32 s31, s58, s33
	global_load_lds_dwordx4 v[206:207], off
	v_lshl_add_u64 v[226:227], s[68:69], 0, v[132:133]
	s_mov_b32 m0, s31
	v_lshl_add_u64 v[228:229], s[28:29], 0, v[134:135]
	global_load_lds_dwordx4 v[226:227], off
	v_lshl_add_u64 v[226:227], s[68:69], 0, v[136:137]
	s_add_i32 m0, s31, 0x2000
	s_nop 0
	global_load_lds_dwordx4 v[226:227], off
	v_lshl_add_u64 v[226:227], s[28:29], 0, v[130:131]
	s_mov_b32 m0, s34
	s_nop 0
	global_load_lds_dwordx4 v[226:227], off
	s_mov_b32 m0, s35
	s_nop 0
	global_load_lds_dwordx4 v[228:229], off
	s_waitcnt vmcnt(8)
	s_waitcnt lgkmcnt(0)
	s_barrier
	s_setprio 1
	s_waitcnt lgkmcnt(0)
	v_mfma_f32_16x16x32_bf16 v[62:65], v[144:147], v[182:185], v[62:65]
	v_mfma_f32_16x16x32_bf16 v[58:61], v[152:155], v[182:185], v[58:61]
	v_mfma_f32_16x16x32_bf16 v[46:49], v[144:147], v[190:193], v[46:49]
	v_mfma_f32_16x16x32_bf16 v[42:45], v[152:155], v[190:193], v[42:45]
	v_mfma_f32_16x16x32_bf16 v[30:33], v[144:147], v[210:213], v[30:33]
	v_mfma_f32_16x16x32_bf16 v[26:29], v[152:155], v[210:213], v[26:29]
	v_mfma_f32_16x16x32_bf16 v[14:17], v[144:147], v[218:221], v[14:17]
	v_mfma_f32_16x16x32_bf16 v[10:13], v[152:155], v[218:221], v[10:13]
	v_mfma_f32_16x16x32_bf16 v[62:65], v[148:151], v[186:189], v[62:65]
	v_mfma_f32_16x16x32_bf16 v[58:61], v[156:159], v[186:189], v[58:61]
	v_mfma_f32_16x16x32_bf16 v[46:49], v[148:151], v[198:201], v[46:49]
	v_mfma_f32_16x16x32_bf16 v[42:45], v[156:159], v[198:201], v[42:45]
	v_mfma_f32_16x16x32_bf16 v[30:33], v[148:151], v[214:217], v[30:33]
	v_mfma_f32_16x16x32_bf16 v[26:29], v[156:159], v[214:217], v[26:29]
	v_mfma_f32_16x16x32_bf16 v[14:17], v[148:151], v[222:225], v[14:17]
	v_mfma_f32_16x16x32_bf16 v[10:13], v[156:159], v[222:225], v[10:13]
	v_mfma_f32_16x16x32_bf16 v[54:57], v[160:163], v[182:185], v[54:57]
	v_mfma_f32_16x16x32_bf16 v[50:53], v[174:177], v[182:185], v[50:53]
	v_mfma_f32_16x16x32_bf16 v[38:41], v[160:163], v[190:193], v[38:41]
	v_mfma_f32_16x16x32_bf16 v[34:37], v[174:177], v[190:193], v[34:37]
	v_mfma_f32_16x16x32_bf16 v[22:25], v[160:163], v[210:213], v[22:25]
	v_mfma_f32_16x16x32_bf16 v[18:21], v[174:177], v[210:213], v[18:21]
	v_mfma_f32_16x16x32_bf16 v[6:9], v[160:163], v[218:221], v[6:9]
	v_mfma_f32_16x16x32_bf16 v[2:5], v[174:177], v[218:221], v[2:5]
	v_mfma_f32_16x16x32_bf16 v[54:57], v[170:173], v[186:189], v[54:57]
	v_mfma_f32_16x16x32_bf16 v[50:53], v[178:181], v[186:189], v[50:53]
	v_mfma_f32_16x16x32_bf16 v[38:41], v[170:173], v[198:201], v[38:41]
	v_mfma_f32_16x16x32_bf16 v[34:37], v[178:181], v[198:201], v[34:37]
	v_mfma_f32_16x16x32_bf16 v[22:25], v[170:173], v[214:217], v[22:25]
	v_mfma_f32_16x16x32_bf16 v[18:21], v[178:181], v[214:217], v[18:21]
	v_mfma_f32_16x16x32_bf16 v[6:9], v[170:173], v[222:225], v[6:9]
	s_barrier
	v_mfma_f32_16x16x32_bf16 v[2:5], v[178:181], v[222:225], v[2:5]
	s_setprio 2
	s_add_i32 s31, 0, 0x18000
	s_add_i32 s68, 0, 0x1c000
	v_add_u32_e32 v156, s31, v164
	v_add_u32_e32 v169, s68, v164
	ds_read_b128 v[144:147], v156
	ds_read_b128 v[148:151], v156 offset:1024
	ds_read_b128 v[152:155], v156 offset:2048
	ds_read_b128 v[156:159], v156 offset:3072
	ds_read_b128 v[160:163], v169
	ds_read_b128 v[170:173], v169 offset:1024
	ds_read_b128 v[174:177], v169 offset:2048
	ds_read_b128 v[178:181], v169 offset:3072
	s_add_u32 s28, s28, 0x160000
	s_addc_u32 s29, s29, 0
	s_mov_b32 m0, s36
	v_lshl_add_u64 v[230:231], s[28:29], 0, v[130:131]
	ds_read_b128 v[182:185], v168 offset:32768
	ds_read_b128 v[186:189], v168 offset:33792
	ds_read_b128 v[190:193], v168 offset:34816
	ds_read_b128 v[198:201], v168 offset:35840
	ds_read_b128 v[210:213], v168 offset:36864
	ds_read_b128 v[214:217], v168 offset:37888
	ds_read_b128 v[218:221], v168 offset:38912
	ds_read_b128 v[222:225], v168 offset:39936
	global_load_lds_dwordx4 v[230:231], off
	v_lshl_add_u64 v[230:231], s[28:29], 0, v[134:135]
	s_mov_b32 m0, s37
	s_nop 0
	global_load_lds_dwordx4 v[230:231], off
	s_waitcnt vmcnt(8)
	s_waitcnt lgkmcnt(0)
	s_barrier
	s_setprio 1
	s_waitcnt lgkmcnt(0)
	v_mfma_f32_16x16x32_bf16 v[126:129], v[144:147], v[182:185], v[126:129]
	v_mfma_f32_16x16x32_bf16 v[122:125], v[152:155], v[182:185], v[122:125]
	v_mfma_f32_16x16x32_bf16 v[114:117], v[144:147], v[190:193], v[114:117]
	v_mfma_f32_16x16x32_bf16 v[106:109], v[152:155], v[190:193], v[106:109]
	v_mfma_f32_16x16x32_bf16 v[94:97], v[144:147], v[210:213], v[94:97]
	v_mfma_f32_16x16x32_bf16 v[90:93], v[152:155], v[210:213], v[90:93]
	v_mfma_f32_16x16x32_bf16 v[78:81], v[144:147], v[218:221], v[78:81]
	v_mfma_f32_16x16x32_bf16 v[74:77], v[152:155], v[218:221], v[74:77]
	v_mfma_f32_16x16x32_bf16 v[126:129], v[148:151], v[186:189], v[126:129]
	v_mfma_f32_16x16x32_bf16 v[122:125], v[156:159], v[186:189], v[122:125]
	v_mfma_f32_16x16x32_bf16 v[114:117], v[148:151], v[198:201], v[114:117]
	v_mfma_f32_16x16x32_bf16 v[106:109], v[156:159], v[198:201], v[106:109]
	v_mfma_f32_16x16x32_bf16 v[94:97], v[148:151], v[214:217], v[94:97]
	v_mfma_f32_16x16x32_bf16 v[90:93], v[156:159], v[214:217], v[90:93]
	v_mfma_f32_16x16x32_bf16 v[78:81], v[148:151], v[222:225], v[78:81]
	v_mfma_f32_16x16x32_bf16 v[74:77], v[156:159], v[222:225], v[74:77]
	v_mfma_f32_16x16x32_bf16 v[118:121], v[160:163], v[182:185], v[118:121]
	v_mfma_f32_16x16x32_bf16 v[110:113], v[174:177], v[182:185], v[110:113]
	v_mfma_f32_16x16x32_bf16 v[102:105], v[160:163], v[190:193], v[102:105]
	v_mfma_f32_16x16x32_bf16 v[98:101], v[174:177], v[190:193], v[98:101]
	v_mfma_f32_16x16x32_bf16 v[86:89], v[160:163], v[210:213], v[86:89]
	v_mfma_f32_16x16x32_bf16 v[82:85], v[174:177], v[210:213], v[82:85]
	v_mfma_f32_16x16x32_bf16 v[70:73], v[160:163], v[218:221], v[70:73]
	v_mfma_f32_16x16x32_bf16 v[66:69], v[174:177], v[218:221], v[66:69]
	v_mfma_f32_16x16x32_bf16 v[118:121], v[170:173], v[186:189], v[118:121]
	v_mfma_f32_16x16x32_bf16 v[110:113], v[178:181], v[186:189], v[110:113]
	v_mfma_f32_16x16x32_bf16 v[102:105], v[170:173], v[198:201], v[102:105]
	v_mfma_f32_16x16x32_bf16 v[98:101], v[178:181], v[198:201], v[98:101]
	v_mfma_f32_16x16x32_bf16 v[86:89], v[170:173], v[214:217], v[86:89]
	v_mfma_f32_16x16x32_bf16 v[82:85], v[178:181], v[214:217], v[82:85]
	v_mfma_f32_16x16x32_bf16 v[70:73], v[170:173], v[222:225], v[70:73]
	s_barrier
	v_mfma_f32_16x16x32_bf16 v[66:69], v[178:181], v[222:225], v[66:69]
	s_setprio 2
	s_add_i32 s28, s31, s33
	v_lshl_add_u64 v[202:203], v[202:203], 0, s[12:13]
	s_mov_b32 m0, s28
	ds_read_b128 v[182:185], v168 offset:49152
	ds_read_b128 v[186:189], v168 offset:50176
	ds_read_b128 v[190:193], v168 offset:51200
	ds_read_b128 v[198:201], v168 offset:52224
	ds_read_b128 v[210:213], v168 offset:53248
	ds_read_b128 v[214:217], v168 offset:54272
	ds_read_b128 v[218:221], v168 offset:55296
	ds_read_b128 v[222:225], v168 offset:56320
	global_load_lds_dwordx4 v[202:203], off
	s_add_i32 m0, s28, 0x2000
	s_add_u32 s26, s26, 0x160080
	v_lshl_add_u64 v[202:203], v[206:207], 0, s[12:13]
	s_addc_u32 s27, s27, 0
	s_add_i32 s28, s68, s33
	global_load_lds_dwordx4 v[202:203], off
	v_lshl_add_u64 v[202:203], s[26:27], 0, v[132:133]
	s_mov_b32 m0, s28
	s_nop 0
	global_load_lds_dwordx4 v[202:203], off
	v_lshl_add_u64 v[202:203], s[26:27], 0, v[136:137]
	s_add_i32 m0, s28, 0x2000
	s_nop 0
	global_load_lds_dwordx4 v[202:203], off
	v_lshl_add_u64 v[202:203], v[226:227], 0, s[12:13]
	s_mov_b32 m0, s47
	s_nop 0
	global_load_lds_dwordx4 v[202:203], off
	v_lshl_add_u64 v[202:203], v[228:229], 0, s[12:13]
	s_mov_b32 m0, s48
	s_nop 0
	global_load_lds_dwordx4 v[202:203], off
	s_waitcnt vmcnt(8)
	s_waitcnt lgkmcnt(0)
	s_barrier
	s_setprio 1
	s_waitcnt lgkmcnt(0)
	v_mfma_f32_16x16x32_bf16 v[62:65], v[144:147], v[182:185], v[62:65]
	v_mfma_f32_16x16x32_bf16 v[58:61], v[152:155], v[182:185], v[58:61]
	v_mfma_f32_16x16x32_bf16 v[46:49], v[144:147], v[190:193], v[46:49]
	v_mfma_f32_16x16x32_bf16 v[42:45], v[152:155], v[190:193], v[42:45]
	v_mfma_f32_16x16x32_bf16 v[30:33], v[144:147], v[210:213], v[30:33]
	v_mfma_f32_16x16x32_bf16 v[26:29], v[152:155], v[210:213], v[26:29]
	v_mfma_f32_16x16x32_bf16 v[14:17], v[144:147], v[218:221], v[14:17]
	v_mfma_f32_16x16x32_bf16 v[10:13], v[152:155], v[218:221], v[10:13]
	v_mfma_f32_16x16x32_bf16 v[62:65], v[148:151], v[186:189], v[62:65]
	v_mfma_f32_16x16x32_bf16 v[58:61], v[156:159], v[186:189], v[58:61]
	v_mfma_f32_16x16x32_bf16 v[46:49], v[148:151], v[198:201], v[46:49]
	v_mfma_f32_16x16x32_bf16 v[42:45], v[156:159], v[198:201], v[42:45]
	v_mfma_f32_16x16x32_bf16 v[30:33], v[148:151], v[214:217], v[30:33]
	v_mfma_f32_16x16x32_bf16 v[26:29], v[156:159], v[214:217], v[26:29]
	v_mfma_f32_16x16x32_bf16 v[14:17], v[148:151], v[222:225], v[14:17]
	v_mfma_f32_16x16x32_bf16 v[10:13], v[156:159], v[222:225], v[10:13]
	v_mfma_f32_16x16x32_bf16 v[54:57], v[160:163], v[182:185], v[54:57]
	v_mfma_f32_16x16x32_bf16 v[50:53], v[174:177], v[182:185], v[50:53]
	v_mfma_f32_16x16x32_bf16 v[38:41], v[160:163], v[190:193], v[38:41]
	v_mfma_f32_16x16x32_bf16 v[34:37], v[174:177], v[190:193], v[34:37]
	v_mfma_f32_16x16x32_bf16 v[22:25], v[160:163], v[210:213], v[22:25]
	v_mfma_f32_16x16x32_bf16 v[18:21], v[174:177], v[210:213], v[18:21]
	v_mfma_f32_16x16x32_bf16 v[6:9], v[160:163], v[218:221], v[6:9]
	v_mfma_f32_16x16x32_bf16 v[2:5], v[174:177], v[218:221], v[2:5]
	v_mfma_f32_16x16x32_bf16 v[54:57], v[170:173], v[186:189], v[54:57]
	v_mfma_f32_16x16x32_bf16 v[50:53], v[178:181], v[186:189], v[50:53]
	v_mfma_f32_16x16x32_bf16 v[38:41], v[170:173], v[198:201], v[38:41]
	v_mfma_f32_16x16x32_bf16 v[34:37], v[178:181], v[198:201], v[34:37]
	v_mfma_f32_16x16x32_bf16 v[22:25], v[170:173], v[214:217], v[22:25]
	v_mfma_f32_16x16x32_bf16 v[18:21], v[178:181], v[214:217], v[18:21]
	v_mfma_f32_16x16x32_bf16 v[6:9], v[170:173], v[222:225], v[6:9]
	s_barrier
	v_mfma_f32_16x16x32_bf16 v[2:5], v[178:181], v[222:225], v[2:5]
	s_setprio 2
	s_add_u32 s24, s24, 0x100
	s_addc_u32 s25, s25, 0
	s_add_u32 s17, s17, 0x100
	s_addc_u32 s23, s23, 0
	s_cmp_ge_i32 s30, s67
	s_mov_b32 s26, s30
	s_cbranch_scc0 .LBB0_1451

.Lpeel_3:
	s_add_i32 s29, s23, 2
	s_add_u32 s34, s30, 0xfff80080
	s_addc_u32 s35, s31, -1
	s_cmp_eq_u32 s28, s23
	s_cselect_b32 s37, s25, s35
	s_cselect_b32 s36, s24, s34
	s_cselect_b32 s35, s27, s21
	s_cselect_b32 s34, s26, s19
	v_lshl_add_u64 v[202:203], s[30:31], 0, v[140:141]
	s_add_i32 m0, s15, 0xc000
	global_load_lds_dwordx4 v[202:203], off
	v_lshl_add_u64 v[202:203], s[30:31], 0, v[142:143]
	s_add_i32 m0, s15, 0xe000
	s_nop 0
	global_load_lds_dwordx4 v[202:203], off
	s_waitcnt vmcnt(8)
	s_waitcnt lgkmcnt(0)
	s_barrier
	s_setprio 1
	s_waitcnt lgkmcnt(0)
	v_mfma_f32_16x16x32_bf16 v[126:129], v[150:153], v[182:185], 0
	v_mfma_f32_16x16x32_bf16 v[122:125], v[158:161], v[182:185], 0
	v_mfma_f32_16x16x32_bf16 v[118:121], v[150:153], v[190:193], 0
	v_mfma_f32_16x16x32_bf16 v[114:117], v[158:161], v[190:193], 0
	v_mfma_f32_16x16x32_bf16 v[110:113], v[150:153], v[210:213], 0
	v_mfma_f32_16x16x32_bf16 v[106:109], v[158:161], v[210:213], 0
	v_mfma_f32_16x16x32_bf16 v[102:105], v[150:153], v[218:221], 0
	v_mfma_f32_16x16x32_bf16 v[98:101], v[158:161], v[218:221], 0
	v_mfma_f32_16x16x32_bf16 v[126:129], v[154:157], v[186:189], v[126:129]
	v_mfma_f32_16x16x32_bf16 v[122:125], v[162:165], v[186:189], v[122:125]
	v_mfma_f32_16x16x32_bf16 v[118:121], v[154:157], v[198:201], v[118:121]
	v_mfma_f32_16x16x32_bf16 v[114:117], v[162:165], v[198:201], v[114:117]
	v_mfma_f32_16x16x32_bf16 v[110:113], v[154:157], v[214:217], v[110:113]
	v_mfma_f32_16x16x32_bf16 v[106:109], v[162:165], v[214:217], v[106:109]
	v_mfma_f32_16x16x32_bf16 v[102:105], v[154:157], v[222:225], v[102:105]
	v_mfma_f32_16x16x32_bf16 v[98:101], v[162:165], v[222:225], v[98:101]
	v_mfma_f32_16x16x32_bf16 v[94:97], v[166:169], v[182:185], 0
	v_mfma_f32_16x16x32_bf16 v[90:93], v[174:177], v[182:185], 0
	v_mfma_f32_16x16x32_bf16 v[86:89], v[166:169], v[190:193], 0
	v_mfma_f32_16x16x32_bf16 v[82:85], v[174:177], v[190:193], 0
	v_mfma_f32_16x16x32_bf16 v[78:81], v[166:169], v[210:213], 0
	v_mfma_f32_16x16x32_bf16 v[74:77], v[174:177], v[210:213], 0
	v_mfma_f32_16x16x32_bf16 v[70:73], v[166:169], v[218:221], 0
	v_mfma_f32_16x16x32_bf16 v[66:69], v[174:177], v[218:221], 0
	v_mfma_f32_16x16x32_bf16 v[94:97], v[170:173], v[186:189], v[94:97]
	v_mfma_f32_16x16x32_bf16 v[90:93], v[178:181], v[186:189], v[90:93]
	v_mfma_f32_16x16x32_bf16 v[86:89], v[170:173], v[198:201], v[86:89]
	v_mfma_f32_16x16x32_bf16 v[82:85], v[178:181], v[198:201], v[82:85]
	v_mfma_f32_16x16x32_bf16 v[78:81], v[170:173], v[214:217], v[78:81]
	v_mfma_f32_16x16x32_bf16 v[74:77], v[178:181], v[214:217], v[74:77]
	v_mfma_f32_16x16x32_bf16 v[70:73], v[170:173], v[222:225], v[70:73]
	s_barrier
	v_mfma_f32_16x16x32_bf16 v[66:69], v[178:181], v[222:225], v[66:69]
	s_setprio 2
	s_add_i32 s23, s60, s33
	v_lshl_add_u64 v[202:203], s[34:35], 0, v[132:133]
	s_mov_b32 m0, s23
	ds_read_b128 v[182:185], v148 offset:16384
	ds_read_b128 v[186:189], v148 offset:17408
	ds_read_b128 v[190:193], v148 offset:18432
	ds_read_b128 v[198:201], v148 offset:19456
	ds_read_b128 v[210:213], v148 offset:20480
	ds_read_b128 v[214:217], v148 offset:21504
	ds_read_b128 v[218:221], v148 offset:22528
	ds_read_b128 v[222:225], v148 offset:23552
	global_load_lds_dwordx4 v[202:203], off
	s_add_i32 m0, s23, 0x2000
	s_add_u32 s38, s34, 0x80000
	v_lshl_add_u64 v[206:207], s[34:35], 0, v[136:137]
	s_addc_u32 s39, s35, 0
	s_add_i32 s23, s61, s33
	global_load_lds_dwordx4 v[206:207], off
	v_lshl_add_u64 v[226:227], s[38:39], 0, v[132:133]
	s_mov_b32 m0, s23
	v_lshl_add_u64 v[228:229], s[36:37], 0, v[134:135]
	global_load_lds_dwordx4 v[226:227], off
	v_lshl_add_u64 v[226:227], s[38:39], 0, v[136:137]
	s_add_i32 m0, s23, 0x2000
	s_nop 0
	global_load_lds_dwordx4 v[226:227], off
	v_lshl_add_u64 v[226:227], s[36:37], 0, v[130:131]
	s_mov_b32 m0, s15
	s_nop 0
	global_load_lds_dwordx4 v[226:227], off
	s_mov_b32 m0, s41
	s_nop 0
	global_load_lds_dwordx4 v[228:229], off
	s_waitcnt vmcnt(8)
	s_waitcnt lgkmcnt(0)
	s_barrier
	s_setprio 1
	s_waitcnt lgkmcnt(0)
	v_mfma_f32_16x16x32_bf16 v[62:65], v[150:153], v[182:185], 0
	v_mfma_f32_16x16x32_bf16 v[58:61], v[158:161], v[182:185], 0
	v_mfma_f32_16x16x32_bf16 v[54:57], v[150:153], v[190:193], 0
	v_mfma_f32_16x16x32_bf16 v[50:53], v[158:161], v[190:193], 0
	v_mfma_f32_16x16x32_bf16 v[46:49], v[150:153], v[210:213], 0
	v_mfma_f32_16x16x32_bf16 v[42:45], v[158:161], v[210:213], 0
	v_mfma_f32_16x16x32_bf16 v[38:41], v[150:153], v[218:221], 0
	v_mfma_f32_16x16x32_bf16 v[34:37], v[158:161], v[218:221], 0
	v_mfma_f32_16x16x32_bf16 v[62:65], v[154:157], v[186:189], v[62:65]
	v_mfma_f32_16x16x32_bf16 v[58:61], v[162:165], v[186:189], v[58:61]
	v_mfma_f32_16x16x32_bf16 v[54:57], v[154:157], v[198:201], v[54:57]
	v_mfma_f32_16x16x32_bf16 v[50:53], v[162:165], v[198:201], v[50:53]
	v_mfma_f32_16x16x32_bf16 v[46:49], v[154:157], v[214:217], v[46:49]
	v_mfma_f32_16x16x32_bf16 v[42:45], v[162:165], v[214:217], v[42:45]
	v_mfma_f32_16x16x32_bf16 v[38:41], v[154:157], v[222:225], v[38:41]
	v_mfma_f32_16x16x32_bf16 v[34:37], v[162:165], v[222:225], v[34:37]
	v_mfma_f32_16x16x32_bf16 v[30:33], v[166:169], v[182:185], 0
	v_mfma_f32_16x16x32_bf16 v[26:29], v[174:177], v[182:185], 0
	v_mfma_f32_16x16x32_bf16 v[22:25], v[166:169], v[190:193], 0
	v_mfma_f32_16x16x32_bf16 v[18:21], v[174:177], v[190:193], 0
	v_mfma_f32_16x16x32_bf16 v[14:17], v[166:169], v[210:213], 0
	v_mfma_f32_16x16x32_bf16 v[10:13], v[174:177], v[210:213], 0
	v_mfma_f32_16x16x32_bf16 v[6:9], v[166:169], v[218:221], 0
	v_mfma_f32_16x16x32_bf16 v[2:5], v[174:177], v[218:221], 0
	v_mfma_f32_16x16x32_bf16 v[30:33], v[170:173], v[186:189], v[30:33]
	v_mfma_f32_16x16x32_bf16 v[26:29], v[178:181], v[186:189], v[26:29]
	v_mfma_f32_16x16x32_bf16 v[22:25], v[170:173], v[198:201], v[22:25]
	v_mfma_f32_16x16x32_bf16 v[18:21], v[178:181], v[198:201], v[18:21]
	v_mfma_f32_16x16x32_bf16 v[14:17], v[170:173], v[214:217], v[14:17]
	v_mfma_f32_16x16x32_bf16 v[10:13], v[178:181], v[214:217], v[10:13]
	v_mfma_f32_16x16x32_bf16 v[6:9], v[170:173], v[222:225], v[6:9]
	s_barrier
	v_mfma_f32_16x16x32_bf16 v[2:5], v[178:181], v[222:225], v[2:5]
	s_setprio 2
	s_add_i32 s23, 0, 0x18000
	v_add_u32_e32 v149, s23, v144
	s_add_i32 s38, 0, 0x1c000
	ds_read_b128 v[150:153], v149
	ds_read_b128 v[154:157], v149 offset:1024
	ds_read_b128 v[158:161], v149 offset:2048
	ds_read_b128 v[162:165], v149 offset:3072
	v_add_u32_e32 v149, s38, v144
	ds_read_b128 v[166:169], v149
	ds_read_b128 v[170:173], v149 offset:1024
	ds_read_b128 v[174:177], v149 offset:2048
	ds_read_b128 v[178:181], v149 offset:3072
	s_add_u32 s36, s36, 0x80000
	s_addc_u32 s37, s37, 0
	s_mov_b32 m0, s42
	v_lshl_add_u64 v[230:231], s[36:37], 0, v[130:131]
	ds_read_b128 v[182:185], v148 offset:32768
	ds_read_b128 v[186:189], v148 offset:33792
	ds_read_b128 v[190:193], v148 offset:34816
	ds_read_b128 v[198:201], v148 offset:35840
	ds_read_b128 v[210:213], v148 offset:36864
	ds_read_b128 v[214:217], v148 offset:37888
	ds_read_b128 v[218:221], v148 offset:38912
	ds_read_b128 v[222:225], v148 offset:39936
	global_load_lds_dwordx4 v[230:231], off
	v_lshl_add_u64 v[230:231], s[36:37], 0, v[134:135]
	s_mov_b32 m0, s43
	s_nop 0
	global_load_lds_dwordx4 v[230:231], off
	s_waitcnt vmcnt(8)
	s_waitcnt lgkmcnt(0)
	s_barrier
	s_setprio 1
	s_waitcnt lgkmcnt(0)
	v_mfma_f32_16x16x32_bf16 v[126:129], v[150:153], v[182:185], v[126:129]
	v_mfma_f32_16x16x32_bf16 v[122:125], v[158:161], v[182:185], v[122:125]
	v_mfma_f32_16x16x32_bf16 v[118:121], v[150:153], v[190:193], v[118:121]
	v_mfma_f32_16x16x32_bf16 v[114:117], v[158:161], v[190:193], v[114:117]
	v_mfma_f32_16x16x32_bf16 v[110:113], v[150:153], v[210:213], v[110:113]
	v_mfma_f32_16x16x32_bf16 v[106:109], v[158:161], v[210:213], v[106:109]
	v_mfma_f32_16x16x32_bf16 v[102:105], v[150:153], v[218:221], v[102:105]
	v_mfma_f32_16x16x32_bf16 v[98:101], v[158:161], v[218:221], v[98:101]
	v_mfma_f32_16x16x32_bf16 v[126:129], v[154:157], v[186:189], v[126:129]
	v_mfma_f32_16x16x32_bf16 v[122:125], v[162:165], v[186:189], v[122:125]
	v_mfma_f32_16x16x32_bf16 v[118:121], v[154:157], v[198:201], v[118:121]
	v_mfma_f32_16x16x32_bf16 v[114:117], v[162:165], v[198:201], v[114:117]
	v_mfma_f32_16x16x32_bf16 v[110:113], v[154:157], v[214:217], v[110:113]
	v_mfma_f32_16x16x32_bf16 v[106:109], v[162:165], v[214:217], v[106:109]
	v_mfma_f32_16x16x32_bf16 v[102:105], v[154:157], v[222:225], v[102:105]
	v_mfma_f32_16x16x32_bf16 v[98:101], v[162:165], v[222:225], v[98:101]
	v_mfma_f32_16x16x32_bf16 v[94:97], v[166:169], v[182:185], v[94:97]
	v_mfma_f32_16x16x32_bf16 v[90:93], v[174:177], v[182:185], v[90:93]
	v_mfma_f32_16x16x32_bf16 v[86:89], v[166:169], v[190:193], v[86:89]
	v_mfma_f32_16x16x32_bf16 v[82:85], v[174:177], v[190:193], v[82:85]
	v_mfma_f32_16x16x32_bf16 v[78:81], v[166:169], v[210:213], v[78:81]
	v_mfma_f32_16x16x32_bf16 v[74:77], v[174:177], v[210:213], v[74:77]
	v_mfma_f32_16x16x32_bf16 v[70:73], v[166:169], v[218:221], v[70:73]
	v_mfma_f32_16x16x32_bf16 v[66:69], v[174:177], v[218:221], v[66:69]
	v_mfma_f32_16x16x32_bf16 v[94:97], v[170:173], v[186:189], v[94:97]
	v_mfma_f32_16x16x32_bf16 v[90:93], v[178:181], v[186:189], v[90:93]
	v_mfma_f32_16x16x32_bf16 v[86:89], v[170:173], v[198:201], v[86:89]
	v_mfma_f32_16x16x32_bf16 v[82:85], v[178:181], v[198:201], v[82:85]
	v_mfma_f32_16x16x32_bf16 v[78:81], v[170:173], v[214:217], v[78:81]
	v_mfma_f32_16x16x32_bf16 v[74:77], v[178:181], v[214:217], v[74:77]
	v_mfma_f32_16x16x32_bf16 v[70:73], v[170:173], v[222:225], v[70:73]
	s_barrier
	v_mfma_f32_16x16x32_bf16 v[66:69], v[178:181], v[222:225], v[66:69]
	s_setprio 2
	s_add_i32 s23, s23, s33
	v_lshl_add_u64 v[202:203], v[202:203], 0, s[10:11]
	s_mov_b32 m0, s23
	ds_read_b128 v[182:185], v148 offset:49152
	ds_read_b128 v[186:189], v148 offset:50176
	ds_read_b128 v[190:193], v148 offset:51200
	ds_read_b128 v[198:201], v148 offset:52224
	ds_read_b128 v[210:213], v148 offset:53248
	ds_read_b128 v[214:217], v148 offset:54272
	ds_read_b128 v[218:221], v148 offset:55296
	ds_read_b128 v[222:225], v148 offset:56320
	global_load_lds_dwordx4 v[202:203], off
	s_add_i32 m0, s23, 0x2000
	s_add_u32 s34, s34, 0x80080
	v_lshl_add_u64 v[202:203], v[206:207], 0, s[10:11]
	s_addc_u32 s35, s35, 0
	s_add_i32 s23, s38, s33
	global_load_lds_dwordx4 v[202:203], off
	v_lshl_add_u64 v[202:203], s[34:35], 0, v[132:133]
	s_mov_b32 m0, s23
	s_nop 0
	global_load_lds_dwordx4 v[202:203], off
	v_lshl_add_u64 v[202:203], s[34:35], 0, v[136:137]
	s_add_i32 m0, s23, 0x2000
	s_nop 0
	global_load_lds_dwordx4 v[202:203], off
	v_lshl_add_u64 v[202:203], v[226:227], 0, s[10:11]
	s_mov_b32 m0, s51
	s_nop 0
	global_load_lds_dwordx4 v[202:203], off
	v_lshl_add_u64 v[202:203], v[228:229], 0, s[10:11]
	s_mov_b32 m0, s52
	s_nop 0
	global_load_lds_dwordx4 v[202:203], off
	s_waitcnt vmcnt(8)
	s_waitcnt lgkmcnt(0)
	s_barrier
	s_setprio 1
	s_waitcnt lgkmcnt(0)
	v_mfma_f32_16x16x32_bf16 v[62:65], v[150:153], v[182:185], v[62:65]
	v_mfma_f32_16x16x32_bf16 v[58:61], v[158:161], v[182:185], v[58:61]
	v_mfma_f32_16x16x32_bf16 v[54:57], v[150:153], v[190:193], v[54:57]
	v_mfma_f32_16x16x32_bf16 v[50:53], v[158:161], v[190:193], v[50:53]
	v_mfma_f32_16x16x32_bf16 v[46:49], v[150:153], v[210:213], v[46:49]
	v_mfma_f32_16x16x32_bf16 v[42:45], v[158:161], v[210:213], v[42:45]
	v_mfma_f32_16x16x32_bf16 v[38:41], v[150:153], v[218:221], v[38:41]
	v_mfma_f32_16x16x32_bf16 v[34:37], v[158:161], v[218:221], v[34:37]
	v_mfma_f32_16x16x32_bf16 v[62:65], v[154:157], v[186:189], v[62:65]
	v_mfma_f32_16x16x32_bf16 v[58:61], v[162:165], v[186:189], v[58:61]
	v_mfma_f32_16x16x32_bf16 v[54:57], v[154:157], v[198:201], v[54:57]
	v_mfma_f32_16x16x32_bf16 v[50:53], v[162:165], v[198:201], v[50:53]
	v_mfma_f32_16x16x32_bf16 v[46:49], v[154:157], v[214:217], v[46:49]
	v_mfma_f32_16x16x32_bf16 v[42:45], v[162:165], v[214:217], v[42:45]
	v_mfma_f32_16x16x32_bf16 v[38:41], v[154:157], v[222:225], v[38:41]
	v_mfma_f32_16x16x32_bf16 v[34:37], v[162:165], v[222:225], v[34:37]
	v_mfma_f32_16x16x32_bf16 v[30:33], v[166:169], v[182:185], v[30:33]
	v_mfma_f32_16x16x32_bf16 v[26:29], v[174:177], v[182:185], v[26:29]
	v_mfma_f32_16x16x32_bf16 v[22:25], v[166:169], v[190:193], v[22:25]
	v_mfma_f32_16x16x32_bf16 v[18:21], v[174:177], v[190:193], v[18:21]
	v_mfma_f32_16x16x32_bf16 v[14:17], v[166:169], v[210:213], v[14:17]
	v_mfma_f32_16x16x32_bf16 v[10:13], v[174:177], v[210:213], v[10:13]
	v_mfma_f32_16x16x32_bf16 v[6:9], v[166:169], v[218:221], v[6:9]
	v_mfma_f32_16x16x32_bf16 v[2:5], v[174:177], v[218:221], v[2:5]
	v_mfma_f32_16x16x32_bf16 v[30:33], v[170:173], v[186:189], v[30:33]
	v_mfma_f32_16x16x32_bf16 v[26:29], v[178:181], v[186:189], v[26:29]
	v_mfma_f32_16x16x32_bf16 v[22:25], v[170:173], v[198:201], v[22:25]
	v_mfma_f32_16x16x32_bf16 v[18:21], v[178:181], v[198:201], v[18:21]
	v_mfma_f32_16x16x32_bf16 v[14:17], v[170:173], v[214:217], v[14:17]
	v_mfma_f32_16x16x32_bf16 v[10:13], v[178:181], v[214:217], v[10:13]
	v_mfma_f32_16x16x32_bf16 v[6:9], v[170:173], v[222:225], v[6:9]
	s_barrier
	v_mfma_f32_16x16x32_bf16 v[2:5], v[178:181], v[222:225], v[2:5]
	s_setprio 2
	s_add_u32 s30, s30, 0x100
	s_addc_u32 s31, s31, 0
	s_add_u32 s19, s19, 0x100
	s_addc_u32 s21, s21, 0
	s_cmp_ge_i32 s29, s68
	s_mov_b32 s23, s29
	s_cbranch_scc0 .LBB0_1973
	s_branch .Lpeeldone_3
.LBB0_1973:
	ds_read_b128 v[150:153], v146
	ds_read_b128 v[154:157], v146 offset:1024
	ds_read_b128 v[158:161], v146 offset:2048
	ds_read_b128 v[162:165], v146 offset:3072
	ds_read_b128 v[166:169], v147
	ds_read_b128 v[170:173], v147 offset:1024
	ds_read_b128 v[174:177], v147 offset:2048
	ds_read_b128 v[178:181], v147 offset:3072
	s_add_i32 s29, s23, 2
	s_add_u32 s34, s30, 0xfff80080
	s_addc_u32 s35, s31, -1
	s_cmp_eq_u32 s28, s23
	s_cselect_b32 s37, s25, s35
	s_cselect_b32 s36, s24, s34
	s_cselect_b32 s35, s27, s21
	s_cselect_b32 s34, s26, s19
	v_lshl_add_u64 v[202:203], s[30:31], 0, v[140:141]
	s_add_i32 m0, s15, 0xc000
	ds_read_b128 v[182:185], v148
	ds_read_b128 v[186:189], v148 offset:1024
	ds_read_b128 v[190:193], v148 offset:2048
	ds_read_b128 v[198:201], v148 offset:3072
	ds_read_b128 v[210:213], v148 offset:4096
	ds_read_b128 v[214:217], v148 offset:5120
	ds_read_b128 v[218:221], v148 offset:6144
	ds_read_b128 v[222:225], v148 offset:7168
	global_load_lds_dwordx4 v[202:203], off
	v_lshl_add_u64 v[202:203], s[30:31], 0, v[142:143]
	s_add_i32 m0, s15, 0xe000
	s_nop 0
	global_load_lds_dwordx4 v[202:203], off
	s_waitcnt vmcnt(8)
	s_waitcnt lgkmcnt(0)
	s_barrier
	s_setprio 1
	s_waitcnt lgkmcnt(0)
	v_mfma_f32_16x16x32_bf16 v[126:129], v[150:153], v[182:185], v[126:129]
	v_mfma_f32_16x16x32_bf16 v[122:125], v[158:161], v[182:185], v[122:125]
	v_mfma_f32_16x16x32_bf16 v[118:121], v[150:153], v[190:193], v[118:121]
	v_mfma_f32_16x16x32_bf16 v[114:117], v[158:161], v[190:193], v[114:117]
	v_mfma_f32_16x16x32_bf16 v[110:113], v[150:153], v[210:213], v[110:113]
	v_mfma_f32_16x16x32_bf16 v[106:109], v[158:161], v[210:213], v[106:109]
	v_mfma_f32_16x16x32_bf16 v[102:105], v[150:153], v[218:221], v[102:105]
	v_mfma_f32_16x16x32_bf16 v[98:101], v[158:161], v[218:221], v[98:101]
	v_mfma_f32_16x16x32_bf16 v[126:129], v[154:157], v[186:189], v[126:129]
	v_mfma_f32_16x16x32_bf16 v[122:125], v[162:165], v[186:189], v[122:125]
	v_mfma_f32_16x16x32_bf16 v[118:121], v[154:157], v[198:201], v[118:121]
	v_mfma_f32_16x16x32_bf16 v[114:117], v[162:165], v[198:201], v[114:117]
	v_mfma_f32_16x16x32_bf16 v[110:113], v[154:157], v[214:217], v[110:113]
	v_mfma_f32_16x16x32_bf16 v[106:109], v[162:165], v[214:217], v[106:109]
	v_mfma_f32_16x16x32_bf16 v[102:105], v[154:157], v[222:225], v[102:105]
	v_mfma_f32_16x16x32_bf16 v[98:101], v[162:165], v[222:225], v[98:101]
	v_mfma_f32_16x16x32_bf16 v[94:97], v[166:169], v[182:185], v[94:97]
	v_mfma_f32_16x16x32_bf16 v[90:93], v[174:177], v[182:185], v[90:93]
	v_mfma_f32_16x16x32_bf16 v[86:89], v[166:169], v[190:193], v[86:89]
	v_mfma_f32_16x16x32_bf16 v[82:85], v[174:177], v[190:193], v[82:85]
	v_mfma_f32_16x16x32_bf16 v[78:81], v[166:169], v[210:213], v[78:81]
	v_mfma_f32_16x16x32_bf16 v[74:77], v[174:177], v[210:213], v[74:77]
	v_mfma_f32_16x16x32_bf16 v[70:73], v[166:169], v[218:221], v[70:73]
	v_mfma_f32_16x16x32_bf16 v[66:69], v[174:177], v[218:221], v[66:69]
	v_mfma_f32_16x16x32_bf16 v[94:97], v[170:173], v[186:189], v[94:97]
	v_mfma_f32_16x16x32_bf16 v[90:93], v[178:181], v[186:189], v[90:93]
	v_mfma_f32_16x16x32_bf16 v[86:89], v[170:173], v[198:201], v[86:89]
	v_mfma_f32_16x16x32_bf16 v[82:85], v[178:181], v[198:201], v[82:85]
	v_mfma_f32_16x16x32_bf16 v[78:81], v[170:173], v[214:217], v[78:81]
	v_mfma_f32_16x16x32_bf16 v[74:77], v[178:181], v[214:217], v[74:77]
	v_mfma_f32_16x16x32_bf16 v[70:73], v[170:173], v[222:225], v[70:73]
	s_barrier
	v_mfma_f32_16x16x32_bf16 v[66:69], v[178:181], v[222:225], v[66:69]
	s_setprio 2
	s_add_i32 s23, s60, s33
	v_lshl_add_u64 v[202:203], s[34:35], 0, v[132:133]
	s_mov_b32 m0, s23
	ds_read_b128 v[182:185], v148 offset:16384
	ds_read_b128 v[186:189], v148 offset:17408
	ds_read_b128 v[190:193], v148 offset:18432
	ds_read_b128 v[198:201], v148 offset:19456
	ds_read_b128 v[210:213], v148 offset:20480
	ds_read_b128 v[214:217], v148 offset:21504
	ds_read_b128 v[218:221], v148 offset:22528
	ds_read_b128 v[222:225], v148 offset:23552
	global_load_lds_dwordx4 v[202:203], off
	s_add_i32 m0, s23, 0x2000
	s_add_u32 s38, s34, 0x80000
	v_lshl_add_u64 v[206:207], s[34:35], 0, v[136:137]
	s_addc_u32 s39, s35, 0
	s_add_i32 s23, s61, s33
	global_load_lds_dwordx4 v[206:207], off
	v_lshl_add_u64 v[226:227], s[38:39], 0, v[132:133]
	s_mov_b32 m0, s23
	v_lshl_add_u64 v[228:229], s[36:37], 0, v[134:135]
	global_load_lds_dwordx4 v[226:227], off
	v_lshl_add_u64 v[226:227], s[38:39], 0, v[136:137]
	s_add_i32 m0, s23, 0x2000
	s_nop 0
	global_load_lds_dwordx4 v[226:227], off
	v_lshl_add_u64 v[226:227], s[36:37], 0, v[130:131]
	s_mov_b32 m0, s15
	s_nop 0
	global_load_lds_dwordx4 v[226:227], off
	s_mov_b32 m0, s41
	s_nop 0
	global_load_lds_dwordx4 v[228:229], off
	s_waitcnt vmcnt(8)
	s_waitcnt lgkmcnt(0)
	s_barrier
	s_setprio 1
	s_waitcnt lgkmcnt(0)
	v_mfma_f32_16x16x32_bf16 v[62:65], v[150:153], v[182:185], v[62:65]
	v_mfma_f32_16x16x32_bf16 v[58:61], v[158:161], v[182:185], v[58:61]
	v_mfma_f32_16x16x32_bf16 v[54:57], v[150:153], v[190:193], v[54:57]
	v_mfma_f32_16x16x32_bf16 v[50:53], v[158:161], v[190:193], v[50:53]
	v_mfma_f32_16x16x32_bf16 v[46:49], v[150:153], v[210:213], v[46:49]
	v_mfma_f32_16x16x32_bf16 v[42:45], v[158:161], v[210:213], v[42:45]
	v_mfma_f32_16x16x32_bf16 v[38:41], v[150:153], v[218:221], v[38:41]
	v_mfma_f32_16x16x32_bf16 v[34:37], v[158:161], v[218:221], v[34:37]
	v_mfma_f32_16x16x32_bf16 v[62:65], v[154:157], v[186:189], v[62:65]
	v_mfma_f32_16x16x32_bf16 v[58:61], v[162:165], v[186:189], v[58:61]
	v_mfma_f32_16x16x32_bf16 v[54:57], v[154:157], v[198:201], v[54:57]
	v_mfma_f32_16x16x32_bf16 v[50:53], v[162:165], v[198:201], v[50:53]
	v_mfma_f32_16x16x32_bf16 v[46:49], v[154:157], v[214:217], v[46:49]
	v_mfma_f32_16x16x32_bf16 v[42:45], v[162:165], v[214:217], v[42:45]
	v_mfma_f32_16x16x32_bf16 v[38:41], v[154:157], v[222:225], v[38:41]
	v_mfma_f32_16x16x32_bf16 v[34:37], v[162:165], v[222:225], v[34:37]
	v_mfma_f32_16x16x32_bf16 v[30:33], v[166:169], v[182:185], v[30:33]
	v_mfma_f32_16x16x32_bf16 v[26:29], v[174:177], v[182:185], v[26:29]
	v_mfma_f32_16x16x32_bf16 v[22:25], v[166:169], v[190:193], v[22:25]
	v_mfma_f32_16x16x32_bf16 v[18:21], v[174:177], v[190:193], v[18:21]
	v_mfma_f32_16x16x32_bf16 v[14:17], v[166:169], v[210:213], v[14:17]
	v_mfma_f32_16x16x32_bf16 v[10:13], v[174:177], v[210:213], v[10:13]
	v_mfma_f32_16x16x32_bf16 v[6:9], v[166:169], v[218:221], v[6:9]
	v_mfma_f32_16x16x32_bf16 v[2:5], v[174:177], v[218:221], v[2:5]
	v_mfma_f32_16x16x32_bf16 v[30:33], v[170:173], v[186:189], v[30:33]
	v_mfma_f32_16x16x32_bf16 v[26:29], v[178:181], v[186:189], v[26:29]
	v_mfma_f32_16x16x32_bf16 v[22:25], v[170:173], v[198:201], v[22:25]
	v_mfma_f32_16x16x32_bf16 v[18:21], v[178:181], v[198:201], v[18:21]
	v_mfma_f32_16x16x32_bf16 v[14:17], v[170:173], v[214:217], v[14:17]
	v_mfma_f32_16x16x32_bf16 v[10:13], v[178:181], v[214:217], v[10:13]
	v_mfma_f32_16x16x32_bf16 v[6:9], v[170:173], v[222:225], v[6:9]
	s_barrier
	v_mfma_f32_16x16x32_bf16 v[2:5], v[178:181], v[222:225], v[2:5]
	s_setprio 2
	s_add_i32 s23, 0, 0x18000
	v_add_u32_e32 v149, s23, v144
	s_add_i32 s38, 0, 0x1c000
	ds_read_b128 v[150:153], v149
	ds_read_b128 v[154:157], v149 offset:1024
	ds_read_b128 v[158:161], v149 offset:2048
	ds_read_b128 v[162:165], v149 offset:3072
	v_add_u32_e32 v149, s38, v144
	ds_read_b128 v[166:169], v149
	ds_read_b128 v[170:173], v149 offset:1024
	ds_read_b128 v[174:177], v149 offset:2048
	ds_read_b128 v[178:181], v149 offset:3072
	s_add_u32 s36, s36, 0x80000
	s_addc_u32 s37, s37, 0
	s_mov_b32 m0, s42
	v_lshl_add_u64 v[230:231], s[36:37], 0, v[130:131]
	ds_read_b128 v[182:185], v148 offset:32768
	ds_read_b128 v[186:189], v148 offset:33792
	ds_read_b128 v[190:193], v148 offset:34816
	ds_read_b128 v[198:201], v148 offset:35840
	ds_read_b128 v[210:213], v148 offset:36864
	ds_read_b128 v[214:217], v148 offset:37888
	ds_read_b128 v[218:221], v148 offset:38912
	ds_read_b128 v[222:225], v148 offset:39936
	global_load_lds_dwordx4 v[230:231], off
	v_lshl_add_u64 v[230:231], s[36:37], 0, v[134:135]
	s_mov_b32 m0, s43
	s_nop 0
	global_load_lds_dwordx4 v[230:231], off
	s_waitcnt vmcnt(8)
	s_waitcnt lgkmcnt(0)
	s_barrier
	s_setprio 1
	s_waitcnt lgkmcnt(0)
	v_mfma_f32_16x16x32_bf16 v[126:129], v[150:153], v[182:185], v[126:129]
	v_mfma_f32_16x16x32_bf16 v[122:125], v[158:161], v[182:185], v[122:125]
	v_mfma_f32_16x16x32_bf16 v[118:121], v[150:153], v[190:193], v[118:121]
	v_mfma_f32_16x16x32_bf16 v[114:117], v[158:161], v[190:193], v[114:117]
	v_mfma_f32_16x16x32_bf16 v[110:113], v[150:153], v[210:213], v[110:113]
	v_mfma_f32_16x16x32_bf16 v[106:109], v[158:161], v[210:213], v[106:109]
	v_mfma_f32_16x16x32_bf16 v[102:105], v[150:153], v[218:221], v[102:105]
	v_mfma_f32_16x16x32_bf16 v[98:101], v[158:161], v[218:221], v[98:101]
	v_mfma_f32_16x16x32_bf16 v[126:129], v[154:157], v[186:189], v[126:129]
	v_mfma_f32_16x16x32_bf16 v[122:125], v[162:165], v[186:189], v[122:125]
	v_mfma_f32_16x16x32_bf16 v[118:121], v[154:157], v[198:201], v[118:121]
	v_mfma_f32_16x16x32_bf16 v[114:117], v[162:165], v[198:201], v[114:117]
	v_mfma_f32_16x16x32_bf16 v[110:113], v[154:157], v[214:217], v[110:113]
	v_mfma_f32_16x16x32_bf16 v[106:109], v[162:165], v[214:217], v[106:109]
	v_mfma_f32_16x16x32_bf16 v[102:105], v[154:157], v[222:225], v[102:105]
	v_mfma_f32_16x16x32_bf16 v[98:101], v[162:165], v[222:225], v[98:101]
	v_mfma_f32_16x16x32_bf16 v[94:97], v[166:169], v[182:185], v[94:97]
	v_mfma_f32_16x16x32_bf16 v[90:93], v[174:177], v[182:185], v[90:93]
	v_mfma_f32_16x16x32_bf16 v[86:89], v[166:169], v[190:193], v[86:89]
	v_mfma_f32_16x16x32_bf16 v[82:85], v[174:177], v[190:193], v[82:85]
	v_mfma_f32_16x16x32_bf16 v[78:81], v[166:169], v[210:213], v[78:81]
	v_mfma_f32_16x16x32_bf16 v[74:77], v[174:177], v[210:213], v[74:77]
	v_mfma_f32_16x16x32_bf16 v[70:73], v[166:169], v[218:221], v[70:73]
	v_mfma_f32_16x16x32_bf16 v[66:69], v[174:177], v[218:221], v[66:69]
	v_mfma_f32_16x16x32_bf16 v[94:97], v[170:173], v[186:189], v[94:97]
	v_mfma_f32_16x16x32_bf16 v[90:93], v[178:181], v[186:189], v[90:93]
	v_mfma_f32_16x16x32_bf16 v[86:89], v[170:173], v[198:201], v[86:89]
	v_mfma_f32_16x16x32_bf16 v[82:85], v[178:181], v[198:201], v[82:85]
	v_mfma_f32_16x16x32_bf16 v[78:81], v[170:173], v[214:217], v[78:81]
	v_mfma_f32_16x16x32_bf16 v[74:77], v[178:181], v[214:217], v[74:77]
	v_mfma_f32_16x16x32_bf16 v[70:73], v[170:173], v[222:225], v[70:73]
	s_barrier
	v_mfma_f32_16x16x32_bf16 v[66:69], v[178:181], v[222:225], v[66:69]
	s_setprio 2
	s_add_i32 s23, s23, s33
	v_lshl_add_u64 v[202:203], v[202:203], 0, s[10:11]
	s_mov_b32 m0, s23
	ds_read_b128 v[182:185], v148 offset:49152
	ds_read_b128 v[186:189], v148 offset:50176
	ds_read_b128 v[190:193], v148 offset:51200
	ds_read_b128 v[198:201], v148 offset:52224
	ds_read_b128 v[210:213], v148 offset:53248
	ds_read_b128 v[214:217], v148 offset:54272
	ds_read_b128 v[218:221], v148 offset:55296
	ds_read_b128 v[222:225], v148 offset:56320
	global_load_lds_dwordx4 v[202:203], off
	s_add_i32 m0, s23, 0x2000
	s_add_u32 s34, s34, 0x80080
	v_lshl_add_u64 v[202:203], v[206:207], 0, s[10:11]
	s_addc_u32 s35, s35, 0
	s_add_i32 s23, s38, s33
	global_load_lds_dwordx4 v[202:203], off
	v_lshl_add_u64 v[202:203], s[34:35], 0, v[132:133]
	s_mov_b32 m0, s23
	s_nop 0
	global_load_lds_dwordx4 v[202:203], off
	v_lshl_add_u64 v[202:203], s[34:35], 0, v[136:137]
	s_add_i32 m0, s23, 0x2000
	s_nop 0
	global_load_lds_dwordx4 v[202:203], off
	v_lshl_add_u64 v[202:203], v[226:227], 0, s[10:11]
	s_mov_b32 m0, s51
	s_nop 0
	global_load_lds_dwordx4 v[202:203], off
	v_lshl_add_u64 v[202:203], v[228:229], 0, s[10:11]
	s_mov_b32 m0, s52
	s_nop 0
	global_load_lds_dwordx4 v[202:203], off
	s_waitcnt vmcnt(8)
	s_waitcnt lgkmcnt(0)
	s_barrier
	s_setprio 1
	s_waitcnt lgkmcnt(0)
	v_mfma_f32_16x16x32_bf16 v[62:65], v[150:153], v[182:185], v[62:65]
	v_mfma_f32_16x16x32_bf16 v[58:61], v[158:161], v[182:185], v[58:61]
	v_mfma_f32_16x16x32_bf16 v[54:57], v[150:153], v[190:193], v[54:57]
	v_mfma_f32_16x16x32_bf16 v[50:53], v[158:161], v[190:193], v[50:53]
	v_mfma_f32_16x16x32_bf16 v[46:49], v[150:153], v[210:213], v[46:49]
	v_mfma_f32_16x16x32_bf16 v[42:45], v[158:161], v[210:213], v[42:45]
	v_mfma_f32_16x16x32_bf16 v[38:41], v[150:153], v[218:221], v[38:41]
	v_mfma_f32_16x16x32_bf16 v[34:37], v[158:161], v[218:221], v[34:37]
	v_mfma_f32_16x16x32_bf16 v[62:65], v[154:157], v[186:189], v[62:65]
	v_mfma_f32_16x16x32_bf16 v[58:61], v[162:165], v[186:189], v[58:61]
	v_mfma_f32_16x16x32_bf16 v[54:57], v[154:157], v[198:201], v[54:57]
	v_mfma_f32_16x16x32_bf16 v[50:53], v[162:165], v[198:201], v[50:53]
	v_mfma_f32_16x16x32_bf16 v[46:49], v[154:157], v[214:217], v[46:49]
	v_mfma_f32_16x16x32_bf16 v[42:45], v[162:165], v[214:217], v[42:45]
	v_mfma_f32_16x16x32_bf16 v[38:41], v[154:157], v[222:225], v[38:41]
	v_mfma_f32_16x16x32_bf16 v[34:37], v[162:165], v[222:225], v[34:37]
	v_mfma_f32_16x16x32_bf16 v[30:33], v[166:169], v[182:185], v[30:33]
	v_mfma_f32_16x16x32_bf16 v[26:29], v[174:177], v[182:185], v[26:29]
	v_mfma_f32_16x16x32_bf16 v[22:25], v[166:169], v[190:193], v[22:25]
	v_mfma_f32_16x16x32_bf16 v[18:21], v[174:177], v[190:193], v[18:21]
	v_mfma_f32_16x16x32_bf16 v[14:17], v[166:169], v[210:213], v[14:17]
	v_mfma_f32_16x16x32_bf16 v[10:13], v[174:177], v[210:213], v[10:13]
	v_mfma_f32_16x16x32_bf16 v[6:9], v[166:169], v[218:221], v[6:9]
	v_mfma_f32_16x16x32_bf16 v[2:5], v[174:177], v[218:221], v[2:5]
	v_mfma_f32_16x16x32_bf16 v[30:33], v[170:173], v[186:189], v[30:33]
	v_mfma_f32_16x16x32_bf16 v[26:29], v[178:181], v[186:189], v[26:29]
	v_mfma_f32_16x16x32_bf16 v[22:25], v[170:173], v[198:201], v[22:25]
	v_mfma_f32_16x16x32_bf16 v[18:21], v[178:181], v[198:201], v[18:21]
	v_mfma_f32_16x16x32_bf16 v[14:17], v[170:173], v[214:217], v[14:17]
	v_mfma_f32_16x16x32_bf16 v[10:13], v[178:181], v[214:217], v[10:13]
	v_mfma_f32_16x16x32_bf16 v[6:9], v[170:173], v[222:225], v[6:9]
	s_barrier
	v_mfma_f32_16x16x32_bf16 v[2:5], v[178:181], v[222:225], v[2:5]
	s_setprio 2
	s_add_u32 s30, s30, 0x100
	s_addc_u32 s31, s31, 0
	s_add_u32 s19, s19, 0x100
	s_addc_u32 s21, s21, 0
	s_cmp_ge_i32 s29, s68
	s_mov_b32 s23, s29
	s_cbranch_scc0 .LBB0_1973

.Lpeel_1:
	ds_read_b128 v[152:155], v148
	ds_read_b128 v[156:159], v148 offset:1024
	s_add_i32 s29, s19, 2
	s_add_u32 s34, s30, 0xfff80080
	s_addc_u32 s35, s31, -1
	s_cmp_eq_u32 s28, s19
	s_cselect_b32 s37, s21, s35
	s_cselect_b32 s36, s20, s34
	s_cselect_b32 s35, s23, s17
	s_cselect_b32 s34, s22, s15
	v_lshl_add_u64 v[144:145], s[30:31], 0, v[140:141]
	s_add_i32 m0, s27, 0xc000
	global_load_lds_dwordx4 v[144:145], off
	v_lshl_add_u64 v[144:145], s[30:31], 0, v[142:143]
	s_add_i32 m0, s27, 0xe000
	s_nop 0
	global_load_lds_dwordx4 v[144:145], off
	s_waitcnt vmcnt(8)
	s_waitcnt lgkmcnt(0)
	s_barrier
	s_setprio 1
	s_waitcnt lgkmcnt(0)
	v_mfma_f32_16x16x32_bf16 v[126:129], v[152:155], v[184:187], 0
	v_mfma_f32_16x16x32_bf16 v[122:125], v[160:163], v[184:187], 0
	v_mfma_f32_16x16x32_bf16 v[110:113], v[152:155], v[192:195], 0
	v_mfma_f32_16x16x32_bf16 v[106:109], v[160:163], v[192:195], 0
	v_mfma_f32_16x16x32_bf16 v[94:97], v[152:155], v[210:213], 0
	v_mfma_f32_16x16x32_bf16 v[90:93], v[160:163], v[210:213], 0
	v_mfma_f32_16x16x32_bf16 v[78:81], v[152:155], v[218:221], 0
	v_mfma_f32_16x16x32_bf16 v[74:77], v[160:163], v[218:221], 0
	v_mfma_f32_16x16x32_bf16 v[126:129], v[156:159], v[188:191], v[126:129]
	v_mfma_f32_16x16x32_bf16 v[122:125], v[164:167], v[188:191], v[122:125]
	v_mfma_f32_16x16x32_bf16 v[110:113], v[156:159], v[198:201], v[110:113]
	v_mfma_f32_16x16x32_bf16 v[106:109], v[164:167], v[198:201], v[106:109]
	v_mfma_f32_16x16x32_bf16 v[94:97], v[156:159], v[214:217], v[94:97]
	v_mfma_f32_16x16x32_bf16 v[90:93], v[164:167], v[214:217], v[90:93]
	v_mfma_f32_16x16x32_bf16 v[78:81], v[156:159], v[222:225], v[78:81]
	v_mfma_f32_16x16x32_bf16 v[74:77], v[164:167], v[222:225], v[74:77]
	v_mfma_f32_16x16x32_bf16 v[118:121], v[168:171], v[184:187], 0
	v_mfma_f32_16x16x32_bf16 v[114:117], v[176:179], v[184:187], 0
	v_mfma_f32_16x16x32_bf16 v[102:105], v[168:171], v[192:195], 0
	v_mfma_f32_16x16x32_bf16 v[98:101], v[176:179], v[192:195], 0
	v_mfma_f32_16x16x32_bf16 v[86:89], v[168:171], v[210:213], 0
	v_mfma_f32_16x16x32_bf16 v[82:85], v[176:179], v[210:213], 0
	v_mfma_f32_16x16x32_bf16 v[70:73], v[168:171], v[218:221], 0
	v_mfma_f32_16x16x32_bf16 v[66:69], v[176:179], v[218:221], 0
	v_mfma_f32_16x16x32_bf16 v[118:121], v[172:175], v[188:191], v[118:121]
	v_mfma_f32_16x16x32_bf16 v[114:117], v[180:183], v[188:191], v[114:117]
	v_mfma_f32_16x16x32_bf16 v[102:105], v[172:175], v[198:201], v[102:105]
	v_mfma_f32_16x16x32_bf16 v[98:101], v[180:183], v[198:201], v[98:101]
	v_mfma_f32_16x16x32_bf16 v[86:89], v[172:175], v[214:217], v[86:89]
	v_mfma_f32_16x16x32_bf16 v[82:85], v[180:183], v[214:217], v[82:85]
	v_mfma_f32_16x16x32_bf16 v[70:73], v[172:175], v[222:225], v[70:73]
	s_barrier
	v_mfma_f32_16x16x32_bf16 v[66:69], v[180:183], v[222:225], v[66:69]
	s_setprio 2
	s_add_i32 s19, s60, s33
	v_lshl_add_u64 v[144:145], s[34:35], 0, v[132:133]
	s_mov_b32 m0, s19
	ds_read_b128 v[184:187], v150 offset:16384
	ds_read_b128 v[188:191], v150 offset:17408
	ds_read_b128 v[192:195], v150 offset:18432
	ds_read_b128 v[198:201], v150 offset:19456
	ds_read_b128 v[210:213], v150 offset:20480
	ds_read_b128 v[214:217], v150 offset:21504
	ds_read_b128 v[218:221], v150 offset:22528
	ds_read_b128 v[222:225], v150 offset:23552
	global_load_lds_dwordx4 v[144:145], off
	s_add_i32 m0, s19, 0x2000
	s_add_u32 s38, s34, 0x80000
	v_lshl_add_u64 v[202:203], s[34:35], 0, v[136:137]
	s_addc_u32 s39, s35, 0
	s_add_i32 s19, s61, s33
	global_load_lds_dwordx4 v[202:203], off
	v_lshl_add_u64 v[206:207], s[38:39], 0, v[132:133]
	s_mov_b32 m0, s19
	v_lshl_add_u64 v[226:227], s[36:37], 0, v[134:135]
	global_load_lds_dwordx4 v[206:207], off
	v_lshl_add_u64 v[206:207], s[38:39], 0, v[136:137]
	s_add_i32 m0, s19, 0x2000
	s_nop 0
	global_load_lds_dwordx4 v[206:207], off
	v_lshl_add_u64 v[206:207], s[36:37], 0, v[130:131]
	s_mov_b32 m0, s27
	s_nop 0
	global_load_lds_dwordx4 v[206:207], off
	s_mov_b32 m0, s41
	s_nop 0
	global_load_lds_dwordx4 v[226:227], off
	s_waitcnt vmcnt(8)
	s_waitcnt lgkmcnt(0)
	s_barrier
	s_setprio 1
	s_waitcnt lgkmcnt(0)
	v_mfma_f32_16x16x32_bf16 v[62:65], v[152:155], v[184:187], 0
	v_mfma_f32_16x16x32_bf16 v[58:61], v[160:163], v[184:187], 0
	v_mfma_f32_16x16x32_bf16 v[46:49], v[152:155], v[192:195], 0
	v_mfma_f32_16x16x32_bf16 v[42:45], v[160:163], v[192:195], 0
	v_mfma_f32_16x16x32_bf16 v[30:33], v[152:155], v[210:213], 0
	v_mfma_f32_16x16x32_bf16 v[26:29], v[160:163], v[210:213], 0
	v_mfma_f32_16x16x32_bf16 v[14:17], v[152:155], v[218:221], 0
	v_mfma_f32_16x16x32_bf16 v[10:13], v[160:163], v[218:221], 0
	v_mfma_f32_16x16x32_bf16 v[62:65], v[156:159], v[188:191], v[62:65]
	v_mfma_f32_16x16x32_bf16 v[58:61], v[164:167], v[188:191], v[58:61]
	v_mfma_f32_16x16x32_bf16 v[46:49], v[156:159], v[198:201], v[46:49]
	v_mfma_f32_16x16x32_bf16 v[42:45], v[164:167], v[198:201], v[42:45]
	v_mfma_f32_16x16x32_bf16 v[30:33], v[156:159], v[214:217], v[30:33]
	v_mfma_f32_16x16x32_bf16 v[26:29], v[164:167], v[214:217], v[26:29]
	v_mfma_f32_16x16x32_bf16 v[14:17], v[156:159], v[222:225], v[14:17]
	v_mfma_f32_16x16x32_bf16 v[10:13], v[164:167], v[222:225], v[10:13]
	v_mfma_f32_16x16x32_bf16 v[54:57], v[168:171], v[184:187], 0
	v_mfma_f32_16x16x32_bf16 v[50:53], v[176:179], v[184:187], 0
	v_mfma_f32_16x16x32_bf16 v[38:41], v[168:171], v[192:195], 0
	v_mfma_f32_16x16x32_bf16 v[34:37], v[176:179], v[192:195], 0
	v_mfma_f32_16x16x32_bf16 v[22:25], v[168:171], v[210:213], 0
	v_mfma_f32_16x16x32_bf16 v[18:21], v[176:179], v[210:213], 0
	v_mfma_f32_16x16x32_bf16 v[6:9], v[168:171], v[218:221], 0
	v_mfma_f32_16x16x32_bf16 v[2:5], v[176:179], v[218:221], 0
	v_mfma_f32_16x16x32_bf16 v[54:57], v[172:175], v[188:191], v[54:57]
	v_mfma_f32_16x16x32_bf16 v[50:53], v[180:183], v[188:191], v[50:53]
	v_mfma_f32_16x16x32_bf16 v[38:41], v[172:175], v[198:201], v[38:41]
	v_mfma_f32_16x16x32_bf16 v[34:37], v[180:183], v[198:201], v[34:37]
	v_mfma_f32_16x16x32_bf16 v[22:25], v[172:175], v[214:217], v[22:25]
	v_mfma_f32_16x16x32_bf16 v[18:21], v[180:183], v[214:217], v[18:21]
	v_mfma_f32_16x16x32_bf16 v[6:9], v[172:175], v[222:225], v[6:9]
	s_barrier
	v_mfma_f32_16x16x32_bf16 v[2:5], v[180:183], v[222:225], v[2:5]
	s_setprio 2
	s_add_i32 s19, 0, 0x18000
	v_add_u32_e32 v151, s19, v146
	s_add_i32 s38, 0, 0x1c000
	ds_read_b128 v[152:155], v151
	ds_read_b128 v[156:159], v151 offset:1024
	ds_read_b128 v[160:163], v151 offset:2048
	ds_read_b128 v[164:167], v151 offset:3072
	v_add_u32_e32 v151, s38, v146
	ds_read_b128 v[168:171], v151
	ds_read_b128 v[172:175], v151 offset:1024
	ds_read_b128 v[176:179], v151 offset:2048
	ds_read_b128 v[180:183], v151 offset:3072
	s_add_u32 s36, s36, 0x80000
	s_addc_u32 s37, s37, 0
	s_mov_b32 m0, s42
	v_lshl_add_u64 v[228:229], s[36:37], 0, v[130:131]
	ds_read_b128 v[184:187], v150 offset:32768
	ds_read_b128 v[188:191], v150 offset:33792
	ds_read_b128 v[192:195], v150 offset:34816
	ds_read_b128 v[198:201], v150 offset:35840
	ds_read_b128 v[210:213], v150 offset:36864
	ds_read_b128 v[214:217], v150 offset:37888
	ds_read_b128 v[218:221], v150 offset:38912
	ds_read_b128 v[222:225], v150 offset:39936
	global_load_lds_dwordx4 v[228:229], off
	v_lshl_add_u64 v[228:229], s[36:37], 0, v[134:135]
	s_mov_b32 m0, s43
	s_nop 0
	global_load_lds_dwordx4 v[228:229], off
	s_waitcnt vmcnt(8)
	s_waitcnt lgkmcnt(0)
	s_barrier
	s_setprio 1
	s_waitcnt lgkmcnt(0)
	v_mfma_f32_16x16x32_bf16 v[126:129], v[152:155], v[184:187], v[126:129]
	v_mfma_f32_16x16x32_bf16 v[122:125], v[160:163], v[184:187], v[122:125]
	v_mfma_f32_16x16x32_bf16 v[110:113], v[152:155], v[192:195], v[110:113]
	v_mfma_f32_16x16x32_bf16 v[106:109], v[160:163], v[192:195], v[106:109]
	v_mfma_f32_16x16x32_bf16 v[94:97], v[152:155], v[210:213], v[94:97]
	v_mfma_f32_16x16x32_bf16 v[90:93], v[160:163], v[210:213], v[90:93]
	v_mfma_f32_16x16x32_bf16 v[78:81], v[152:155], v[218:221], v[78:81]
	v_mfma_f32_16x16x32_bf16 v[74:77], v[160:163], v[218:221], v[74:77]
	v_mfma_f32_16x16x32_bf16 v[126:129], v[156:159], v[188:191], v[126:129]
	v_mfma_f32_16x16x32_bf16 v[122:125], v[164:167], v[188:191], v[122:125]
	v_mfma_f32_16x16x32_bf16 v[110:113], v[156:159], v[198:201], v[110:113]
	v_mfma_f32_16x16x32_bf16 v[106:109], v[164:167], v[198:201], v[106:109]
	v_mfma_f32_16x16x32_bf16 v[94:97], v[156:159], v[214:217], v[94:97]
	v_mfma_f32_16x16x32_bf16 v[90:93], v[164:167], v[214:217], v[90:93]
	v_mfma_f32_16x16x32_bf16 v[78:81], v[156:159], v[222:225], v[78:81]
	v_mfma_f32_16x16x32_bf16 v[74:77], v[164:167], v[222:225], v[74:77]
	v_mfma_f32_16x16x32_bf16 v[118:121], v[168:171], v[184:187], v[118:121]
	v_mfma_f32_16x16x32_bf16 v[114:117], v[176:179], v[184:187], v[114:117]
	v_mfma_f32_16x16x32_bf16 v[102:105], v[168:171], v[192:195], v[102:105]
	v_mfma_f32_16x16x32_bf16 v[98:101], v[176:179], v[192:195], v[98:101]
	v_mfma_f32_16x16x32_bf16 v[86:89], v[168:171], v[210:213], v[86:89]
	v_mfma_f32_16x16x32_bf16 v[82:85], v[176:179], v[210:213], v[82:85]
	v_mfma_f32_16x16x32_bf16 v[70:73], v[168:171], v[218:221], v[70:73]
	v_mfma_f32_16x16x32_bf16 v[66:69], v[176:179], v[218:221], v[66:69]
	v_mfma_f32_16x16x32_bf16 v[118:121], v[172:175], v[188:191], v[118:121]
	v_mfma_f32_16x16x32_bf16 v[114:117], v[180:183], v[188:191], v[114:117]
	v_mfma_f32_16x16x32_bf16 v[102:105], v[172:175], v[198:201], v[102:105]
	v_mfma_f32_16x16x32_bf16 v[98:101], v[180:183], v[198:201], v[98:101]
	v_mfma_f32_16x16x32_bf16 v[86:89], v[172:175], v[214:217], v[86:89]
	v_mfma_f32_16x16x32_bf16 v[82:85], v[180:183], v[214:217], v[82:85]
	v_mfma_f32_16x16x32_bf16 v[70:73], v[172:175], v[222:225], v[70:73]
	s_barrier
	v_mfma_f32_16x16x32_bf16 v[66:69], v[180:183], v[222:225], v[66:69]
	s_setprio 2
	s_add_i32 s19, s19, s33
	v_lshl_add_u64 v[144:145], v[144:145], 0, s[10:11]
	s_mov_b32 m0, s19
	ds_read_b128 v[184:187], v150 offset:49152
	ds_read_b128 v[188:191], v150 offset:50176
	ds_read_b128 v[192:195], v150 offset:51200
	ds_read_b128 v[198:201], v150 offset:52224
	ds_read_b128 v[210:213], v150 offset:53248
	ds_read_b128 v[214:217], v150 offset:54272
	ds_read_b128 v[218:221], v150 offset:55296
	ds_read_b128 v[222:225], v150 offset:56320
	global_load_lds_dwordx4 v[144:145], off
	s_add_i32 m0, s19, 0x2000
	s_add_u32 s34, s34, 0x80080
	v_lshl_add_u64 v[144:145], v[202:203], 0, s[10:11]
	s_addc_u32 s35, s35, 0
	s_add_i32 s19, s38, s33
	global_load_lds_dwordx4 v[144:145], off
	v_lshl_add_u64 v[144:145], s[34:35], 0, v[132:133]
	s_mov_b32 m0, s19
	s_nop 0
	global_load_lds_dwordx4 v[144:145], off
	v_lshl_add_u64 v[144:145], s[34:35], 0, v[136:137]
	s_add_i32 m0, s19, 0x2000
	s_nop 0
	global_load_lds_dwordx4 v[144:145], off
	v_lshl_add_u64 v[144:145], v[206:207], 0, s[10:11]
	s_mov_b32 m0, s51
	s_nop 0
	global_load_lds_dwordx4 v[144:145], off
	v_lshl_add_u64 v[144:145], v[226:227], 0, s[10:11]
	s_mov_b32 m0, s52
	s_nop 0
	global_load_lds_dwordx4 v[144:145], off
	s_waitcnt vmcnt(8)
	s_waitcnt lgkmcnt(0)
	s_barrier
	s_setprio 1
	s_waitcnt lgkmcnt(0)
	v_mfma_f32_16x16x32_bf16 v[62:65], v[152:155], v[184:187], v[62:65]
	v_mfma_f32_16x16x32_bf16 v[58:61], v[160:163], v[184:187], v[58:61]
	v_mfma_f32_16x16x32_bf16 v[46:49], v[152:155], v[192:195], v[46:49]
	v_mfma_f32_16x16x32_bf16 v[42:45], v[160:163], v[192:195], v[42:45]
	v_mfma_f32_16x16x32_bf16 v[30:33], v[152:155], v[210:213], v[30:33]
	v_mfma_f32_16x16x32_bf16 v[26:29], v[160:163], v[210:213], v[26:29]
	v_mfma_f32_16x16x32_bf16 v[14:17], v[152:155], v[218:221], v[14:17]
	v_mfma_f32_16x16x32_bf16 v[10:13], v[160:163], v[218:221], v[10:13]
	v_mfma_f32_16x16x32_bf16 v[62:65], v[156:159], v[188:191], v[62:65]
	v_mfma_f32_16x16x32_bf16 v[58:61], v[164:167], v[188:191], v[58:61]
	v_mfma_f32_16x16x32_bf16 v[46:49], v[156:159], v[198:201], v[46:49]
	v_mfma_f32_16x16x32_bf16 v[42:45], v[164:167], v[198:201], v[42:45]
	v_mfma_f32_16x16x32_bf16 v[30:33], v[156:159], v[214:217], v[30:33]
	v_mfma_f32_16x16x32_bf16 v[26:29], v[164:167], v[214:217], v[26:29]
	v_mfma_f32_16x16x32_bf16 v[14:17], v[156:159], v[222:225], v[14:17]
	v_mfma_f32_16x16x32_bf16 v[10:13], v[164:167], v[222:225], v[10:13]
	v_mfma_f32_16x16x32_bf16 v[54:57], v[168:171], v[184:187], v[54:57]
	v_mfma_f32_16x16x32_bf16 v[50:53], v[176:179], v[184:187], v[50:53]
	v_mfma_f32_16x16x32_bf16 v[38:41], v[168:171], v[192:195], v[38:41]
	v_mfma_f32_16x16x32_bf16 v[34:37], v[176:179], v[192:195], v[34:37]
	v_mfma_f32_16x16x32_bf16 v[22:25], v[168:171], v[210:213], v[22:25]
	v_mfma_f32_16x16x32_bf16 v[18:21], v[176:179], v[210:213], v[18:21]
	v_mfma_f32_16x16x32_bf16 v[6:9], v[168:171], v[218:221], v[6:9]
	v_mfma_f32_16x16x32_bf16 v[2:5], v[176:179], v[218:221], v[2:5]
	v_mfma_f32_16x16x32_bf16 v[54:57], v[172:175], v[188:191], v[54:57]
	v_mfma_f32_16x16x32_bf16 v[50:53], v[180:183], v[188:191], v[50:53]
	v_mfma_f32_16x16x32_bf16 v[38:41], v[172:175], v[198:201], v[38:41]
	v_mfma_f32_16x16x32_bf16 v[34:37], v[180:183], v[198:201], v[34:37]
	v_mfma_f32_16x16x32_bf16 v[22:25], v[172:175], v[214:217], v[22:25]
	v_mfma_f32_16x16x32_bf16 v[18:21], v[180:183], v[214:217], v[18:21]
	v_mfma_f32_16x16x32_bf16 v[6:9], v[172:175], v[222:225], v[6:9]
	s_barrier
	v_mfma_f32_16x16x32_bf16 v[2:5], v[180:183], v[222:225], v[2:5]
	s_setprio 2
	s_add_u32 s30, s30, 0x100
	s_addc_u32 s31, s31, 0
	s_add_u32 s15, s15, 0x100
	s_addc_u32 s17, s17, 0
	s_cmp_ge_i32 s29, s68
	s_mov_b32 s19, s29
	s_cbranch_scc0 .LBB0_2547
	s_branch .Lpeeldone_1
.LBB0_2547:
	ds_read_b128 v[152:155], v148
	ds_read_b128 v[156:159], v148 offset:1024
	ds_read_b128 v[160:163], v148 offset:2048
	ds_read_b128 v[164:167], v148 offset:3072
	ds_read_b128 v[168:171], v149
	ds_read_b128 v[172:175], v149 offset:1024
	ds_read_b128 v[176:179], v149 offset:2048
	ds_read_b128 v[180:183], v149 offset:3072
	s_add_i32 s29, s19, 2
	s_add_u32 s34, s30, 0xfff80080
	s_addc_u32 s35, s31, -1
	s_cmp_eq_u32 s28, s19
	s_cselect_b32 s37, s21, s35
	s_cselect_b32 s36, s20, s34
	s_cselect_b32 s35, s23, s17
	s_cselect_b32 s34, s22, s15
	v_lshl_add_u64 v[144:145], s[30:31], 0, v[140:141]
	s_add_i32 m0, s27, 0xc000
	ds_read_b128 v[184:187], v150
	ds_read_b128 v[188:191], v150 offset:1024
	ds_read_b128 v[192:195], v150 offset:2048
	ds_read_b128 v[198:201], v150 offset:3072
	ds_read_b128 v[210:213], v150 offset:4096
	ds_read_b128 v[214:217], v150 offset:5120
	ds_read_b128 v[218:221], v150 offset:6144
	ds_read_b128 v[222:225], v150 offset:7168
	global_load_lds_dwordx4 v[144:145], off
	v_lshl_add_u64 v[144:145], s[30:31], 0, v[142:143]
	s_add_i32 m0, s27, 0xe000
	s_nop 0
	global_load_lds_dwordx4 v[144:145], off
	s_waitcnt vmcnt(8)
	s_waitcnt lgkmcnt(0)
	s_barrier
	s_setprio 1
	s_waitcnt lgkmcnt(0)
	v_mfma_f32_16x16x32_bf16 v[126:129], v[152:155], v[184:187], v[126:129]
	v_mfma_f32_16x16x32_bf16 v[122:125], v[160:163], v[184:187], v[122:125]
	v_mfma_f32_16x16x32_bf16 v[110:113], v[152:155], v[192:195], v[110:113]
	v_mfma_f32_16x16x32_bf16 v[106:109], v[160:163], v[192:195], v[106:109]
	v_mfma_f32_16x16x32_bf16 v[94:97], v[152:155], v[210:213], v[94:97]
	v_mfma_f32_16x16x32_bf16 v[90:93], v[160:163], v[210:213], v[90:93]
	v_mfma_f32_16x16x32_bf16 v[78:81], v[152:155], v[218:221], v[78:81]
	v_mfma_f32_16x16x32_bf16 v[74:77], v[160:163], v[218:221], v[74:77]
	v_mfma_f32_16x16x32_bf16 v[126:129], v[156:159], v[188:191], v[126:129]
	v_mfma_f32_16x16x32_bf16 v[122:125], v[164:167], v[188:191], v[122:125]
	v_mfma_f32_16x16x32_bf16 v[110:113], v[156:159], v[198:201], v[110:113]
	v_mfma_f32_16x16x32_bf16 v[106:109], v[164:167], v[198:201], v[106:109]
	v_mfma_f32_16x16x32_bf16 v[94:97], v[156:159], v[214:217], v[94:97]
	v_mfma_f32_16x16x32_bf16 v[90:93], v[164:167], v[214:217], v[90:93]
	v_mfma_f32_16x16x32_bf16 v[78:81], v[156:159], v[222:225], v[78:81]
	v_mfma_f32_16x16x32_bf16 v[74:77], v[164:167], v[222:225], v[74:77]
	v_mfma_f32_16x16x32_bf16 v[118:121], v[168:171], v[184:187], v[118:121]
	v_mfma_f32_16x16x32_bf16 v[114:117], v[176:179], v[184:187], v[114:117]
	v_mfma_f32_16x16x32_bf16 v[102:105], v[168:171], v[192:195], v[102:105]
	v_mfma_f32_16x16x32_bf16 v[98:101], v[176:179], v[192:195], v[98:101]
	v_mfma_f32_16x16x32_bf16 v[86:89], v[168:171], v[210:213], v[86:89]
	v_mfma_f32_16x16x32_bf16 v[82:85], v[176:179], v[210:213], v[82:85]
	v_mfma_f32_16x16x32_bf16 v[70:73], v[168:171], v[218:221], v[70:73]
	v_mfma_f32_16x16x32_bf16 v[66:69], v[176:179], v[218:221], v[66:69]
	v_mfma_f32_16x16x32_bf16 v[118:121], v[172:175], v[188:191], v[118:121]
	v_mfma_f32_16x16x32_bf16 v[114:117], v[180:183], v[188:191], v[114:117]
	v_mfma_f32_16x16x32_bf16 v[102:105], v[172:175], v[198:201], v[102:105]
	v_mfma_f32_16x16x32_bf16 v[98:101], v[180:183], v[198:201], v[98:101]
	v_mfma_f32_16x16x32_bf16 v[86:89], v[172:175], v[214:217], v[86:89]
	v_mfma_f32_16x16x32_bf16 v[82:85], v[180:183], v[214:217], v[82:85]
	v_mfma_f32_16x16x32_bf16 v[70:73], v[172:175], v[222:225], v[70:73]
	s_barrier
	v_mfma_f32_16x16x32_bf16 v[66:69], v[180:183], v[222:225], v[66:69]
	s_setprio 2
	s_add_i32 s19, s60, s33
	v_lshl_add_u64 v[144:145], s[34:35], 0, v[132:133]
	s_mov_b32 m0, s19
	ds_read_b128 v[184:187], v150 offset:16384
	ds_read_b128 v[188:191], v150 offset:17408
	ds_read_b128 v[192:195], v150 offset:18432
	ds_read_b128 v[198:201], v150 offset:19456
	ds_read_b128 v[210:213], v150 offset:20480
	ds_read_b128 v[214:217], v150 offset:21504
	ds_read_b128 v[218:221], v150 offset:22528
	ds_read_b128 v[222:225], v150 offset:23552
	global_load_lds_dwordx4 v[144:145], off
	s_add_i32 m0, s19, 0x2000
	s_add_u32 s38, s34, 0x80000
	v_lshl_add_u64 v[202:203], s[34:35], 0, v[136:137]
	s_addc_u32 s39, s35, 0
	s_add_i32 s19, s61, s33
	global_load_lds_dwordx4 v[202:203], off
	v_lshl_add_u64 v[206:207], s[38:39], 0, v[132:133]
	s_mov_b32 m0, s19
	v_lshl_add_u64 v[226:227], s[36:37], 0, v[134:135]
	global_load_lds_dwordx4 v[206:207], off
	v_lshl_add_u64 v[206:207], s[38:39], 0, v[136:137]
	s_add_i32 m0, s19, 0x2000
	s_nop 0
	global_load_lds_dwordx4 v[206:207], off
	v_lshl_add_u64 v[206:207], s[36:37], 0, v[130:131]
	s_mov_b32 m0, s27
	s_nop 0
	global_load_lds_dwordx4 v[206:207], off
	s_mov_b32 m0, s41
	s_nop 0
	global_load_lds_dwordx4 v[226:227], off
	s_waitcnt vmcnt(8)
	s_waitcnt lgkmcnt(0)
	s_barrier
	s_setprio 1
	s_waitcnt lgkmcnt(0)
	v_mfma_f32_16x16x32_bf16 v[62:65], v[152:155], v[184:187], v[62:65]
	v_mfma_f32_16x16x32_bf16 v[58:61], v[160:163], v[184:187], v[58:61]
	v_mfma_f32_16x16x32_bf16 v[46:49], v[152:155], v[192:195], v[46:49]
	v_mfma_f32_16x16x32_bf16 v[42:45], v[160:163], v[192:195], v[42:45]
	v_mfma_f32_16x16x32_bf16 v[30:33], v[152:155], v[210:213], v[30:33]
	v_mfma_f32_16x16x32_bf16 v[26:29], v[160:163], v[210:213], v[26:29]
	v_mfma_f32_16x16x32_bf16 v[14:17], v[152:155], v[218:221], v[14:17]
	v_mfma_f32_16x16x32_bf16 v[10:13], v[160:163], v[218:221], v[10:13]
	v_mfma_f32_16x16x32_bf16 v[62:65], v[156:159], v[188:191], v[62:65]
	v_mfma_f32_16x16x32_bf16 v[58:61], v[164:167], v[188:191], v[58:61]
	v_mfma_f32_16x16x32_bf16 v[46:49], v[156:159], v[198:201], v[46:49]
	v_mfma_f32_16x16x32_bf16 v[42:45], v[164:167], v[198:201], v[42:45]
	v_mfma_f32_16x16x32_bf16 v[30:33], v[156:159], v[214:217], v[30:33]
	v_mfma_f32_16x16x32_bf16 v[26:29], v[164:167], v[214:217], v[26:29]
	v_mfma_f32_16x16x32_bf16 v[14:17], v[156:159], v[222:225], v[14:17]
	v_mfma_f32_16x16x32_bf16 v[10:13], v[164:167], v[222:225], v[10:13]
	v_mfma_f32_16x16x32_bf16 v[54:57], v[168:171], v[184:187], v[54:57]
	v_mfma_f32_16x16x32_bf16 v[50:53], v[176:179], v[184:187], v[50:53]
	v_mfma_f32_16x16x32_bf16 v[38:41], v[168:171], v[192:195], v[38:41]
	v_mfma_f32_16x16x32_bf16 v[34:37], v[176:179], v[192:195], v[34:37]
	v_mfma_f32_16x16x32_bf16 v[22:25], v[168:171], v[210:213], v[22:25]
	v_mfma_f32_16x16x32_bf16 v[18:21], v[176:179], v[210:213], v[18:21]
	v_mfma_f32_16x16x32_bf16 v[6:9], v[168:171], v[218:221], v[6:9]
	v_mfma_f32_16x16x32_bf16 v[2:5], v[176:179], v[218:221], v[2:5]
	v_mfma_f32_16x16x32_bf16 v[54:57], v[172:175], v[188:191], v[54:57]
	v_mfma_f32_16x16x32_bf16 v[50:53], v[180:183], v[188:191], v[50:53]
	v_mfma_f32_16x16x32_bf16 v[38:41], v[172:175], v[198:201], v[38:41]
	v_mfma_f32_16x16x32_bf16 v[34:37], v[180:183], v[198:201], v[34:37]
	v_mfma_f32_16x16x32_bf16 v[22:25], v[172:175], v[214:217], v[22:25]
	v_mfma_f32_16x16x32_bf16 v[18:21], v[180:183], v[214:217], v[18:21]
	v_mfma_f32_16x16x32_bf16 v[6:9], v[172:175], v[222:225], v[6:9]
	s_barrier
	v_mfma_f32_16x16x32_bf16 v[2:5], v[180:183], v[222:225], v[2:5]
	s_setprio 2
	s_add_i32 s19, 0, 0x18000
	v_add_u32_e32 v151, s19, v146
	s_add_i32 s38, 0, 0x1c000
	ds_read_b128 v[152:155], v151
	ds_read_b128 v[156:159], v151 offset:1024
	ds_read_b128 v[160:163], v151 offset:2048
	ds_read_b128 v[164:167], v151 offset:3072
	v_add_u32_e32 v151, s38, v146
	ds_read_b128 v[168:171], v151
	ds_read_b128 v[172:175], v151 offset:1024
	ds_read_b128 v[176:179], v151 offset:2048
	ds_read_b128 v[180:183], v151 offset:3072
	s_add_u32 s36, s36, 0x80000
	s_addc_u32 s37, s37, 0
	s_mov_b32 m0, s42
	v_lshl_add_u64 v[228:229], s[36:37], 0, v[130:131]
	ds_read_b128 v[184:187], v150 offset:32768
	ds_read_b128 v[188:191], v150 offset:33792
	ds_read_b128 v[192:195], v150 offset:34816
	ds_read_b128 v[198:201], v150 offset:35840
	ds_read_b128 v[210:213], v150 offset:36864
	ds_read_b128 v[214:217], v150 offset:37888
	ds_read_b128 v[218:221], v150 offset:38912
	ds_read_b128 v[222:225], v150 offset:39936
	global_load_lds_dwordx4 v[228:229], off
	v_lshl_add_u64 v[228:229], s[36:37], 0, v[134:135]
	s_mov_b32 m0, s43
	s_nop 0
	global_load_lds_dwordx4 v[228:229], off
	s_waitcnt vmcnt(8)
	s_waitcnt lgkmcnt(0)
	s_barrier
	s_setprio 1
	s_waitcnt lgkmcnt(0)
	v_mfma_f32_16x16x32_bf16 v[126:129], v[152:155], v[184:187], v[126:129]
	v_mfma_f32_16x16x32_bf16 v[122:125], v[160:163], v[184:187], v[122:125]
	v_mfma_f32_16x16x32_bf16 v[110:113], v[152:155], v[192:195], v[110:113]
	v_mfma_f32_16x16x32_bf16 v[106:109], v[160:163], v[192:195], v[106:109]
	v_mfma_f32_16x16x32_bf16 v[94:97], v[152:155], v[210:213], v[94:97]
	v_mfma_f32_16x16x32_bf16 v[90:93], v[160:163], v[210:213], v[90:93]
	v_mfma_f32_16x16x32_bf16 v[78:81], v[152:155], v[218:221], v[78:81]
	v_mfma_f32_16x16x32_bf16 v[74:77], v[160:163], v[218:221], v[74:77]
	v_mfma_f32_16x16x32_bf16 v[126:129], v[156:159], v[188:191], v[126:129]
	v_mfma_f32_16x16x32_bf16 v[122:125], v[164:167], v[188:191], v[122:125]
	v_mfma_f32_16x16x32_bf16 v[110:113], v[156:159], v[198:201], v[110:113]
	v_mfma_f32_16x16x32_bf16 v[106:109], v[164:167], v[198:201], v[106:109]
	v_mfma_f32_16x16x32_bf16 v[94:97], v[156:159], v[214:217], v[94:97]
	v_mfma_f32_16x16x32_bf16 v[90:93], v[164:167], v[214:217], v[90:93]
	v_mfma_f32_16x16x32_bf16 v[78:81], v[156:159], v[222:225], v[78:81]
	v_mfma_f32_16x16x32_bf16 v[74:77], v[164:167], v[222:225], v[74:77]
	v_mfma_f32_16x16x32_bf16 v[118:121], v[168:171], v[184:187], v[118:121]
	v_mfma_f32_16x16x32_bf16 v[114:117], v[176:179], v[184:187], v[114:117]
	v_mfma_f32_16x16x32_bf16 v[102:105], v[168:171], v[192:195], v[102:105]
	v_mfma_f32_16x16x32_bf16 v[98:101], v[176:179], v[192:195], v[98:101]
	v_mfma_f32_16x16x32_bf16 v[86:89], v[168:171], v[210:213], v[86:89]
	v_mfma_f32_16x16x32_bf16 v[82:85], v[176:179], v[210:213], v[82:85]
	v_mfma_f32_16x16x32_bf16 v[70:73], v[168:171], v[218:221], v[70:73]
	v_mfma_f32_16x16x32_bf16 v[66:69], v[176:179], v[218:221], v[66:69]
	v_mfma_f32_16x16x32_bf16 v[118:121], v[172:175], v[188:191], v[118:121]
	v_mfma_f32_16x16x32_bf16 v[114:117], v[180:183], v[188:191], v[114:117]
	v_mfma_f32_16x16x32_bf16 v[102:105], v[172:175], v[198:201], v[102:105]
	v_mfma_f32_16x16x32_bf16 v[98:101], v[180:183], v[198:201], v[98:101]
	v_mfma_f32_16x16x32_bf16 v[86:89], v[172:175], v[214:217], v[86:89]
	v_mfma_f32_16x16x32_bf16 v[82:85], v[180:183], v[214:217], v[82:85]
	v_mfma_f32_16x16x32_bf16 v[70:73], v[172:175], v[222:225], v[70:73]
	s_barrier
	v_mfma_f32_16x16x32_bf16 v[66:69], v[180:183], v[222:225], v[66:69]
	s_setprio 2
	s_add_i32 s19, s19, s33
	v_lshl_add_u64 v[144:145], v[144:145], 0, s[10:11]
	s_mov_b32 m0, s19
	ds_read_b128 v[184:187], v150 offset:49152
	ds_read_b128 v[188:191], v150 offset:50176
	ds_read_b128 v[192:195], v150 offset:51200
	ds_read_b128 v[198:201], v150 offset:52224
	ds_read_b128 v[210:213], v150 offset:53248
	ds_read_b128 v[214:217], v150 offset:54272
	ds_read_b128 v[218:221], v150 offset:55296
	ds_read_b128 v[222:225], v150 offset:56320
	global_load_lds_dwordx4 v[144:145], off
	s_add_i32 m0, s19, 0x2000
	s_add_u32 s34, s34, 0x80080
	v_lshl_add_u64 v[144:145], v[202:203], 0, s[10:11]
	s_addc_u32 s35, s35, 0
	s_add_i32 s19, s38, s33
	global_load_lds_dwordx4 v[144:145], off
	v_lshl_add_u64 v[144:145], s[34:35], 0, v[132:133]
	s_mov_b32 m0, s19
	s_nop 0
	global_load_lds_dwordx4 v[144:145], off
	v_lshl_add_u64 v[144:145], s[34:35], 0, v[136:137]
	s_add_i32 m0, s19, 0x2000
	s_nop 0
	global_load_lds_dwordx4 v[144:145], off
	v_lshl_add_u64 v[144:145], v[206:207], 0, s[10:11]
	s_mov_b32 m0, s51
	s_nop 0
	global_load_lds_dwordx4 v[144:145], off
	v_lshl_add_u64 v[144:145], v[226:227], 0, s[10:11]
	s_mov_b32 m0, s52
	s_nop 0
	global_load_lds_dwordx4 v[144:145], off
	s_waitcnt vmcnt(8)
	s_waitcnt lgkmcnt(0)
	s_barrier
	s_setprio 1
	s_waitcnt lgkmcnt(0)
	v_mfma_f32_16x16x32_bf16 v[62:65], v[152:155], v[184:187], v[62:65]
	v_mfma_f32_16x16x32_bf16 v[58:61], v[160:163], v[184:187], v[58:61]
	v_mfma_f32_16x16x32_bf16 v[46:49], v[152:155], v[192:195], v[46:49]
	v_mfma_f32_16x16x32_bf16 v[42:45], v[160:163], v[192:195], v[42:45]
	v_mfma_f32_16x16x32_bf16 v[30:33], v[152:155], v[210:213], v[30:33]
	v_mfma_f32_16x16x32_bf16 v[26:29], v[160:163], v[210:213], v[26:29]
	v_mfma_f32_16x16x32_bf16 v[14:17], v[152:155], v[218:221], v[14:17]
	v_mfma_f32_16x16x32_bf16 v[10:13], v[160:163], v[218:221], v[10:13]
	v_mfma_f32_16x16x32_bf16 v[62:65], v[156:159], v[188:191], v[62:65]
	v_mfma_f32_16x16x32_bf16 v[58:61], v[164:167], v[188:191], v[58:61]
	v_mfma_f32_16x16x32_bf16 v[46:49], v[156:159], v[198:201], v[46:49]
	v_mfma_f32_16x16x32_bf16 v[42:45], v[164:167], v[198:201], v[42:45]
	v_mfma_f32_16x16x32_bf16 v[30:33], v[156:159], v[214:217], v[30:33]
	v_mfma_f32_16x16x32_bf16 v[26:29], v[164:167], v[214:217], v[26:29]
	v_mfma_f32_16x16x32_bf16 v[14:17], v[156:159], v[222:225], v[14:17]
	v_mfma_f32_16x16x32_bf16 v[10:13], v[164:167], v[222:225], v[10:13]
	v_mfma_f32_16x16x32_bf16 v[54:57], v[168:171], v[184:187], v[54:57]
	v_mfma_f32_16x16x32_bf16 v[50:53], v[176:179], v[184:187], v[50:53]
	v_mfma_f32_16x16x32_bf16 v[38:41], v[168:171], v[192:195], v[38:41]
	v_mfma_f32_16x16x32_bf16 v[34:37], v[176:179], v[192:195], v[34:37]
	v_mfma_f32_16x16x32_bf16 v[22:25], v[168:171], v[210:213], v[22:25]
	v_mfma_f32_16x16x32_bf16 v[18:21], v[176:179], v[210:213], v[18:21]
	v_mfma_f32_16x16x32_bf16 v[6:9], v[168:171], v[218:221], v[6:9]
	v_mfma_f32_16x16x32_bf16 v[2:5], v[176:179], v[218:221], v[2:5]
	v_mfma_f32_16x16x32_bf16 v[54:57], v[172:175], v[188:191], v[54:57]
	v_mfma_f32_16x16x32_bf16 v[50:53], v[180:183], v[188:191], v[50:53]
	v_mfma_f32_16x16x32_bf16 v[38:41], v[172:175], v[198:201], v[38:41]
	v_mfma_f32_16x16x32_bf16 v[34:37], v[180:183], v[198:201], v[34:37]
	v_mfma_f32_16x16x32_bf16 v[22:25], v[172:175], v[214:217], v[22:25]
	v_mfma_f32_16x16x32_bf16 v[18:21], v[180:183], v[214:217], v[18:21]
	v_mfma_f32_16x16x32_bf16 v[6:9], v[172:175], v[222:225], v[6:9]
	s_barrier
	v_mfma_f32_16x16x32_bf16 v[2:5], v[180:183], v[222:225], v[2:5]
	s_setprio 2
	s_add_u32 s30, s30, 0x100
	s_addc_u32 s31, s31, 0
	s_add_u32 s15, s15, 0x100
	s_addc_u32 s17, s17, 0
	s_cmp_ge_i32 s29, s68
	s_mov_b32 s19, s29
	s_cbranch_scc0 .LBB0_2547

.Lpeel_0:
	ds_read_b128 v[144:147], v170
	ds_read_b128 v[148:151], v170 offset:1024
	ds_read_b128 v[152:155], v170 offset:2048
	ds_read_b128 v[156:159], v170 offset:3072
	ds_read_b128 v[160:163], v171
	ds_read_b128 v[164:167], v171 offset:1024
	ds_read_b128 v[174:177], v171 offset:2048
	ds_read_b128 v[178:181], v171 offset:3072
	s_add_i32 s30, s26, 2
	s_add_u32 s27, s24, 0xffea0080
	s_addc_u32 s28, s25, -1
	s_cmp_eq_u32 s22, s26
	s_cselect_b32 s26, s20, s17
	s_cselect_b32 s29, s19, s28
	s_cselect_b32 s28, s18, s27
	s_cselect_b32 s27, s21, s23
	v_lshl_add_u64 v[214:215], s[24:25], 0, v[140:141]
	s_add_i32 m0, s34, 0xc000
	ds_read_b128 v[182:185], v172
	ds_read_b128 v[186:189], v172 offset:1024
	ds_read_b128 v[190:193], v172 offset:2048
	ds_read_b128 v[194:197], v172 offset:3072
	ds_read_b128 v[198:201], v172 offset:4096
	ds_read_b128 v[202:205], v172 offset:5120
	ds_read_b128 v[206:209], v172 offset:6144
	ds_read_b128 v[210:213], v172 offset:7168
	global_load_lds_dwordx4 v[214:215], off
	v_lshl_add_u64 v[214:215], s[24:25], 0, v[142:143]
	s_add_i32 m0, s34, 0xe000
	s_nop 0
	global_load_lds_dwordx4 v[214:215], off
	s_waitcnt vmcnt(8)
	s_waitcnt lgkmcnt(0)
	s_barrier
	s_setprio 1
	s_waitcnt lgkmcnt(0)
	v_mfma_f32_16x16x32_bf16 v[126:129], v[144:147], v[182:185], 0
	v_mfma_f32_16x16x32_bf16 v[122:125], v[152:155], v[182:185], 0
	v_mfma_f32_16x16x32_bf16 v[118:121], v[144:147], v[190:193], 0
	v_mfma_f32_16x16x32_bf16 v[110:113], v[152:155], v[190:193], 0
	v_mfma_f32_16x16x32_bf16 v[94:97], v[144:147], v[198:201], 0
	v_mfma_f32_16x16x32_bf16 v[90:93], v[152:155], v[198:201], 0
	v_mfma_f32_16x16x32_bf16 v[82:85], v[144:147], v[206:209], 0
	v_mfma_f32_16x16x32_bf16 v[74:77], v[152:155], v[206:209], 0
	v_mfma_f32_16x16x32_bf16 v[126:129], v[148:151], v[186:189], v[126:129]
	v_mfma_f32_16x16x32_bf16 v[122:125], v[156:159], v[186:189], v[122:125]
	v_mfma_f32_16x16x32_bf16 v[118:121], v[148:151], v[194:197], v[118:121]
	v_mfma_f32_16x16x32_bf16 v[110:113], v[156:159], v[194:197], v[110:113]
	v_mfma_f32_16x16x32_bf16 v[94:97], v[148:151], v[202:205], v[94:97]
	v_mfma_f32_16x16x32_bf16 v[90:93], v[156:159], v[202:205], v[90:93]
	v_mfma_f32_16x16x32_bf16 v[82:85], v[148:151], v[210:213], v[82:85]
	v_mfma_f32_16x16x32_bf16 v[74:77], v[156:159], v[210:213], v[74:77]
	v_mfma_f32_16x16x32_bf16 v[114:117], v[160:163], v[182:185], 0
	v_mfma_f32_16x16x32_bf16 v[106:109], v[174:177], v[182:185], 0
	v_mfma_f32_16x16x32_bf16 v[102:105], v[160:163], v[190:193], 0
	v_mfma_f32_16x16x32_bf16 v[98:101], v[174:177], v[190:193], 0
	v_mfma_f32_16x16x32_bf16 v[86:89], v[160:163], v[198:201], 0
	v_mfma_f32_16x16x32_bf16 v[78:81], v[174:177], v[198:201], 0
	v_mfma_f32_16x16x32_bf16 v[70:73], v[160:163], v[206:209], 0
	v_mfma_f32_16x16x32_bf16 v[66:69], v[174:177], v[206:209], 0
	v_mfma_f32_16x16x32_bf16 v[114:117], v[164:167], v[186:189], v[114:117]
	v_mfma_f32_16x16x32_bf16 v[106:109], v[178:181], v[186:189], v[106:109]
	v_mfma_f32_16x16x32_bf16 v[102:105], v[164:167], v[194:197], v[102:105]
	v_mfma_f32_16x16x32_bf16 v[98:101], v[178:181], v[194:197], v[98:101]
	v_mfma_f32_16x16x32_bf16 v[86:89], v[164:167], v[202:205], v[86:89]
	v_mfma_f32_16x16x32_bf16 v[78:81], v[178:181], v[202:205], v[78:81]
	v_mfma_f32_16x16x32_bf16 v[70:73], v[164:167], v[210:213], v[70:73]
	s_barrier
	v_mfma_f32_16x16x32_bf16 v[66:69], v[178:181], v[210:213], v[66:69]
	s_setprio 2
	s_add_i32 s31, s57, s33
	v_lshl_add_u64 v[214:215], s[26:27], 0, v[132:133]
	s_mov_b32 m0, s31
	ds_read_b128 v[182:185], v172 offset:16384
	ds_read_b128 v[186:189], v172 offset:17408
	ds_read_b128 v[190:193], v172 offset:18432
	ds_read_b128 v[194:197], v172 offset:19456
	ds_read_b128 v[198:201], v172 offset:20480
	ds_read_b128 v[202:205], v172 offset:21504
	ds_read_b128 v[206:209], v172 offset:22528
	ds_read_b128 v[210:213], v172 offset:23552
	global_load_lds_dwordx4 v[214:215], off
	s_add_i32 m0, s31, 0x2000
	s_add_u32 s68, s26, 0x160000
	v_lshl_add_u64 v[216:217], s[26:27], 0, v[136:137]
	s_addc_u32 s69, s27, 0
	s_add_i32 s31, s58, s33
	global_load_lds_dwordx4 v[216:217], off
	v_lshl_add_u64 v[218:219], s[68:69], 0, v[132:133]
	s_mov_b32 m0, s31
	v_lshl_add_u64 v[220:221], s[28:29], 0, v[134:135]
	global_load_lds_dwordx4 v[218:219], off
	v_lshl_add_u64 v[218:219], s[68:69], 0, v[136:137]
	s_add_i32 m0, s31, 0x2000
	s_nop 0
	global_load_lds_dwordx4 v[218:219], off
	v_lshl_add_u64 v[218:219], s[28:29], 0, v[130:131]
	s_mov_b32 m0, s34
	s_nop 0
	global_load_lds_dwordx4 v[218:219], off
	s_mov_b32 m0, s35
	s_nop 0
	global_load_lds_dwordx4 v[220:221], off
	s_waitcnt vmcnt(8)
	s_waitcnt lgkmcnt(0)
	s_barrier
	s_setprio 1
	s_waitcnt lgkmcnt(0)
	v_mfma_f32_16x16x32_bf16 v[62:65], v[144:147], v[182:185], 0
	v_mfma_f32_16x16x32_bf16 v[58:61], v[152:155], v[182:185], 0
	v_mfma_f32_16x16x32_bf16 v[50:53], v[144:147], v[190:193], 0
	v_mfma_f32_16x16x32_bf16 v[42:45], v[152:155], v[190:193], 0
	v_mfma_f32_16x16x32_bf16 v[30:33], v[144:147], v[198:201], 0
	v_mfma_f32_16x16x32_bf16 v[26:29], v[152:155], v[198:201], 0
	v_mfma_f32_16x16x32_bf16 v[18:21], v[144:147], v[206:209], 0
	v_mfma_f32_16x16x32_bf16 v[10:13], v[152:155], v[206:209], 0
	v_mfma_f32_16x16x32_bf16 v[62:65], v[148:151], v[186:189], v[62:65]
	v_mfma_f32_16x16x32_bf16 v[58:61], v[156:159], v[186:189], v[58:61]
	v_mfma_f32_16x16x32_bf16 v[50:53], v[148:151], v[194:197], v[50:53]
	v_mfma_f32_16x16x32_bf16 v[42:45], v[156:159], v[194:197], v[42:45]
	v_mfma_f32_16x16x32_bf16 v[30:33], v[148:151], v[202:205], v[30:33]
	v_mfma_f32_16x16x32_bf16 v[26:29], v[156:159], v[202:205], v[26:29]
	v_mfma_f32_16x16x32_bf16 v[18:21], v[148:151], v[210:213], v[18:21]
	v_mfma_f32_16x16x32_bf16 v[10:13], v[156:159], v[210:213], v[10:13]
	v_mfma_f32_16x16x32_bf16 v[54:57], v[160:163], v[182:185], 0
	v_mfma_f32_16x16x32_bf16 v[46:49], v[174:177], v[182:185], 0
	v_mfma_f32_16x16x32_bf16 v[38:41], v[160:163], v[190:193], 0
	v_mfma_f32_16x16x32_bf16 v[34:37], v[174:177], v[190:193], 0
	v_mfma_f32_16x16x32_bf16 v[22:25], v[160:163], v[198:201], 0
	v_mfma_f32_16x16x32_bf16 v[14:17], v[174:177], v[198:201], 0
	v_mfma_f32_16x16x32_bf16 v[6:9], v[160:163], v[206:209], 0
	v_mfma_f32_16x16x32_bf16 v[2:5], v[174:177], v[206:209], 0
	v_mfma_f32_16x16x32_bf16 v[54:57], v[164:167], v[186:189], v[54:57]
	v_mfma_f32_16x16x32_bf16 v[46:49], v[178:181], v[186:189], v[46:49]
	v_mfma_f32_16x16x32_bf16 v[38:41], v[164:167], v[194:197], v[38:41]
	v_mfma_f32_16x16x32_bf16 v[34:37], v[178:181], v[194:197], v[34:37]
	v_mfma_f32_16x16x32_bf16 v[22:25], v[164:167], v[202:205], v[22:25]
	v_mfma_f32_16x16x32_bf16 v[14:17], v[178:181], v[202:205], v[14:17]
	v_mfma_f32_16x16x32_bf16 v[6:9], v[164:167], v[210:213], v[6:9]
	s_barrier
	v_mfma_f32_16x16x32_bf16 v[2:5], v[178:181], v[210:213], v[2:5]
	s_setprio 2
	s_add_i32 s31, 0, 0x18000
	s_add_i32 s68, 0, 0x1c000
	v_add_u32_e32 v156, s31, v168
	v_add_u32_e32 v173, s68, v168
	ds_read_b128 v[144:147], v156
	ds_read_b128 v[148:151], v156 offset:1024
	ds_read_b128 v[152:155], v156 offset:2048
	ds_read_b128 v[156:159], v156 offset:3072
	ds_read_b128 v[160:163], v173
	ds_read_b128 v[164:167], v173 offset:1024
	ds_read_b128 v[174:177], v173 offset:2048
	ds_read_b128 v[178:181], v173 offset:3072
	s_add_u32 s28, s28, 0x160000
	s_addc_u32 s29, s29, 0
	s_mov_b32 m0, s36
	v_lshl_add_u64 v[222:223], s[28:29], 0, v[130:131]
	ds_read_b128 v[182:185], v172 offset:32768
	ds_read_b128 v[186:189], v172 offset:33792
	ds_read_b128 v[190:193], v172 offset:34816
	ds_read_b128 v[194:197], v172 offset:35840
	ds_read_b128 v[198:201], v172 offset:36864
	ds_read_b128 v[202:205], v172 offset:37888
	ds_read_b128 v[206:209], v172 offset:38912
	ds_read_b128 v[210:213], v172 offset:39936
	global_load_lds_dwordx4 v[222:223], off
	v_lshl_add_u64 v[222:223], s[28:29], 0, v[134:135]
	s_mov_b32 m0, s37
	s_nop 0
	global_load_lds_dwordx4 v[222:223], off
	s_waitcnt vmcnt(8)
	s_waitcnt lgkmcnt(0)
	s_barrier
	s_setprio 1
	s_waitcnt lgkmcnt(0)
	v_mfma_f32_16x16x32_bf16 v[126:129], v[144:147], v[182:185], v[126:129]
	v_mfma_f32_16x16x32_bf16 v[122:125], v[152:155], v[182:185], v[122:125]
	v_mfma_f32_16x16x32_bf16 v[118:121], v[144:147], v[190:193], v[118:121]
	v_mfma_f32_16x16x32_bf16 v[110:113], v[152:155], v[190:193], v[110:113]
	v_mfma_f32_16x16x32_bf16 v[94:97], v[144:147], v[198:201], v[94:97]
	v_mfma_f32_16x16x32_bf16 v[90:93], v[152:155], v[198:201], v[90:93]
	v_mfma_f32_16x16x32_bf16 v[82:85], v[144:147], v[206:209], v[82:85]
	v_mfma_f32_16x16x32_bf16 v[74:77], v[152:155], v[206:209], v[74:77]
	v_mfma_f32_16x16x32_bf16 v[126:129], v[148:151], v[186:189], v[126:129]
	v_mfma_f32_16x16x32_bf16 v[122:125], v[156:159], v[186:189], v[122:125]
	v_mfma_f32_16x16x32_bf16 v[118:121], v[148:151], v[194:197], v[118:121]
	v_mfma_f32_16x16x32_bf16 v[110:113], v[156:159], v[194:197], v[110:113]
	v_mfma_f32_16x16x32_bf16 v[94:97], v[148:151], v[202:205], v[94:97]
	v_mfma_f32_16x16x32_bf16 v[90:93], v[156:159], v[202:205], v[90:93]
	v_mfma_f32_16x16x32_bf16 v[82:85], v[148:151], v[210:213], v[82:85]
	v_mfma_f32_16x16x32_bf16 v[74:77], v[156:159], v[210:213], v[74:77]
	v_mfma_f32_16x16x32_bf16 v[114:117], v[160:163], v[182:185], v[114:117]
	v_mfma_f32_16x16x32_bf16 v[106:109], v[174:177], v[182:185], v[106:109]
	v_mfma_f32_16x16x32_bf16 v[102:105], v[160:163], v[190:193], v[102:105]
	v_mfma_f32_16x16x32_bf16 v[98:101], v[174:177], v[190:193], v[98:101]
	v_mfma_f32_16x16x32_bf16 v[86:89], v[160:163], v[198:201], v[86:89]
	v_mfma_f32_16x16x32_bf16 v[78:81], v[174:177], v[198:201], v[78:81]
	v_mfma_f32_16x16x32_bf16 v[70:73], v[160:163], v[206:209], v[70:73]
	v_mfma_f32_16x16x32_bf16 v[66:69], v[174:177], v[206:209], v[66:69]
	v_mfma_f32_16x16x32_bf16 v[114:117], v[164:167], v[186:189], v[114:117]
	v_mfma_f32_16x16x32_bf16 v[106:109], v[178:181], v[186:189], v[106:109]
	v_mfma_f32_16x16x32_bf16 v[102:105], v[164:167], v[194:197], v[102:105]
	v_mfma_f32_16x16x32_bf16 v[98:101], v[178:181], v[194:197], v[98:101]
	v_mfma_f32_16x16x32_bf16 v[86:89], v[164:167], v[202:205], v[86:89]
	v_mfma_f32_16x16x32_bf16 v[78:81], v[178:181], v[202:205], v[78:81]
	v_mfma_f32_16x16x32_bf16 v[70:73], v[164:167], v[210:213], v[70:73]
	s_barrier
	v_mfma_f32_16x16x32_bf16 v[66:69], v[178:181], v[210:213], v[66:69]
	s_setprio 2
	s_add_i32 s28, s31, s33
	v_lshl_add_u64 v[214:215], v[214:215], 0, s[12:13]
	s_mov_b32 m0, s28
	ds_read_b128 v[182:185], v172 offset:49152
	ds_read_b128 v[186:189], v172 offset:50176
	ds_read_b128 v[190:193], v172 offset:51200
	ds_read_b128 v[194:197], v172 offset:52224
	ds_read_b128 v[198:201], v172 offset:53248
	ds_read_b128 v[202:205], v172 offset:54272
	ds_read_b128 v[206:209], v172 offset:55296
	ds_read_b128 v[210:213], v172 offset:56320
	global_load_lds_dwordx4 v[214:215], off
	s_add_i32 m0, s28, 0x2000
	s_add_u32 s26, s26, 0x160080
	v_lshl_add_u64 v[214:215], v[216:217], 0, s[12:13]
	s_addc_u32 s27, s27, 0
	s_add_i32 s28, s68, s33
	global_load_lds_dwordx4 v[214:215], off
	v_lshl_add_u64 v[214:215], s[26:27], 0, v[132:133]
	s_mov_b32 m0, s28
	s_nop 0
	global_load_lds_dwordx4 v[214:215], off
	v_lshl_add_u64 v[214:215], s[26:27], 0, v[136:137]
	s_add_i32 m0, s28, 0x2000
	s_nop 0
	global_load_lds_dwordx4 v[214:215], off
	v_lshl_add_u64 v[214:215], v[218:219], 0, s[12:13]
	s_mov_b32 m0, s47
	s_nop 0
	global_load_lds_dwordx4 v[214:215], off
	v_lshl_add_u64 v[214:215], v[220:221], 0, s[12:13]
	s_mov_b32 m0, s48
	s_nop 0
	global_load_lds_dwordx4 v[214:215], off
	s_waitcnt vmcnt(8)
	s_waitcnt lgkmcnt(0)
	s_barrier
	s_setprio 1
	s_waitcnt lgkmcnt(0)
	v_mfma_f32_16x16x32_bf16 v[62:65], v[144:147], v[182:185], v[62:65]
	v_mfma_f32_16x16x32_bf16 v[58:61], v[152:155], v[182:185], v[58:61]
	v_mfma_f32_16x16x32_bf16 v[50:53], v[144:147], v[190:193], v[50:53]
	v_mfma_f32_16x16x32_bf16 v[42:45], v[152:155], v[190:193], v[42:45]
	v_mfma_f32_16x16x32_bf16 v[30:33], v[144:147], v[198:201], v[30:33]
	v_mfma_f32_16x16x32_bf16 v[26:29], v[152:155], v[198:201], v[26:29]
	v_mfma_f32_16x16x32_bf16 v[18:21], v[144:147], v[206:209], v[18:21]
	v_mfma_f32_16x16x32_bf16 v[10:13], v[152:155], v[206:209], v[10:13]
	v_mfma_f32_16x16x32_bf16 v[62:65], v[148:151], v[186:189], v[62:65]
	v_mfma_f32_16x16x32_bf16 v[58:61], v[156:159], v[186:189], v[58:61]
	v_mfma_f32_16x16x32_bf16 v[50:53], v[148:151], v[194:197], v[50:53]
	v_mfma_f32_16x16x32_bf16 v[42:45], v[156:159], v[194:197], v[42:45]
	v_mfma_f32_16x16x32_bf16 v[30:33], v[148:151], v[202:205], v[30:33]
	v_mfma_f32_16x16x32_bf16 v[26:29], v[156:159], v[202:205], v[26:29]
	v_mfma_f32_16x16x32_bf16 v[18:21], v[148:151], v[210:213], v[18:21]
	v_mfma_f32_16x16x32_bf16 v[10:13], v[156:159], v[210:213], v[10:13]
	v_mfma_f32_16x16x32_bf16 v[54:57], v[160:163], v[182:185], v[54:57]
	v_mfma_f32_16x16x32_bf16 v[46:49], v[174:177], v[182:185], v[46:49]
	v_mfma_f32_16x16x32_bf16 v[38:41], v[160:163], v[190:193], v[38:41]
	v_mfma_f32_16x16x32_bf16 v[34:37], v[174:177], v[190:193], v[34:37]
	v_mfma_f32_16x16x32_bf16 v[22:25], v[160:163], v[198:201], v[22:25]
	v_mfma_f32_16x16x32_bf16 v[14:17], v[174:177], v[198:201], v[14:17]
	v_mfma_f32_16x16x32_bf16 v[6:9], v[160:163], v[206:209], v[6:9]
	v_mfma_f32_16x16x32_bf16 v[2:5], v[174:177], v[206:209], v[2:5]
	v_mfma_f32_16x16x32_bf16 v[54:57], v[164:167], v[186:189], v[54:57]
	v_mfma_f32_16x16x32_bf16 v[46:49], v[178:181], v[186:189], v[46:49]
	v_mfma_f32_16x16x32_bf16 v[38:41], v[164:167], v[194:197], v[38:41]
	v_mfma_f32_16x16x32_bf16 v[34:37], v[178:181], v[194:197], v[34:37]
	v_mfma_f32_16x16x32_bf16 v[22:25], v[164:167], v[202:205], v[22:25]
	v_mfma_f32_16x16x32_bf16 v[14:17], v[178:181], v[202:205], v[14:17]
	v_mfma_f32_16x16x32_bf16 v[6:9], v[164:167], v[210:213], v[6:9]
	s_barrier
	v_mfma_f32_16x16x32_bf16 v[2:5], v[178:181], v[210:213], v[2:5]
	s_setprio 2
	s_add_u32 s24, s24, 0x100
	s_addc_u32 s25, s25, 0
	s_add_u32 s17, s17, 0x100
	s_addc_u32 s23, s23, 0
	s_cmp_ge_i32 s30, s67
	s_mov_b32 s26, s30
	s_cbranch_scc0 .LBB0_2683
	s_branch .Lpeeldone_0
.LBB0_2683:
	ds_read_b128 v[144:147], v170
	ds_read_b128 v[148:151], v170 offset:1024
	ds_read_b128 v[152:155], v170 offset:2048
	ds_read_b128 v[156:159], v170 offset:3072
	ds_read_b128 v[160:163], v171
	ds_read_b128 v[164:167], v171 offset:1024
	ds_read_b128 v[174:177], v171 offset:2048
	ds_read_b128 v[178:181], v171 offset:3072
	s_add_i32 s30, s26, 2
	s_add_u32 s27, s24, 0xffea0080
	s_addc_u32 s28, s25, -1
	s_cmp_eq_u32 s22, s26
	s_cselect_b32 s26, s20, s17
	s_cselect_b32 s29, s19, s28
	s_cselect_b32 s28, s18, s27
	s_cselect_b32 s27, s21, s23
	v_lshl_add_u64 v[214:215], s[24:25], 0, v[140:141]
	s_add_i32 m0, s34, 0xc000
	ds_read_b128 v[182:185], v172
	ds_read_b128 v[186:189], v172 offset:1024
	ds_read_b128 v[190:193], v172 offset:2048
	ds_read_b128 v[194:197], v172 offset:3072
	ds_read_b128 v[198:201], v172 offset:4096
	ds_read_b128 v[202:205], v172 offset:5120
	ds_read_b128 v[206:209], v172 offset:6144
	ds_read_b128 v[210:213], v172 offset:7168
	global_load_lds_dwordx4 v[214:215], off
	v_lshl_add_u64 v[214:215], s[24:25], 0, v[142:143]
	s_add_i32 m0, s34, 0xe000
	s_nop 0
	global_load_lds_dwordx4 v[214:215], off
	s_waitcnt vmcnt(8)
	s_waitcnt lgkmcnt(0)
	s_barrier
	s_setprio 1
	s_waitcnt lgkmcnt(0)
	v_mfma_f32_16x16x32_bf16 v[126:129], v[144:147], v[182:185], v[126:129]
	v_mfma_f32_16x16x32_bf16 v[122:125], v[152:155], v[182:185], v[122:125]
	v_mfma_f32_16x16x32_bf16 v[118:121], v[144:147], v[190:193], v[118:121]
	v_mfma_f32_16x16x32_bf16 v[110:113], v[152:155], v[190:193], v[110:113]
	v_mfma_f32_16x16x32_bf16 v[94:97], v[144:147], v[198:201], v[94:97]
	v_mfma_f32_16x16x32_bf16 v[90:93], v[152:155], v[198:201], v[90:93]
	v_mfma_f32_16x16x32_bf16 v[82:85], v[144:147], v[206:209], v[82:85]
	v_mfma_f32_16x16x32_bf16 v[74:77], v[152:155], v[206:209], v[74:77]
	v_mfma_f32_16x16x32_bf16 v[126:129], v[148:151], v[186:189], v[126:129]
	v_mfma_f32_16x16x32_bf16 v[122:125], v[156:159], v[186:189], v[122:125]
	v_mfma_f32_16x16x32_bf16 v[118:121], v[148:151], v[194:197], v[118:121]
	v_mfma_f32_16x16x32_bf16 v[110:113], v[156:159], v[194:197], v[110:113]
	v_mfma_f32_16x16x32_bf16 v[94:97], v[148:151], v[202:205], v[94:97]
	v_mfma_f32_16x16x32_bf16 v[90:93], v[156:159], v[202:205], v[90:93]
	v_mfma_f32_16x16x32_bf16 v[82:85], v[148:151], v[210:213], v[82:85]
	v_mfma_f32_16x16x32_bf16 v[74:77], v[156:159], v[210:213], v[74:77]
	v_mfma_f32_16x16x32_bf16 v[114:117], v[160:163], v[182:185], v[114:117]
	v_mfma_f32_16x16x32_bf16 v[106:109], v[174:177], v[182:185], v[106:109]
	v_mfma_f32_16x16x32_bf16 v[102:105], v[160:163], v[190:193], v[102:105]
	v_mfma_f32_16x16x32_bf16 v[98:101], v[174:177], v[190:193], v[98:101]
	v_mfma_f32_16x16x32_bf16 v[86:89], v[160:163], v[198:201], v[86:89]
	v_mfma_f32_16x16x32_bf16 v[78:81], v[174:177], v[198:201], v[78:81]
	v_mfma_f32_16x16x32_bf16 v[70:73], v[160:163], v[206:209], v[70:73]
	v_mfma_f32_16x16x32_bf16 v[66:69], v[174:177], v[206:209], v[66:69]
	v_mfma_f32_16x16x32_bf16 v[114:117], v[164:167], v[186:189], v[114:117]
	v_mfma_f32_16x16x32_bf16 v[106:109], v[178:181], v[186:189], v[106:109]
	v_mfma_f32_16x16x32_bf16 v[102:105], v[164:167], v[194:197], v[102:105]
	v_mfma_f32_16x16x32_bf16 v[98:101], v[178:181], v[194:197], v[98:101]
	v_mfma_f32_16x16x32_bf16 v[86:89], v[164:167], v[202:205], v[86:89]
	v_mfma_f32_16x16x32_bf16 v[78:81], v[178:181], v[202:205], v[78:81]
	v_mfma_f32_16x16x32_bf16 v[70:73], v[164:167], v[210:213], v[70:73]
	s_barrier
	v_mfma_f32_16x16x32_bf16 v[66:69], v[178:181], v[210:213], v[66:69]
	s_setprio 2
	s_add_i32 s31, s57, s33
	v_lshl_add_u64 v[214:215], s[26:27], 0, v[132:133]
	s_mov_b32 m0, s31
	ds_read_b128 v[182:185], v172 offset:16384
	ds_read_b128 v[186:189], v172 offset:17408
	ds_read_b128 v[190:193], v172 offset:18432
	ds_read_b128 v[194:197], v172 offset:19456
	ds_read_b128 v[198:201], v172 offset:20480
	ds_read_b128 v[202:205], v172 offset:21504
	ds_read_b128 v[206:209], v172 offset:22528
	ds_read_b128 v[210:213], v172 offset:23552
	global_load_lds_dwordx4 v[214:215], off
	s_add_i32 m0, s31, 0x2000
	s_add_u32 s68, s26, 0x160000
	v_lshl_add_u64 v[216:217], s[26:27], 0, v[136:137]
	s_addc_u32 s69, s27, 0
	s_add_i32 s31, s58, s33
	global_load_lds_dwordx4 v[216:217], off
	v_lshl_add_u64 v[218:219], s[68:69], 0, v[132:133]
	s_mov_b32 m0, s31
	v_lshl_add_u64 v[220:221], s[28:29], 0, v[134:135]
	global_load_lds_dwordx4 v[218:219], off
	v_lshl_add_u64 v[218:219], s[68:69], 0, v[136:137]
	s_add_i32 m0, s31, 0x2000
	s_nop 0
	global_load_lds_dwordx4 v[218:219], off
	v_lshl_add_u64 v[218:219], s[28:29], 0, v[130:131]
	s_mov_b32 m0, s34
	s_nop 0
	global_load_lds_dwordx4 v[218:219], off
	s_mov_b32 m0, s35
	s_nop 0
	global_load_lds_dwordx4 v[220:221], off
	s_waitcnt vmcnt(8)
	s_waitcnt lgkmcnt(0)
	s_barrier
	s_setprio 1
	s_waitcnt lgkmcnt(0)
	v_mfma_f32_16x16x32_bf16 v[62:65], v[144:147], v[182:185], v[62:65]
	v_mfma_f32_16x16x32_bf16 v[58:61], v[152:155], v[182:185], v[58:61]
	v_mfma_f32_16x16x32_bf16 v[50:53], v[144:147], v[190:193], v[50:53]
	v_mfma_f32_16x16x32_bf16 v[42:45], v[152:155], v[190:193], v[42:45]
	v_mfma_f32_16x16x32_bf16 v[30:33], v[144:147], v[198:201], v[30:33]
	v_mfma_f32_16x16x32_bf16 v[26:29], v[152:155], v[198:201], v[26:29]
	v_mfma_f32_16x16x32_bf16 v[18:21], v[144:147], v[206:209], v[18:21]
	v_mfma_f32_16x16x32_bf16 v[10:13], v[152:155], v[206:209], v[10:13]
	v_mfma_f32_16x16x32_bf16 v[62:65], v[148:151], v[186:189], v[62:65]
	v_mfma_f32_16x16x32_bf16 v[58:61], v[156:159], v[186:189], v[58:61]
	v_mfma_f32_16x16x32_bf16 v[50:53], v[148:151], v[194:197], v[50:53]
	v_mfma_f32_16x16x32_bf16 v[42:45], v[156:159], v[194:197], v[42:45]
	v_mfma_f32_16x16x32_bf16 v[30:33], v[148:151], v[202:205], v[30:33]
	v_mfma_f32_16x16x32_bf16 v[26:29], v[156:159], v[202:205], v[26:29]
	v_mfma_f32_16x16x32_bf16 v[18:21], v[148:151], v[210:213], v[18:21]
	v_mfma_f32_16x16x32_bf16 v[10:13], v[156:159], v[210:213], v[10:13]
	v_mfma_f32_16x16x32_bf16 v[54:57], v[160:163], v[182:185], v[54:57]
	v_mfma_f32_16x16x32_bf16 v[46:49], v[174:177], v[182:185], v[46:49]
	v_mfma_f32_16x16x32_bf16 v[38:41], v[160:163], v[190:193], v[38:41]
	v_mfma_f32_16x16x32_bf16 v[34:37], v[174:177], v[190:193], v[34:37]
	v_mfma_f32_16x16x32_bf16 v[22:25], v[160:163], v[198:201], v[22:25]
	v_mfma_f32_16x16x32_bf16 v[14:17], v[174:177], v[198:201], v[14:17]
	v_mfma_f32_16x16x32_bf16 v[6:9], v[160:163], v[206:209], v[6:9]
	v_mfma_f32_16x16x32_bf16 v[2:5], v[174:177], v[206:209], v[2:5]
	v_mfma_f32_16x16x32_bf16 v[54:57], v[164:167], v[186:189], v[54:57]
	v_mfma_f32_16x16x32_bf16 v[46:49], v[178:181], v[186:189], v[46:49]
	v_mfma_f32_16x16x32_bf16 v[38:41], v[164:167], v[194:197], v[38:41]
	v_mfma_f32_16x16x32_bf16 v[34:37], v[178:181], v[194:197], v[34:37]
	v_mfma_f32_16x16x32_bf16 v[22:25], v[164:167], v[202:205], v[22:25]
	v_mfma_f32_16x16x32_bf16 v[14:17], v[178:181], v[202:205], v[14:17]
	v_mfma_f32_16x16x32_bf16 v[6:9], v[164:167], v[210:213], v[6:9]
	s_barrier
	v_mfma_f32_16x16x32_bf16 v[2:5], v[178:181], v[210:213], v[2:5]
	s_setprio 2
	s_add_i32 s31, 0, 0x18000
	s_add_i32 s68, 0, 0x1c000
	v_add_u32_e32 v156, s31, v168
	v_add_u32_e32 v173, s68, v168
	ds_read_b128 v[144:147], v156
	ds_read_b128 v[148:151], v156 offset:1024
	ds_read_b128 v[152:155], v156 offset:2048
	ds_read_b128 v[156:159], v156 offset:3072
	ds_read_b128 v[160:163], v173
	ds_read_b128 v[164:167], v173 offset:1024
	ds_read_b128 v[174:177], v173 offset:2048
	ds_read_b128 v[178:181], v173 offset:3072
	s_add_u32 s28, s28, 0x160000
	s_addc_u32 s29, s29, 0
	s_mov_b32 m0, s36
	v_lshl_add_u64 v[222:223], s[28:29], 0, v[130:131]
	ds_read_b128 v[182:185], v172 offset:32768
	ds_read_b128 v[186:189], v172 offset:33792
	ds_read_b128 v[190:193], v172 offset:34816
	ds_read_b128 v[194:197], v172 offset:35840
	ds_read_b128 v[198:201], v172 offset:36864
	ds_read_b128 v[202:205], v172 offset:37888
	ds_read_b128 v[206:209], v172 offset:38912
	ds_read_b128 v[210:213], v172 offset:39936
	global_load_lds_dwordx4 v[222:223], off
	v_lshl_add_u64 v[222:223], s[28:29], 0, v[134:135]
	s_mov_b32 m0, s37
	s_nop 0
	global_load_lds_dwordx4 v[222:223], off
	s_waitcnt vmcnt(8)
	s_waitcnt lgkmcnt(0)
	s_barrier
	s_setprio 1
	s_waitcnt lgkmcnt(0)
	v_mfma_f32_16x16x32_bf16 v[126:129], v[144:147], v[182:185], v[126:129]
	v_mfma_f32_16x16x32_bf16 v[122:125], v[152:155], v[182:185], v[122:125]
	v_mfma_f32_16x16x32_bf16 v[118:121], v[144:147], v[190:193], v[118:121]
	v_mfma_f32_16x16x32_bf16 v[110:113], v[152:155], v[190:193], v[110:113]
	v_mfma_f32_16x16x32_bf16 v[94:97], v[144:147], v[198:201], v[94:97]
	v_mfma_f32_16x16x32_bf16 v[90:93], v[152:155], v[198:201], v[90:93]
	v_mfma_f32_16x16x32_bf16 v[82:85], v[144:147], v[206:209], v[82:85]
	v_mfma_f32_16x16x32_bf16 v[74:77], v[152:155], v[206:209], v[74:77]
	v_mfma_f32_16x16x32_bf16 v[126:129], v[148:151], v[186:189], v[126:129]
	v_mfma_f32_16x16x32_bf16 v[122:125], v[156:159], v[186:189], v[122:125]
	v_mfma_f32_16x16x32_bf16 v[118:121], v[148:151], v[194:197], v[118:121]
	v_mfma_f32_16x16x32_bf16 v[110:113], v[156:159], v[194:197], v[110:113]
	v_mfma_f32_16x16x32_bf16 v[94:97], v[148:151], v[202:205], v[94:97]
	v_mfma_f32_16x16x32_bf16 v[90:93], v[156:159], v[202:205], v[90:93]
	v_mfma_f32_16x16x32_bf16 v[82:85], v[148:151], v[210:213], v[82:85]
	v_mfma_f32_16x16x32_bf16 v[74:77], v[156:159], v[210:213], v[74:77]
	v_mfma_f32_16x16x32_bf16 v[114:117], v[160:163], v[182:185], v[114:117]
	v_mfma_f32_16x16x32_bf16 v[106:109], v[174:177], v[182:185], v[106:109]
	v_mfma_f32_16x16x32_bf16 v[102:105], v[160:163], v[190:193], v[102:105]
	v_mfma_f32_16x16x32_bf16 v[98:101], v[174:177], v[190:193], v[98:101]
	v_mfma_f32_16x16x32_bf16 v[86:89], v[160:163], v[198:201], v[86:89]
	v_mfma_f32_16x16x32_bf16 v[78:81], v[174:177], v[198:201], v[78:81]
	v_mfma_f32_16x16x32_bf16 v[70:73], v[160:163], v[206:209], v[70:73]
	v_mfma_f32_16x16x32_bf16 v[66:69], v[174:177], v[206:209], v[66:69]
	v_mfma_f32_16x16x32_bf16 v[114:117], v[164:167], v[186:189], v[114:117]
	v_mfma_f32_16x16x32_bf16 v[106:109], v[178:181], v[186:189], v[106:109]
	v_mfma_f32_16x16x32_bf16 v[102:105], v[164:167], v[194:197], v[102:105]
	v_mfma_f32_16x16x32_bf16 v[98:101], v[178:181], v[194:197], v[98:101]
	v_mfma_f32_16x16x32_bf16 v[86:89], v[164:167], v[202:205], v[86:89]
	v_mfma_f32_16x16x32_bf16 v[78:81], v[178:181], v[202:205], v[78:81]
	v_mfma_f32_16x16x32_bf16 v[70:73], v[164:167], v[210:213], v[70:73]
	s_barrier
	v_mfma_f32_16x16x32_bf16 v[66:69], v[178:181], v[210:213], v[66:69]
	s_setprio 2
	s_add_i32 s28, s31, s33
	v_lshl_add_u64 v[214:215], v[214:215], 0, s[12:13]
	s_mov_b32 m0, s28
	ds_read_b128 v[182:185], v172 offset:49152
	ds_read_b128 v[186:189], v172 offset:50176
	ds_read_b128 v[190:193], v172 offset:51200
	ds_read_b128 v[194:197], v172 offset:52224
	ds_read_b128 v[198:201], v172 offset:53248
	ds_read_b128 v[202:205], v172 offset:54272
	ds_read_b128 v[206:209], v172 offset:55296
	ds_read_b128 v[210:213], v172 offset:56320
	global_load_lds_dwordx4 v[214:215], off
	s_add_i32 m0, s28, 0x2000
	s_add_u32 s26, s26, 0x160080
	v_lshl_add_u64 v[214:215], v[216:217], 0, s[12:13]
	s_addc_u32 s27, s27, 0
	s_add_i32 s28, s68, s33
	global_load_lds_dwordx4 v[214:215], off
	v_lshl_add_u64 v[214:215], s[26:27], 0, v[132:133]
	s_mov_b32 m0, s28
	s_nop 0
	global_load_lds_dwordx4 v[214:215], off
	v_lshl_add_u64 v[214:215], s[26:27], 0, v[136:137]
	s_add_i32 m0, s28, 0x2000
	s_nop 0
	global_load_lds_dwordx4 v[214:215], off
	v_lshl_add_u64 v[214:215], v[218:219], 0, s[12:13]
	s_mov_b32 m0, s47
	s_nop 0
	global_load_lds_dwordx4 v[214:215], off
	v_lshl_add_u64 v[214:215], v[220:221], 0, s[12:13]
	s_mov_b32 m0, s48
	s_nop 0
	global_load_lds_dwordx4 v[214:215], off
	s_waitcnt vmcnt(8)
	s_waitcnt lgkmcnt(0)
	s_barrier
	s_setprio 1
	s_waitcnt lgkmcnt(0)
	v_mfma_f32_16x16x32_bf16 v[62:65], v[144:147], v[182:185], v[62:65]
	v_mfma_f32_16x16x32_bf16 v[58:61], v[152:155], v[182:185], v[58:61]
	v_mfma_f32_16x16x32_bf16 v[50:53], v[144:147], v[190:193], v[50:53]
	v_mfma_f32_16x16x32_bf16 v[42:45], v[152:155], v[190:193], v[42:45]
	v_mfma_f32_16x16x32_bf16 v[30:33], v[144:147], v[198:201], v[30:33]
	v_mfma_f32_16x16x32_bf16 v[26:29], v[152:155], v[198:201], v[26:29]
	v_mfma_f32_16x16x32_bf16 v[18:21], v[144:147], v[206:209], v[18:21]
	v_mfma_f32_16x16x32_bf16 v[10:13], v[152:155], v[206:209], v[10:13]
	v_mfma_f32_16x16x32_bf16 v[62:65], v[148:151], v[186:189], v[62:65]
	v_mfma_f32_16x16x32_bf16 v[58:61], v[156:159], v[186:189], v[58:61]
	v_mfma_f32_16x16x32_bf16 v[50:53], v[148:151], v[194:197], v[50:53]
	v_mfma_f32_16x16x32_bf16 v[42:45], v[156:159], v[194:197], v[42:45]
	v_mfma_f32_16x16x32_bf16 v[30:33], v[148:151], v[202:205], v[30:33]
	v_mfma_f32_16x16x32_bf16 v[26:29], v[156:159], v[202:205], v[26:29]
	v_mfma_f32_16x16x32_bf16 v[18:21], v[148:151], v[210:213], v[18:21]
	v_mfma_f32_16x16x32_bf16 v[10:13], v[156:159], v[210:213], v[10:13]
	v_mfma_f32_16x16x32_bf16 v[54:57], v[160:163], v[182:185], v[54:57]
	v_mfma_f32_16x16x32_bf16 v[46:49], v[174:177], v[182:185], v[46:49]
	v_mfma_f32_16x16x32_bf16 v[38:41], v[160:163], v[190:193], v[38:41]
	v_mfma_f32_16x16x32_bf16 v[34:37], v[174:177], v[190:193], v[34:37]
	v_mfma_f32_16x16x32_bf16 v[22:25], v[160:163], v[198:201], v[22:25]
	v_mfma_f32_16x16x32_bf16 v[14:17], v[174:177], v[198:201], v[14:17]
	v_mfma_f32_16x16x32_bf16 v[6:9], v[160:163], v[206:209], v[6:9]
	v_mfma_f32_16x16x32_bf16 v[2:5], v[174:177], v[206:209], v[2:5]
	v_mfma_f32_16x16x32_bf16 v[54:57], v[164:167], v[186:189], v[54:57]
	v_mfma_f32_16x16x32_bf16 v[46:49], v[178:181], v[186:189], v[46:49]
	v_mfma_f32_16x16x32_bf16 v[38:41], v[164:167], v[194:197], v[38:41]
	v_mfma_f32_16x16x32_bf16 v[34:37], v[178:181], v[194:197], v[34:37]
	v_mfma_f32_16x16x32_bf16 v[22:25], v[164:167], v[202:205], v[22:25]
	v_mfma_f32_16x16x32_bf16 v[14:17], v[178:181], v[202:205], v[14:17]
	v_mfma_f32_16x16x32_bf16 v[6:9], v[164:167], v[210:213], v[6:9]
	s_barrier
	v_mfma_f32_16x16x32_bf16 v[2:5], v[178:181], v[210:213], v[2:5]
	s_setprio 2
	s_add_u32 s24, s24, 0x100
	s_addc_u32 s25, s25, 0
	s_add_u32 s17, s17, 0x100
	s_addc_u32 s23, s23, 0
	s_cmp_ge_i32 s30, s67
	s_mov_b32 s26, s30
	s_cbranch_scc0 .LBB0_2683
